# GEMM core K-loop rotated: second k16 half of tile k-1 runs right after the barrier from registers while the LDS reads of tile k are in flight (no exposed LDS latency), DMA issue moved right behind the
# speedup vs baseline: 1.1070x; 1.0049x over previous
; #define MFMA32(a, b, c) __builtin_amdgcn_mfma_f32_32x32x16_bf16((a), (b), (c), 0, 0, 0)
; #define GA_LOAD(pr_) do { _Pragma("unroll") for (int i = 0; i < 4; ++i) ra[i] = *(const u32x4*)(Ab + (i * 32) * lda + (pr_) * 64); } while (0)
; #define GB_LOAD(kt_) do { const bfr* bk_ = Bb + (kt_) * NB * 32; \
;     _Pragma("unroll") for (int i = 0; i < 4; ++i) rb[i] = *(const u32x4*)(bk_ + (i * 64) * 32); } while (0)
; #define G_STORE(kt_) do { bfr* as_ = S0 + ((kt_) & 1) * GSTAGE; bfr* bs_ = as_ + 128 * 40; \
;     if (apar == ((kt_) & 1)) { _Pragma("unroll") for (int i = 0; i < 4; ++i) *(u32x4*)(as_ + asoff + i * 32 * 40) = ra[i]; } \
;     _Pragma("unroll") for (int i = 0; i < 4; ++i) *(u32x4*)(bs_ + bsoff + i * 64 * 40) = rb[i]; } while (0)
; template <int lda>
; DI void gemm_mainloop(const bfr* __restrict__ A, const bfr* __restrict__ Bt, int NB, int K, int m0, int n0, char* smem, f32x16 (&acc)[2][4]) {
;     ...
; #pragma unroll
;   for (int i = 0; i < 2; ++i)
; #pragma unroll
;     for (int j = 0; j < 4; ++j)
; #pragma unroll
;       for (int q = 0; q < 16; ++q) acc[i][j][q] = 0.f;
;     ...
;   for (int kt = 0; kt < nk; ++kt) {
;     if (kt + 1 < nk) G_STORE(kt + 1);
;     if (kt + 2 < nk) {
;       GB_LOAD(kt + 2);
;       if ((kt & 1) == 0) GA_LOAD((kt >> 1) + 1);
;     }
;     const bfr* As = S0 + (kt & 1) * GSTAGE;
;     const bfr* Bs = As + 128 * 40;
; #pragma unroll
;     for (int ks = 0; ks < 2; ++ks) {
;       bf16x8 af[2], bfg[4];
; #pragma unroll
;       for (int i = 0; i < 2; ++i) af[i] = *(const bf16x8*)(As + (wr * 64 + i * 32 + r) * 40 + ks * 16 + hl * 8);
; #pragma unroll
;       for (int j = 0; j < 4; ++j) bfg[j] = *(const bf16x8*)(Bs + (wc * 128 + j * 32 + r) * 40 + ks * 16 + hl * 8);
; #pragma unroll
;       for (int i = 0; i < 2; ++i)
; #pragma unroll
;         for (int j = 0; j < 4; ++j) acc[i][j] = MFMA32(af[i], bfg[j], acc[i][j]);
;     }
.Lp1v_nostag:
	v_mov_b32_e32 v112, 0
	v_mov_b32_e32 v113, 0
	v_mov_b32_e32 v114, 0
	v_mov_b32_e32 v115, 0
	v_mov_b32_e32 v116, 0
	v_mov_b32_e32 v117, 0
	v_mov_b32_e32 v118, 0
	v_mov_b32_e32 v119, 0
	v_mov_b32_e32 v120, 0
	v_mov_b32_e32 v121, 0
	v_mov_b32_e32 v122, 0
	v_mov_b32_e32 v123, 0
	v_mov_b32_e32 v124, 0
	v_mov_b32_e32 v125, 0
	v_mov_b32_e32 v126, 0
	v_mov_b32_e32 v127, 0
	v_mov_b32_e32 v96, 0
	v_mov_b32_e32 v97, 0
	v_mov_b32_e32 v98, 0
	v_mov_b32_e32 v99, 0
	v_mov_b32_e32 v100, 0
	v_mov_b32_e32 v101, 0
	v_mov_b32_e32 v102, 0
	v_mov_b32_e32 v103, 0
	v_mov_b32_e32 v104, 0
	v_mov_b32_e32 v105, 0
	v_mov_b32_e32 v106, 0
	v_mov_b32_e32 v107, 0
	v_mov_b32_e32 v108, 0
	v_mov_b32_e32 v109, 0
	v_mov_b32_e32 v110, 0
	v_mov_b32_e32 v111, 0
	v_mov_b32_e32 v80, 0
	v_mov_b32_e32 v81, 0
	v_mov_b32_e32 v82, 0
	v_mov_b32_e32 v83, 0
	v_mov_b32_e32 v84, 0
	v_mov_b32_e32 v85, 0
	v_mov_b32_e32 v86, 0
	v_mov_b32_e32 v87, 0
	v_mov_b32_e32 v88, 0
	v_mov_b32_e32 v89, 0
	v_mov_b32_e32 v90, 0
	v_mov_b32_e32 v91, 0
	v_mov_b32_e32 v92, 0
	v_mov_b32_e32 v93, 0
	v_mov_b32_e32 v94, 0
	v_mov_b32_e32 v95, 0
	v_mov_b32_e32 v64, 0
	v_mov_b32_e32 v65, 0
	v_mov_b32_e32 v66, 0
	v_mov_b32_e32 v67, 0
	v_mov_b32_e32 v68, 0
	v_mov_b32_e32 v69, 0
	v_mov_b32_e32 v70, 0
	v_mov_b32_e32 v71, 0
	v_mov_b32_e32 v72, 0
	v_mov_b32_e32 v73, 0
	v_mov_b32_e32 v74, 0
	v_mov_b32_e32 v75, 0
	v_mov_b32_e32 v76, 0
	v_mov_b32_e32 v77, 0
	v_mov_b32_e32 v78, 0
	v_mov_b32_e32 v79, 0
	v_mov_b32_e32 v48, 0
	v_mov_b32_e32 v49, 0
	v_mov_b32_e32 v50, 0
	v_mov_b32_e32 v51, 0
	v_mov_b32_e32 v52, 0
	v_mov_b32_e32 v53, 0
	v_mov_b32_e32 v54, 0
	v_mov_b32_e32 v55, 0
	v_mov_b32_e32 v56, 0
	v_mov_b32_e32 v57, 0
	v_mov_b32_e32 v58, 0
	v_mov_b32_e32 v59, 0
	v_mov_b32_e32 v60, 0
	v_mov_b32_e32 v61, 0
	v_mov_b32_e32 v62, 0
	v_mov_b32_e32 v63, 0
	v_mov_b32_e32 v32, 0
	v_mov_b32_e32 v33, 0
	v_mov_b32_e32 v34, 0
	v_mov_b32_e32 v35, 0
	v_mov_b32_e32 v36, 0
	v_mov_b32_e32 v37, 0
	v_mov_b32_e32 v38, 0
	v_mov_b32_e32 v39, 0
	v_mov_b32_e32 v40, 0
	v_mov_b32_e32 v41, 0
	v_mov_b32_e32 v42, 0
	v_mov_b32_e32 v43, 0
	v_mov_b32_e32 v44, 0
	v_mov_b32_e32 v45, 0
	v_mov_b32_e32 v46, 0
	v_mov_b32_e32 v47, 0
	v_mov_b32_e32 v16, 0
	v_mov_b32_e32 v17, 0
	v_mov_b32_e32 v18, 0
	v_mov_b32_e32 v19, 0
	v_mov_b32_e32 v20, 0
	v_mov_b32_e32 v21, 0
	v_mov_b32_e32 v22, 0
	v_mov_b32_e32 v23, 0
	v_mov_b32_e32 v24, 0
	v_mov_b32_e32 v25, 0
	v_mov_b32_e32 v26, 0
	v_mov_b32_e32 v27, 0
	v_mov_b32_e32 v28, 0
	v_mov_b32_e32 v29, 0
	v_mov_b32_e32 v30, 0
	v_mov_b32_e32 v31, 0
	v_mov_b32_e32 v0, 0
	v_mov_b32_e32 v1, 0
	v_mov_b32_e32 v2, 0
	v_mov_b32_e32 v3, 0
	v_mov_b32_e32 v4, 0
	v_mov_b32_e32 v5, 0
	v_mov_b32_e32 v6, 0
	v_mov_b32_e32 v7, 0
	v_mov_b32_e32 v8, 0
	v_mov_b32_e32 v9, 0
	v_mov_b32_e32 v10, 0
	v_mov_b32_e32 v11, 0
	v_mov_b32_e32 v12, 0
	v_mov_b32_e32 v13, 0
	v_mov_b32_e32 v14, 0
	v_mov_b32_e32 v15, 0
	s_waitcnt vmcnt(6)
	s_barrier
	s_mul_i32 s74, s71, 0x6000
	s_add_u32 s75, s74, 0x2000
	s_cmp_eq_u32 s71, 2
	s_cselect_b32 s75, 0x10000, s75
	v_add_u32_e32 v184, s74, v180
	v_add_u32_e32 v186, s75, v182
	v_add_u32_e32 v185, s74, v181
	v_add_u32_e32 v187, s75, v183
	s_add_u32 s71, s71, 1
	s_cmp_eq_u32 s71, 3
	s_cselect_b32 s71, 0, s71
	ds_read_b128 v[128:131], v184
	ds_read_b128 v[144:147], v186
	ds_read_b128 v[148:151], v186 offset:2048
	ds_read_b128 v[152:155], v186 offset:4096
	ds_read_b128 v[156:159], v186 offset:6144
	ds_read_b128 v[132:135], v184 offset:2048
	ds_read_b128 v[136:139], v185
	ds_read_b128 v[164:167], v187
	ds_read_b128 v[168:171], v187 offset:2048
	ds_read_b128 v[172:175], v187 offset:4096
	ds_read_b128 v[176:179], v187 offset:6144
	ds_read_b128 v[140:143], v185 offset:2048
	s_waitcnt lgkmcnt(10)
	v_mfma_f32_32x32x16_bf16 v[112:127], v[128:131], v[144:147], v[112:127]
	s_mul_i32 s74, s70, 0x6000
	s_add_u32 s75, s74, s68
	s_mov_b32 m0, s75
	s_add_u32 s76, s74, 0x2000
	s_cmp_eq_u32 s70, 2
	s_cselect_b32 s76, 0x10000, s76
	global_load_lds_dwordx4 v160, s[64:65]
	s_waitcnt lgkmcnt(9)
	v_mfma_f32_32x32x16_bf16 v[96:111], v[128:131], v[148:151], v[96:111]
	s_add_u32 m0, s75, 0x400
	s_add_u32 s76, s76, s69
	global_load_lds_dwordx4 v162, s[64:65]
	s_waitcnt lgkmcnt(8)
	v_mfma_f32_32x32x16_bf16 v[80:95], v[128:131], v[152:155], v[80:95]
	s_mov_b32 m0, s76
	s_add_u32 s64, s64, 64
	s_addc_u32 s65, s65, 0
	global_load_lds_dwordx4 v163, s[66:67]
	s_waitcnt lgkmcnt(7)
	v_mfma_f32_32x32x16_bf16 v[64:79], v[128:131], v[156:159], v[64:79]
	global_load_lds_dwordx4 v163, s[66:67] offset:1024
	s_waitcnt lgkmcnt(6)
	v_mfma_f32_32x32x16_bf16 v[48:63], v[132:135], v[144:147], v[48:63]
	global_load_lds_dwordx4 v163, s[66:67] offset:2048
	v_mfma_f32_32x32x16_bf16 v[32:47], v[132:135], v[148:151], v[32:47]
	global_load_lds_dwordx4 v163, s[66:67] offset:3072
	s_add_u32 s66, s66, 0x10000
	s_addc_u32 s67, s67, 0
	v_mfma_f32_32x32x16_bf16 v[16:31], v[132:135], v[152:155], v[16:31]
	s_add_u32 s70, s70, 1
	s_cmp_eq_u32 s70, 3
	s_cselect_b32 s70, 0, s70
	v_mfma_f32_32x32x16_bf16 v[0:15], v[132:135], v[156:159], v[0:15]
; #define MFMA32(a, b, c) __builtin_amdgcn_mfma_f32_32x32x16_bf16((a), (b), (c), 0, 0, 0)
; #define GA_LOAD(pr_) do { _Pragma("unroll") for (int i = 0; i < 4; ++i) ra[i] = *(const u32x4*)(Ab + (i * 32) * lda + (pr_) * 64); } while (0)
; #define GB_LOAD(kt_) do { const bfr* bk_ = Bb + (kt_) * NB * 32; \
;     _Pragma("unroll") for (int i = 0; i < 4; ++i) rb[i] = *(const u32x4*)(bk_ + (i * 64) * 32); } while (0)
; #define G_STORE(kt_) do { bfr* as_ = S0 + ((kt_) & 1) * GSTAGE; bfr* bs_ = as_ + 128 * 40; \
;     if (apar == ((kt_) & 1)) { _Pragma("unroll") for (int i = 0; i < 4; ++i) *(u32x4*)(as_ + asoff + i * 32 * 40) = ra[i]; } \
;     _Pragma("unroll") for (int i = 0; i < 4; ++i) *(u32x4*)(bs_ + bsoff + i * 64 * 40) = rb[i]; } while (0)
; template <int lda>
; DI void gemm_mainloop(const bfr* __restrict__ A, const bfr* __restrict__ Bt, int NB, int K, int m0, int n0, char* smem, f32x16 (&acc)[2][4]) {
;     ...
;   for (int kt = 0; kt < nk; ++kt) {
;     if (kt + 1 < nk) G_STORE(kt + 1);
;     if (kt + 2 < nk) {
;       GB_LOAD(kt + 2);
;       if ((kt & 1) == 0) GA_LOAD((kt >> 1) + 1);
;     }
;     const bfr* As = S0 + (kt & 1) * GSTAGE;
;     const bfr* Bs = As + 128 * 40;
; #pragma unroll
;     for (int ks = 0; ks < 2; ++ks) {
;       bf16x8 af[2], bfg[4];
; #pragma unroll
;       for (int i = 0; i < 2; ++i) af[i] = *(const bf16x8*)(As + (wr * 64 + i * 32 + r) * 40 + ks * 16 + hl * 8);
; #pragma unroll
;       for (int j = 0; j < 4; ++j) bfg[j] = *(const bf16x8*)(Bs + (wc * 128 + j * 32 + r) * 40 + ks * 16 + hl * 8);
; #pragma unroll
;       for (int i = 0; i < 2; ++i)
; #pragma unroll
;         for (int j = 0; j < 4; ++j) acc[i][j] = MFMA32(af[i], bfg[j], acc[i][j]);
;     }
;     __syncthreads();
;   }
.Lp1v_loop:
	s_waitcnt vmcnt(6) lgkmcnt(0)
	s_barrier
	s_mul_i32 s74, s71, 0x6000
	s_add_u32 s75, s74, 0x2000
	s_cmp_eq_u32 s71, 2
	s_cselect_b32 s75, 0x10000, s75
	v_add_u32_e32 v184, s74, v180
	v_add_u32_e32 v186, s75, v182
	v_add_u32_e32 v185, s74, v181
	v_add_u32_e32 v187, s75, v183
	s_add_u32 s71, s71, 1
	s_cmp_eq_u32 s71, 3
	s_cselect_b32 s71, 0, s71
	ds_read_b128 v[128:131], v184
	ds_read_b128 v[144:147], v186
	ds_read_b128 v[148:151], v186 offset:2048
	ds_read_b128 v[152:155], v186 offset:4096
	ds_read_b128 v[156:159], v186 offset:6144
	ds_read_b128 v[132:135], v184 offset:2048
	v_mfma_f32_32x32x16_bf16 v[112:127], v[136:139], v[164:167], v[112:127]
	s_mul_i32 s74, s70, 0x6000
	s_add_u32 s75, s74, s68
	s_mov_b32 m0, s75
	s_add_u32 s76, s74, 0x2000
	s_cmp_eq_u32 s70, 2
	s_cselect_b32 s76, 0x10000, s76
	global_load_lds_dwordx4 v160, s[64:65]
	v_mfma_f32_32x32x16_bf16 v[96:111], v[136:139], v[168:171], v[96:111]
	s_add_u32 m0, s75, 0x400
	s_add_u32 s76, s76, s69
	global_load_lds_dwordx4 v162, s[64:65]
	v_mfma_f32_32x32x16_bf16 v[80:95], v[136:139], v[172:175], v[80:95]
	s_mov_b32 m0, s76
	s_add_u32 s64, s64, 64
	s_addc_u32 s65, s65, 0
	global_load_lds_dwordx4 v163, s[66:67]
	v_mfma_f32_32x32x16_bf16 v[64:79], v[136:139], v[176:179], v[64:79]
	global_load_lds_dwordx4 v163, s[66:67] offset:1024
	v_mfma_f32_32x32x16_bf16 v[48:63], v[140:143], v[164:167], v[48:63]
	global_load_lds_dwordx4 v163, s[66:67] offset:2048
	v_mfma_f32_32x32x16_bf16 v[32:47], v[140:143], v[168:171], v[32:47]
	global_load_lds_dwordx4 v163, s[66:67] offset:3072
	s_add_u32 s66, s66, 0x10000
	s_addc_u32 s67, s67, 0
	v_mfma_f32_32x32x16_bf16 v[16:31], v[140:143], v[172:175], v[16:31]
	s_add_u32 s70, s70, 1
	s_cmp_eq_u32 s70, 3
	s_cselect_b32 s70, 0, s70
	v_mfma_f32_32x32x16_bf16 v[0:15], v[140:143], v[176:179], v[0:15]
	ds_read_b128 v[136:139], v185
	ds_read_b128 v[164:167], v187
	ds_read_b128 v[168:171], v187 offset:2048
	ds_read_b128 v[172:175], v187 offset:4096
	ds_read_b128 v[176:179], v187 offset:6144
	ds_read_b128 v[140:143], v185 offset:2048
	s_waitcnt lgkmcnt(10)
	v_mfma_f32_32x32x16_bf16 v[112:127], v[128:131], v[144:147], v[112:127]
	s_waitcnt lgkmcnt(9)
	v_mfma_f32_32x32x16_bf16 v[96:111], v[128:131], v[148:151], v[96:111]
	s_waitcnt lgkmcnt(8)
	v_mfma_f32_32x32x16_bf16 v[80:95], v[128:131], v[152:155], v[80:95]
	s_waitcnt lgkmcnt(7)
	v_mfma_f32_32x32x16_bf16 v[64:79], v[128:131], v[156:159], v[64:79]
	s_waitcnt lgkmcnt(6)
	v_mfma_f32_32x32x16_bf16 v[48:63], v[132:135], v[144:147], v[48:63]
	v_mfma_f32_32x32x16_bf16 v[32:47], v[132:135], v[148:151], v[32:47]
	v_mfma_f32_32x32x16_bf16 v[16:31], v[132:135], v[152:155], v[16:31]
	v_mfma_f32_32x32x16_bf16 v[0:15], v[132:135], v[156:159], v[0:15]
	s_add_u32 s72, s72, 1
	s_cmp_lt_u32 s72, 29
	s_cbranch_scc1 .Lp1v_loop
	s_waitcnt vmcnt(6) lgkmcnt(0)
	s_barrier
	s_mul_i32 s74, s71, 0x6000
	s_add_u32 s75, s74, 0x2000
	s_cmp_eq_u32 s71, 2
	s_cselect_b32 s75, 0x10000, s75
	v_add_u32_e32 v184, s74, v180
	v_add_u32_e32 v186, s75, v182
	v_add_u32_e32 v185, s74, v181
	v_add_u32_e32 v187, s75, v183
	s_add_u32 s71, s71, 1
	s_cmp_eq_u32 s71, 3
	s_cselect_b32 s71, 0, s71
	ds_read_b128 v[128:131], v184
	ds_read_b128 v[144:147], v186
	ds_read_b128 v[148:151], v186 offset:2048
	ds_read_b128 v[152:155], v186 offset:4096
	ds_read_b128 v[156:159], v186 offset:6144
	ds_read_b128 v[132:135], v184 offset:2048
	v_mfma_f32_32x32x16_bf16 v[112:127], v[136:139], v[164:167], v[112:127]
	v_mfma_f32_32x32x16_bf16 v[96:111], v[136:139], v[168:171], v[96:111]
	v_mfma_f32_32x32x16_bf16 v[80:95], v[136:139], v[172:175], v[80:95]
	v_mfma_f32_32x32x16_bf16 v[64:79], v[136:139], v[176:179], v[64:79]
	v_mfma_f32_32x32x16_bf16 v[48:63], v[140:143], v[164:167], v[48:63]
	v_mfma_f32_32x32x16_bf16 v[32:47], v[140:143], v[168:171], v[32:47]
	v_mfma_f32_32x32x16_bf16 v[16:31], v[140:143], v[172:175], v[16:31]
	v_mfma_f32_32x32x16_bf16 v[0:15], v[140:143], v[176:179], v[0:15]
	ds_read_b128 v[136:139], v185
	ds_read_b128 v[164:167], v187
	ds_read_b128 v[168:171], v187 offset:2048
	ds_read_b128 v[172:175], v187 offset:4096
	ds_read_b128 v[176:179], v187 offset:6144
	ds_read_b128 v[140:143], v185 offset:2048
	s_waitcnt lgkmcnt(10)
	v_mfma_f32_32x32x16_bf16 v[112:127], v[128:131], v[144:147], v[112:127]
	s_waitcnt lgkmcnt(9)
	v_mfma_f32_32x32x16_bf16 v[96:111], v[128:131], v[148:151], v[96:111]
	s_waitcnt lgkmcnt(8)
	v_mfma_f32_32x32x16_bf16 v[80:95], v[128:131], v[152:155], v[80:95]
	s_waitcnt lgkmcnt(7)
	v_mfma_f32_32x32x16_bf16 v[64:79], v[128:131], v[156:159], v[64:79]
	s_waitcnt lgkmcnt(6)
	v_mfma_f32_32x32x16_bf16 v[48:63], v[132:135], v[144:147], v[48:63]
	v_mfma_f32_32x32x16_bf16 v[32:47], v[132:135], v[148:151], v[32:47]
	v_mfma_f32_32x32x16_bf16 v[16:31], v[132:135], v[152:155], v[16:31]
	v_mfma_f32_32x32x16_bf16 v[0:15], v[132:135], v[156:159], v[0:15]
	s_waitcnt vmcnt(0) lgkmcnt(0)
	s_barrier
; #define MFMA32(a, b, c) __builtin_amdgcn_mfma_f32_32x32x16_bf16((a), (b), (c), 0, 0, 0)
; DI int crow(int reg, int h) { return (reg & 3) + 8 * (reg >> 2) + 4 * h; }
; #define GA_LOAD(pr_) do { _Pragma("unroll") for (int i = 0; i < 4; ++i) ra[i] = *(const u32x4*)(Ab + (i * 32) * lda + (pr_) * 64); } while (0)
; #define GB_LOAD(kt_) do { const bfr* bk_ = Bb + (kt_) * NB * 32; \
;     _Pragma("unroll") for (int i = 0; i < 4; ++i) rb[i] = *(const u32x4*)(bk_ + (i * 64) * 32); } while (0)
; #define G_STORE(kt_) do { bfr* as_ = S0 + ((kt_) & 1) * GSTAGE; bfr* bs_ = as_ + 128 * 40; \
;     if (apar == ((kt_) & 1)) { _Pragma("unroll") for (int i = 0; i < 4; ++i) *(u32x4*)(as_ + asoff + i * 32 * 40) = ra[i]; } \
;     _Pragma("unroll") for (int i = 0; i < 4; ++i) *(u32x4*)(bs_ + bsoff + i * 64 * 40) = rb[i]; } while (0)
; template <int lda>
; DI void gemm_mainloop(const bfr* __restrict__ A, const bfr* __restrict__ Bt, int NB, int K, int m0, int n0, char* smem, f32x16 (&acc)[2][4]) {
;     ...
;   for (int kt = 0; kt < nk; ++kt) {
;     if (kt + 1 < nk) G_STORE(kt + 1);
;     if (kt + 2 < nk) {
;       GB_LOAD(kt + 2);
;       if ((kt & 1) == 0) GA_LOAD((kt >> 1) + 1);
;     }
;     const bfr* As = S0 + (kt & 1) * GSTAGE;
;     const bfr* Bs = As + 128 * 40;
; #pragma unroll
;     for (int ks = 0; ks < 2; ++ks) {
;       bf16x8 af[2], bfg[4];
; #pragma unroll
;       for (int i = 0; i < 2; ++i) af[i] = *(const bf16x8*)(As + (wr * 64 + i * 32 + r) * 40 + ks * 16 + hl * 8);
; #pragma unroll
;       for (int j = 0; j < 4; ++j) bfg[j] = *(const bf16x8*)(Bs + (wc * 128 + j * 32 + r) * 40 + ks * 16 + hl * 8);
; #pragma unroll
;       for (int i = 0; i < 2; ++i)
; #pragma unroll
;         for (int j = 0; j < 4; ++j) acc[i][j] = MFMA32(af[i], bfg[j], acc[i][j]);
;     }
;     __syncthreads();
;   }
; template <int lda, class Epi>
; DI void gemm_tile(const bfr* __restrict__ A, const bfr* __restrict__ Bt, int NB, int K, int m0, int n0, char* smem, Epi epi) {
;     ...
; #pragma unroll
;   for (int i = 0; i < 2; ++i)
; #pragma unroll
;     for (int j = 0; j < 4; ++j)
; #pragma unroll
;       for (int q = 0; q < 16; ++q) {
;         int row = m0 + wr * 64 + i * 32 + crow(q, hl);
;         int col = n0 + wc * 128 + j * 32 + r;
;         epi(row, col, acc[i][j][q]);
	s_mul_i32 s74, s71, 0x6000
	s_add_u32 s75, s74, 0x2000
	s_cmp_eq_u32 s71, 2
	s_cselect_b32 s75, 0x10000, s75
	v_add_u32_e32 v184, s74, v180
	v_add_u32_e32 v186, s75, v182
	v_add_u32_e32 v185, s74, v181
	v_add_u32_e32 v187, s75, v183
	s_add_u32 s71, s71, 1
	s_cmp_eq_u32 s71, 3
	s_cselect_b32 s71, 0, s71
	ds_read_b128 v[128:131], v184
	ds_read_b128 v[144:147], v186
	ds_read_b128 v[148:151], v186 offset:2048
	ds_read_b128 v[152:155], v186 offset:4096
	ds_read_b128 v[156:159], v186 offset:6144
	ds_read_b128 v[132:135], v184 offset:2048
	v_mfma_f32_32x32x16_bf16 v[112:127], v[136:139], v[164:167], v[112:127]
	v_mfma_f32_32x32x16_bf16 v[96:111], v[136:139], v[168:171], v[96:111]
	v_mfma_f32_32x32x16_bf16 v[80:95], v[136:139], v[172:175], v[80:95]
	v_mfma_f32_32x32x16_bf16 v[64:79], v[136:139], v[176:179], v[64:79]
	v_mfma_f32_32x32x16_bf16 v[48:63], v[140:143], v[164:167], v[48:63]
	v_mfma_f32_32x32x16_bf16 v[32:47], v[140:143], v[168:171], v[32:47]
	v_mfma_f32_32x32x16_bf16 v[16:31], v[140:143], v[172:175], v[16:31]
	v_mfma_f32_32x32x16_bf16 v[0:15], v[140:143], v[176:179], v[0:15]
	ds_read_b128 v[136:139], v185
	ds_read_b128 v[164:167], v187
	ds_read_b128 v[168:171], v187 offset:2048
	ds_read_b128 v[172:175], v187 offset:4096
	ds_read_b128 v[176:179], v187 offset:6144
	ds_read_b128 v[140:143], v185 offset:2048
	s_waitcnt lgkmcnt(10)
	v_mfma_f32_32x32x16_bf16 v[112:127], v[128:131], v[144:147], v[112:127]
	s_waitcnt lgkmcnt(9)
	v_mfma_f32_32x32x16_bf16 v[96:111], v[128:131], v[148:151], v[96:111]
	s_waitcnt lgkmcnt(8)
	v_mfma_f32_32x32x16_bf16 v[80:95], v[128:131], v[152:155], v[80:95]
	s_waitcnt lgkmcnt(7)
	v_mfma_f32_32x32x16_bf16 v[64:79], v[128:131], v[156:159], v[64:79]
	s_waitcnt lgkmcnt(6)
	v_mfma_f32_32x32x16_bf16 v[48:63], v[132:135], v[144:147], v[48:63]
	v_mfma_f32_32x32x16_bf16 v[32:47], v[132:135], v[148:151], v[32:47]
	v_mfma_f32_32x32x16_bf16 v[16:31], v[132:135], v[152:155], v[16:31]
	v_mfma_f32_32x32x16_bf16 v[0:15], v[132:135], v[156:159], v[0:15]
	s_waitcnt lgkmcnt(0)
	v_mfma_f32_32x32x16_bf16 v[112:127], v[136:139], v[164:167], v[112:127]
	v_mfma_f32_32x32x16_bf16 v[96:111], v[136:139], v[168:171], v[96:111]
	v_mfma_f32_32x32x16_bf16 v[80:95], v[136:139], v[172:175], v[80:95]
	v_mfma_f32_32x32x16_bf16 v[64:79], v[136:139], v[176:179], v[64:79]
	v_mfma_f32_32x32x16_bf16 v[48:63], v[140:143], v[164:167], v[48:63]
	v_mfma_f32_32x32x16_bf16 v[32:47], v[140:143], v[168:171], v[32:47]
	v_mfma_f32_32x32x16_bf16 v[16:31], v[140:143], v[172:175], v[16:31]
	v_mfma_f32_32x32x16_bf16 v[0:15], v[140:143], v[176:179], v[0:15]
	s_nop 7
	v_readlane_b32 s64, v188, 0
	v_readlane_b32 s65, v188, 1
	v_readlane_b32 s66, v188, 2
	v_readlane_b32 s67, v188, 3
	v_readlane_b32 s68, v188, 4
	v_readlane_b32 s69, v188, 5
	v_readlane_b32 s70, v188, 6
	v_readlane_b32 s71, v188, 7
	v_readlane_b32 s72, v188, 8
	v_readlane_b32 s73, v188, 9
	v_readlane_b32 s74, v188, 10
	v_readlane_b32 s75, v188, 11
	v_readlane_b32 s76, v188, 12
	v_readlane_b32 s77, v188, 13
	v_readlane_b32 s78, v188, 14
	v_readlane_b32 s79, v188, 15
	s_nop 7
	s_waitcnt vmcnt(1)
	s_nop 0
	s_nop 0
	s_nop 0
	s_waitcnt vmcnt(0)
	s_nop 0
	v_add_u32_e32 v140, v171, v173
	s_nop 0
	v_add_u32_e32 v160, v171, v172
	s_nop 0
	s_nop 0
	s_nop 0
	s_nop 0
	s_nop 0
	s_nop 0
	s_nop 0
	s_nop 0
	s_nop 0
	s_nop 0
	s_nop 0
	s_waitcnt lgkmcnt(0)
	s_nop 0
	s_nop 0
	s_lshl_b32 s0, s2, 2
	s_add_u32 s30, s33, s0
	s_addc_u32 s31, s38, 0
	s_lshl_b32 s0, s2, 1
	s_add_u32 s0, s6, s0
	s_nop 0
	s_addc_u32 s1, s7, 0
	s_nop 0
	s_nop 0
	s_nop 0
	s_nop 0
	s_nop 0
	s_nop 0
	s_nop 0
	s_nop 0
	s_nop 0
	s_waitcnt lgkmcnt(3)
	s_nop 0
	s_nop 0
	v_mov_b32_e32 v152, v196
	s_nop 0
	s_nop 0
	s_nop 0
	s_nop 0
	s_nop 0
	s_nop 0
	s_nop 0
	s_waitcnt lgkmcnt(0)
	s_nop 0
	s_nop 0
	v_ashrrev_i32_e32 v153, 1, v152
	v_and_b32_e32 v153, 0xffffffc0, v153
	v_and_b32_e32 v155, 31, v152
	v_add_u32_e32 v173, s58, v153
	v_lshrrev_b32_e32 v153, 3, v152
	v_lshlrev_b32_e32 v152, 1, v152
	v_and_b32_e32 v152, 0x80, v152
	v_or_b32_e32 v170, s57, v152
	v_or_b32_e32 v152, v170, v155
	v_lshlrev_b32_e32 v175, 8, v170
	s_nop 0
	v_lshlrev_b32_e32 v170, 10, v173
	v_and_b32_e32 v174, 4, v153
	v_and_b32_e32 v172, 0xfffc0000, v170
	v_lshlrev_b32_e32 v170, 5, v173
	v_lshlrev_b32_e32 v160, 2, v152
	v_lshlrev_b32_e32 v197, 3, v155
	v_and_b32_e32 v170, 0x1800, v170
	v_lshlrev_b32_e32 v228, 6, v174
	v_lshl_add_u64 v[152:153], s[30:31], 0, v[160:161]
	v_or_b32_e32 v160, v175, v197
	s_nop 0
	v_or3_b32 v229, v228, v170, v172
	v_or_b32_e32 v231, 10, v174
	v_or_b32_e32 v156, v229, v160
	v_ashrrev_i32_e32 v157, 31, v156
	v_or_b32_e32 v230, 1, v174
	v_or_b32_e32 v154, v173, v174
	v_lshl_add_u64 v[226:227], v[156:157], 1, s[0:1]
	s_nop 0
	v_or_b32_e32 v188, 2, v174
	v_or_b32_e32 v191, 9, v174
	v_or_b32_e32 v158, v173, v188
	v_or_b32_e32 v189, 3, v174
	v_ashrrev_i32_e32 v159, 31, v158
	v_or_b32_e32 v162, v173, v189
	v_or_b32_e32 v190, 8, v174
	s_nop 0
	v_or_b32_e32 v178, 11, v174
	v_or_b32_e32 v170, v173, v178
	v_ashrrev_i32_e32 v171, 31, v170
	v_or_b32_e32 v156, v173, v230
	v_lshlrev_b64 v[158:159], 12, v[158:159]
	v_ashrrev_i32_e32 v163, 31, v162
	v_or_b32_e32 v164, v173, v190
	s_nop 0
	v_lshlrev_b64 v[170:171], 12, v[170:171]
	v_ashrrev_i32_e32 v155, 31, v154
	v_ashrrev_i32_e32 v157, 31, v156
	v_lshl_add_u64 v[158:159], v[152:153], 0, v[158:159]
	v_lshlrev_b64 v[162:163], 12, v[162:163]
	v_ashrrev_i32_e32 v165, 31, v164
	v_lshl_add_u64 v[170:171], v[152:153], 0, v[170:171]
	s_nop 0
	v_or_b32_e32 v179, 16, v174
	v_lshlrev_b64 v[154:155], 12, v[154:155]
	v_lshlrev_b64 v[156:157], 12, v[156:157]
	global_store_dword v[158:159], v114, off
	v_lshl_add_u64 v[162:163], v[152:153], 0, v[162:163]
; DI bfr f2bf(float a) { return (bfr)(pack2(a, 0.f) & 0xffffu); }
; DI int crow(int reg, int h) { return (reg & 3) + 8 * (reg >> 2) + 4 * h; }
; template <int lda, class Epi>
; DI void gemm_tile(const bfr* __restrict__ A, const bfr* __restrict__ Bt, int NB, int K, int m0, int n0, char* smem, Epi epi) {
;     ...
; #pragma unroll
;   for (int i = 0; i < 2; ++i)
; #pragma unroll
;     for (int j = 0; j < 4; ++j)
; #pragma unroll
;       for (int q = 0; q < 16; ++q) {
;         int row = m0 + wr * 64 + i * 32 + crow(q, hl);
;         int col = n0 + wc * 128 + j * 32 + r;
;         epi(row, col, acc[i][j][q]);
; DI void phase_gemm_in_even(const Params& p, char* smem) {
;     ...
;         float* o = p.out + O_MEMV + (size_t)l * 2097152;
;         bfr* vt = p.VT + (size_t)l * 2097152;
;         gemm_tile<1024>(p.MPB, p.WtXv + (size_t)l * 1048576, 1024, 1024, mt * 128, nt * 256, smem,
;                   [=](int row, int col, float v) {
;                     o[(size_t)row * 1024 + col] = v;
;                     const int ml = row & 15;
;                     const int rowpart = (row >> 8) * 262144 + ((row & 255) >> 4) * 512 + ((ml >> 2) & 1) * 256 + (((ml >> 3) << 2) | (ml & 3));
;                     const int colpart = (col >> 8) * 65536 + ((col & 255) >> 5) * 8192 + (col & 31) * 8;
;                     vt[rowpart + colpart] = f2bf(v);
	v_lshlrev_b64 v[164:165], 12, v[164:165]
	global_store_dword v[170:171], v119, off
	s_nop 0
	v_or_b32_e32 v166, v173, v191
	v_or_b32_e32 v168, v173, v231
	v_ashrrev_i32_e32 v167, 31, v166
	v_ashrrev_i32_e32 v169, 31, v168
	v_lshlrev_b64 v[166:167], 12, v[166:167]
	v_lshlrev_b64 v[168:169], 12, v[168:169]
	v_lshl_add_u64 v[166:167], v[152:153], 0, v[166:167]
	v_lshl_add_u64 v[168:169], v[152:153], 0, v[168:169]
	global_store_dword v[166:167], v117, off
	global_store_dword v[168:169], v118, off
	v_cvt_pk_bf16_f32 v119, v118, v119
	v_cvt_pk_bf16_f32 v118, v116, v117
	v_cvt_pk_bf16_f32 v117, v114, v115
	v_or_b32_e32 v114, v173, v179
	v_lshl_add_u64 v[154:155], v[152:153], 0, v[154:155]
	v_lshl_add_u64 v[156:157], v[152:153], 0, v[156:157]
	global_store_dword v[162:163], v115, off
	v_lshl_add_u64 v[164:165], v[152:153], 0, v[164:165]
	v_ashrrev_i32_e32 v115, 31, v114
	global_store_dword v[154:155], v112, off
	global_store_dword v[156:157], v113, off
	global_store_dword v[164:165], v116, off
	v_cvt_pk_bf16_f32 v116, v112, v113
	v_lshlrev_b64 v[112:113], 12, v[114:115]
	v_lshlrev_b32_e32 v114, 5, v114
	v_or_b32_e32 v172, v172, v228
	s_nop 0
	v_and_or_b32 v180, v114, s49, v172
	v_or_b32_e32 v114, v180, v160
	v_ashrrev_i32_e32 v115, 31, v114
	global_store_dwordx4 v[226:227], v[116:119], off
	v_lshl_add_u64 v[114:115], v[114:115], 1, s[0:1]
	v_or_b32_e32 v181, 17, v174
	v_cvt_pk_bf16_f32 v116, v120, s0
	global_store_short v[114:115], v116, off
	v_or_b32_e32 v116, v173, v181
	v_ashrrev_i32_e32 v117, 31, v116
	v_lshlrev_b64 v[114:115], 12, v[116:117]
	v_lshlrev_b32_e32 v116, 5, v116
	v_and_or_b32 v182, v116, s49, v172
	v_or_b32_e32 v116, v182, v160
	v_ashrrev_i32_e32 v117, 31, v116
	v_cvt_pk_bf16_f32 v118, v121, s0
	v_lshl_add_u64 v[116:117], v[116:117], 1, s[0:1]
	v_or_b32_e32 v183, 18, v174
	global_store_short v[116:117], v118, off offset:2
	v_or_b32_e32 v118, v173, v183
	v_ashrrev_i32_e32 v119, 31, v118
	v_lshlrev_b64 v[116:117], 12, v[118:119]
	v_lshlrev_b32_e32 v118, 5, v118
	s_nop 0
	v_and_or_b32 v184, v118, s49, v172
	v_or_b32_e32 v118, v184, v160
	v_lshl_add_u64 v[112:113], v[152:153], 0, v[112:113]
	v_ashrrev_i32_e32 v119, 31, v118
	global_store_dword v[112:113], v120, off
	v_cvt_pk_bf16_f32 v120, v122, s0
	v_lshl_add_u64 v[118:119], v[118:119], 1, s[0:1]
	v_or_b32_e32 v185, 19, v174
	v_lshl_add_u64 v[114:115], v[152:153], 0, v[114:115]
	global_store_short v[118:119], v120, off offset:4
	v_or_b32_e32 v120, v173, v185
	global_store_dword v[114:115], v121, off
	v_ashrrev_i32_e32 v121, 31, v120
	v_lshlrev_b64 v[118:119], 12, v[120:121]
	v_lshlrev_b32_e32 v120, 5, v120
	v_and_or_b32 v186, v120, s49, v172
	v_or_b32_e32 v120, v186, v160
	v_lshl_add_u64 v[116:117], v[152:153], 0, v[116:117]
	v_ashrrev_i32_e32 v121, 31, v120
	global_store_dword v[116:117], v122, off
	v_cvt_pk_bf16_f32 v122, v123, s0
	v_lshl_add_u64 v[120:121], v[120:121], 1, s[0:1]
	v_or_b32_e32 v187, 24, v174
	v_lshl_add_u64 v[118:119], v[152:153], 0, v[118:119]
	global_store_short v[120:121], v122, off offset:6
	v_or_b32_e32 v122, v173, v187
	s_nop 0
	global_store_dword v[118:119], v123, off
	v_ashrrev_i32_e32 v123, 31, v122
	v_lshlrev_b64 v[120:121], 12, v[122:123]
	v_lshlrev_b32_e32 v122, 5, v122
	v_lshl_add_u64 v[120:121], v[152:153], 0, v[120:121]
	global_store_dword v[120:121], v124, off
	v_cvt_pk_bf16_f32 v124, v124, s0
	s_nop 0
	s_nop 0
	s_nop 0
	v_and_or_b32 v192, v122, s49, v172
	v_or_b32_e32 v122, v192, v160
	v_ashrrev_i32_e32 v123, 31, v122
	v_or_b32_e32 v193, 25, v174
	v_lshl_add_u64 v[122:123], v[122:123], 1, s[0:1]
	v_or_b32_e32 v176, v173, v193
	global_store_short v[122:123], v124, off offset:8
	s_nop 0
	v_ashrrev_i32_e32 v177, 31, v176
	v_lshlrev_b32_e32 v124, 5, v176
	v_lshlrev_b64 v[122:123], 12, v[176:177]
	v_and_or_b32 v177, v124, s49, v172
	v_lshl_add_u64 v[122:123], v[152:153], 0, v[122:123]
	v_or_b32_e32 v124, v177, v160
	global_store_dword v[122:123], v125, off
	s_nop 0
	v_cvt_pk_bf16_f32 v176, v125, s0
	v_ashrrev_i32_e32 v125, 31, v124
	v_lshl_add_u64 v[124:125], v[124:125], 1, s[0:1]
	global_store_short v[124:125], v176, off offset:10
	s_nop 0
	s_nop 6
	global_store_dword v[154:155], v96, off offset:128
	s_nop 0
	v_or_b32_e32 v146, 26, v174
	v_or_b32_e32 v144, v173, v146
	v_ashrrev_i32_e32 v145, 31, v144
	v_lshlrev_b64 v[124:125], 12, v[144:145]
	v_lshl_add_u64 v[124:125], v[152:153], 0, v[124:125]
	v_or_b32_e32 v145, 27, v174
	global_store_dword v[124:125], v126, off
	s_nop 0
	v_lshlrev_b32_e32 v136, 5, v144
	v_and_or_b32 v144, v136, s49, v172
	v_or_b32_e32 v136, v144, v160
	v_ashrrev_i32_e32 v137, 31, v136
	v_cvt_pk_bf16_f32 v126, v126, s0
	v_lshl_add_u64 v[136:137], v[136:137], 1, s[0:1]
	v_or_b32_e32 v138, v173, v145
	s_nop 0
	global_store_short v[136:137], v126, off offset:12
	v_ashrrev_i32_e32 v139, 31, v138
	v_lshlrev_b32_e32 v126, 5, v138
	v_lshlrev_b64 v[136:137], 12, v[138:139]
	v_and_or_b32 v139, v126, s49, v172
	v_lshl_add_u64 v[136:137], v[152:153], 0, v[136:137]
	v_or_b32_e32 v126, v139, v160
	s_nop 0
	global_store_dword v[136:137], v127, off
	v_cvt_pk_bf16_f32 v138, v127, s0
	v_ashrrev_i32_e32 v127, 31, v126
	v_lshl_add_u64 v[126:127], v[126:127], 1, s[0:1]
	global_store_short v[126:127], v138, off offset:14
	v_or_b32_e32 v126, 0x2000, v175
	v_and_or_b32 v126, v126, s50, v197
	s_nop 0
	global_store_dword v[156:157], v97, off offset:128
	global_store_dword v[158:159], v98, off offset:128
	global_store_dword v[162:163], v99, off offset:128
	global_store_dword v[164:165], v100, off offset:128
	global_store_dword v[166:167], v101, off offset:128
	global_store_dword v[168:169], v102, off offset:128
	global_store_dword v[170:171], v103, off offset:128
; DI bfr f2bf(float a) { return (bfr)(pack2(a, 0.f) & 0xffffu); }
; DI int crow(int reg, int h) { return (reg & 3) + 8 * (reg >> 2) + 4 * h; }
; template <int lda, class Epi>
; DI void gemm_tile(const bfr* __restrict__ A, const bfr* __restrict__ Bt, int NB, int K, int m0, int n0, char* smem, Epi epi) {
;     ...
; #pragma unroll
;   for (int i = 0; i < 2; ++i)
; #pragma unroll
;     for (int j = 0; j < 4; ++j)
; #pragma unroll
;       for (int q = 0; q < 16; ++q) {
;         int row = m0 + wr * 64 + i * 32 + crow(q, hl);
;         int col = n0 + wc * 128 + j * 32 + r;
;         epi(row, col, acc[i][j][q]);
; DI void phase_gemm_in_even(const Params& p, char* smem) {
;     ...
;         float* o = p.out + O_MEMV + (size_t)l * 2097152;
;         bfr* vt = p.VT + (size_t)l * 2097152;
;         gemm_tile<1024>(p.MPB, p.WtXv + (size_t)l * 1048576, 1024, 1024, mt * 128, nt * 256, smem,
;                   [=](int row, int col, float v) {
;                     o[(size_t)row * 1024 + col] = v;
;                     const int ml = row & 15;
;                     const int rowpart = (row >> 8) * 262144 + ((row & 255) >> 4) * 512 + ((ml >> 2) & 1) * 256 + (((ml >> 3) << 2) | (ml & 3));
;                     const int colpart = (col >> 8) * 65536 + ((col & 255) >> 5) * 8192 + (col & 31) * 8;
;                     vt[rowpart + colpart] = f2bf(v);
	v_cvt_pk_bf16_f32 v103, v102, v103
	v_cvt_pk_bf16_f32 v102, v100, v101
	v_cvt_pk_bf16_f32 v100, v96, v97
	v_or_b32_e32 v96, v126, v180
	v_ashrrev_i32_e32 v97, 31, v96
	v_cvt_pk_bf16_f32 v101, v98, v99
	s_nop 0
	v_cvt_pk_bf16_f32 v98, v104, s0
	v_lshl_add_u64 v[96:97], v[96:97], 1, s[0:1]
	s_nop 0
	s_nop 0
	v_or_b32_e32 v128, v126, v229
	v_ashrrev_i32_e32 v129, 31, v128
	v_lshl_add_u64 v[128:129], v[128:129], 1, s[0:1]
	global_store_dwordx4 v[128:129], v[100:103], off
	global_store_dword v[112:113], v104, off offset:128
	global_store_short v[96:97], v98, off
	global_store_dword v[114:115], v105, off offset:128
	v_or_b32_e32 v96, v126, v182
	v_ashrrev_i32_e32 v97, 31, v96
	v_cvt_pk_bf16_f32 v98, v105, s0
	v_lshl_add_u64 v[96:97], v[96:97], 1, s[0:1]
	global_store_short v[96:97], v98, off offset:2
	global_store_dword v[116:117], v106, off offset:128
	v_or_b32_e32 v96, v126, v184
	v_ashrrev_i32_e32 v97, 31, v96
	v_cvt_pk_bf16_f32 v98, v106, s0
	v_lshl_add_u64 v[96:97], v[96:97], 1, s[0:1]
	global_store_short v[96:97], v98, off offset:4
	global_store_dword v[118:119], v107, off offset:128
	v_or_b32_e32 v96, v126, v186
	v_ashrrev_i32_e32 v97, 31, v96
	v_cvt_pk_bf16_f32 v98, v107, s0
	v_lshl_add_u64 v[96:97], v[96:97], 1, s[0:1]
	global_store_short v[96:97], v98, off offset:6
	global_store_dword v[120:121], v108, off offset:128
	v_or_b32_e32 v96, v126, v192
	v_ashrrev_i32_e32 v97, 31, v96
	v_cvt_pk_bf16_f32 v98, v108, s0
	v_lshl_add_u64 v[96:97], v[96:97], 1, s[0:1]
	global_store_short v[96:97], v98, off offset:8
	global_store_dword v[122:123], v109, off offset:128
	v_or_b32_e32 v96, v126, v177
	v_ashrrev_i32_e32 v97, 31, v96
	v_cvt_pk_bf16_f32 v98, v109, s0
	v_lshl_add_u64 v[96:97], v[96:97], 1, s[0:1]
	global_store_short v[96:97], v98, off offset:10
	global_store_dword v[124:125], v110, off offset:128
	v_or_b32_e32 v96, v126, v144
	v_ashrrev_i32_e32 v97, 31, v96
	v_cvt_pk_bf16_f32 v98, v110, s0
	v_lshl_add_u64 v[96:97], v[96:97], 1, s[0:1]
	global_store_short v[96:97], v98, off offset:12
	global_store_dword v[136:137], v111, off offset:128
	v_or_b32_e32 v96, v126, v139
	v_ashrrev_i32_e32 v97, 31, v96
	v_cvt_pk_bf16_f32 v98, v111, s0
	v_lshl_add_u64 v[96:97], v[96:97], 1, s[0:1]
	global_store_short v[96:97], v98, off offset:14
	v_or_b32_e32 v96, 0x4000, v175
	v_and_or_b32 v96, v96, s51, v197
	global_store_dword v[154:155], v80, off offset:256
	v_or_b32_e32 v98, v96, v229
	global_store_dword v[156:157], v81, off offset:256
	global_store_dword v[158:159], v82, off offset:256
	global_store_dword v[162:163], v83, off offset:256
	global_store_dword v[164:165], v84, off offset:256
	global_store_dword v[166:167], v85, off offset:256
	global_store_dword v[168:169], v86, off offset:256
	global_store_dword v[170:171], v87, off offset:256
	v_cvt_pk_bf16_f32 v87, v86, v87
	v_cvt_pk_bf16_f32 v86, v84, v85
	v_cvt_pk_bf16_f32 v84, v80, v81
	v_or_b32_e32 v80, v96, v180
	v_ashrrev_i32_e32 v99, 31, v98
	v_ashrrev_i32_e32 v81, 31, v80
	v_lshl_add_u64 v[98:99], v[98:99], 1, s[0:1]
	v_cvt_pk_bf16_f32 v85, v82, v83
	v_cvt_pk_bf16_f32 v82, v88, s0
	v_lshl_add_u64 v[80:81], v[80:81], 1, s[0:1]
	global_store_dwordx4 v[98:99], v[84:87], off
	global_store_dword v[112:113], v88, off offset:256
	global_store_short v[80:81], v82, off
	global_store_dword v[114:115], v89, off offset:256
	v_or_b32_e32 v80, v96, v182
	v_ashrrev_i32_e32 v81, 31, v80
	v_cvt_pk_bf16_f32 v82, v89, s0
	v_lshl_add_u64 v[80:81], v[80:81], 1, s[0:1]
	global_store_short v[80:81], v82, off offset:2
	global_store_dword v[116:117], v90, off offset:256
	v_or_b32_e32 v80, v96, v184
	v_ashrrev_i32_e32 v81, 31, v80
	v_cvt_pk_bf16_f32 v82, v90, s0
	v_lshl_add_u64 v[80:81], v[80:81], 1, s[0:1]
	global_store_short v[80:81], v82, off offset:4
	global_store_dword v[118:119], v91, off offset:256
	v_or_b32_e32 v80, v96, v186
	v_ashrrev_i32_e32 v81, 31, v80
	v_cvt_pk_bf16_f32 v82, v91, s0
	v_lshl_add_u64 v[80:81], v[80:81], 1, s[0:1]
	global_store_short v[80:81], v82, off offset:6
	global_store_dword v[120:121], v92, off offset:256
	v_or_b32_e32 v80, v96, v192
	v_ashrrev_i32_e32 v81, 31, v80
	v_cvt_pk_bf16_f32 v82, v92, s0
	v_lshl_add_u64 v[80:81], v[80:81], 1, s[0:1]
	global_store_short v[80:81], v82, off offset:8
	global_store_dword v[122:123], v93, off offset:256
	v_or_b32_e32 v80, v96, v177
	v_ashrrev_i32_e32 v81, 31, v80
	v_cvt_pk_bf16_f32 v82, v93, s0
	v_lshl_add_u64 v[80:81], v[80:81], 1, s[0:1]
	global_store_short v[80:81], v82, off offset:10
	global_store_dword v[124:125], v94, off offset:256
	v_or_b32_e32 v80, v96, v144
	v_ashrrev_i32_e32 v81, 31, v80
	v_cvt_pk_bf16_f32 v82, v94, s0
	v_lshl_add_u64 v[80:81], v[80:81], 1, s[0:1]
	global_store_short v[80:81], v82, off offset:12
	global_store_dword v[136:137], v95, off offset:256
	v_or_b32_e32 v80, v96, v139
	v_ashrrev_i32_e32 v81, 31, v80
	v_cvt_pk_bf16_f32 v82, v95, s0
	v_lshl_add_u64 v[80:81], v[80:81], 1, s[0:1]
	global_store_short v[80:81], v82, off offset:14
	v_or_b32_e32 v80, 0x6000, v175
	v_and_or_b32 v82, v80, s52, v197
	global_store_dword v[154:155], v64, off offset:384
	v_or_b32_e32 v80, v82, v229
	global_store_dword v[156:157], v65, off offset:384
	global_store_dword v[158:159], v66, off offset:384
	global_store_dword v[162:163], v67, off offset:384
	global_store_dword v[164:165], v68, off offset:384
	global_store_dword v[166:167], v69, off offset:384
	global_store_dword v[168:169], v70, off offset:384
	global_store_dword v[170:171], v71, off offset:384
	v_cvt_pk_bf16_f32 v71, v70, v71
	v_cvt_pk_bf16_f32 v70, v68, v69
	v_cvt_pk_bf16_f32 v68, v64, v65
	v_or_b32_e32 v64, v82, v180
	v_ashrrev_i32_e32 v81, 31, v80
	v_ashrrev_i32_e32 v65, 31, v64
; DI bfr f2bf(float a) { return (bfr)(pack2(a, 0.f) & 0xffffu); }
; DI int crow(int reg, int h) { return (reg & 3) + 8 * (reg >> 2) + 4 * h; }
; template <int lda, class Epi>
; DI void gemm_tile(const bfr* __restrict__ A, const bfr* __restrict__ Bt, int NB, int K, int m0, int n0, char* smem, Epi epi) {
;     ...
; #pragma unroll
;   for (int i = 0; i < 2; ++i)
; #pragma unroll
;     for (int j = 0; j < 4; ++j)
; #pragma unroll
;       for (int q = 0; q < 16; ++q) {
;         int row = m0 + wr * 64 + i * 32 + crow(q, hl);
;         int col = n0 + wc * 128 + j * 32 + r;
;         epi(row, col, acc[i][j][q]);
; DI void phase_gemm_in_even(const Params& p, char* smem) {
;     ...
;         float* o = p.out + O_MEMV + (size_t)l * 2097152;
;         bfr* vt = p.VT + (size_t)l * 2097152;
;         gemm_tile<1024>(p.MPB, p.WtXv + (size_t)l * 1048576, 1024, 1024, mt * 128, nt * 256, smem,
;                   [=](int row, int col, float v) {
;                     o[(size_t)row * 1024 + col] = v;
;                     const int ml = row & 15;
;                     const int rowpart = (row >> 8) * 262144 + ((row & 255) >> 4) * 512 + ((ml >> 2) & 1) * 256 + (((ml >> 3) << 2) | (ml & 3));
;                     const int colpart = (col >> 8) * 65536 + ((col & 255) >> 5) * 8192 + (col & 31) * 8;
;                     vt[rowpart + colpart] = f2bf(v);
	v_lshl_add_u64 v[80:81], v[80:81], 1, s[0:1]
	v_cvt_pk_bf16_f32 v69, v66, v67
	v_cvt_pk_bf16_f32 v66, v72, s0
	v_lshl_add_u64 v[64:65], v[64:65], 1, s[0:1]
	global_store_dwordx4 v[80:81], v[68:71], off
	global_store_dword v[112:113], v72, off offset:384
	global_store_short v[64:65], v66, off
	global_store_dword v[114:115], v73, off offset:384
	v_or_b32_e32 v64, v82, v182
	v_ashrrev_i32_e32 v65, 31, v64
	v_cvt_pk_bf16_f32 v66, v73, s0
	v_lshl_add_u64 v[64:65], v[64:65], 1, s[0:1]
	global_store_short v[64:65], v66, off offset:2
	global_store_dword v[116:117], v74, off offset:384
	v_or_b32_e32 v64, v82, v184
	v_ashrrev_i32_e32 v65, 31, v64
	v_cvt_pk_bf16_f32 v66, v74, s0
	v_lshl_add_u64 v[64:65], v[64:65], 1, s[0:1]
	global_store_short v[64:65], v66, off offset:4
	global_store_dword v[118:119], v75, off offset:384
	v_or_b32_e32 v64, v82, v186
	v_ashrrev_i32_e32 v65, 31, v64
	v_cvt_pk_bf16_f32 v66, v75, s0
	v_lshl_add_u64 v[64:65], v[64:65], 1, s[0:1]
	global_store_short v[64:65], v66, off offset:6
	global_store_dword v[120:121], v76, off offset:384
	v_or_b32_e32 v64, v82, v192
	v_ashrrev_i32_e32 v65, 31, v64
	v_cvt_pk_bf16_f32 v66, v76, s0
	v_lshl_add_u64 v[64:65], v[64:65], 1, s[0:1]
	global_store_short v[64:65], v66, off offset:8
	global_store_dword v[122:123], v77, off offset:384
	v_or_b32_e32 v64, v82, v177
	v_ashrrev_i32_e32 v65, 31, v64
	v_cvt_pk_bf16_f32 v66, v77, s0
	v_lshl_add_u64 v[64:65], v[64:65], 1, s[0:1]
	global_store_short v[64:65], v66, off offset:10
	global_store_dword v[124:125], v78, off offset:384
	v_or_b32_e32 v64, v82, v144
	v_ashrrev_i32_e32 v65, 31, v64
	v_cvt_pk_bf16_f32 v66, v78, s0
	v_lshl_add_u64 v[64:65], v[64:65], 1, s[0:1]
	global_store_short v[64:65], v66, off offset:12
	global_store_dword v[136:137], v79, off offset:384
	v_or_b32_e32 v64, v82, v139
	v_ashrrev_i32_e32 v65, 31, v64
	v_cvt_pk_bf16_f32 v66, v79, s0
	v_lshl_add_u64 v[64:65], v[64:65], 1, s[0:1]
	v_or_b32_e32 v83, 32, v173
	global_store_short v[64:65], v66, off offset:14
	v_lshlrev_b32_e32 v66, 5, v83
	v_and_or_b32 v86, v66, s53, v172
	v_or_b32_e32 v66, v86, v160
	v_or_b32_e32 v68, v83, v188
	v_or_b32_e32 v74, v83, v191
	v_or_b32_e32 v76, v83, v231
	v_or_b32_e32 v78, v83, v178
	v_ashrrev_i32_e32 v67, 31, v66
	v_ashrrev_i32_e32 v69, 31, v68
	v_or_b32_e32 v70, v83, v189
	v_ashrrev_i32_e32 v75, 31, v74
	v_ashrrev_i32_e32 v77, 31, v76
	v_ashrrev_i32_e32 v79, 31, v78
	v_or_b32_e32 v64, v83, v174
	v_lshl_add_u64 v[80:81], v[66:67], 1, s[0:1]
	v_or_b32_e32 v66, v83, v230
	v_lshlrev_b64 v[68:69], 12, v[68:69]
	v_ashrrev_i32_e32 v71, 31, v70
	v_or_b32_e32 v72, v83, v190
	v_lshlrev_b64 v[74:75], 12, v[74:75]
	v_lshlrev_b64 v[76:77], 12, v[76:77]
	v_lshlrev_b64 v[78:79], 12, v[78:79]
	v_ashrrev_i32_e32 v65, 31, v64
	v_ashrrev_i32_e32 v67, 31, v66
	v_lshl_add_u64 v[68:69], v[152:153], 0, v[68:69]
	v_lshlrev_b64 v[70:71], 12, v[70:71]
	v_ashrrev_i32_e32 v73, 31, v72
	v_lshl_add_u64 v[74:75], v[152:153], 0, v[74:75]
	v_lshl_add_u64 v[76:77], v[152:153], 0, v[76:77]
	v_lshl_add_u64 v[78:79], v[152:153], 0, v[78:79]
	v_lshlrev_b64 v[64:65], 12, v[64:65]
	v_lshlrev_b64 v[66:67], 12, v[66:67]
	global_store_dword v[68:69], v50, off
	v_lshl_add_u64 v[70:71], v[152:153], 0, v[70:71]
	v_lshlrev_b64 v[72:73], 12, v[72:73]
	global_store_dword v[74:75], v53, off
	global_store_dword v[76:77], v54, off
	global_store_dword v[78:79], v55, off
	v_cvt_pk_bf16_f32 v55, v54, v55
	v_cvt_pk_bf16_f32 v54, v52, v53
	v_cvt_pk_bf16_f32 v53, v50, v51
	v_or_b32_e32 v50, v83, v179
	v_lshl_add_u64 v[64:65], v[152:153], 0, v[64:65]
	v_lshl_add_u64 v[66:67], v[152:153], 0, v[66:67]
	global_store_dword v[70:71], v51, off
	v_lshl_add_u64 v[72:73], v[152:153], 0, v[72:73]
	v_ashrrev_i32_e32 v51, 31, v50
	global_store_dword v[64:65], v48, off
	global_store_dword v[66:67], v49, off
	global_store_dword v[72:73], v52, off
	v_cvt_pk_bf16_f32 v52, v48, v49
	v_lshlrev_b64 v[48:49], 12, v[50:51]
	v_lshlrev_b32_e32 v50, 5, v50
	v_and_or_b32 v87, v50, s54, v172
	v_or_b32_e32 v50, v87, v160
	v_ashrrev_i32_e32 v51, 31, v50
	global_store_dwordx4 v[80:81], v[52:55], off
	v_lshl_add_u64 v[50:51], v[50:51], 1, s[0:1]
	v_lshl_add_u64 v[48:49], v[152:153], 0, v[48:49]
	v_cvt_pk_bf16_f32 v52, v56, s0
	global_store_short v[50:51], v52, off
	v_or_b32_e32 v52, v83, v181
	v_ashrrev_i32_e32 v53, 31, v52
	v_lshlrev_b64 v[50:51], 12, v[52:53]
	v_lshlrev_b32_e32 v52, 5, v52
	v_and_or_b32 v88, v52, s54, v172
	v_or_b32_e32 v52, v88, v160
	v_ashrrev_i32_e32 v53, 31, v52
	v_cvt_pk_bf16_f32 v54, v57, s0
	v_lshl_add_u64 v[52:53], v[52:53], 1, s[0:1]
	global_store_short v[52:53], v54, off offset:2
	v_or_b32_e32 v54, v83, v183
	v_ashrrev_i32_e32 v55, 31, v54
	v_lshlrev_b64 v[52:53], 12, v[54:55]
	v_lshlrev_b32_e32 v54, 5, v54
	v_and_or_b32 v89, v54, s54, v172
	v_or_b32_e32 v54, v89, v160
	v_ashrrev_i32_e32 v55, 31, v54
	global_store_dword v[48:49], v56, off
	v_cvt_pk_bf16_f32 v56, v58, s0
	v_lshl_add_u64 v[54:55], v[54:55], 1, s[0:1]
	v_lshl_add_u64 v[50:51], v[152:153], 0, v[50:51]
	global_store_short v[54:55], v56, off offset:4
	v_or_b32_e32 v56, v83, v185
	global_store_dword v[50:51], v57, off
	v_ashrrev_i32_e32 v57, 31, v56
	v_lshlrev_b64 v[54:55], 12, v[56:57]
	v_lshlrev_b32_e32 v56, 5, v56
	v_and_or_b32 v90, v56, s54, v172
	v_or_b32_e32 v56, v90, v160
	v_lshl_add_u64 v[52:53], v[152:153], 0, v[52:53]
	v_ashrrev_i32_e32 v57, 31, v56
	global_store_dword v[52:53], v58, off
	v_cvt_pk_bf16_f32 v58, v59, s0
	v_lshl_add_u64 v[56:57], v[56:57], 1, s[0:1]
	v_lshl_add_u64 v[54:55], v[152:153], 0, v[54:55]
	global_store_short v[56:57], v58, off offset:6
	v_or_b32_e32 v58, v83, v187
	global_store_dword v[54:55], v59, off
; DI bfr f2bf(float a) { return (bfr)(pack2(a, 0.f) & 0xffffu); }
; DI void phase_gemm_in_even(const Params& p, char* smem) {
;     ...
;         float* o = p.out + O_MEMV + (size_t)l * 2097152;
;         bfr* vt = p.VT + (size_t)l * 2097152;
;         gemm_tile<1024>(p.MPB, p.WtXv + (size_t)l * 1048576, 1024, 1024, mt * 128, nt * 256, smem,
;                   [=](int row, int col, float v) {
;                     o[(size_t)row * 1024 + col] = v;
;                     const int ml = row & 15;
;                     const int rowpart = (row >> 8) * 262144 + ((row & 255) >> 4) * 512 + ((ml >> 2) & 1) * 256 + (((ml >> 3) << 2) | (ml & 3));
;                     const int colpart = (col >> 8) * 65536 + ((col & 255) >> 5) * 8192 + (col & 31) * 8;
;                     vt[rowpart + colpart] = f2bf(v);
;                   });
	v_ashrrev_i32_e32 v59, 31, v58
	v_lshlrev_b64 v[56:57], 12, v[58:59]
	v_lshlrev_b32_e32 v58, 5, v58
	v_and_or_b32 v91, v58, s54, v172
	v_or_b32_e32 v58, v91, v160
	v_lshl_add_u64 v[56:57], v[152:153], 0, v[56:57]
	v_ashrrev_i32_e32 v59, 31, v58
	global_store_dword v[56:57], v60, off
	v_cvt_pk_bf16_f32 v60, v60, s0
	v_lshl_add_u64 v[58:59], v[58:59], 1, s[0:1]
	v_or_b32_e32 v80, v83, v193
	global_store_short v[58:59], v60, off offset:8
	v_ashrrev_i32_e32 v81, 31, v80
	v_lshlrev_b32_e32 v60, 5, v80
	v_lshlrev_b64 v[58:59], 12, v[80:81]
	v_and_or_b32 v92, v60, s54, v172
	v_lshl_add_u64 v[58:59], v[152:153], 0, v[58:59]
	v_or_b32_e32 v60, v92, v160
	global_store_dword v[58:59], v61, off
	v_cvt_pk_bf16_f32 v80, v61, s0
	v_ashrrev_i32_e32 v61, 31, v60
	v_lshl_add_u64 v[60:61], v[60:61], 1, s[0:1]
	global_store_short v[60:61], v80, off offset:10
	v_or_b32_e32 v80, v83, v146
	v_ashrrev_i32_e32 v81, 31, v80
	v_lshlrev_b64 v[60:61], 12, v[80:81]
	v_lshlrev_b32_e32 v80, 5, v80
	v_and_or_b32 v93, v80, s54, v172
	v_or_b32_e32 v80, v93, v160
	v_lshl_add_u64 v[60:61], v[152:153], 0, v[60:61]
	v_ashrrev_i32_e32 v81, 31, v80
	global_store_dword v[60:61], v62, off
	v_cvt_pk_bf16_f32 v62, v62, s0
	v_lshl_add_u64 v[80:81], v[80:81], 1, s[0:1]
	v_or_b32_e32 v84, v83, v145
	global_store_short v[80:81], v62, off offset:12
	v_ashrrev_i32_e32 v85, 31, v84
	v_lshlrev_b32_e32 v62, 5, v84
	v_lshlrev_b64 v[80:81], 12, v[84:85]
	v_and_or_b32 v84, v62, s54, v172
	v_lshl_add_u64 v[80:81], v[152:153], 0, v[80:81]
	v_or_b32_e32 v62, v84, v160
	global_store_dword v[80:81], v63, off
	v_cvt_pk_bf16_f32 v83, v63, s0
	v_ashrrev_i32_e32 v63, 31, v62
	v_lshl_add_u64 v[62:63], v[62:63], 1, s[0:1]
	global_store_short v[62:63], v83, off offset:14
	global_store_dword v[64:65], v32, off offset:128
	v_or_b32_e32 v62, v126, v86
	global_store_dword v[66:67], v33, off offset:128
	global_store_dword v[68:69], v34, off offset:128
	global_store_dword v[70:71], v35, off offset:128
	global_store_dword v[72:73], v36, off offset:128
	global_store_dword v[74:75], v37, off offset:128
	global_store_dword v[76:77], v38, off offset:128
	global_store_dword v[78:79], v39, off offset:128
	v_cvt_pk_bf16_f32 v39, v38, v39
	v_cvt_pk_bf16_f32 v38, v36, v37
	v_cvt_pk_bf16_f32 v36, v32, v33
	v_or_b32_e32 v32, v87, v126
	v_ashrrev_i32_e32 v63, 31, v62
	v_ashrrev_i32_e32 v33, 31, v32
	v_lshl_add_u64 v[62:63], v[62:63], 1, s[0:1]
	v_cvt_pk_bf16_f32 v37, v34, v35
	v_cvt_pk_bf16_f32 v34, v40, s0
	v_lshl_add_u64 v[32:33], v[32:33], 1, s[0:1]
	global_store_dwordx4 v[62:63], v[36:39], off
	global_store_dword v[48:49], v40, off offset:128
	global_store_short v[32:33], v34, off
	global_store_dword v[50:51], v41, off offset:128
	v_or_b32_e32 v32, v88, v126
	v_ashrrev_i32_e32 v33, 31, v32
	v_cvt_pk_bf16_f32 v34, v41, s0
	v_lshl_add_u64 v[32:33], v[32:33], 1, s[0:1]
	global_store_short v[32:33], v34, off offset:2
	global_store_dword v[52:53], v42, off offset:128
	v_or_b32_e32 v32, v89, v126
	v_ashrrev_i32_e32 v33, 31, v32
	v_cvt_pk_bf16_f32 v34, v42, s0
	v_lshl_add_u64 v[32:33], v[32:33], 1, s[0:1]
	global_store_short v[32:33], v34, off offset:4
	global_store_dword v[54:55], v43, off offset:128
	v_or_b32_e32 v32, v90, v126
	v_ashrrev_i32_e32 v33, 31, v32
	v_cvt_pk_bf16_f32 v34, v43, s0
	v_lshl_add_u64 v[32:33], v[32:33], 1, s[0:1]
	global_store_short v[32:33], v34, off offset:6
	global_store_dword v[56:57], v44, off offset:128
	v_or_b32_e32 v32, v91, v126
	v_ashrrev_i32_e32 v33, 31, v32
	v_cvt_pk_bf16_f32 v34, v44, s0
	v_lshl_add_u64 v[32:33], v[32:33], 1, s[0:1]
	global_store_short v[32:33], v34, off offset:8
	global_store_dword v[58:59], v45, off offset:128
	v_or_b32_e32 v32, v92, v126
	v_ashrrev_i32_e32 v33, 31, v32
	v_cvt_pk_bf16_f32 v34, v45, s0
	v_lshl_add_u64 v[32:33], v[32:33], 1, s[0:1]
	global_store_short v[32:33], v34, off offset:10
	global_store_dword v[60:61], v46, off offset:128
	v_or_b32_e32 v32, v93, v126
	v_ashrrev_i32_e32 v33, 31, v32
	v_cvt_pk_bf16_f32 v34, v46, s0
	v_lshl_add_u64 v[32:33], v[32:33], 1, s[0:1]
	global_store_short v[32:33], v34, off offset:12
	global_store_dword v[80:81], v47, off offset:128
	v_or_b32_e32 v32, v84, v126
	v_ashrrev_i32_e32 v33, 31, v32
	v_cvt_pk_bf16_f32 v34, v47, s0
	v_lshl_add_u64 v[32:33], v[32:33], 1, s[0:1]
	global_store_short v[32:33], v34, off offset:14
	global_store_dword v[64:65], v16, off offset:256
	v_or_b32_e32 v32, v96, v86
	global_store_dword v[66:67], v17, off offset:256
	global_store_dword v[68:69], v18, off offset:256
	global_store_dword v[70:71], v19, off offset:256
	global_store_dword v[72:73], v20, off offset:256
	global_store_dword v[74:75], v21, off offset:256
	global_store_dword v[76:77], v22, off offset:256
; DI bfr f2bf(float a) { return (bfr)(pack2(a, 0.f) & 0xffffu); }
; DI void phase_gemm_in_even(const Params& p, char* smem) {
;     ...
;         float* o = p.out + O_MEMV + (size_t)l * 2097152;
;         bfr* vt = p.VT + (size_t)l * 2097152;
;         gemm_tile<1024>(p.MPB, p.WtXv + (size_t)l * 1048576, 1024, 1024, mt * 128, nt * 256, smem,
;                   [=](int row, int col, float v) {
;                     o[(size_t)row * 1024 + col] = v;
;                     const int ml = row & 15;
;                     const int rowpart = (row >> 8) * 262144 + ((row & 255) >> 4) * 512 + ((ml >> 2) & 1) * 256 + (((ml >> 3) << 2) | (ml & 3));
;                     const int colpart = (col >> 8) * 65536 + ((col & 255) >> 5) * 8192 + (col & 31) * 8;
;                     vt[rowpart + colpart] = f2bf(v);
;                   });
	global_store_dword v[78:79], v23, off offset:256
	v_cvt_pk_bf16_f32 v23, v22, v23
	v_cvt_pk_bf16_f32 v22, v20, v21
	v_cvt_pk_bf16_f32 v20, v16, v17
	v_or_b32_e32 v16, v87, v96
	v_ashrrev_i32_e32 v33, 31, v32
	v_ashrrev_i32_e32 v17, 31, v16
	v_lshl_add_u64 v[32:33], v[32:33], 1, s[0:1]
	v_cvt_pk_bf16_f32 v21, v18, v19
	v_cvt_pk_bf16_f32 v18, v24, s0
	v_lshl_add_u64 v[16:17], v[16:17], 1, s[0:1]
	global_store_dwordx4 v[32:33], v[20:23], off
	global_store_dword v[48:49], v24, off offset:256
	global_store_short v[16:17], v18, off
	global_store_dword v[50:51], v25, off offset:256
	v_or_b32_e32 v16, v88, v96
	v_ashrrev_i32_e32 v17, 31, v16
	v_cvt_pk_bf16_f32 v18, v25, s0
	v_lshl_add_u64 v[16:17], v[16:17], 1, s[0:1]
	global_store_short v[16:17], v18, off offset:2
	global_store_dword v[52:53], v26, off offset:256
	v_or_b32_e32 v16, v89, v96
	v_ashrrev_i32_e32 v17, 31, v16
	v_cvt_pk_bf16_f32 v18, v26, s0
	v_lshl_add_u64 v[16:17], v[16:17], 1, s[0:1]
	global_store_short v[16:17], v18, off offset:4
	global_store_dword v[54:55], v27, off offset:256
	v_or_b32_e32 v16, v90, v96
	v_ashrrev_i32_e32 v17, 31, v16
	v_cvt_pk_bf16_f32 v18, v27, s0
	v_lshl_add_u64 v[16:17], v[16:17], 1, s[0:1]
	global_store_short v[16:17], v18, off offset:6
	global_store_dword v[56:57], v28, off offset:256
	v_or_b32_e32 v16, v91, v96
	v_ashrrev_i32_e32 v17, 31, v16
	v_cvt_pk_bf16_f32 v18, v28, s0
	v_lshl_add_u64 v[16:17], v[16:17], 1, s[0:1]
	global_store_short v[16:17], v18, off offset:8
	global_store_dword v[58:59], v29, off offset:256
	v_or_b32_e32 v16, v92, v96
	v_ashrrev_i32_e32 v17, 31, v16
	v_cvt_pk_bf16_f32 v18, v29, s0
	v_lshl_add_u64 v[16:17], v[16:17], 1, s[0:1]
	global_store_short v[16:17], v18, off offset:10
	global_store_dword v[60:61], v30, off offset:256
	v_or_b32_e32 v16, v93, v96
	v_ashrrev_i32_e32 v17, 31, v16
	v_cvt_pk_bf16_f32 v18, v30, s0
	v_lshl_add_u64 v[16:17], v[16:17], 1, s[0:1]
	global_store_short v[16:17], v18, off offset:12
	global_store_dword v[80:81], v31, off offset:256
	v_or_b32_e32 v16, v84, v96
	v_ashrrev_i32_e32 v17, 31, v16
	v_cvt_pk_bf16_f32 v18, v31, s0
	v_lshl_add_u64 v[16:17], v[16:17], 1, s[0:1]
	global_store_short v[16:17], v18, off offset:14
	global_store_dword v[64:65], v0, off offset:384
	v_or_b32_e32 v16, v82, v86
	global_store_dword v[66:67], v1, off offset:384
	global_store_dword v[68:69], v2, off offset:384
	global_store_dword v[70:71], v3, off offset:384
	global_store_dword v[72:73], v4, off offset:384
	global_store_dword v[74:75], v5, off offset:384
	global_store_dword v[76:77], v6, off offset:384
	global_store_dword v[78:79], v7, off offset:384
	v_cvt_pk_bf16_f32 v7, v6, v7
	v_cvt_pk_bf16_f32 v6, v4, v5
	v_cvt_pk_bf16_f32 v4, v0, v1
	v_or_b32_e32 v0, v87, v82
	v_ashrrev_i32_e32 v17, 31, v16
	v_ashrrev_i32_e32 v1, 31, v0
	v_lshl_add_u64 v[16:17], v[16:17], 1, s[0:1]
	v_cvt_pk_bf16_f32 v5, v2, v3
	v_cvt_pk_bf16_f32 v2, v8, s0
	v_lshl_add_u64 v[0:1], v[0:1], 1, s[0:1]
	global_store_dwordx4 v[16:17], v[4:7], off
	global_store_dword v[48:49], v8, off offset:384
	global_store_short v[0:1], v2, off
	global_store_dword v[50:51], v9, off offset:384
	v_or_b32_e32 v0, v88, v82
	v_ashrrev_i32_e32 v1, 31, v0
	v_cvt_pk_bf16_f32 v2, v9, s0
	v_lshl_add_u64 v[0:1], v[0:1], 1, s[0:1]
	global_store_short v[0:1], v2, off offset:2
	global_store_dword v[52:53], v10, off offset:384
	v_or_b32_e32 v0, v89, v82
	v_ashrrev_i32_e32 v1, 31, v0
	v_cvt_pk_bf16_f32 v2, v10, s0
	v_lshl_add_u64 v[0:1], v[0:1], 1, s[0:1]
	global_store_short v[0:1], v2, off offset:4
	global_store_dword v[54:55], v11, off offset:384
	v_or_b32_e32 v0, v90, v82
	v_ashrrev_i32_e32 v1, 31, v0
	v_cvt_pk_bf16_f32 v2, v11, s0
	v_lshl_add_u64 v[0:1], v[0:1], 1, s[0:1]
	global_store_short v[0:1], v2, off offset:6
	global_store_dword v[56:57], v12, off offset:384
	v_or_b32_e32 v0, v91, v82
	v_ashrrev_i32_e32 v1, 31, v0
	v_cvt_pk_bf16_f32 v2, v12, s0
	v_lshl_add_u64 v[0:1], v[0:1], 1, s[0:1]
	global_store_short v[0:1], v2, off offset:8
	global_store_dword v[58:59], v13, off offset:384
	v_or_b32_e32 v0, v92, v82
	v_ashrrev_i32_e32 v1, 31, v0
	v_cvt_pk_bf16_f32 v2, v13, s0
	v_lshl_add_u64 v[0:1], v[0:1], 1, s[0:1]
	global_store_short v[0:1], v2, off offset:10
	global_store_dword v[60:61], v14, off offset:384
	v_or_b32_e32 v0, v93, v82
	v_ashrrev_i32_e32 v1, 31, v0
	v_cvt_pk_bf16_f32 v2, v14, s0
	v_lshl_add_u64 v[0:1], v[0:1], 1, s[0:1]
	global_store_short v[0:1], v2, off offset:12
	global_store_dword v[80:81], v15, off offset:384
	v_or_b32_e32 v0, v84, v82
	v_ashrrev_i32_e32 v1, 31, v0
	v_cvt_pk_bf16_f32 v2, v15, s0
	v_lshl_add_u64 v[0:1], v[0:1], 1, s[0:1]
	global_store_short v[0:1], v2, off offset:14
	s_mov_b64 s[0:1], 0

; #define MFMA32(a, b, c) __builtin_amdgcn_mfma_f32_32x32x16_bf16((a), (b), (c), 0, 0, 0)
; #define GA_LOAD(pr_) do { _Pragma("unroll") for (int i = 0; i < 4; ++i) ra[i] = *(const u32x4*)(Ab + (i * 32) * lda + (pr_) * 64); } while (0)
; #define GB_LOAD(kt_) do { const bfr* bk_ = Bb + (kt_) * NB * 32; \
;     _Pragma("unroll") for (int i = 0; i < 4; ++i) rb[i] = *(const u32x4*)(bk_ + (i * 64) * 32); } while (0)
; #define G_STORE(kt_) do { bfr* as_ = S0 + ((kt_) & 1) * GSTAGE; bfr* bs_ = as_ + 128 * 40; \
;     if (apar == ((kt_) & 1)) { _Pragma("unroll") for (int i = 0; i < 4; ++i) *(u32x4*)(as_ + asoff + i * 32 * 40) = ra[i]; } \
;     _Pragma("unroll") for (int i = 0; i < 4; ++i) *(u32x4*)(bs_ + bsoff + i * 64 * 40) = rb[i]; } while (0)
; template <int lda>
; DI void gemm_mainloop(const bfr* __restrict__ A, const bfr* __restrict__ Bt, int NB, int K, int m0, int n0, char* smem, f32x16 (&acc)[2][4]) {
;     ...
;   for (int kt = 0; kt < nk; ++kt) {
;     if (kt + 1 < nk) G_STORE(kt + 1);
;     if (kt + 2 < nk) {
;       GB_LOAD(kt + 2);
;       if ((kt & 1) == 0) GA_LOAD((kt >> 1) + 1);
;     }
;     const bfr* As = S0 + (kt & 1) * GSTAGE;
;     const bfr* Bs = As + 128 * 40;
; #pragma unroll
;     for (int ks = 0; ks < 2; ++ks) {
;       bf16x8 af[2], bfg[4];
; #pragma unroll
;       for (int i = 0; i < 2; ++i) af[i] = *(const bf16x8*)(As + (wr * 64 + i * 32 + r) * 40 + ks * 16 + hl * 8);
; #pragma unroll
;       for (int j = 0; j < 4; ++j) bfg[j] = *(const bf16x8*)(Bs + (wc * 128 + j * 32 + r) * 40 + ks * 16 + hl * 8);
; #pragma unroll
;       for (int i = 0; i < 2; ++i)
; #pragma unroll
;         for (int j = 0; j < 4; ++j) acc[i][j] = MFMA32(af[i], bfg[j], acc[i][j]);
;     }
;     __syncthreads();
;   }
.Lp1k_loop:
	s_waitcnt vmcnt(6) lgkmcnt(0)
	s_barrier
	s_mul_i32 s74, s71, 0x6000
	s_add_u32 s75, s74, 0x2000
	s_cmp_eq_u32 s71, 2
	s_cselect_b32 s75, 0x10000, s75
	v_add_u32_e32 v184, s74, v180
	v_add_u32_e32 v186, s75, v182
	v_add_u32_e32 v185, s74, v181
	v_add_u32_e32 v187, s75, v183
	s_add_u32 s71, s71, 1
	s_cmp_eq_u32 s71, 3
	s_cselect_b32 s71, 0, s71
	ds_read_b128 v[128:131], v184
	ds_read_b128 v[144:147], v186
	ds_read_b128 v[148:151], v186 offset:2048
	ds_read_b128 v[152:155], v186 offset:4096
	ds_read_b128 v[156:159], v186 offset:6144
	ds_read_b128 v[132:135], v184 offset:2048
	v_mfma_f32_32x32x16_bf16 v[112:127], v[136:139], v[164:167], v[112:127]
	s_mul_i32 s74, s70, 0x6000
	s_add_u32 s75, s74, s68
	s_mov_b32 m0, s75
	s_add_u32 s76, s74, 0x2000
	s_cmp_eq_u32 s70, 2
	s_cselect_b32 s76, 0x10000, s76
	global_load_lds_dwordx4 v160, s[64:65]
	v_mfma_f32_32x32x16_bf16 v[96:111], v[136:139], v[168:171], v[96:111]
	s_add_u32 m0, s75, 0x400
	s_add_u32 s76, s76, s69
	global_load_lds_dwordx4 v162, s[64:65]
	v_mfma_f32_32x32x16_bf16 v[80:95], v[136:139], v[172:175], v[80:95]
	s_mov_b32 m0, s76
	s_add_u32 s64, s64, 64
	s_addc_u32 s65, s65, 0
	global_load_lds_dwordx4 v163, s[66:67]
	v_mfma_f32_32x32x16_bf16 v[64:79], v[136:139], v[176:179], v[64:79]
	global_load_lds_dwordx4 v163, s[66:67] offset:1024
	v_mfma_f32_32x32x16_bf16 v[48:63], v[140:143], v[164:167], v[48:63]
	global_load_lds_dwordx4 v163, s[66:67] offset:2048
	v_mfma_f32_32x32x16_bf16 v[32:47], v[140:143], v[168:171], v[32:47]
	global_load_lds_dwordx4 v163, s[66:67] offset:3072
	s_add_u32 s66, s66, 0x10000
	s_addc_u32 s67, s67, 0
	v_mfma_f32_32x32x16_bf16 v[16:31], v[140:143], v[172:175], v[16:31]
	s_add_u32 s70, s70, 1
	s_cmp_eq_u32 s70, 3
	s_cselect_b32 s70, 0, s70
	v_mfma_f32_32x32x16_bf16 v[0:15], v[140:143], v[176:179], v[0:15]
	ds_read_b128 v[136:139], v185
	ds_read_b128 v[164:167], v187
	ds_read_b128 v[168:171], v187 offset:2048
	ds_read_b128 v[172:175], v187 offset:4096
	ds_read_b128 v[176:179], v187 offset:6144
	ds_read_b128 v[140:143], v185 offset:2048
	s_waitcnt lgkmcnt(10)
	v_mfma_f32_32x32x16_bf16 v[112:127], v[128:131], v[144:147], v[112:127]
	s_waitcnt lgkmcnt(9)
	v_mfma_f32_32x32x16_bf16 v[96:111], v[128:131], v[148:151], v[96:111]
	s_waitcnt lgkmcnt(8)
	v_mfma_f32_32x32x16_bf16 v[80:95], v[128:131], v[152:155], v[80:95]
	s_waitcnt lgkmcnt(7)
	v_mfma_f32_32x32x16_bf16 v[64:79], v[128:131], v[156:159], v[64:79]
	s_waitcnt lgkmcnt(6)
	v_mfma_f32_32x32x16_bf16 v[48:63], v[132:135], v[144:147], v[48:63]
	v_mfma_f32_32x32x16_bf16 v[32:47], v[132:135], v[148:151], v[32:47]
	v_mfma_f32_32x32x16_bf16 v[16:31], v[132:135], v[152:155], v[16:31]
	v_mfma_f32_32x32x16_bf16 v[0:15], v[132:135], v[156:159], v[0:15]
	s_add_u32 s72, s72, 1
	s_cmp_lt_u32 s72, 29
	s_cbranch_scc1 .Lp1k_loop
	s_waitcnt vmcnt(6) lgkmcnt(0)
	s_barrier
	s_mul_i32 s74, s71, 0x6000
	s_add_u32 s75, s74, 0x2000
	s_cmp_eq_u32 s71, 2
	s_cselect_b32 s75, 0x10000, s75
	v_add_u32_e32 v184, s74, v180
	v_add_u32_e32 v186, s75, v182
	v_add_u32_e32 v185, s74, v181
	v_add_u32_e32 v187, s75, v183
	s_add_u32 s71, s71, 1
	s_cmp_eq_u32 s71, 3
	s_cselect_b32 s71, 0, s71
	ds_read_b128 v[128:131], v184
	ds_read_b128 v[144:147], v186
	ds_read_b128 v[148:151], v186 offset:2048
	ds_read_b128 v[152:155], v186 offset:4096
	ds_read_b128 v[156:159], v186 offset:6144
	ds_read_b128 v[132:135], v184 offset:2048
	v_mfma_f32_32x32x16_bf16 v[112:127], v[136:139], v[164:167], v[112:127]
	v_mfma_f32_32x32x16_bf16 v[96:111], v[136:139], v[168:171], v[96:111]
	v_mfma_f32_32x32x16_bf16 v[80:95], v[136:139], v[172:175], v[80:95]
	v_mfma_f32_32x32x16_bf16 v[64:79], v[136:139], v[176:179], v[64:79]
	v_mfma_f32_32x32x16_bf16 v[48:63], v[140:143], v[164:167], v[48:63]
	v_mfma_f32_32x32x16_bf16 v[32:47], v[140:143], v[168:171], v[32:47]
	v_mfma_f32_32x32x16_bf16 v[16:31], v[140:143], v[172:175], v[16:31]
	v_mfma_f32_32x32x16_bf16 v[0:15], v[140:143], v[176:179], v[0:15]
	ds_read_b128 v[136:139], v185
	ds_read_b128 v[164:167], v187
	ds_read_b128 v[168:171], v187 offset:2048
	ds_read_b128 v[172:175], v187 offset:4096
	ds_read_b128 v[176:179], v187 offset:6144
	ds_read_b128 v[140:143], v185 offset:2048
	s_waitcnt lgkmcnt(10)
	v_mfma_f32_32x32x16_bf16 v[112:127], v[128:131], v[144:147], v[112:127]
	s_waitcnt lgkmcnt(9)
	v_mfma_f32_32x32x16_bf16 v[96:111], v[128:131], v[148:151], v[96:111]
	s_waitcnt lgkmcnt(8)
	v_mfma_f32_32x32x16_bf16 v[80:95], v[128:131], v[152:155], v[80:95]
	s_waitcnt lgkmcnt(7)
	v_mfma_f32_32x32x16_bf16 v[64:79], v[128:131], v[156:159], v[64:79]
	s_waitcnt lgkmcnt(6)
	v_mfma_f32_32x32x16_bf16 v[48:63], v[132:135], v[144:147], v[48:63]
	v_mfma_f32_32x32x16_bf16 v[32:47], v[132:135], v[148:151], v[32:47]
	v_mfma_f32_32x32x16_bf16 v[16:31], v[132:135], v[152:155], v[16:31]
	v_mfma_f32_32x32x16_bf16 v[0:15], v[132:135], v[156:159], v[0:15]
	s_waitcnt vmcnt(0) lgkmcnt(0)
	s_barrier
; #define MFMA32(a, b, c) __builtin_amdgcn_mfma_f32_32x32x16_bf16((a), (b), (c), 0, 0, 0)
; #define GA_LOAD(pr_) do { _Pragma("unroll") for (int i = 0; i < 4; ++i) ra[i] = *(const u32x4*)(Ab + (i * 32) * lda + (pr_) * 64); } while (0)
; #define GB_LOAD(kt_) do { const bfr* bk_ = Bb + (kt_) * NB * 32; \
;     _Pragma("unroll") for (int i = 0; i < 4; ++i) rb[i] = *(const u32x4*)(bk_ + (i * 64) * 32); } while (0)
; #define G_STORE(kt_) do { bfr* as_ = S0 + ((kt_) & 1) * GSTAGE; bfr* bs_ = as_ + 128 * 40; \
;     if (apar == ((kt_) & 1)) { _Pragma("unroll") for (int i = 0; i < 4; ++i) *(u32x4*)(as_ + asoff + i * 32 * 40) = ra[i]; } \
;     _Pragma("unroll") for (int i = 0; i < 4; ++i) *(u32x4*)(bs_ + bsoff + i * 64 * 40) = rb[i]; } while (0)
; template <int lda>
; DI void gemm_mainloop(const bfr* __restrict__ A, const bfr* __restrict__ Bt, int NB, int K, int m0, int n0, char* smem, f32x16 (&acc)[2][4]) {
;     ...
;   for (int kt = 0; kt < nk; ++kt) {
;     if (kt + 1 < nk) G_STORE(kt + 1);
;     if (kt + 2 < nk) {
;       GB_LOAD(kt + 2);
;       if ((kt & 1) == 0) GA_LOAD((kt >> 1) + 1);
;     }
;     const bfr* As = S0 + (kt & 1) * GSTAGE;
;     const bfr* Bs = As + 128 * 40;
; #pragma unroll
;     for (int ks = 0; ks < 2; ++ks) {
;       bf16x8 af[2], bfg[4];
; #pragma unroll
;       for (int i = 0; i < 2; ++i) af[i] = *(const bf16x8*)(As + (wr * 64 + i * 32 + r) * 40 + ks * 16 + hl * 8);
; #pragma unroll
;       for (int j = 0; j < 4; ++j) bfg[j] = *(const bf16x8*)(Bs + (wc * 128 + j * 32 + r) * 40 + ks * 16 + hl * 8);
; #pragma unroll
;       for (int i = 0; i < 2; ++i)
; #pragma unroll
;         for (int j = 0; j < 4; ++j) acc[i][j] = MFMA32(af[i], bfg[j], acc[i][j]);
;     }
;     __syncthreads();
;   }
	s_mul_i32 s74, s71, 0x6000
	s_add_u32 s75, s74, 0x2000
	s_cmp_eq_u32 s71, 2
	s_cselect_b32 s75, 0x10000, s75
	v_add_u32_e32 v184, s74, v180
	v_add_u32_e32 v186, s75, v182
	v_add_u32_e32 v185, s74, v181
	v_add_u32_e32 v187, s75, v183
	s_add_u32 s71, s71, 1
	s_cmp_eq_u32 s71, 3
	s_cselect_b32 s71, 0, s71
	ds_read_b128 v[128:131], v184
	ds_read_b128 v[144:147], v186
	ds_read_b128 v[148:151], v186 offset:2048
	ds_read_b128 v[152:155], v186 offset:4096
	ds_read_b128 v[156:159], v186 offset:6144
	ds_read_b128 v[132:135], v184 offset:2048
	v_mfma_f32_32x32x16_bf16 v[112:127], v[136:139], v[164:167], v[112:127]
	v_mfma_f32_32x32x16_bf16 v[96:111], v[136:139], v[168:171], v[96:111]
	v_mfma_f32_32x32x16_bf16 v[80:95], v[136:139], v[172:175], v[80:95]
	v_mfma_f32_32x32x16_bf16 v[64:79], v[136:139], v[176:179], v[64:79]
	v_mfma_f32_32x32x16_bf16 v[48:63], v[140:143], v[164:167], v[48:63]
	v_mfma_f32_32x32x16_bf16 v[32:47], v[140:143], v[168:171], v[32:47]
	v_mfma_f32_32x32x16_bf16 v[16:31], v[140:143], v[172:175], v[16:31]
	v_mfma_f32_32x32x16_bf16 v[0:15], v[140:143], v[176:179], v[0:15]
	ds_read_b128 v[136:139], v185
	ds_read_b128 v[164:167], v187
	ds_read_b128 v[168:171], v187 offset:2048
	ds_read_b128 v[172:175], v187 offset:4096
	ds_read_b128 v[176:179], v187 offset:6144
	ds_read_b128 v[140:143], v185 offset:2048
	s_waitcnt lgkmcnt(10)
	v_mfma_f32_32x32x16_bf16 v[112:127], v[128:131], v[144:147], v[112:127]
	s_waitcnt lgkmcnt(9)
	v_mfma_f32_32x32x16_bf16 v[96:111], v[128:131], v[148:151], v[96:111]
	s_waitcnt lgkmcnt(8)
	v_mfma_f32_32x32x16_bf16 v[80:95], v[128:131], v[152:155], v[80:95]
	s_waitcnt lgkmcnt(7)
	v_mfma_f32_32x32x16_bf16 v[64:79], v[128:131], v[156:159], v[64:79]
	s_waitcnt lgkmcnt(6)
	v_mfma_f32_32x32x16_bf16 v[48:63], v[132:135], v[144:147], v[48:63]
	v_mfma_f32_32x32x16_bf16 v[32:47], v[132:135], v[148:151], v[32:47]
	v_mfma_f32_32x32x16_bf16 v[16:31], v[132:135], v[152:155], v[16:31]
	v_mfma_f32_32x32x16_bf16 v[0:15], v[132:135], v[156:159], v[0:15]
	s_waitcnt lgkmcnt(0)
	v_mfma_f32_32x32x16_bf16 v[112:127], v[136:139], v[164:167], v[112:127]
	v_mfma_f32_32x32x16_bf16 v[96:111], v[136:139], v[168:171], v[96:111]
	v_mfma_f32_32x32x16_bf16 v[80:95], v[136:139], v[172:175], v[80:95]
	v_mfma_f32_32x32x16_bf16 v[64:79], v[136:139], v[176:179], v[64:79]
	v_mfma_f32_32x32x16_bf16 v[48:63], v[140:143], v[164:167], v[48:63]
	v_mfma_f32_32x32x16_bf16 v[32:47], v[140:143], v[168:171], v[32:47]
	v_mfma_f32_32x32x16_bf16 v[16:31], v[140:143], v[172:175], v[16:31]
	v_mfma_f32_32x32x16_bf16 v[0:15], v[140:143], v[176:179], v[0:15]
	s_nop 7
	v_readlane_b32 s64, v188, 0
	v_readlane_b32 s65, v188, 1
	v_readlane_b32 s66, v188, 2
	v_readlane_b32 s67, v188, 3
	v_readlane_b32 s68, v188, 4
	v_readlane_b32 s69, v188, 5
	v_readlane_b32 s70, v188, 6
	v_readlane_b32 s71, v188, 7
	v_readlane_b32 s72, v188, 8
	v_readlane_b32 s73, v188, 9
	v_readlane_b32 s74, v188, 10
	v_readlane_b32 s75, v188, 11
	v_readlane_b32 s76, v188, 12
	v_readlane_b32 s77, v188, 13
	v_readlane_b32 s78, v188, 14
	v_readlane_b32 s79, v188, 15
	s_nop 7
	s_branch .Lp1k_tail

; #define MFMA32(a, b, c) __builtin_amdgcn_mfma_f32_32x32x16_bf16((a), (b), (c), 0, 0, 0)
; #define GA_LOAD(pr_) do { _Pragma("unroll") for (int i = 0; i < 4; ++i) ra[i] = *(const u32x4*)(Ab + (i * 32) * lda + (pr_) * 64); } while (0)
; #define GB_LOAD(kt_) do { const bfr* bk_ = Bb + (kt_) * NB * 32; \
;     _Pragma("unroll") for (int i = 0; i < 4; ++i) rb[i] = *(const u32x4*)(bk_ + (i * 64) * 32); } while (0)
; #define G_STORE(kt_) do { bfr* as_ = S0 + ((kt_) & 1) * GSTAGE; bfr* bs_ = as_ + 128 * 40; \
;     if (apar == ((kt_) & 1)) { _Pragma("unroll") for (int i = 0; i < 4; ++i) *(u32x4*)(as_ + asoff + i * 32 * 40) = ra[i]; } \
;     _Pragma("unroll") for (int i = 0; i < 4; ++i) *(u32x4*)(bs_ + bsoff + i * 64 * 40) = rb[i]; } while (0)
; template <int lda>
; DI void gemm_mainloop(const bfr* __restrict__ A, const bfr* __restrict__ Bt, int NB, int K, int m0, int n0, char* smem, f32x16 (&acc)[2][4]) {
;     ...
; #pragma unroll
;   for (int i = 0; i < 2; ++i)
; #pragma unroll
;     for (int j = 0; j < 4; ++j)
; #pragma unroll
;       for (int q = 0; q < 16; ++q) acc[i][j][q] = 0.f;
;   u32x4 ra[4], rb[4];
;   const int nk = K >> 5;
;   const int arow = tid >> 3, ac8 = tid & 7, apar = ac8 >> 2;
;   const bfr* Ab = A + (m0 + arow) * lda + ac8 * 8;
;   const int asoff = arow * 40 + (ac8 & 3) * 8;
;   const int brow = tid >> 2, bc4 = tid & 3;
;   const bfr* Bb = Bt + (n0 + brow) * 32 + bc4 * 8;
;   const int bsoff = brow * 40 + bc4 * 8;
;     ...
;   GA_LOAD(0);
;   GB_LOAD(0);
;   G_STORE(0);
;   GB_LOAD(1);
;   __syncthreads();
;   for (int kt = 0; kt < nk; ++kt) {
;     if (kt + 1 < nk) G_STORE(kt + 1);
;     if (kt + 2 < nk) {
;       GB_LOAD(kt + 2);
;       if ((kt & 1) == 0) GA_LOAD((kt >> 1) + 1);
;     }
;     const bfr* As = S0 + (kt & 1) * GSTAGE;
;     const bfr* Bs = As + 128 * 40;
; #pragma unroll
;     for (int ks = 0; ks < 2; ++ks) {
;       bf16x8 af[2], bfg[4];
; #pragma unroll
;       for (int i = 0; i < 2; ++i) af[i] = *(const bf16x8*)(As + (wr * 64 + i * 32 + r) * 40 + ks * 16 + hl * 8);
; #pragma unroll
;       for (int j = 0; j < 4; ++j) bfg[j] = *(const bf16x8*)(Bs + (wc * 128 + j * 32 + r) * 40 + ks * 16 + hl * 8);
; #pragma unroll
;       for (int i = 0; i < 2; ++i)
; #pragma unroll
;         for (int j = 0; j < 4; ++j) acc[i][j] = MFMA32(af[i], bfg[j], acc[i][j]);
;     }
.Lp1e_nostag:
	v_mov_b32_e32 v112, 0
	v_mov_b32_e32 v113, 0
	v_mov_b32_e32 v114, 0
	v_mov_b32_e32 v115, 0
	v_mov_b32_e32 v116, 0
	v_mov_b32_e32 v117, 0
	v_mov_b32_e32 v118, 0
	v_mov_b32_e32 v119, 0
	v_mov_b32_e32 v120, 0
	v_mov_b32_e32 v121, 0
	v_mov_b32_e32 v122, 0
	v_mov_b32_e32 v123, 0
	v_mov_b32_e32 v124, 0
	v_mov_b32_e32 v125, 0
	v_mov_b32_e32 v126, 0
	v_mov_b32_e32 v127, 0
	v_mov_b32_e32 v96, 0
	v_mov_b32_e32 v97, 0
	v_mov_b32_e32 v98, 0
	v_mov_b32_e32 v99, 0
	v_mov_b32_e32 v100, 0
	v_mov_b32_e32 v101, 0
	v_mov_b32_e32 v102, 0
	v_mov_b32_e32 v103, 0
	v_mov_b32_e32 v104, 0
	v_mov_b32_e32 v105, 0
	v_mov_b32_e32 v106, 0
	v_mov_b32_e32 v107, 0
	v_mov_b32_e32 v108, 0
	v_mov_b32_e32 v109, 0
	v_mov_b32_e32 v110, 0
	v_mov_b32_e32 v111, 0
	v_mov_b32_e32 v80, 0
	v_mov_b32_e32 v81, 0
	v_mov_b32_e32 v82, 0
	v_mov_b32_e32 v83, 0
	v_mov_b32_e32 v84, 0
	v_mov_b32_e32 v85, 0
	v_mov_b32_e32 v86, 0
	v_mov_b32_e32 v87, 0
	v_mov_b32_e32 v88, 0
	v_mov_b32_e32 v89, 0
	v_mov_b32_e32 v90, 0
	v_mov_b32_e32 v91, 0
	v_mov_b32_e32 v92, 0
	v_mov_b32_e32 v93, 0
	v_mov_b32_e32 v94, 0
	v_mov_b32_e32 v95, 0
	v_mov_b32_e32 v64, 0
	v_mov_b32_e32 v65, 0
	v_mov_b32_e32 v66, 0
	v_mov_b32_e32 v67, 0
	v_mov_b32_e32 v68, 0
	v_mov_b32_e32 v69, 0
	v_mov_b32_e32 v70, 0
	v_mov_b32_e32 v71, 0
	v_mov_b32_e32 v72, 0
	v_mov_b32_e32 v73, 0
	v_mov_b32_e32 v74, 0
	v_mov_b32_e32 v75, 0
	v_mov_b32_e32 v76, 0
	v_mov_b32_e32 v77, 0
	v_mov_b32_e32 v78, 0
	v_mov_b32_e32 v79, 0
	v_mov_b32_e32 v48, 0
	v_mov_b32_e32 v49, 0
	v_mov_b32_e32 v50, 0
	v_mov_b32_e32 v51, 0
	v_mov_b32_e32 v52, 0
	v_mov_b32_e32 v53, 0
	v_mov_b32_e32 v54, 0
	v_mov_b32_e32 v55, 0
	v_mov_b32_e32 v56, 0
	v_mov_b32_e32 v57, 0
	v_mov_b32_e32 v58, 0
	v_mov_b32_e32 v59, 0
	v_mov_b32_e32 v60, 0
	v_mov_b32_e32 v61, 0
	v_mov_b32_e32 v62, 0
	v_mov_b32_e32 v63, 0
	v_mov_b32_e32 v32, 0
	v_mov_b32_e32 v33, 0
	v_mov_b32_e32 v34, 0
	v_mov_b32_e32 v35, 0
	v_mov_b32_e32 v36, 0
	v_mov_b32_e32 v37, 0
	v_mov_b32_e32 v38, 0
	v_mov_b32_e32 v39, 0
	v_mov_b32_e32 v40, 0
	v_mov_b32_e32 v41, 0
	v_mov_b32_e32 v42, 0
	v_mov_b32_e32 v43, 0
	v_mov_b32_e32 v44, 0
	v_mov_b32_e32 v45, 0
	v_mov_b32_e32 v46, 0
	v_mov_b32_e32 v47, 0
	v_mov_b32_e32 v16, 0
	v_mov_b32_e32 v17, 0
	v_mov_b32_e32 v18, 0
	v_mov_b32_e32 v19, 0
	v_mov_b32_e32 v20, 0
	v_mov_b32_e32 v21, 0
	v_mov_b32_e32 v22, 0
	v_mov_b32_e32 v23, 0
	v_mov_b32_e32 v24, 0
	v_mov_b32_e32 v25, 0
	v_mov_b32_e32 v26, 0
	v_mov_b32_e32 v27, 0
	v_mov_b32_e32 v28, 0
	v_mov_b32_e32 v29, 0
	v_mov_b32_e32 v30, 0
	v_mov_b32_e32 v31, 0
	v_mov_b32_e32 v0, 0
	v_mov_b32_e32 v1, 0
	v_mov_b32_e32 v2, 0
	v_mov_b32_e32 v3, 0
	v_mov_b32_e32 v4, 0
	v_mov_b32_e32 v5, 0
	v_mov_b32_e32 v6, 0
	v_mov_b32_e32 v7, 0
	v_mov_b32_e32 v8, 0
	v_mov_b32_e32 v9, 0
	v_mov_b32_e32 v10, 0
	v_mov_b32_e32 v11, 0
	v_mov_b32_e32 v12, 0
	v_mov_b32_e32 v13, 0
	v_mov_b32_e32 v14, 0
	v_mov_b32_e32 v15, 0
	s_waitcnt vmcnt(6)
	s_barrier
	s_mul_i32 s74, s71, 0x6000
	s_add_u32 s75, s74, 0x2000
	s_cmp_eq_u32 s71, 2
	s_cselect_b32 s75, 0x10000, s75
	v_add_u32_e32 v184, s74, v180
	v_add_u32_e32 v186, s75, v182
	v_add_u32_e32 v185, s74, v181
	v_add_u32_e32 v187, s75, v183
	s_add_u32 s71, s71, 1
	s_cmp_eq_u32 s71, 3
	s_cselect_b32 s71, 0, s71
	ds_read_b128 v[128:131], v184
	ds_read_b128 v[144:147], v186
	ds_read_b128 v[148:151], v186 offset:2048
	ds_read_b128 v[152:155], v186 offset:4096
	ds_read_b128 v[156:159], v186 offset:6144
	ds_read_b128 v[132:135], v184 offset:2048
	ds_read_b128 v[136:139], v185
	ds_read_b128 v[164:167], v187
	ds_read_b128 v[168:171], v187 offset:2048
	ds_read_b128 v[172:175], v187 offset:4096
	ds_read_b128 v[176:179], v187 offset:6144
	ds_read_b128 v[140:143], v185 offset:2048
	s_waitcnt lgkmcnt(10)
	v_mfma_f32_32x32x16_bf16 v[112:127], v[144:147], v[128:131], v[112:127]
	s_mul_i32 s74, s70, 0x6000
	s_add_u32 s75, s74, s68
	s_mov_b32 m0, s75
	s_add_u32 s76, s74, 0x2000
	s_cmp_eq_u32 s70, 2
	s_cselect_b32 s76, 0x10000, s76
	global_load_lds_dwordx4 v160, s[64:65]
	s_waitcnt lgkmcnt(9)
	v_mfma_f32_32x32x16_bf16 v[96:111], v[148:151], v[128:131], v[96:111]
	s_add_u32 m0, s75, 0x400
	s_add_u32 s76, s76, s69
	global_load_lds_dwordx4 v162, s[64:65]
	s_waitcnt lgkmcnt(8)
	v_mfma_f32_32x32x16_bf16 v[80:95], v[152:155], v[128:131], v[80:95]
	s_mov_b32 m0, s76
	s_add_u32 s64, s64, 64
	s_addc_u32 s65, s65, 0
	global_load_lds_dwordx4 v163, s[66:67]
	s_waitcnt lgkmcnt(7)
	v_mfma_f32_32x32x16_bf16 v[64:79], v[156:159], v[128:131], v[64:79]
	global_load_lds_dwordx4 v163, s[66:67] offset:1024
	s_waitcnt lgkmcnt(6)
	v_mfma_f32_32x32x16_bf16 v[48:63], v[144:147], v[132:135], v[48:63]
	global_load_lds_dwordx4 v163, s[66:67] offset:2048
	v_mfma_f32_32x32x16_bf16 v[32:47], v[148:151], v[132:135], v[32:47]
	global_load_lds_dwordx4 v163, s[66:67] offset:3072
	s_add_u32 s66, s66, 0x3a000
	s_addc_u32 s67, s67, 0
	v_mfma_f32_32x32x16_bf16 v[16:31], v[152:155], v[132:135], v[16:31]
	s_add_u32 s70, s70, 1
	s_cmp_eq_u32 s70, 3
	s_cselect_b32 s70, 0, s70
	v_mfma_f32_32x32x16_bf16 v[0:15], v[156:159], v[132:135], v[0:15]
; #define MFMA32(a, b, c) __builtin_amdgcn_mfma_f32_32x32x16_bf16((a), (b), (c), 0, 0, 0)
; #define GA_LOAD(pr_) do { _Pragma("unroll") for (int i = 0; i < 4; ++i) ra[i] = *(const u32x4*)(Ab + (i * 32) * lda + (pr_) * 64); } while (0)
; #define GB_LOAD(kt_) do { const bfr* bk_ = Bb + (kt_) * NB * 32; \
;     _Pragma("unroll") for (int i = 0; i < 4; ++i) rb[i] = *(const u32x4*)(bk_ + (i * 64) * 32); } while (0)
; #define G_STORE(kt_) do { bfr* as_ = S0 + ((kt_) & 1) * GSTAGE; bfr* bs_ = as_ + 128 * 40; \
;     if (apar == ((kt_) & 1)) { _Pragma("unroll") for (int i = 0; i < 4; ++i) *(u32x4*)(as_ + asoff + i * 32 * 40) = ra[i]; } \
;     _Pragma("unroll") for (int i = 0; i < 4; ++i) *(u32x4*)(bs_ + bsoff + i * 64 * 40) = rb[i]; } while (0)
; template <int lda>
; DI void gemm_mainloop(const bfr* __restrict__ A, const bfr* __restrict__ Bt, int NB, int K, int m0, int n0, char* smem, f32x16 (&acc)[2][4]) {
;     ...
;   for (int kt = 0; kt < nk; ++kt) {
;     if (kt + 1 < nk) G_STORE(kt + 1);
;     if (kt + 2 < nk) {
;       GB_LOAD(kt + 2);
;       if ((kt & 1) == 0) GA_LOAD((kt >> 1) + 1);
;     }
;     const bfr* As = S0 + (kt & 1) * GSTAGE;
;     const bfr* Bs = As + 128 * 40;
; #pragma unroll
;     for (int ks = 0; ks < 2; ++ks) {
;       bf16x8 af[2], bfg[4];
; #pragma unroll
;       for (int i = 0; i < 2; ++i) af[i] = *(const bf16x8*)(As + (wr * 64 + i * 32 + r) * 40 + ks * 16 + hl * 8);
; #pragma unroll
;       for (int j = 0; j < 4; ++j) bfg[j] = *(const bf16x8*)(Bs + (wc * 128 + j * 32 + r) * 40 + ks * 16 + hl * 8);
; #pragma unroll
;       for (int i = 0; i < 2; ++i)
; #pragma unroll
;         for (int j = 0; j < 4; ++j) acc[i][j] = MFMA32(af[i], bfg[j], acc[i][j]);
;     }
;     __syncthreads();
;   }
.Lp1e_loop:
	s_waitcnt vmcnt(6) lgkmcnt(0)
	s_barrier
	s_mul_i32 s74, s71, 0x6000
	s_add_u32 s75, s74, 0x2000
	s_cmp_eq_u32 s71, 2
	s_cselect_b32 s75, 0x10000, s75
	v_add_u32_e32 v184, s74, v180
	v_add_u32_e32 v186, s75, v182
	v_add_u32_e32 v185, s74, v181
	v_add_u32_e32 v187, s75, v183
	s_add_u32 s71, s71, 1
	s_cmp_eq_u32 s71, 3
	s_cselect_b32 s71, 0, s71
	ds_read_b128 v[128:131], v184
	ds_read_b128 v[144:147], v186
	ds_read_b128 v[148:151], v186 offset:2048
	ds_read_b128 v[152:155], v186 offset:4096
	ds_read_b128 v[156:159], v186 offset:6144
	ds_read_b128 v[132:135], v184 offset:2048
	v_mfma_f32_32x32x16_bf16 v[112:127], v[164:167], v[136:139], v[112:127]
	s_mul_i32 s74, s70, 0x6000
	s_add_u32 s75, s74, s68
	s_mov_b32 m0, s75
	s_add_u32 s76, s74, 0x2000
	s_cmp_eq_u32 s70, 2
	s_cselect_b32 s76, 0x10000, s76
	global_load_lds_dwordx4 v160, s[64:65]
	v_mfma_f32_32x32x16_bf16 v[96:111], v[168:171], v[136:139], v[96:111]
	s_add_u32 m0, s75, 0x400
	s_add_u32 s76, s76, s69
	global_load_lds_dwordx4 v162, s[64:65]
	v_mfma_f32_32x32x16_bf16 v[80:95], v[172:175], v[136:139], v[80:95]
	s_mov_b32 m0, s76
	s_add_u32 s64, s64, 64
	s_addc_u32 s65, s65, 0
	global_load_lds_dwordx4 v163, s[66:67]
	v_mfma_f32_32x32x16_bf16 v[64:79], v[176:179], v[136:139], v[64:79]
	global_load_lds_dwordx4 v163, s[66:67] offset:1024
	v_mfma_f32_32x32x16_bf16 v[48:63], v[164:167], v[140:143], v[48:63]
	global_load_lds_dwordx4 v163, s[66:67] offset:2048
	v_mfma_f32_32x32x16_bf16 v[32:47], v[168:171], v[140:143], v[32:47]
	global_load_lds_dwordx4 v163, s[66:67] offset:3072
	s_add_u32 s66, s66, 0x3a000
	s_addc_u32 s67, s67, 0
	v_mfma_f32_32x32x16_bf16 v[16:31], v[172:175], v[140:143], v[16:31]
	s_add_u32 s70, s70, 1
	s_cmp_eq_u32 s70, 3
	s_cselect_b32 s70, 0, s70
	v_mfma_f32_32x32x16_bf16 v[0:15], v[176:179], v[140:143], v[0:15]
	ds_read_b128 v[136:139], v185
	ds_read_b128 v[164:167], v187
	ds_read_b128 v[168:171], v187 offset:2048
	ds_read_b128 v[172:175], v187 offset:4096
	ds_read_b128 v[176:179], v187 offset:6144
	ds_read_b128 v[140:143], v185 offset:2048
	s_waitcnt lgkmcnt(10)
	v_mfma_f32_32x32x16_bf16 v[112:127], v[144:147], v[128:131], v[112:127]
	s_waitcnt lgkmcnt(9)
	v_mfma_f32_32x32x16_bf16 v[96:111], v[148:151], v[128:131], v[96:111]
	s_waitcnt lgkmcnt(8)
	v_mfma_f32_32x32x16_bf16 v[80:95], v[152:155], v[128:131], v[80:95]
	s_waitcnt lgkmcnt(7)
	v_mfma_f32_32x32x16_bf16 v[64:79], v[156:159], v[128:131], v[64:79]
	s_waitcnt lgkmcnt(6)
	v_mfma_f32_32x32x16_bf16 v[48:63], v[144:147], v[132:135], v[48:63]
	v_mfma_f32_32x32x16_bf16 v[32:47], v[148:151], v[132:135], v[32:47]
	v_mfma_f32_32x32x16_bf16 v[16:31], v[152:155], v[132:135], v[16:31]
	v_mfma_f32_32x32x16_bf16 v[0:15], v[156:159], v[132:135], v[0:15]
	s_add_u32 s72, s72, 1
	s_cmp_lt_u32 s72, 29
	s_cbranch_scc1 .Lp1e_loop
	s_waitcnt vmcnt(6) lgkmcnt(0)
	s_barrier
	s_mul_i32 s74, s71, 0x6000
	s_add_u32 s75, s74, 0x2000
	s_cmp_eq_u32 s71, 2
	s_cselect_b32 s75, 0x10000, s75
	v_add_u32_e32 v184, s74, v180
	v_add_u32_e32 v186, s75, v182
	v_add_u32_e32 v185, s74, v181
	v_add_u32_e32 v187, s75, v183
	s_add_u32 s71, s71, 1
	s_cmp_eq_u32 s71, 3
	s_cselect_b32 s71, 0, s71
	ds_read_b128 v[128:131], v184
	ds_read_b128 v[144:147], v186
	ds_read_b128 v[148:151], v186 offset:2048
	ds_read_b128 v[152:155], v186 offset:4096
	ds_read_b128 v[156:159], v186 offset:6144
	ds_read_b128 v[132:135], v184 offset:2048
	v_mfma_f32_32x32x16_bf16 v[112:127], v[164:167], v[136:139], v[112:127]
	v_mfma_f32_32x32x16_bf16 v[96:111], v[168:171], v[136:139], v[96:111]
	v_mfma_f32_32x32x16_bf16 v[80:95], v[172:175], v[136:139], v[80:95]
	v_mfma_f32_32x32x16_bf16 v[64:79], v[176:179], v[136:139], v[64:79]
	v_mfma_f32_32x32x16_bf16 v[48:63], v[164:167], v[140:143], v[48:63]
	v_mfma_f32_32x32x16_bf16 v[32:47], v[168:171], v[140:143], v[32:47]
	v_mfma_f32_32x32x16_bf16 v[16:31], v[172:175], v[140:143], v[16:31]
	v_mfma_f32_32x32x16_bf16 v[0:15], v[176:179], v[140:143], v[0:15]
	ds_read_b128 v[136:139], v185
	ds_read_b128 v[164:167], v187
	ds_read_b128 v[168:171], v187 offset:2048
	ds_read_b128 v[172:175], v187 offset:4096
	ds_read_b128 v[176:179], v187 offset:6144
	ds_read_b128 v[140:143], v185 offset:2048
	s_waitcnt lgkmcnt(10)
	v_mfma_f32_32x32x16_bf16 v[112:127], v[144:147], v[128:131], v[112:127]
	s_waitcnt lgkmcnt(9)
	v_mfma_f32_32x32x16_bf16 v[96:111], v[148:151], v[128:131], v[96:111]
	s_waitcnt lgkmcnt(8)
	v_mfma_f32_32x32x16_bf16 v[80:95], v[152:155], v[128:131], v[80:95]
	s_waitcnt lgkmcnt(7)
	v_mfma_f32_32x32x16_bf16 v[64:79], v[156:159], v[128:131], v[64:79]
	s_waitcnt lgkmcnt(6)
	v_mfma_f32_32x32x16_bf16 v[48:63], v[144:147], v[132:135], v[48:63]
	v_mfma_f32_32x32x16_bf16 v[32:47], v[148:151], v[132:135], v[32:47]
	v_mfma_f32_32x32x16_bf16 v[16:31], v[152:155], v[132:135], v[16:31]
	v_mfma_f32_32x32x16_bf16 v[0:15], v[156:159], v[132:135], v[0:15]
	s_waitcnt vmcnt(0) lgkmcnt(0)
	s_barrier
; #define MFMA32(a, b, c) __builtin_amdgcn_mfma_f32_32x32x16_bf16((a), (b), (c), 0, 0, 0)
; DI int crow(int reg, int h) { return (reg & 3) + 8 * (reg >> 2) + 4 * h; }
; template <int lda>
; DI void gemm_mainloop(const bfr* __restrict__ A, const bfr* __restrict__ Bt, int NB, int K, int m0, int n0, char* smem, f32x16 (&acc)[2][4]) {
;     ...
;     const bfr* As = S0 + (kt & 1) * GSTAGE;
;     const bfr* Bs = As + 128 * 40;
; #pragma unroll
;     for (int ks = 0; ks < 2; ++ks) {
;       bf16x8 af[2], bfg[4];
; #pragma unroll
;       for (int i = 0; i < 2; ++i) af[i] = *(const bf16x8*)(As + (wr * 64 + i * 32 + r) * 40 + ks * 16 + hl * 8);
; #pragma unroll
;       for (int j = 0; j < 4; ++j) bfg[j] = *(const bf16x8*)(Bs + (wc * 128 + j * 32 + r) * 40 + ks * 16 + hl * 8);
; #pragma unroll
;       for (int i = 0; i < 2; ++i)
; #pragma unroll
;         for (int j = 0; j < 4; ++j) acc[i][j] = MFMA32(af[i], bfg[j], acc[i][j]);
;     }
;     __syncthreads();
; template <int lda, class Epi>
; DI void gemm_tile(const bfr* __restrict__ A, const bfr* __restrict__ Bt, int NB, int K, int m0, int n0, char* smem, Epi epi) {
;     ...
; #pragma unroll
;   for (int i = 0; i < 2; ++i)
; #pragma unroll
;     for (int j = 0; j < 4; ++j)
; #pragma unroll
;       for (int q = 0; q < 16; ++q) {
;         int row = m0 + wr * 64 + i * 32 + crow(q, hl);
;         int col = n0 + wc * 128 + j * 32 + r;
;         epi(row, col, acc[i][j][q]);
;       }
	s_mul_i32 s74, s71, 0x6000
	s_add_u32 s75, s74, 0x2000
	s_cmp_eq_u32 s71, 2
	s_cselect_b32 s75, 0x10000, s75
	v_add_u32_e32 v184, s74, v180
	v_add_u32_e32 v186, s75, v182
	v_add_u32_e32 v185, s74, v181
	v_add_u32_e32 v187, s75, v183
	s_add_u32 s71, s71, 1
	s_cmp_eq_u32 s71, 3
	s_cselect_b32 s71, 0, s71
	ds_read_b128 v[128:131], v184
	ds_read_b128 v[144:147], v186
	ds_read_b128 v[148:151], v186 offset:2048
	ds_read_b128 v[152:155], v186 offset:4096
	ds_read_b128 v[156:159], v186 offset:6144
	ds_read_b128 v[132:135], v184 offset:2048
	v_mfma_f32_32x32x16_bf16 v[112:127], v[164:167], v[136:139], v[112:127]
	v_mfma_f32_32x32x16_bf16 v[96:111], v[168:171], v[136:139], v[96:111]
	v_mfma_f32_32x32x16_bf16 v[80:95], v[172:175], v[136:139], v[80:95]
	v_mfma_f32_32x32x16_bf16 v[64:79], v[176:179], v[136:139], v[64:79]
	v_mfma_f32_32x32x16_bf16 v[48:63], v[164:167], v[140:143], v[48:63]
	v_mfma_f32_32x32x16_bf16 v[32:47], v[168:171], v[140:143], v[32:47]
	v_mfma_f32_32x32x16_bf16 v[16:31], v[172:175], v[140:143], v[16:31]
	v_mfma_f32_32x32x16_bf16 v[0:15], v[176:179], v[140:143], v[0:15]
	ds_read_b128 v[136:139], v185
	ds_read_b128 v[164:167], v187
	ds_read_b128 v[168:171], v187 offset:2048
	ds_read_b128 v[172:175], v187 offset:4096
	ds_read_b128 v[176:179], v187 offset:6144
	ds_read_b128 v[140:143], v185 offset:2048
	s_waitcnt lgkmcnt(10)
	v_mfma_f32_32x32x16_bf16 v[112:127], v[144:147], v[128:131], v[112:127]
	s_waitcnt lgkmcnt(9)
	v_mfma_f32_32x32x16_bf16 v[96:111], v[148:151], v[128:131], v[96:111]
	s_waitcnt lgkmcnt(8)
	v_mfma_f32_32x32x16_bf16 v[80:95], v[152:155], v[128:131], v[80:95]
	s_waitcnt lgkmcnt(7)
	v_mfma_f32_32x32x16_bf16 v[64:79], v[156:159], v[128:131], v[64:79]
	s_waitcnt lgkmcnt(6)
	v_mfma_f32_32x32x16_bf16 v[48:63], v[144:147], v[132:135], v[48:63]
	v_mfma_f32_32x32x16_bf16 v[32:47], v[148:151], v[132:135], v[32:47]
	v_mfma_f32_32x32x16_bf16 v[16:31], v[152:155], v[132:135], v[16:31]
	v_mfma_f32_32x32x16_bf16 v[0:15], v[156:159], v[132:135], v[0:15]
	s_waitcnt lgkmcnt(0)
	v_mfma_f32_32x32x16_bf16 v[112:127], v[164:167], v[136:139], v[112:127]
	v_mfma_f32_32x32x16_bf16 v[96:111], v[168:171], v[136:139], v[96:111]
	v_mfma_f32_32x32x16_bf16 v[80:95], v[172:175], v[136:139], v[80:95]
	v_mfma_f32_32x32x16_bf16 v[64:79], v[176:179], v[136:139], v[64:79]
	v_mfma_f32_32x32x16_bf16 v[48:63], v[164:167], v[140:143], v[48:63]
	v_mfma_f32_32x32x16_bf16 v[32:47], v[168:171], v[140:143], v[32:47]
	v_mfma_f32_32x32x16_bf16 v[16:31], v[172:175], v[140:143], v[16:31]
	v_mfma_f32_32x32x16_bf16 v[0:15], v[176:179], v[140:143], v[0:15]
	s_nop 7
	s_nop 3
	s_barrier
	s_load_dwordx2 s[64:65], s[92:93], 0x150
	v_and_b32_e32 v160, 31, v196
	v_bfe_u32 v162, v196, 5, 1
	s_lshr_b32 s74, s73, 1
	s_lshl_b32 s74, s74, 6
	s_add_u32 s74, s74, s77
	v_add_u32_e32 v163, s74, v160
	s_mul_i32 s76, s73, 8704
	v_mul_u32_u24_e32 v181, 272, v160
	v_lshl_add_u32 v181, v162, 3, v181
	v_add_u32_e32 v181, s76, v181
	v_bfe_u32 v186, v196, 4, 2
	v_and_b32_e32 v187, 15, v196
	v_mul_u32_u24_e32 v182, 272, v186
	v_lshl_add_u32 v182, v187, 4, v182
	v_add_u32_e32 v182, s76, v182
	s_and_b32 s75, s73, 1
	s_lshl_b32 s75, s75, 7
	s_add_u32 s75, s75, s78
	v_add_u32_e32 v180, s74, v186
	v_mul_u32_u24_e32 v180, 0xe00, v180
	v_lshl_add_u32 v180, v187, 3, v180
	v_add_lshl_u32 v183, v180, s75, 1
	s_waitcnt lgkmcnt(0)
	v_cvt_pk_bf16_f32 v112, v112, v113
	v_cvt_pk_bf16_f32 v113, v114, v115
	ds_write_b64 v181, v[112:113]
	v_cvt_pk_bf16_f32 v116, v116, v117
	v_cvt_pk_bf16_f32 v117, v118, v119
	ds_write_b64 v181, v[116:117] offset:16
	v_cvt_pk_bf16_f32 v120, v120, v121
	v_cvt_pk_bf16_f32 v121, v122, v123
	ds_write_b64 v181, v[120:121] offset:32
	v_cvt_pk_bf16_f32 v124, v124, v125
	v_cvt_pk_bf16_f32 v125, v126, v127
	ds_write_b64 v181, v[124:125] offset:48
	v_cvt_pk_bf16_f32 v96, v96, v97
	v_cvt_pk_bf16_f32 v97, v98, v99
	ds_write_b64 v181, v[96:97] offset:64
	v_cvt_pk_bf16_f32 v100, v100, v101
	v_cvt_pk_bf16_f32 v101, v102, v103
	ds_write_b64 v181, v[100:101] offset:80
	v_cvt_pk_bf16_f32 v104, v104, v105
	v_cvt_pk_bf16_f32 v105, v106, v107
	ds_write_b64 v181, v[104:105] offset:96
	v_cvt_pk_bf16_f32 v108, v108, v109
	v_cvt_pk_bf16_f32 v109, v110, v111
	ds_write_b64 v181, v[108:109] offset:112
	v_cvt_pk_bf16_f32 v80, v80, v81
	v_cvt_pk_bf16_f32 v81, v82, v83
	ds_write_b64 v181, v[80:81] offset:128
	v_cvt_pk_bf16_f32 v84, v84, v85
	v_cvt_pk_bf16_f32 v85, v86, v87
	ds_write_b64 v181, v[84:85] offset:144
	v_cvt_pk_bf16_f32 v88, v88, v89
	v_cvt_pk_bf16_f32 v89, v90, v91
	ds_write_b64 v181, v[88:89] offset:160
	v_cvt_pk_bf16_f32 v92, v92, v93
	v_cvt_pk_bf16_f32 v93, v94, v95
	ds_write_b64 v181, v[92:93] offset:176
	v_cvt_pk_bf16_f32 v64, v64, v65
	v_cvt_pk_bf16_f32 v65, v66, v67
	ds_write_b64 v181, v[64:65] offset:192
	v_cvt_pk_bf16_f32 v68, v68, v69
	v_cvt_pk_bf16_f32 v69, v70, v71
	ds_write_b64 v181, v[68:69] offset:208
	v_cvt_pk_bf16_f32 v72, v72, v73
	v_cvt_pk_bf16_f32 v73, v74, v75
	ds_write_b64 v181, v[72:73] offset:224
	v_cvt_pk_bf16_f32 v76, v76, v77
	v_cvt_pk_bf16_f32 v77, v78, v79
	ds_write_b64 v181, v[76:77] offset:240
	s_waitcnt lgkmcnt(0)
; DI bfr f2bf(float a) { return (bfr)(pack2(a, 0.f) & 0xffffu); }
; DI int crow(int reg, int h) { return (reg & 3) + 8 * (reg >> 2) + 4 * h; }
; template <int lda, class Epi>
; DI void gemm_tile(const bfr* __restrict__ A, const bfr* __restrict__ Bt, int NB, int K, int m0, int n0, char* smem, Epi epi) {
;     ...
; #pragma unroll
;   for (int i = 0; i < 2; ++i)
; #pragma unroll
;     for (int j = 0; j < 4; ++j)
; #pragma unroll
;       for (int q = 0; q < 16; ++q) {
;         int row = m0 + wr * 64 + i * 32 + crow(q, hl);
;         int col = n0 + wc * 128 + j * 32 + r;
;         epi(row, col, acc[i][j][q]);
;       }
; DI void phase_gemm_in_even(const Params& p, char* smem) {
;     ...
;       gemm_tile<1024>(p.H, p.WtInE, 3712, 1024, mt * 128, nt * 256, smem,
;                 [=](int row, int col, float v) { PB[(size_t)row * EINP + col] = f2bf(v); });
	ds_read_b128 v[112:115], v182
	ds_read_b128 v[116:119], v182 offset:1088
	ds_read_b128 v[120:123], v182 offset:2176
	ds_read_b128 v[124:127], v182 offset:3264
	ds_read_b128 v[96:99], v182 offset:4352
	ds_read_b128 v[100:103], v182 offset:5440
	ds_read_b128 v[104:107], v182 offset:6528
	ds_read_b128 v[108:111], v182 offset:7616
	s_add_u32 s66, s64, 0x0
	s_addc_u32 s67, s65, 0
	s_waitcnt lgkmcnt(7)
	global_store_dwordx4 v183, v[112:115], s[66:67]
	s_add_u32 s66, s64, 0x7000
	s_addc_u32 s67, s65, 0
	s_waitcnt lgkmcnt(6)
	global_store_dwordx4 v183, v[116:119], s[66:67]
	s_add_u32 s66, s64, 0xe000
	s_addc_u32 s67, s65, 0
	s_waitcnt lgkmcnt(5)
	global_store_dwordx4 v183, v[120:123], s[66:67]
	s_add_u32 s66, s64, 0x15000
	s_addc_u32 s67, s65, 0
	s_waitcnt lgkmcnt(4)
	global_store_dwordx4 v183, v[124:127], s[66:67]
	s_add_u32 s66, s64, 0x1c000
	s_addc_u32 s67, s65, 0
	s_waitcnt lgkmcnt(3)
	global_store_dwordx4 v183, v[96:99], s[66:67]
	s_add_u32 s66, s64, 0x23000
	s_addc_u32 s67, s65, 0
	s_waitcnt lgkmcnt(2)
	global_store_dwordx4 v183, v[100:103], s[66:67]
	s_add_u32 s66, s64, 0x2a000
	s_addc_u32 s67, s65, 0
	s_waitcnt lgkmcnt(1)
	global_store_dwordx4 v183, v[104:107], s[66:67]
	s_add_u32 s66, s64, 0x31000
	s_addc_u32 s67, s65, 0
	s_waitcnt lgkmcnt(0)
	global_store_dwordx4 v183, v[108:111], s[66:67]
	v_cvt_pk_bf16_f32 v48, v48, v49
	v_cvt_pk_bf16_f32 v49, v50, v51
	ds_write_b64 v181, v[48:49]
	v_cvt_pk_bf16_f32 v52, v52, v53
	v_cvt_pk_bf16_f32 v53, v54, v55
	ds_write_b64 v181, v[52:53] offset:16
	v_cvt_pk_bf16_f32 v56, v56, v57
	v_cvt_pk_bf16_f32 v57, v58, v59
	ds_write_b64 v181, v[56:57] offset:32
	v_cvt_pk_bf16_f32 v60, v60, v61
	v_cvt_pk_bf16_f32 v61, v62, v63
	ds_write_b64 v181, v[60:61] offset:48
	v_cvt_pk_bf16_f32 v32, v32, v33
	v_cvt_pk_bf16_f32 v33, v34, v35
	ds_write_b64 v181, v[32:33] offset:64
	v_cvt_pk_bf16_f32 v36, v36, v37
	v_cvt_pk_bf16_f32 v37, v38, v39
	ds_write_b64 v181, v[36:37] offset:80
	v_cvt_pk_bf16_f32 v40, v40, v41
	v_cvt_pk_bf16_f32 v41, v42, v43
	ds_write_b64 v181, v[40:41] offset:96
	v_cvt_pk_bf16_f32 v44, v44, v45
	v_cvt_pk_bf16_f32 v45, v46, v47
	ds_write_b64 v181, v[44:45] offset:112
	v_cvt_pk_bf16_f32 v16, v16, v17
	v_cvt_pk_bf16_f32 v17, v18, v19
	ds_write_b64 v181, v[16:17] offset:128
	v_cvt_pk_bf16_f32 v20, v20, v21
	v_cvt_pk_bf16_f32 v21, v22, v23
	ds_write_b64 v181, v[20:21] offset:144
	v_cvt_pk_bf16_f32 v24, v24, v25
	v_cvt_pk_bf16_f32 v25, v26, v27
	ds_write_b64 v181, v[24:25] offset:160
	v_cvt_pk_bf16_f32 v28, v28, v29
	v_cvt_pk_bf16_f32 v29, v30, v31
	ds_write_b64 v181, v[28:29] offset:176
	v_cvt_pk_bf16_f32 v0, v0, v1
	v_cvt_pk_bf16_f32 v1, v2, v3
	ds_write_b64 v181, v[0:1] offset:192
	v_cvt_pk_bf16_f32 v4, v4, v5
	v_cvt_pk_bf16_f32 v5, v6, v7
	ds_write_b64 v181, v[4:5] offset:208
	v_cvt_pk_bf16_f32 v8, v8, v9
	v_cvt_pk_bf16_f32 v9, v10, v11
	ds_write_b64 v181, v[8:9] offset:224
	v_cvt_pk_bf16_f32 v12, v12, v13
	v_cvt_pk_bf16_f32 v13, v14, v15
	ds_write_b64 v181, v[12:13] offset:240
	s_waitcnt lgkmcnt(0)
	ds_read_b128 v[48:51], v182
	ds_read_b128 v[52:55], v182 offset:1088
	ds_read_b128 v[56:59], v182 offset:2176
	ds_read_b128 v[60:63], v182 offset:3264
	ds_read_b128 v[32:35], v182 offset:4352
	ds_read_b128 v[36:39], v182 offset:5440
	ds_read_b128 v[40:43], v182 offset:6528
	ds_read_b128 v[44:47], v182 offset:7616
	s_add_u32 s66, s64, 0x38000
	s_addc_u32 s67, s65, 0
	s_waitcnt lgkmcnt(7)
	global_store_dwordx4 v183, v[48:51], s[66:67]
	s_add_u32 s66, s64, 0x3f000
	s_addc_u32 s67, s65, 0
	s_waitcnt lgkmcnt(6)
	global_store_dwordx4 v183, v[52:55], s[66:67]
	s_add_u32 s66, s64, 0x46000
	s_addc_u32 s67, s65, 0
	s_waitcnt lgkmcnt(5)
	global_store_dwordx4 v183, v[56:59], s[66:67]
	s_add_u32 s66, s64, 0x4d000
	s_addc_u32 s67, s65, 0
	s_waitcnt lgkmcnt(4)
	global_store_dwordx4 v183, v[60:63], s[66:67]
	s_add_u32 s66, s64, 0x54000
	s_addc_u32 s67, s65, 0
	s_waitcnt lgkmcnt(3)
	global_store_dwordx4 v183, v[32:35], s[66:67]
	s_add_u32 s66, s64, 0x5b000
	s_addc_u32 s67, s65, 0
	s_waitcnt lgkmcnt(2)
	global_store_dwordx4 v183, v[36:39], s[66:67]
	s_add_u32 s66, s64, 0x62000
	s_addc_u32 s67, s65, 0
	s_waitcnt lgkmcnt(1)
	global_store_dwordx4 v183, v[40:43], s[66:67]
	s_add_u32 s66, s64, 0x69000
	s_addc_u32 s67, s65, 0
	s_waitcnt lgkmcnt(0)
	global_store_dwordx4 v183, v[44:47], s[66:67]
	v_readlane_b32 s64, v188, 0
	v_readlane_b32 s65, v188, 1
	v_readlane_b32 s66, v188, 2
	v_readlane_b32 s67, v188, 3
	v_readlane_b32 s68, v188, 4
	v_readlane_b32 s69, v188, 5
	v_readlane_b32 s70, v188, 6
	v_readlane_b32 s71, v188, 7
	v_readlane_b32 s72, v188, 8
	v_readlane_b32 s73, v188, 9
	v_readlane_b32 s74, v188, 10
	v_readlane_b32 s75, v188, 11
	v_readlane_b32 s76, v188, 12
	v_readlane_b32 s77, v188, 13
	v_readlane_b32 s78, v188, 14
	v_readlane_b32 s79, v188, 15
	s_nop 7
	s_branch .LBB0_119

; #define MFMA32(a, b, c) __builtin_amdgcn_mfma_f32_32x32x16_bf16((a), (b), (c), 0, 0, 0)
; #define GA_LOAD(pr_) do { _Pragma("unroll") for (int i = 0; i < 4; ++i) ra[i] = *(const u32x4*)(Ab + (i * 32) * lda + (pr_) * 64); } while (0)
; #define GB_LOAD(kt_) do { const bfr* bk_ = Bb + (kt_) * NB * 32; \
;     _Pragma("unroll") for (int i = 0; i < 4; ++i) rb[i] = *(const u32x4*)(bk_ + (i * 64) * 32); } while (0)
; #define G_STORE(kt_) do { bfr* as_ = S0 + ((kt_) & 1) * GSTAGE; bfr* bs_ = as_ + 128 * 40; \
;     if (apar == ((kt_) & 1)) { _Pragma("unroll") for (int i = 0; i < 4; ++i) *(u32x4*)(as_ + asoff + i * 32 * 40) = ra[i]; } \
;     _Pragma("unroll") for (int i = 0; i < 4; ++i) *(u32x4*)(bs_ + bsoff + i * 64 * 40) = rb[i]; } while (0)
; template <int lda>
; DI void gemm_mainloop(const bfr* __restrict__ A, const bfr* __restrict__ Bt, int NB, int K, int m0, int n0, char* smem, f32x16 (&acc)[2][4]) {
;     ...
; #pragma unroll
;   for (int i = 0; i < 2; ++i)
; #pragma unroll
;     for (int j = 0; j < 4; ++j)
; #pragma unroll
;       for (int q = 0; q < 16; ++q) acc[i][j][q] = 0.f;
;   u32x4 ra[4], rb[4];
;   const int nk = K >> 5;
;   const int arow = tid >> 3, ac8 = tid & 7, apar = ac8 >> 2;
;   const bfr* Ab = A + (m0 + arow) * lda + ac8 * 8;
;   const int asoff = arow * 40 + (ac8 & 3) * 8;
;   const int brow = tid >> 2, bc4 = tid & 3;
;   const bfr* Bb = Bt + (n0 + brow) * 32 + bc4 * 8;
;   const int bsoff = brow * 40 + bc4 * 8;
;     ...
;   GA_LOAD(0);
;   GB_LOAD(0);
;   G_STORE(0);
;   GB_LOAD(1);
;   __syncthreads();
;   for (int kt = 0; kt < nk; ++kt) {
;     if (kt + 1 < nk) G_STORE(kt + 1);
;     if (kt + 2 < nk) {
;       GB_LOAD(kt + 2);
;       if ((kt & 1) == 0) GA_LOAD((kt >> 1) + 1);
;     }
;     const bfr* As = S0 + (kt & 1) * GSTAGE;
;     const bfr* Bs = As + 128 * 40;
; #pragma unroll
;     for (int ks = 0; ks < 2; ++ks) {
;       bf16x8 af[2], bfg[4];
; #pragma unroll
;       for (int i = 0; i < 2; ++i) af[i] = *(const bf16x8*)(As + (wr * 64 + i * 32 + r) * 40 + ks * 16 + hl * 8);
; #pragma unroll
;       for (int j = 0; j < 4; ++j) bfg[j] = *(const bf16x8*)(Bs + (wc * 128 + j * 32 + r) * 40 + ks * 16 + hl * 8);
; #pragma unroll
;       for (int i = 0; i < 2; ++i)
; #pragma unroll
;         for (int j = 0; j < 4; ++j) acc[i][j] = MFMA32(af[i], bfg[j], acc[i][j]);
;     }
.Lp6_nostag:
	v_mov_b32_e32 v112, 0
	v_mov_b32_e32 v113, 0
	v_mov_b32_e32 v114, 0
	v_mov_b32_e32 v115, 0
	v_mov_b32_e32 v116, 0
	v_mov_b32_e32 v117, 0
	v_mov_b32_e32 v118, 0
	v_mov_b32_e32 v119, 0
	v_mov_b32_e32 v120, 0
	v_mov_b32_e32 v121, 0
	v_mov_b32_e32 v122, 0
	v_mov_b32_e32 v123, 0
	v_mov_b32_e32 v124, 0
	v_mov_b32_e32 v125, 0
	v_mov_b32_e32 v126, 0
	v_mov_b32_e32 v127, 0
	v_mov_b32_e32 v96, 0
	v_mov_b32_e32 v97, 0
	v_mov_b32_e32 v98, 0
	v_mov_b32_e32 v99, 0
	v_mov_b32_e32 v100, 0
	v_mov_b32_e32 v101, 0
	v_mov_b32_e32 v102, 0
	v_mov_b32_e32 v103, 0
	v_mov_b32_e32 v104, 0
	v_mov_b32_e32 v105, 0
	v_mov_b32_e32 v106, 0
	v_mov_b32_e32 v107, 0
	v_mov_b32_e32 v108, 0
	v_mov_b32_e32 v109, 0
	v_mov_b32_e32 v110, 0
	v_mov_b32_e32 v111, 0
	v_mov_b32_e32 v80, 0
	v_mov_b32_e32 v81, 0
	v_mov_b32_e32 v82, 0
	v_mov_b32_e32 v83, 0
	v_mov_b32_e32 v84, 0
	v_mov_b32_e32 v85, 0
	v_mov_b32_e32 v86, 0
	v_mov_b32_e32 v87, 0
	v_mov_b32_e32 v88, 0
	v_mov_b32_e32 v89, 0
	v_mov_b32_e32 v90, 0
	v_mov_b32_e32 v91, 0
	v_mov_b32_e32 v92, 0
	v_mov_b32_e32 v93, 0
	v_mov_b32_e32 v94, 0
	v_mov_b32_e32 v95, 0
	v_mov_b32_e32 v64, 0
	v_mov_b32_e32 v65, 0
	v_mov_b32_e32 v66, 0
	v_mov_b32_e32 v67, 0
	v_mov_b32_e32 v68, 0
	v_mov_b32_e32 v69, 0
	v_mov_b32_e32 v70, 0
	v_mov_b32_e32 v71, 0
	v_mov_b32_e32 v72, 0
	v_mov_b32_e32 v73, 0
	v_mov_b32_e32 v74, 0
	v_mov_b32_e32 v75, 0
	v_mov_b32_e32 v76, 0
	v_mov_b32_e32 v77, 0
	v_mov_b32_e32 v78, 0
	v_mov_b32_e32 v79, 0
	v_mov_b32_e32 v48, 0
	v_mov_b32_e32 v49, 0
	v_mov_b32_e32 v50, 0
	v_mov_b32_e32 v51, 0
	v_mov_b32_e32 v52, 0
	v_mov_b32_e32 v53, 0
	v_mov_b32_e32 v54, 0
	v_mov_b32_e32 v55, 0
	v_mov_b32_e32 v56, 0
	v_mov_b32_e32 v57, 0
	v_mov_b32_e32 v58, 0
	v_mov_b32_e32 v59, 0
	v_mov_b32_e32 v60, 0
	v_mov_b32_e32 v61, 0
	v_mov_b32_e32 v62, 0
	v_mov_b32_e32 v63, 0
	v_mov_b32_e32 v32, 0
	v_mov_b32_e32 v33, 0
	v_mov_b32_e32 v34, 0
	v_mov_b32_e32 v35, 0
	v_mov_b32_e32 v36, 0
	v_mov_b32_e32 v37, 0
	v_mov_b32_e32 v38, 0
	v_mov_b32_e32 v39, 0
	v_mov_b32_e32 v40, 0
	v_mov_b32_e32 v41, 0
	v_mov_b32_e32 v42, 0
	v_mov_b32_e32 v43, 0
	v_mov_b32_e32 v44, 0
	v_mov_b32_e32 v45, 0
	v_mov_b32_e32 v46, 0
	v_mov_b32_e32 v47, 0
	v_mov_b32_e32 v16, 0
	v_mov_b32_e32 v17, 0
	v_mov_b32_e32 v18, 0
	v_mov_b32_e32 v19, 0
	v_mov_b32_e32 v20, 0
	v_mov_b32_e32 v21, 0
	v_mov_b32_e32 v22, 0
	v_mov_b32_e32 v23, 0
	v_mov_b32_e32 v24, 0
	v_mov_b32_e32 v25, 0
	v_mov_b32_e32 v26, 0
	v_mov_b32_e32 v27, 0
	v_mov_b32_e32 v28, 0
	v_mov_b32_e32 v29, 0
	v_mov_b32_e32 v30, 0
	v_mov_b32_e32 v31, 0
	v_mov_b32_e32 v0, 0
	v_mov_b32_e32 v1, 0
	v_mov_b32_e32 v2, 0
	v_mov_b32_e32 v3, 0
	v_mov_b32_e32 v4, 0
	v_mov_b32_e32 v5, 0
	v_mov_b32_e32 v6, 0
	v_mov_b32_e32 v7, 0
	v_mov_b32_e32 v8, 0
	v_mov_b32_e32 v9, 0
	v_mov_b32_e32 v10, 0
	v_mov_b32_e32 v11, 0
	v_mov_b32_e32 v12, 0
	v_mov_b32_e32 v13, 0
	v_mov_b32_e32 v14, 0
	v_mov_b32_e32 v15, 0
	s_waitcnt vmcnt(6)
	s_barrier
	s_mul_i32 s74, s71, 0x6000
	s_add_u32 s75, s74, 0x2000
	s_cmp_eq_u32 s71, 2
	s_cselect_b32 s75, 0x10000, s75
	v_add_u32_e32 v199, s74, v192
	v_add_u32_e32 v205, s75, v194
	v_add_u32_e32 v204, s74, v193
	v_add_u32_e32 v206, s75, v198
	s_add_u32 s71, s71, 1
	s_cmp_eq_u32 s71, 3
	s_cselect_b32 s71, 0, s71
	ds_read_b128 v[128:131], v199
	ds_read_b128 v[144:147], v205
	ds_read_b128 v[148:151], v205 offset:2048
	ds_read_b128 v[152:155], v205 offset:4096
	ds_read_b128 v[156:159], v205 offset:6144
	ds_read_b128 v[132:135], v199 offset:2048
	ds_read_b128 v[136:139], v204
	ds_read_b128 v[160:163], v206
	ds_read_b128 v[164:167], v206 offset:2048
	ds_read_b128 v[168:171], v206 offset:4096
	ds_read_b128 v[172:175], v206 offset:6144
	ds_read_b128 v[140:143], v204 offset:2048
	s_waitcnt lgkmcnt(10)
	v_mfma_f32_32x32x16_bf16 v[112:127], v[144:147], v[128:131], v[112:127]
	s_mul_i32 s74, s70, 0x6000
	s_add_u32 s75, s74, s68
	s_mov_b32 m0, s75
	s_add_u32 s76, s74, 0x2000
	s_cmp_eq_u32 s70, 2
	s_cselect_b32 s76, 0x10000, s76
	global_load_lds_dwordx4 v188, s[64:65]
	s_waitcnt lgkmcnt(9)
	v_mfma_f32_32x32x16_bf16 v[96:111], v[148:151], v[128:131], v[96:111]
	s_add_u32 m0, s75, 0x400
	s_add_u32 s76, s76, s69
	global_load_lds_dwordx4 v190, s[64:65]
	s_waitcnt lgkmcnt(8)
	v_mfma_f32_32x32x16_bf16 v[80:95], v[152:155], v[128:131], v[80:95]
	s_mov_b32 m0, s76
	s_add_u32 s64, s64, 64
	s_addc_u32 s65, s65, 0
	global_load_lds_dwordx4 v191, s[66:67]
	s_waitcnt lgkmcnt(7)
	v_mfma_f32_32x32x16_bf16 v[64:79], v[156:159], v[128:131], v[64:79]
	global_load_lds_dwordx4 v191, s[66:67] offset:1024
	s_waitcnt lgkmcnt(6)
	v_mfma_f32_32x32x16_bf16 v[48:63], v[144:147], v[132:135], v[48:63]
	global_load_lds_dwordx4 v191, s[66:67] offset:2048
	v_mfma_f32_32x32x16_bf16 v[32:47], v[148:151], v[132:135], v[32:47]
	global_load_lds_dwordx4 v191, s[66:67] offset:3072
	s_add_u32 s66, s66, 0x10000
	s_addc_u32 s67, s67, 0
	v_mfma_f32_32x32x16_bf16 v[16:31], v[152:155], v[132:135], v[16:31]
	s_add_u32 s70, s70, 1
	s_cmp_eq_u32 s70, 3
	s_cselect_b32 s70, 0, s70
	v_mfma_f32_32x32x16_bf16 v[0:15], v[156:159], v[132:135], v[0:15]
; #define MFMA32(a, b, c) __builtin_amdgcn_mfma_f32_32x32x16_bf16((a), (b), (c), 0, 0, 0)
; #define GA_LOAD(pr_) do { _Pragma("unroll") for (int i = 0; i < 4; ++i) ra[i] = *(const u32x4*)(Ab + (i * 32) * lda + (pr_) * 64); } while (0)
; #define GB_LOAD(kt_) do { const bfr* bk_ = Bb + (kt_) * NB * 32; \
;     _Pragma("unroll") for (int i = 0; i < 4; ++i) rb[i] = *(const u32x4*)(bk_ + (i * 64) * 32); } while (0)
; #define G_STORE(kt_) do { bfr* as_ = S0 + ((kt_) & 1) * GSTAGE; bfr* bs_ = as_ + 128 * 40; \
;     if (apar == ((kt_) & 1)) { _Pragma("unroll") for (int i = 0; i < 4; ++i) *(u32x4*)(as_ + asoff + i * 32 * 40) = ra[i]; } \
;     _Pragma("unroll") for (int i = 0; i < 4; ++i) *(u32x4*)(bs_ + bsoff + i * 64 * 40) = rb[i]; } while (0)
; template <int lda>
; DI void gemm_mainloop(const bfr* __restrict__ A, const bfr* __restrict__ Bt, int NB, int K, int m0, int n0, char* smem, f32x16 (&acc)[2][4]) {
;     ...
;   for (int kt = 0; kt < nk; ++kt) {
;     if (kt + 1 < nk) G_STORE(kt + 1);
;     if (kt + 2 < nk) {
;       GB_LOAD(kt + 2);
;       if ((kt & 1) == 0) GA_LOAD((kt >> 1) + 1);
;     }
;     const bfr* As = S0 + (kt & 1) * GSTAGE;
;     const bfr* Bs = As + 128 * 40;
; #pragma unroll
;     for (int ks = 0; ks < 2; ++ks) {
;       bf16x8 af[2], bfg[4];
; #pragma unroll
;       for (int i = 0; i < 2; ++i) af[i] = *(const bf16x8*)(As + (wr * 64 + i * 32 + r) * 40 + ks * 16 + hl * 8);
; #pragma unroll
;       for (int j = 0; j < 4; ++j) bfg[j] = *(const bf16x8*)(Bs + (wc * 128 + j * 32 + r) * 40 + ks * 16 + hl * 8);
; #pragma unroll
;       for (int i = 0; i < 2; ++i)
; #pragma unroll
;         for (int j = 0; j < 4; ++j) acc[i][j] = MFMA32(af[i], bfg[j], acc[i][j]);
;     }
;     __syncthreads();
;   }
.Lp6_loop:
	s_waitcnt vmcnt(6) lgkmcnt(0)
	s_barrier
	s_mul_i32 s74, s71, 0x6000
	s_add_u32 s75, s74, 0x2000
	s_cmp_eq_u32 s71, 2
	s_cselect_b32 s75, 0x10000, s75
	v_add_u32_e32 v199, s74, v192
	v_add_u32_e32 v205, s75, v194
	v_add_u32_e32 v204, s74, v193
	v_add_u32_e32 v206, s75, v198
	s_add_u32 s71, s71, 1
	s_cmp_eq_u32 s71, 3
	s_cselect_b32 s71, 0, s71
	ds_read_b128 v[128:131], v199
	ds_read_b128 v[144:147], v205
	ds_read_b128 v[148:151], v205 offset:2048
	ds_read_b128 v[152:155], v205 offset:4096
	ds_read_b128 v[156:159], v205 offset:6144
	ds_read_b128 v[132:135], v199 offset:2048
	v_mfma_f32_32x32x16_bf16 v[112:127], v[160:163], v[136:139], v[112:127]
	s_mul_i32 s74, s70, 0x6000
	s_add_u32 s75, s74, s68
	s_mov_b32 m0, s75
	s_add_u32 s76, s74, 0x2000
	s_cmp_eq_u32 s70, 2
	s_cselect_b32 s76, 0x10000, s76
	global_load_lds_dwordx4 v188, s[64:65]
	v_mfma_f32_32x32x16_bf16 v[96:111], v[164:167], v[136:139], v[96:111]
	s_add_u32 m0, s75, 0x400
	s_add_u32 s76, s76, s69
	global_load_lds_dwordx4 v190, s[64:65]
	v_mfma_f32_32x32x16_bf16 v[80:95], v[168:171], v[136:139], v[80:95]
	s_mov_b32 m0, s76
	s_add_u32 s64, s64, 64
	s_addc_u32 s65, s65, 0
	global_load_lds_dwordx4 v191, s[66:67]
	v_mfma_f32_32x32x16_bf16 v[64:79], v[172:175], v[136:139], v[64:79]
	global_load_lds_dwordx4 v191, s[66:67] offset:1024
	v_mfma_f32_32x32x16_bf16 v[48:63], v[160:163], v[140:143], v[48:63]
	global_load_lds_dwordx4 v191, s[66:67] offset:2048
	v_mfma_f32_32x32x16_bf16 v[32:47], v[164:167], v[140:143], v[32:47]
	global_load_lds_dwordx4 v191, s[66:67] offset:3072
	s_add_u32 s66, s66, 0x10000
	s_addc_u32 s67, s67, 0
	v_mfma_f32_32x32x16_bf16 v[16:31], v[168:171], v[140:143], v[16:31]
	s_add_u32 s70, s70, 1
	s_cmp_eq_u32 s70, 3
	s_cselect_b32 s70, 0, s70
	v_mfma_f32_32x32x16_bf16 v[0:15], v[172:175], v[140:143], v[0:15]
	ds_read_b128 v[136:139], v204
	ds_read_b128 v[160:163], v206
	ds_read_b128 v[164:167], v206 offset:2048
	ds_read_b128 v[168:171], v206 offset:4096
	ds_read_b128 v[172:175], v206 offset:6144
	ds_read_b128 v[140:143], v204 offset:2048
	s_waitcnt lgkmcnt(10)
	v_mfma_f32_32x32x16_bf16 v[112:127], v[144:147], v[128:131], v[112:127]
	s_waitcnt lgkmcnt(9)
	v_mfma_f32_32x32x16_bf16 v[96:111], v[148:151], v[128:131], v[96:111]
	s_waitcnt lgkmcnt(8)
	v_mfma_f32_32x32x16_bf16 v[80:95], v[152:155], v[128:131], v[80:95]
	s_waitcnt lgkmcnt(7)
	v_mfma_f32_32x32x16_bf16 v[64:79], v[156:159], v[128:131], v[64:79]
	s_waitcnt lgkmcnt(6)
	v_mfma_f32_32x32x16_bf16 v[48:63], v[144:147], v[132:135], v[48:63]
	v_mfma_f32_32x32x16_bf16 v[32:47], v[148:151], v[132:135], v[32:47]
	v_mfma_f32_32x32x16_bf16 v[16:31], v[152:155], v[132:135], v[16:31]
	v_mfma_f32_32x32x16_bf16 v[0:15], v[156:159], v[132:135], v[0:15]
	s_add_u32 s72, s72, 1
	s_cmp_lt_u32 s72, 29
	s_cbranch_scc1 .Lp6_loop
	s_waitcnt vmcnt(6) lgkmcnt(0)
	s_barrier
	s_mul_i32 s74, s71, 0x6000
	s_add_u32 s75, s74, 0x2000
	s_cmp_eq_u32 s71, 2
	s_cselect_b32 s75, 0x10000, s75
	v_add_u32_e32 v199, s74, v192
	v_add_u32_e32 v205, s75, v194
	v_add_u32_e32 v204, s74, v193
	v_add_u32_e32 v206, s75, v198
	s_add_u32 s71, s71, 1
	s_cmp_eq_u32 s71, 3
	s_cselect_b32 s71, 0, s71
	ds_read_b128 v[128:131], v199
	ds_read_b128 v[144:147], v205
	ds_read_b128 v[148:151], v205 offset:2048
	ds_read_b128 v[152:155], v205 offset:4096
	ds_read_b128 v[156:159], v205 offset:6144
	ds_read_b128 v[132:135], v199 offset:2048
	v_mfma_f32_32x32x16_bf16 v[112:127], v[160:163], v[136:139], v[112:127]
	v_mfma_f32_32x32x16_bf16 v[96:111], v[164:167], v[136:139], v[96:111]
	v_mfma_f32_32x32x16_bf16 v[80:95], v[168:171], v[136:139], v[80:95]
	v_mfma_f32_32x32x16_bf16 v[64:79], v[172:175], v[136:139], v[64:79]
	v_mfma_f32_32x32x16_bf16 v[48:63], v[160:163], v[140:143], v[48:63]
	v_mfma_f32_32x32x16_bf16 v[32:47], v[164:167], v[140:143], v[32:47]
	v_mfma_f32_32x32x16_bf16 v[16:31], v[168:171], v[140:143], v[16:31]
	v_mfma_f32_32x32x16_bf16 v[0:15], v[172:175], v[140:143], v[0:15]
	ds_read_b128 v[136:139], v204
	ds_read_b128 v[160:163], v206
	ds_read_b128 v[164:167], v206 offset:2048
	ds_read_b128 v[168:171], v206 offset:4096
	ds_read_b128 v[172:175], v206 offset:6144
	ds_read_b128 v[140:143], v204 offset:2048
	s_waitcnt lgkmcnt(10)
	v_mfma_f32_32x32x16_bf16 v[112:127], v[144:147], v[128:131], v[112:127]
	s_waitcnt lgkmcnt(9)
	v_mfma_f32_32x32x16_bf16 v[96:111], v[148:151], v[128:131], v[96:111]
	s_waitcnt lgkmcnt(8)
	v_mfma_f32_32x32x16_bf16 v[80:95], v[152:155], v[128:131], v[80:95]
	s_waitcnt lgkmcnt(7)
	v_mfma_f32_32x32x16_bf16 v[64:79], v[156:159], v[128:131], v[64:79]
	s_waitcnt lgkmcnt(6)
	v_mfma_f32_32x32x16_bf16 v[48:63], v[144:147], v[132:135], v[48:63]
	v_mfma_f32_32x32x16_bf16 v[32:47], v[148:151], v[132:135], v[32:47]
	v_mfma_f32_32x32x16_bf16 v[16:31], v[152:155], v[132:135], v[16:31]
	v_mfma_f32_32x32x16_bf16 v[0:15], v[156:159], v[132:135], v[0:15]
	s_waitcnt vmcnt(0) lgkmcnt(0)
	s_barrier
; #define MFMA32(a, b, c) __builtin_amdgcn_mfma_f32_32x32x16_bf16((a), (b), (c), 0, 0, 0)
; DI int crow(int reg, int h) { return (reg & 3) + 8 * (reg >> 2) + 4 * h; }
; template <int lda>
; DI void gemm_mainloop(const bfr* __restrict__ A, const bfr* __restrict__ Bt, int NB, int K, int m0, int n0, char* smem, f32x16 (&acc)[2][4]) {
;     ...
;     const bfr* As = S0 + (kt & 1) * GSTAGE;
;     const bfr* Bs = As + 128 * 40;
; #pragma unroll
;     for (int ks = 0; ks < 2; ++ks) {
;       bf16x8 af[2], bfg[4];
; #pragma unroll
;       for (int i = 0; i < 2; ++i) af[i] = *(const bf16x8*)(As + (wr * 64 + i * 32 + r) * 40 + ks * 16 + hl * 8);
; #pragma unroll
;       for (int j = 0; j < 4; ++j) bfg[j] = *(const bf16x8*)(Bs + (wc * 128 + j * 32 + r) * 40 + ks * 16 + hl * 8);
; #pragma unroll
;       for (int i = 0; i < 2; ++i)
; #pragma unroll
;         for (int j = 0; j < 4; ++j) acc[i][j] = MFMA32(af[i], bfg[j], acc[i][j]);
;     }
;     __syncthreads();
; template <bool FIRST, bool HAS_H>
; DI void phase_gemm_resid(const Params& p, const bfr* A, const bfr* Wt, const float* gnext, float* ss, char* smem) {
;     ...
;     f32x16 acc[2][4];
;     gemm_mainloop<1024>(A, Wt, 1024, 1024, m0, n0, smem, acc);
;     int tid2 = threadIdx.x;
;     asm volatile("" : "+v"(tid2));
;     const int lane = tid2 & 63, wid = tid2 >> 6, wr = wid >> 1, wc = wid & 1, r = lane & 31, hl = lane >> 5;
;     const float* xsrc = FIRST ? p.x_prompt : X;
;     const int rbase = m0 + wr * 64 + 4 * hl, cbase = n0 + wc * 128 + r;
; #pragma unroll
;     for (int i = 0; i < 2; ++i) {
; #pragma unroll
;       for (int qh = 0; qh < 2; ++qh) {
;         float rs[8];
; #pragma unroll
;         for (int q = 0; q < 8; ++q) rs[q] = 0.f;
; #pragma unroll
;         for (int jh = 0; jh < 2; ++jh) {
;           float xo[2][8];
; #pragma unroll
;           for (int jj = 0; jj < 2; ++jj)
; #pragma unroll
;             for (int q = 0; q < 8; ++q)
;               xo[jj][q] = xsrc[(rbase + i * 32 + crow(qh * 8 + q, 0)) * 1024 + cbase + (jh * 2 + jj) * 32];
	s_mul_i32 s74, s71, 0x6000
	s_add_u32 s75, s74, 0x2000
	s_cmp_eq_u32 s71, 2
	s_cselect_b32 s75, 0x10000, s75
	v_add_u32_e32 v199, s74, v192
	v_add_u32_e32 v205, s75, v194
	v_add_u32_e32 v204, s74, v193
	v_add_u32_e32 v206, s75, v198
	s_add_u32 s71, s71, 1
	s_cmp_eq_u32 s71, 3
	s_cselect_b32 s71, 0, s71
	ds_read_b128 v[128:131], v199
	ds_read_b128 v[144:147], v205
	ds_read_b128 v[148:151], v205 offset:2048
	ds_read_b128 v[152:155], v205 offset:4096
	ds_read_b128 v[156:159], v205 offset:6144
	ds_read_b128 v[132:135], v199 offset:2048
	v_mfma_f32_32x32x16_bf16 v[112:127], v[160:163], v[136:139], v[112:127]
	v_mfma_f32_32x32x16_bf16 v[96:111], v[164:167], v[136:139], v[96:111]
	v_mfma_f32_32x32x16_bf16 v[80:95], v[168:171], v[136:139], v[80:95]
	v_mfma_f32_32x32x16_bf16 v[64:79], v[172:175], v[136:139], v[64:79]
	v_mfma_f32_32x32x16_bf16 v[48:63], v[160:163], v[140:143], v[48:63]
	v_mfma_f32_32x32x16_bf16 v[32:47], v[164:167], v[140:143], v[32:47]
	v_mfma_f32_32x32x16_bf16 v[16:31], v[168:171], v[140:143], v[16:31]
	v_mfma_f32_32x32x16_bf16 v[0:15], v[172:175], v[140:143], v[0:15]
	ds_read_b128 v[136:139], v204
	ds_read_b128 v[160:163], v206
	ds_read_b128 v[164:167], v206 offset:2048
	ds_read_b128 v[168:171], v206 offset:4096
	ds_read_b128 v[172:175], v206 offset:6144
	ds_read_b128 v[140:143], v204 offset:2048
	s_waitcnt lgkmcnt(10)
	v_mfma_f32_32x32x16_bf16 v[112:127], v[144:147], v[128:131], v[112:127]
	s_waitcnt lgkmcnt(9)
	v_mfma_f32_32x32x16_bf16 v[96:111], v[148:151], v[128:131], v[96:111]
	s_waitcnt lgkmcnt(8)
	v_mfma_f32_32x32x16_bf16 v[80:95], v[152:155], v[128:131], v[80:95]
	s_waitcnt lgkmcnt(7)
	v_mfma_f32_32x32x16_bf16 v[64:79], v[156:159], v[128:131], v[64:79]
	s_waitcnt lgkmcnt(6)
	v_mfma_f32_32x32x16_bf16 v[48:63], v[144:147], v[132:135], v[48:63]
	v_mfma_f32_32x32x16_bf16 v[32:47], v[148:151], v[132:135], v[32:47]
	v_mfma_f32_32x32x16_bf16 v[16:31], v[152:155], v[132:135], v[16:31]
	v_mfma_f32_32x32x16_bf16 v[0:15], v[156:159], v[132:135], v[0:15]
	s_waitcnt lgkmcnt(0)
	v_mfma_f32_32x32x16_bf16 v[112:127], v[160:163], v[136:139], v[112:127]
	v_mfma_f32_32x32x16_bf16 v[96:111], v[164:167], v[136:139], v[96:111]
	v_mfma_f32_32x32x16_bf16 v[80:95], v[168:171], v[136:139], v[80:95]
	v_mfma_f32_32x32x16_bf16 v[64:79], v[172:175], v[136:139], v[64:79]
	v_mfma_f32_32x32x16_bf16 v[48:63], v[160:163], v[140:143], v[48:63]
	v_mfma_f32_32x32x16_bf16 v[32:47], v[164:167], v[140:143], v[32:47]
	v_mfma_f32_32x32x16_bf16 v[16:31], v[168:171], v[140:143], v[16:31]
	v_mfma_f32_32x32x16_bf16 v[0:15], v[172:175], v[140:143], v[0:15]
	s_nop 7
	s_nop 3
	s_load_dwordx2 s[64:65], s[92:93], 0x0
	s_load_dwordx2 s[66:67], s[92:93], 0x100
	s_load_dwordx2 s[68:69], s[92:93], 0x148
	s_load_dwordx2 s[70:71], s[92:93], 0x50
	s_mul_i32 s76, s73, 8704
	s_lshr_b32 s74, s73, 1
	s_lshl_b32 s74, s74, 6
	s_add_u32 s74, s74, s77
	s_and_b32 s75, s73, 1
	s_lshl_b32 s75, s75, 7
	s_add_u32 s75, s75, s78
	v_and_b32_e32 v208, 31, v196
	v_bfe_u32 v209, v196, 5, 1
	v_mul_u32_u24_e32 v210, 272, v208
	v_add_u32_e32 v210, s76, v210
	v_lshl_add_u32 v188, v209, 4, v210
	v_lshl_add_u32 v190, v209, 3, v210
	v_lshlrev_b32_e32 v210, 2, v209
	v_add_lshl_u32 v198, v210, s75, 2
	v_add_lshl_u32 v205, v208, s74, 2
	v_and_b32_e32 v210, 63, v196
	v_xor_b32_e32 v210, 32, v210
	v_lshlrev_b32_e32 v206, 2, v210
	v_bfe_u32 v208, v196, 4, 2
	v_and_b32_e32 v209, 15, v196
	v_mul_u32_u24_e32 v210, 272, v208
	v_lshl_add_u32 v210, v209, 4, v210
	v_add_u32_e32 v191, s76, v210
	v_add_u32_e32 v210, s74, v208
	v_lshlrev_b32_e32 v210, 10, v210
	v_lshl_add_u32 v210, v209, 2, v210
	v_add_lshl_u32 v193, v210, s75, 2
	s_mov_b32 s79, s74
	s_mov_b32 s72, s75
	s_waitcnt lgkmcnt(0)
	s_add_u32 s74, s64, 0x0
	s_addc_u32 s75, s65, 0
	global_load_dwordx4 v[128:131], v193, s[74:75]
	s_add_u32 s74, s64, 0x4000
	s_addc_u32 s75, s65, 0
	global_load_dwordx4 v[132:135], v193, s[74:75]
	s_add_u32 s74, s64, 0x8000
	s_addc_u32 s75, s65, 0
	global_load_dwordx4 v[136:139], v193, s[74:75]
	s_add_u32 s74, s64, 0xc000
	s_addc_u32 s75, s65, 0
	global_load_dwordx4 v[140:143], v193, s[74:75]
	s_add_u32 s74, s64, 0x10000
	s_addc_u32 s75, s65, 0
	global_load_dwordx4 v[144:147], v193, s[74:75]
	s_add_u32 s74, s64, 0x14000
	s_addc_u32 s75, s65, 0
	global_load_dwordx4 v[148:151], v193, s[74:75]
	s_add_u32 s74, s64, 0x18000
	s_addc_u32 s75, s65, 0
	global_load_dwordx4 v[152:155], v193, s[74:75]
	s_add_u32 s74, s64, 0x1c000
	s_addc_u32 s75, s65, 0
	global_load_dwordx4 v[156:159], v193, s[74:75]
	s_mov_b32 s74, s79
	s_mov_b32 s75, s72
	v_bfe_u32 v208, v196, 3, 3
	v_and_b32_e32 v209, 7, v196
	v_mul_u32_u24_e32 v210, 272, v208
	v_lshl_add_u32 v210, v209, 4, v210
	v_add_u32_e32 v192, s76, v210
	v_add_u32_e32 v210, s74, v208
	v_lshlrev_b32_e32 v210, 10, v210
	v_lshl_add_u32 v210, v209, 3, v210
	v_add_lshl_u32 v194, v210, s75, 1
	v_mov_b32_e32 v199, 0
	v_mov_b32_e32 v204, 0
	s_waitcnt lgkmcnt(0)
	s_barrier
; DI bfr f2bf(float a) { return (bfr)(pack2(a, 0.f) & 0xffffu); }
; DI int crow(int reg, int h) { return (reg & 3) + 8 * (reg >> 2) + 4 * h; }
; template <bool FIRST, bool HAS_H>
; DI void phase_gemm_resid(const Params& p, const bfr* A, const bfr* Wt, const float* gnext, float* ss, char* smem) {
;     ...
;     const float* xsrc = FIRST ? p.x_prompt : X;
;     const int rbase = m0 + wr * 64 + 4 * hl, cbase = n0 + wc * 128 + r;
; #pragma unroll
;     for (int i = 0; i < 2; ++i) {
; #pragma unroll
;       for (int qh = 0; qh < 2; ++qh) {
;         float rs[8];
; #pragma unroll
;         for (int q = 0; q < 8; ++q) rs[q] = 0.f;
; #pragma unroll
;         for (int jh = 0; jh < 2; ++jh) {
;           float xo[2][8];
; #pragma unroll
;           for (int jj = 0; jj < 2; ++jj)
; #pragma unroll
;             for (int q = 0; q < 8; ++q)
;               xo[jj][q] = xsrc[(rbase + i * 32 + crow(qh * 8 + q, 0)) * 1024 + cbase + (jh * 2 + jj) * 32];
; #pragma unroll
;           for (int q = 0; q < 8; ++q) {
;             const int o = (rbase + i * 32 + crow(qh * 8 + q, 0)) * 1024 + cbase;
; #pragma unroll
;             for (int jj = 0; jj < 2; ++jj) {
;               const int j = jh * 2 + jj;
;               const float xn = xo[jj][q] + acc[i][j][qh * 8 + q];
;               X[o + j * 32] = xn;
;               if (HAS_H) Hn[o + j * 32] = f2bf(xn * gnext[cbase + j * 32]);
;               rs[q] += xn * xn;
;             }
;           }
;         }
; #pragma unroll
;         for (int q = 0; q < 8; ++q) rs[q] = half32_sum_hi(rs[q]);
;         if (r == 31) {
; #pragma unroll
;           for (int q = 0; q < 8; ++q) unsafeAtomicAdd(ss + rbase + i * 32 + crow(qh * 8 + q, 0), rs[q]);
;         }
	s_waitcnt vmcnt(7)
	ds_write_b128 v191, v[128:131]
	s_waitcnt vmcnt(6)
	ds_write_b128 v191, v[132:135] offset:1088
	s_waitcnt vmcnt(5)
	ds_write_b128 v191, v[136:139] offset:2176
	s_waitcnt vmcnt(4)
	ds_write_b128 v191, v[140:143] offset:3264
	s_waitcnt vmcnt(3)
	ds_write_b128 v191, v[144:147] offset:4352
	s_waitcnt vmcnt(2)
	ds_write_b128 v191, v[148:151] offset:5440
	s_waitcnt vmcnt(1)
	ds_write_b128 v191, v[152:155] offset:6528
	s_waitcnt vmcnt(0)
	ds_write_b128 v191, v[156:159] offset:7616
	s_add_u32 s74, s64, 0x100
	s_addc_u32 s75, s65, 0
	global_load_dwordx4 v[128:131], v193, s[74:75]
	s_add_u32 s74, s64, 0x4100
	s_addc_u32 s75, s65, 0
	global_load_dwordx4 v[132:135], v193, s[74:75]
	s_add_u32 s74, s64, 0x8100
	s_addc_u32 s75, s65, 0
	global_load_dwordx4 v[136:139], v193, s[74:75]
	s_add_u32 s74, s64, 0xc100
	s_addc_u32 s75, s65, 0
	global_load_dwordx4 v[140:143], v193, s[74:75]
	s_add_u32 s74, s64, 0x10100
	s_addc_u32 s75, s65, 0
	global_load_dwordx4 v[144:147], v193, s[74:75]
	s_add_u32 s74, s64, 0x14100
	s_addc_u32 s75, s65, 0
	global_load_dwordx4 v[148:151], v193, s[74:75]
	s_add_u32 s74, s64, 0x18100
	s_addc_u32 s75, s65, 0
	global_load_dwordx4 v[152:155], v193, s[74:75]
	s_add_u32 s74, s64, 0x1c100
	s_addc_u32 s75, s65, 0
	global_load_dwordx4 v[156:159], v193, s[74:75]
	ds_read_b128 v[160:163], v188
	ds_read_b128 v[164:167], v188 offset:32
	ds_read_b128 v[168:171], v188 offset:64
	ds_read_b128 v[172:175], v188 offset:96
	ds_read_b128 v[176:179], v188 offset:128
	ds_read_b128 v[180:183], v188 offset:160
	ds_read_b128 v[184:187], v188 offset:192
	ds_read_b128 v[200:203], v188 offset:224
	s_waitcnt lgkmcnt(7)
	v_add_f32_e32 v112, v160, v112
	v_add_f32_e32 v113, v161, v113
	v_add_f32_e32 v114, v162, v114
	v_add_f32_e32 v115, v163, v115
	v_fmac_f32_e32 v199, v112, v112
	v_fmac_f32_e32 v199, v113, v113
	v_fmac_f32_e32 v199, v114, v114
	v_fmac_f32_e32 v199, v115, v115
	ds_write_b128 v188, v[112:115]
	s_waitcnt lgkmcnt(7)
	v_add_f32_e32 v116, v164, v116
	v_add_f32_e32 v117, v165, v117
	v_add_f32_e32 v118, v166, v118
	v_add_f32_e32 v119, v167, v119
	v_fmac_f32_e32 v199, v116, v116
	v_fmac_f32_e32 v199, v117, v117
	v_fmac_f32_e32 v199, v118, v118
	v_fmac_f32_e32 v199, v119, v119
	ds_write_b128 v188, v[116:119] offset:32
	s_waitcnt lgkmcnt(7)
	v_add_f32_e32 v120, v168, v120
	v_add_f32_e32 v121, v169, v121
	v_add_f32_e32 v122, v170, v122
	v_add_f32_e32 v123, v171, v123
	v_fmac_f32_e32 v199, v120, v120
	v_fmac_f32_e32 v199, v121, v121
	v_fmac_f32_e32 v199, v122, v122
	v_fmac_f32_e32 v199, v123, v123
	ds_write_b128 v188, v[120:123] offset:64
	s_waitcnt lgkmcnt(7)
	v_add_f32_e32 v124, v172, v124
	v_add_f32_e32 v125, v173, v125
	v_add_f32_e32 v126, v174, v126
	v_add_f32_e32 v127, v175, v127
	v_fmac_f32_e32 v199, v124, v124
	v_fmac_f32_e32 v199, v125, v125
	v_fmac_f32_e32 v199, v126, v126
	v_fmac_f32_e32 v199, v127, v127
	ds_write_b128 v188, v[124:127] offset:96
	s_waitcnt lgkmcnt(7)
	v_add_f32_e32 v96, v176, v96
	v_add_f32_e32 v97, v177, v97
	v_add_f32_e32 v98, v178, v98
	v_add_f32_e32 v99, v179, v99
	v_fmac_f32_e32 v199, v96, v96
	v_fmac_f32_e32 v199, v97, v97
	v_fmac_f32_e32 v199, v98, v98
	v_fmac_f32_e32 v199, v99, v99
	ds_write_b128 v188, v[96:99] offset:128
	s_waitcnt lgkmcnt(7)
	v_add_f32_e32 v100, v180, v100
	v_add_f32_e32 v101, v181, v101
	v_add_f32_e32 v102, v182, v102
	v_add_f32_e32 v103, v183, v103
	v_fmac_f32_e32 v199, v100, v100
	v_fmac_f32_e32 v199, v101, v101
	v_fmac_f32_e32 v199, v102, v102
	v_fmac_f32_e32 v199, v103, v103
	ds_write_b128 v188, v[100:103] offset:160
	s_waitcnt lgkmcnt(7)
	v_add_f32_e32 v104, v184, v104
	v_add_f32_e32 v105, v185, v105
	v_add_f32_e32 v106, v186, v106
	v_add_f32_e32 v107, v187, v107
	v_fmac_f32_e32 v199, v104, v104
	v_fmac_f32_e32 v199, v105, v105
	v_fmac_f32_e32 v199, v106, v106
	v_fmac_f32_e32 v199, v107, v107
	ds_write_b128 v188, v[104:107] offset:192
	s_waitcnt lgkmcnt(7)
	v_add_f32_e32 v108, v200, v108
	v_add_f32_e32 v109, v201, v109
	v_add_f32_e32 v110, v202, v110
	v_add_f32_e32 v111, v203, v111
	v_fmac_f32_e32 v199, v108, v108
	v_fmac_f32_e32 v199, v109, v109
	v_fmac_f32_e32 v199, v110, v110
	v_fmac_f32_e32 v199, v111, v111
	ds_write_b128 v188, v[108:111] offset:224
	ds_read_b128 v[160:163], v191
	ds_read_b128 v[164:167], v191 offset:1088
	ds_read_b128 v[168:171], v191 offset:2176
	ds_read_b128 v[172:175], v191 offset:3264
	ds_read_b128 v[176:179], v191 offset:4352
	ds_read_b128 v[180:183], v191 offset:5440
	ds_read_b128 v[184:187], v191 offset:6528
	ds_read_b128 v[200:203], v191 offset:7616
	s_add_u32 s74, s66, 0x0
	s_addc_u32 s75, s67, 0
	s_waitcnt lgkmcnt(7)
	global_store_dwordx4 v193, v[160:163], s[74:75]
	s_add_u32 s74, s66, 0x4000
	s_addc_u32 s75, s67, 0
	s_waitcnt lgkmcnt(6)
	global_store_dwordx4 v193, v[164:167], s[74:75]
	s_add_u32 s74, s66, 0x8000
	s_addc_u32 s75, s67, 0
	s_waitcnt lgkmcnt(5)
	global_store_dwordx4 v193, v[168:171], s[74:75]
	s_add_u32 s74, s66, 0xc000
	s_addc_u32 s75, s67, 0
	s_waitcnt lgkmcnt(4)
	global_store_dwordx4 v193, v[172:175], s[74:75]
	s_add_u32 s74, s66, 0x10000
	s_addc_u32 s75, s67, 0
	s_waitcnt lgkmcnt(3)
	global_store_dwordx4 v193, v[176:179], s[74:75]
	s_add_u32 s74, s66, 0x14000
	s_addc_u32 s75, s67, 0
	s_waitcnt lgkmcnt(2)
	global_store_dwordx4 v193, v[180:183], s[74:75]
	s_add_u32 s74, s66, 0x18000
	s_addc_u32 s75, s67, 0
	s_waitcnt lgkmcnt(1)
	global_store_dwordx4 v193, v[184:187], s[74:75]
	s_add_u32 s74, s66, 0x1c000
	s_addc_u32 s75, s67, 0
	s_waitcnt lgkmcnt(0)
; DI bfr f2bf(float a) { return (bfr)(pack2(a, 0.f) & 0xffffu); }
; DI int crow(int reg, int h) { return (reg & 3) + 8 * (reg >> 2) + 4 * h; }
; template <bool FIRST, bool HAS_H>
; DI void phase_gemm_resid(const Params& p, const bfr* A, const bfr* Wt, const float* gnext, float* ss, char* smem) {
;     ...
;     const float* xsrc = FIRST ? p.x_prompt : X;
;     const int rbase = m0 + wr * 64 + 4 * hl, cbase = n0 + wc * 128 + r;
; #pragma unroll
;     for (int i = 0; i < 2; ++i) {
; #pragma unroll
;       for (int qh = 0; qh < 2; ++qh) {
;         float rs[8];
; #pragma unroll
;         for (int q = 0; q < 8; ++q) rs[q] = 0.f;
; #pragma unroll
;         for (int jh = 0; jh < 2; ++jh) {
;           float xo[2][8];
; #pragma unroll
;           for (int jj = 0; jj < 2; ++jj)
; #pragma unroll
;             for (int q = 0; q < 8; ++q)
;               xo[jj][q] = xsrc[(rbase + i * 32 + crow(qh * 8 + q, 0)) * 1024 + cbase + (jh * 2 + jj) * 32];
; #pragma unroll
;           for (int q = 0; q < 8; ++q) {
;             const int o = (rbase + i * 32 + crow(qh * 8 + q, 0)) * 1024 + cbase;
; #pragma unroll
;             for (int jj = 0; jj < 2; ++jj) {
;               const int j = jh * 2 + jj;
;               const float xn = xo[jj][q] + acc[i][j][qh * 8 + q];
;               X[o + j * 32] = xn;
;               if (HAS_H) Hn[o + j * 32] = f2bf(xn * gnext[cbase + j * 32]);
;               rs[q] += xn * xn;
;             }
;           }
;         }
; #pragma unroll
;         for (int q = 0; q < 8; ++q) rs[q] = half32_sum_hi(rs[q]);
;         if (r == 31) {
; #pragma unroll
;           for (int q = 0; q < 8; ++q) unsafeAtomicAdd(ss + rbase + i * 32 + crow(qh * 8 + q, 0), rs[q]);
;         }
	global_store_dwordx4 v193, v[200:203], s[74:75]
	global_load_dwordx4 v[160:163], v198, s[70:71]
	global_load_dwordx4 v[164:167], v198, s[70:71] offset:32
	global_load_dwordx4 v[168:171], v198, s[70:71] offset:64
	global_load_dwordx4 v[172:175], v198, s[70:71] offset:96
	global_load_dwordx4 v[176:179], v198, s[70:71] offset:128
	global_load_dwordx4 v[180:183], v198, s[70:71] offset:160
	global_load_dwordx4 v[184:187], v198, s[70:71] offset:192
	global_load_dwordx4 v[200:203], v198, s[70:71] offset:224
	s_waitcnt vmcnt(7)
	v_mul_f32_e32 v112, v160, v112
	v_mul_f32_e32 v113, v161, v113
	v_mul_f32_e32 v114, v162, v114
	v_mul_f32_e32 v115, v163, v115
	v_cvt_pk_bf16_f32 v112, v112, v113
	v_cvt_pk_bf16_f32 v113, v114, v115
	ds_write_b64 v190, v[112:113]
	s_waitcnt vmcnt(6)
	v_mul_f32_e32 v116, v164, v116
	v_mul_f32_e32 v117, v165, v117
	v_mul_f32_e32 v118, v166, v118
	v_mul_f32_e32 v119, v167, v119
	v_cvt_pk_bf16_f32 v116, v116, v117
	v_cvt_pk_bf16_f32 v117, v118, v119
	ds_write_b64 v190, v[116:117] offset:16
	s_waitcnt vmcnt(5)
	v_mul_f32_e32 v120, v168, v120
	v_mul_f32_e32 v121, v169, v121
	v_mul_f32_e32 v122, v170, v122
	v_mul_f32_e32 v123, v171, v123
	v_cvt_pk_bf16_f32 v120, v120, v121
	v_cvt_pk_bf16_f32 v121, v122, v123
	ds_write_b64 v190, v[120:121] offset:32
	s_waitcnt vmcnt(4)
	v_mul_f32_e32 v124, v172, v124
	v_mul_f32_e32 v125, v173, v125
	v_mul_f32_e32 v126, v174, v126
	v_mul_f32_e32 v127, v175, v127
	v_cvt_pk_bf16_f32 v124, v124, v125
	v_cvt_pk_bf16_f32 v125, v126, v127
	ds_write_b64 v190, v[124:125] offset:48
	s_waitcnt vmcnt(3)
	v_mul_f32_e32 v96, v176, v96
	v_mul_f32_e32 v97, v177, v97
	v_mul_f32_e32 v98, v178, v98
	v_mul_f32_e32 v99, v179, v99
	v_cvt_pk_bf16_f32 v96, v96, v97
	v_cvt_pk_bf16_f32 v97, v98, v99
	ds_write_b64 v190, v[96:97] offset:64
	s_waitcnt vmcnt(2)
	v_mul_f32_e32 v100, v180, v100
	v_mul_f32_e32 v101, v181, v101
	v_mul_f32_e32 v102, v182, v102
	v_mul_f32_e32 v103, v183, v103
	v_cvt_pk_bf16_f32 v100, v100, v101
	v_cvt_pk_bf16_f32 v101, v102, v103
	ds_write_b64 v190, v[100:101] offset:80
	s_waitcnt vmcnt(1)
	v_mul_f32_e32 v104, v184, v104
	v_mul_f32_e32 v105, v185, v105
	v_mul_f32_e32 v106, v186, v106
	v_mul_f32_e32 v107, v187, v107
	v_cvt_pk_bf16_f32 v104, v104, v105
	v_cvt_pk_bf16_f32 v105, v106, v107
	ds_write_b64 v190, v[104:105] offset:96
	s_waitcnt vmcnt(0)
	v_mul_f32_e32 v108, v200, v108
	v_mul_f32_e32 v109, v201, v109
	v_mul_f32_e32 v110, v202, v110
	v_mul_f32_e32 v111, v203, v111
	v_cvt_pk_bf16_f32 v108, v108, v109
	v_cvt_pk_bf16_f32 v109, v110, v111
	ds_write_b64 v190, v[108:109] offset:112
	ds_read_b128 v[160:163], v192
	ds_read_b128 v[164:167], v192 offset:2176
	ds_read_b128 v[168:171], v192 offset:4352
	ds_read_b128 v[172:175], v192 offset:6528
	s_add_u32 s74, s68, 0x0
	s_addc_u32 s75, s69, 0
	s_waitcnt lgkmcnt(3)
	global_store_dwordx4 v194, v[160:163], s[74:75]
	s_add_u32 s74, s68, 0x4000
	s_addc_u32 s75, s69, 0
	s_waitcnt lgkmcnt(2)
	global_store_dwordx4 v194, v[164:167], s[74:75]
	s_add_u32 s74, s68, 0x8000
	s_addc_u32 s75, s69, 0
	s_waitcnt lgkmcnt(1)
	global_store_dwordx4 v194, v[168:171], s[74:75]
	s_add_u32 s74, s68, 0xc000
	s_addc_u32 s75, s69, 0
	s_waitcnt lgkmcnt(0)
	global_store_dwordx4 v194, v[172:175], s[74:75]
	s_waitcnt vmcnt(4)
	ds_write_b128 v191, v[128:131]
	s_waitcnt vmcnt(4)
	ds_write_b128 v191, v[132:135] offset:1088
	s_waitcnt vmcnt(4)
	ds_write_b128 v191, v[136:139] offset:2176
	s_waitcnt vmcnt(4)
	ds_write_b128 v191, v[140:143] offset:3264
	s_waitcnt vmcnt(4)
	ds_write_b128 v191, v[144:147] offset:4352
	s_waitcnt vmcnt(4)
	ds_write_b128 v191, v[148:151] offset:5440
	s_waitcnt vmcnt(4)
	ds_write_b128 v191, v[152:155] offset:6528
	s_waitcnt vmcnt(4)
	ds_write_b128 v191, v[156:159] offset:7616
	s_add_u32 s74, s64, 0x20000
	s_addc_u32 s75, s65, 0
	global_load_dwordx4 v[128:131], v193, s[74:75]
	s_add_u32 s74, s64, 0x24000
	s_addc_u32 s75, s65, 0
	global_load_dwordx4 v[132:135], v193, s[74:75]
	s_add_u32 s74, s64, 0x28000
	s_addc_u32 s75, s65, 0
	global_load_dwordx4 v[136:139], v193, s[74:75]
	s_add_u32 s74, s64, 0x2c000
	s_addc_u32 s75, s65, 0
	global_load_dwordx4 v[140:143], v193, s[74:75]
	s_add_u32 s74, s64, 0x30000
	s_addc_u32 s75, s65, 0
	global_load_dwordx4 v[144:147], v193, s[74:75]
	s_add_u32 s74, s64, 0x34000
	s_addc_u32 s75, s65, 0
	global_load_dwordx4 v[148:151], v193, s[74:75]
	s_add_u32 s74, s64, 0x38000
	s_addc_u32 s75, s65, 0
	global_load_dwordx4 v[152:155], v193, s[74:75]
	s_add_u32 s74, s64, 0x3c000
	s_addc_u32 s75, s65, 0
	global_load_dwordx4 v[156:159], v193, s[74:75]
	ds_read_b128 v[160:163], v188
	ds_read_b128 v[164:167], v188 offset:32
	ds_read_b128 v[168:171], v188 offset:64
	ds_read_b128 v[172:175], v188 offset:96
	ds_read_b128 v[176:179], v188 offset:128
	ds_read_b128 v[180:183], v188 offset:160
	ds_read_b128 v[184:187], v188 offset:192
	ds_read_b128 v[200:203], v188 offset:224
	s_waitcnt lgkmcnt(7)
	v_add_f32_e32 v80, v160, v80
	v_add_f32_e32 v81, v161, v81
	v_add_f32_e32 v82, v162, v82
	v_add_f32_e32 v83, v163, v83
	v_fmac_f32_e32 v199, v80, v80
	v_fmac_f32_e32 v199, v81, v81
	v_fmac_f32_e32 v199, v82, v82
	v_fmac_f32_e32 v199, v83, v83
	ds_write_b128 v188, v[80:83]
	s_waitcnt lgkmcnt(7)
	v_add_f32_e32 v84, v164, v84
	v_add_f32_e32 v85, v165, v85
	v_add_f32_e32 v86, v166, v86
	v_add_f32_e32 v87, v167, v87
	v_fmac_f32_e32 v199, v84, v84
	v_fmac_f32_e32 v199, v85, v85
	v_fmac_f32_e32 v199, v86, v86
	v_fmac_f32_e32 v199, v87, v87
	ds_write_b128 v188, v[84:87] offset:32
	s_waitcnt lgkmcnt(7)
	v_add_f32_e32 v88, v168, v88
	v_add_f32_e32 v89, v169, v89
	v_add_f32_e32 v90, v170, v90
	v_add_f32_e32 v91, v171, v91
	v_fmac_f32_e32 v199, v88, v88
	v_fmac_f32_e32 v199, v89, v89
	v_fmac_f32_e32 v199, v90, v90
	v_fmac_f32_e32 v199, v91, v91
	ds_write_b128 v188, v[88:91] offset:64
	s_waitcnt lgkmcnt(7)
; DI bfr f2bf(float a) { return (bfr)(pack2(a, 0.f) & 0xffffu); }
; DI int crow(int reg, int h) { return (reg & 3) + 8 * (reg >> 2) + 4 * h; }
; template <bool FIRST, bool HAS_H>
; DI void phase_gemm_resid(const Params& p, const bfr* A, const bfr* Wt, const float* gnext, float* ss, char* smem) {
;     ...
;     const float* xsrc = FIRST ? p.x_prompt : X;
;     const int rbase = m0 + wr * 64 + 4 * hl, cbase = n0 + wc * 128 + r;
; #pragma unroll
;     for (int i = 0; i < 2; ++i) {
; #pragma unroll
;       for (int qh = 0; qh < 2; ++qh) {
;         float rs[8];
; #pragma unroll
;         for (int q = 0; q < 8; ++q) rs[q] = 0.f;
; #pragma unroll
;         for (int jh = 0; jh < 2; ++jh) {
;           float xo[2][8];
; #pragma unroll
;           for (int jj = 0; jj < 2; ++jj)
; #pragma unroll
;             for (int q = 0; q < 8; ++q)
;               xo[jj][q] = xsrc[(rbase + i * 32 + crow(qh * 8 + q, 0)) * 1024 + cbase + (jh * 2 + jj) * 32];
; #pragma unroll
;           for (int q = 0; q < 8; ++q) {
;             const int o = (rbase + i * 32 + crow(qh * 8 + q, 0)) * 1024 + cbase;
; #pragma unroll
;             for (int jj = 0; jj < 2; ++jj) {
;               const int j = jh * 2 + jj;
;               const float xn = xo[jj][q] + acc[i][j][qh * 8 + q];
;               X[o + j * 32] = xn;
;               if (HAS_H) Hn[o + j * 32] = f2bf(xn * gnext[cbase + j * 32]);
;               rs[q] += xn * xn;
;             }
;           }
;         }
; #pragma unroll
;         for (int q = 0; q < 8; ++q) rs[q] = half32_sum_hi(rs[q]);
;         if (r == 31) {
; #pragma unroll
;           for (int q = 0; q < 8; ++q) unsafeAtomicAdd(ss + rbase + i * 32 + crow(qh * 8 + q, 0), rs[q]);
;         }
	v_add_f32_e32 v92, v172, v92
	v_add_f32_e32 v93, v173, v93
	v_add_f32_e32 v94, v174, v94
	v_add_f32_e32 v95, v175, v95
	v_fmac_f32_e32 v199, v92, v92
	v_fmac_f32_e32 v199, v93, v93
	v_fmac_f32_e32 v199, v94, v94
	v_fmac_f32_e32 v199, v95, v95
	ds_write_b128 v188, v[92:95] offset:96
	s_waitcnt lgkmcnt(7)
	v_add_f32_e32 v64, v176, v64
	v_add_f32_e32 v65, v177, v65
	v_add_f32_e32 v66, v178, v66
	v_add_f32_e32 v67, v179, v67
	v_fmac_f32_e32 v199, v64, v64
	v_fmac_f32_e32 v199, v65, v65
	v_fmac_f32_e32 v199, v66, v66
	v_fmac_f32_e32 v199, v67, v67
	ds_write_b128 v188, v[64:67] offset:128
	s_waitcnt lgkmcnt(7)
	v_add_f32_e32 v68, v180, v68
	v_add_f32_e32 v69, v181, v69
	v_add_f32_e32 v70, v182, v70
	v_add_f32_e32 v71, v183, v71
	v_fmac_f32_e32 v199, v68, v68
	v_fmac_f32_e32 v199, v69, v69
	v_fmac_f32_e32 v199, v70, v70
	v_fmac_f32_e32 v199, v71, v71
	ds_write_b128 v188, v[68:71] offset:160
	s_waitcnt lgkmcnt(7)
	v_add_f32_e32 v72, v184, v72
	v_add_f32_e32 v73, v185, v73
	v_add_f32_e32 v74, v186, v74
	v_add_f32_e32 v75, v187, v75
	v_fmac_f32_e32 v199, v72, v72
	v_fmac_f32_e32 v199, v73, v73
	v_fmac_f32_e32 v199, v74, v74
	v_fmac_f32_e32 v199, v75, v75
	ds_write_b128 v188, v[72:75] offset:192
	s_waitcnt lgkmcnt(7)
	v_add_f32_e32 v76, v200, v76
	v_add_f32_e32 v77, v201, v77
	v_add_f32_e32 v78, v202, v78
	v_add_f32_e32 v79, v203, v79
	v_fmac_f32_e32 v199, v76, v76
	v_fmac_f32_e32 v199, v77, v77
	v_fmac_f32_e32 v199, v78, v78
	v_fmac_f32_e32 v199, v79, v79
	ds_write_b128 v188, v[76:79] offset:224
	ds_read_b128 v[160:163], v191
	ds_read_b128 v[164:167], v191 offset:1088
	ds_read_b128 v[168:171], v191 offset:2176
	ds_read_b128 v[172:175], v191 offset:3264
	ds_read_b128 v[176:179], v191 offset:4352
	ds_read_b128 v[180:183], v191 offset:5440
	ds_read_b128 v[184:187], v191 offset:6528
	ds_read_b128 v[200:203], v191 offset:7616
	s_add_u32 s74, s66, 0x100
	s_addc_u32 s75, s67, 0
	s_waitcnt lgkmcnt(7)
	global_store_dwordx4 v193, v[160:163], s[74:75]
	s_add_u32 s74, s66, 0x4100
	s_addc_u32 s75, s67, 0
	s_waitcnt lgkmcnt(6)
	global_store_dwordx4 v193, v[164:167], s[74:75]
	s_add_u32 s74, s66, 0x8100
	s_addc_u32 s75, s67, 0
	s_waitcnt lgkmcnt(5)
	global_store_dwordx4 v193, v[168:171], s[74:75]
	s_add_u32 s74, s66, 0xc100
	s_addc_u32 s75, s67, 0
	s_waitcnt lgkmcnt(4)
	global_store_dwordx4 v193, v[172:175], s[74:75]
	s_add_u32 s74, s66, 0x10100
	s_addc_u32 s75, s67, 0
	s_waitcnt lgkmcnt(3)
	global_store_dwordx4 v193, v[176:179], s[74:75]
	s_add_u32 s74, s66, 0x14100
	s_addc_u32 s75, s67, 0
	s_waitcnt lgkmcnt(2)
	global_store_dwordx4 v193, v[180:183], s[74:75]
	s_add_u32 s74, s66, 0x18100
	s_addc_u32 s75, s67, 0
	s_waitcnt lgkmcnt(1)
	global_store_dwordx4 v193, v[184:187], s[74:75]
	s_add_u32 s74, s66, 0x1c100
	s_addc_u32 s75, s67, 0
	s_waitcnt lgkmcnt(0)
	global_store_dwordx4 v193, v[200:203], s[74:75]
	global_load_dwordx4 v[160:163], v198, s[70:71] offset:256
	global_load_dwordx4 v[164:167], v198, s[70:71] offset:288
	global_load_dwordx4 v[168:171], v198, s[70:71] offset:320
	global_load_dwordx4 v[172:175], v198, s[70:71] offset:352
	global_load_dwordx4 v[176:179], v198, s[70:71] offset:384
	global_load_dwordx4 v[180:183], v198, s[70:71] offset:416
	global_load_dwordx4 v[184:187], v198, s[70:71] offset:448
	global_load_dwordx4 v[200:203], v198, s[70:71] offset:480
	s_waitcnt vmcnt(7)
	v_mul_f32_e32 v80, v160, v80
	v_mul_f32_e32 v81, v161, v81
	v_mul_f32_e32 v82, v162, v82
	v_mul_f32_e32 v83, v163, v83
	v_cvt_pk_bf16_f32 v80, v80, v81
	v_cvt_pk_bf16_f32 v81, v82, v83
	ds_write_b64 v190, v[80:81]
	s_waitcnt vmcnt(6)
	v_mul_f32_e32 v84, v164, v84
	v_mul_f32_e32 v85, v165, v85
	v_mul_f32_e32 v86, v166, v86
	v_mul_f32_e32 v87, v167, v87
	v_cvt_pk_bf16_f32 v84, v84, v85
	v_cvt_pk_bf16_f32 v85, v86, v87
	ds_write_b64 v190, v[84:85] offset:16
	s_waitcnt vmcnt(5)
	v_mul_f32_e32 v88, v168, v88
	v_mul_f32_e32 v89, v169, v89
	v_mul_f32_e32 v90, v170, v90
	v_mul_f32_e32 v91, v171, v91
	v_cvt_pk_bf16_f32 v88, v88, v89
	v_cvt_pk_bf16_f32 v89, v90, v91
	ds_write_b64 v190, v[88:89] offset:32
	s_waitcnt vmcnt(4)
	v_mul_f32_e32 v92, v172, v92
	v_mul_f32_e32 v93, v173, v93
	v_mul_f32_e32 v94, v174, v94
	v_mul_f32_e32 v95, v175, v95
	v_cvt_pk_bf16_f32 v92, v92, v93
	v_cvt_pk_bf16_f32 v93, v94, v95
	ds_write_b64 v190, v[92:93] offset:48
	s_waitcnt vmcnt(3)
	v_mul_f32_e32 v64, v176, v64
	v_mul_f32_e32 v65, v177, v65
	v_mul_f32_e32 v66, v178, v66
	v_mul_f32_e32 v67, v179, v67
	v_cvt_pk_bf16_f32 v64, v64, v65
	v_cvt_pk_bf16_f32 v65, v66, v67
	ds_write_b64 v190, v[64:65] offset:64
	s_waitcnt vmcnt(2)
	v_mul_f32_e32 v68, v180, v68
	v_mul_f32_e32 v69, v181, v69
	v_mul_f32_e32 v70, v182, v70
	v_mul_f32_e32 v71, v183, v71
	v_cvt_pk_bf16_f32 v68, v68, v69
	v_cvt_pk_bf16_f32 v69, v70, v71
	ds_write_b64 v190, v[68:69] offset:80
	s_waitcnt vmcnt(1)
	v_mul_f32_e32 v72, v184, v72
	v_mul_f32_e32 v73, v185, v73
	v_mul_f32_e32 v74, v186, v74
	v_mul_f32_e32 v75, v187, v75
	v_cvt_pk_bf16_f32 v72, v72, v73
	v_cvt_pk_bf16_f32 v73, v74, v75
	ds_write_b64 v190, v[72:73] offset:96
	s_waitcnt vmcnt(0)
	v_mul_f32_e32 v76, v200, v76
	v_mul_f32_e32 v77, v201, v77
	v_mul_f32_e32 v78, v202, v78
	v_mul_f32_e32 v79, v203, v79
	v_cvt_pk_bf16_f32 v76, v76, v77
	v_cvt_pk_bf16_f32 v77, v78, v79
	ds_write_b64 v190, v[76:77] offset:112
	ds_read_b128 v[160:163], v192
	ds_read_b128 v[164:167], v192 offset:2176
	ds_read_b128 v[168:171], v192 offset:4352
	ds_read_b128 v[172:175], v192 offset:6528
	s_add_u32 s74, s68, 0x80
	s_addc_u32 s75, s69, 0
	s_waitcnt lgkmcnt(3)
	global_store_dwordx4 v194, v[160:163], s[74:75]
	s_add_u32 s74, s68, 0x4080
	s_addc_u32 s75, s69, 0
	s_waitcnt lgkmcnt(2)
; DI bfr f2bf(float a) { return (bfr)(pack2(a, 0.f) & 0xffffu); }
; DI int crow(int reg, int h) { return (reg & 3) + 8 * (reg >> 2) + 4 * h; }
; template <bool FIRST, bool HAS_H>
; DI void phase_gemm_resid(const Params& p, const bfr* A, const bfr* Wt, const float* gnext, float* ss, char* smem) {
;     ...
;     const float* xsrc = FIRST ? p.x_prompt : X;
;     const int rbase = m0 + wr * 64 + 4 * hl, cbase = n0 + wc * 128 + r;
; #pragma unroll
;     for (int i = 0; i < 2; ++i) {
; #pragma unroll
;       for (int qh = 0; qh < 2; ++qh) {
;         float rs[8];
; #pragma unroll
;         for (int q = 0; q < 8; ++q) rs[q] = 0.f;
; #pragma unroll
;         for (int jh = 0; jh < 2; ++jh) {
;           float xo[2][8];
; #pragma unroll
;           for (int jj = 0; jj < 2; ++jj)
; #pragma unroll
;             for (int q = 0; q < 8; ++q)
;               xo[jj][q] = xsrc[(rbase + i * 32 + crow(qh * 8 + q, 0)) * 1024 + cbase + (jh * 2 + jj) * 32];
; #pragma unroll
;           for (int q = 0; q < 8; ++q) {
;             const int o = (rbase + i * 32 + crow(qh * 8 + q, 0)) * 1024 + cbase;
; #pragma unroll
;             for (int jj = 0; jj < 2; ++jj) {
;               const int j = jh * 2 + jj;
;               const float xn = xo[jj][q] + acc[i][j][qh * 8 + q];
;               X[o + j * 32] = xn;
;               if (HAS_H) Hn[o + j * 32] = f2bf(xn * gnext[cbase + j * 32]);
;               rs[q] += xn * xn;
;             }
;           }
;         }
; #pragma unroll
;         for (int q = 0; q < 8; ++q) rs[q] = half32_sum_hi(rs[q]);
;         if (r == 31) {
; #pragma unroll
;           for (int q = 0; q < 8; ++q) unsafeAtomicAdd(ss + rbase + i * 32 + crow(qh * 8 + q, 0), rs[q]);
;         }
	global_store_dwordx4 v194, v[164:167], s[74:75]
	s_add_u32 s74, s68, 0x8080
	s_addc_u32 s75, s69, 0
	s_waitcnt lgkmcnt(1)
	global_store_dwordx4 v194, v[168:171], s[74:75]
	s_add_u32 s74, s68, 0xc080
	s_addc_u32 s75, s69, 0
	s_waitcnt lgkmcnt(0)
	global_store_dwordx4 v194, v[172:175], s[74:75]
	s_waitcnt vmcnt(4)
	ds_write_b128 v191, v[128:131]
	s_waitcnt vmcnt(4)
	ds_write_b128 v191, v[132:135] offset:1088
	s_waitcnt vmcnt(4)
	ds_write_b128 v191, v[136:139] offset:2176
	s_waitcnt vmcnt(4)
	ds_write_b128 v191, v[140:143] offset:3264
	s_waitcnt vmcnt(4)
	ds_write_b128 v191, v[144:147] offset:4352
	s_waitcnt vmcnt(4)
	ds_write_b128 v191, v[148:151] offset:5440
	s_waitcnt vmcnt(4)
	ds_write_b128 v191, v[152:155] offset:6528
	s_waitcnt vmcnt(4)
	ds_write_b128 v191, v[156:159] offset:7616
	s_add_u32 s74, s64, 0x20100
	s_addc_u32 s75, s65, 0
	global_load_dwordx4 v[128:131], v193, s[74:75]
	s_add_u32 s74, s64, 0x24100
	s_addc_u32 s75, s65, 0
	global_load_dwordx4 v[132:135], v193, s[74:75]
	s_add_u32 s74, s64, 0x28100
	s_addc_u32 s75, s65, 0
	global_load_dwordx4 v[136:139], v193, s[74:75]
	s_add_u32 s74, s64, 0x2c100
	s_addc_u32 s75, s65, 0
	global_load_dwordx4 v[140:143], v193, s[74:75]
	s_add_u32 s74, s64, 0x30100
	s_addc_u32 s75, s65, 0
	global_load_dwordx4 v[144:147], v193, s[74:75]
	s_add_u32 s74, s64, 0x34100
	s_addc_u32 s75, s65, 0
	global_load_dwordx4 v[148:151], v193, s[74:75]
	s_add_u32 s74, s64, 0x38100
	s_addc_u32 s75, s65, 0
	global_load_dwordx4 v[152:155], v193, s[74:75]
	s_add_u32 s74, s64, 0x3c100
	s_addc_u32 s75, s65, 0
	global_load_dwordx4 v[156:159], v193, s[74:75]
	ds_read_b128 v[160:163], v188
	ds_read_b128 v[164:167], v188 offset:32
	ds_read_b128 v[168:171], v188 offset:64
	ds_read_b128 v[172:175], v188 offset:96
	ds_read_b128 v[176:179], v188 offset:128
	ds_read_b128 v[180:183], v188 offset:160
	ds_read_b128 v[184:187], v188 offset:192
	ds_read_b128 v[200:203], v188 offset:224
	s_waitcnt lgkmcnt(7)
	v_add_f32_e32 v48, v160, v48
	v_add_f32_e32 v49, v161, v49
	v_add_f32_e32 v50, v162, v50
	v_add_f32_e32 v51, v163, v51
	v_fmac_f32_e32 v204, v48, v48
	v_fmac_f32_e32 v204, v49, v49
	v_fmac_f32_e32 v204, v50, v50
	v_fmac_f32_e32 v204, v51, v51
	ds_write_b128 v188, v[48:51]
	s_waitcnt lgkmcnt(7)
	v_add_f32_e32 v52, v164, v52
	v_add_f32_e32 v53, v165, v53
	v_add_f32_e32 v54, v166, v54
	v_add_f32_e32 v55, v167, v55
	v_fmac_f32_e32 v204, v52, v52
	v_fmac_f32_e32 v204, v53, v53
	v_fmac_f32_e32 v204, v54, v54
	v_fmac_f32_e32 v204, v55, v55
	ds_write_b128 v188, v[52:55] offset:32
	s_waitcnt lgkmcnt(7)
	v_add_f32_e32 v56, v168, v56
	v_add_f32_e32 v57, v169, v57
	v_add_f32_e32 v58, v170, v58
	v_add_f32_e32 v59, v171, v59
	v_fmac_f32_e32 v204, v56, v56
	v_fmac_f32_e32 v204, v57, v57
	v_fmac_f32_e32 v204, v58, v58
	v_fmac_f32_e32 v204, v59, v59
	ds_write_b128 v188, v[56:59] offset:64
	s_waitcnt lgkmcnt(7)
	v_add_f32_e32 v60, v172, v60
	v_add_f32_e32 v61, v173, v61
	v_add_f32_e32 v62, v174, v62
	v_add_f32_e32 v63, v175, v63
	v_fmac_f32_e32 v204, v60, v60
	v_fmac_f32_e32 v204, v61, v61
	v_fmac_f32_e32 v204, v62, v62
	v_fmac_f32_e32 v204, v63, v63
	ds_write_b128 v188, v[60:63] offset:96
	s_waitcnt lgkmcnt(7)
	v_add_f32_e32 v32, v176, v32
	v_add_f32_e32 v33, v177, v33
	v_add_f32_e32 v34, v178, v34
	v_add_f32_e32 v35, v179, v35
	v_fmac_f32_e32 v204, v32, v32
	v_fmac_f32_e32 v204, v33, v33
	v_fmac_f32_e32 v204, v34, v34
	v_fmac_f32_e32 v204, v35, v35
	ds_write_b128 v188, v[32:35] offset:128
	s_waitcnt lgkmcnt(7)
	v_add_f32_e32 v36, v180, v36
	v_add_f32_e32 v37, v181, v37
	v_add_f32_e32 v38, v182, v38
	v_add_f32_e32 v39, v183, v39
	v_fmac_f32_e32 v204, v36, v36
	v_fmac_f32_e32 v204, v37, v37
	v_fmac_f32_e32 v204, v38, v38
	v_fmac_f32_e32 v204, v39, v39
	ds_write_b128 v188, v[36:39] offset:160
	s_waitcnt lgkmcnt(7)
	v_add_f32_e32 v40, v184, v40
	v_add_f32_e32 v41, v185, v41
	v_add_f32_e32 v42, v186, v42
	v_add_f32_e32 v43, v187, v43
	v_fmac_f32_e32 v204, v40, v40
	v_fmac_f32_e32 v204, v41, v41
	v_fmac_f32_e32 v204, v42, v42
	v_fmac_f32_e32 v204, v43, v43
	ds_write_b128 v188, v[40:43] offset:192
	s_waitcnt lgkmcnt(7)
	v_add_f32_e32 v44, v200, v44
	v_add_f32_e32 v45, v201, v45
	v_add_f32_e32 v46, v202, v46
	v_add_f32_e32 v47, v203, v47
	v_fmac_f32_e32 v204, v44, v44
	v_fmac_f32_e32 v204, v45, v45
	v_fmac_f32_e32 v204, v46, v46
	v_fmac_f32_e32 v204, v47, v47
	ds_write_b128 v188, v[44:47] offset:224
	ds_read_b128 v[160:163], v191
	ds_read_b128 v[164:167], v191 offset:1088
	ds_read_b128 v[168:171], v191 offset:2176
	ds_read_b128 v[172:175], v191 offset:3264
	ds_read_b128 v[176:179], v191 offset:4352
	ds_read_b128 v[180:183], v191 offset:5440
	ds_read_b128 v[184:187], v191 offset:6528
	ds_read_b128 v[200:203], v191 offset:7616
	s_add_u32 s74, s66, 0x20000
	s_addc_u32 s75, s67, 0
	s_waitcnt lgkmcnt(7)
	global_store_dwordx4 v193, v[160:163], s[74:75]
	s_add_u32 s74, s66, 0x24000
	s_addc_u32 s75, s67, 0
	s_waitcnt lgkmcnt(6)
	global_store_dwordx4 v193, v[164:167], s[74:75]
	s_add_u32 s74, s66, 0x28000
	s_addc_u32 s75, s67, 0
	s_waitcnt lgkmcnt(5)
	global_store_dwordx4 v193, v[168:171], s[74:75]
	s_add_u32 s74, s66, 0x2c000
	s_addc_u32 s75, s67, 0
	s_waitcnt lgkmcnt(4)
	global_store_dwordx4 v193, v[172:175], s[74:75]
	s_add_u32 s74, s66, 0x30000
	s_addc_u32 s75, s67, 0
	s_waitcnt lgkmcnt(3)
	global_store_dwordx4 v193, v[176:179], s[74:75]
	s_add_u32 s74, s66, 0x34000
	s_addc_u32 s75, s67, 0
	s_waitcnt lgkmcnt(2)
	global_store_dwordx4 v193, v[180:183], s[74:75]
	s_add_u32 s74, s66, 0x38000
	s_addc_u32 s75, s67, 0
	s_waitcnt lgkmcnt(1)
	global_store_dwordx4 v193, v[184:187], s[74:75]
	s_add_u32 s74, s66, 0x3c000
	s_addc_u32 s75, s67, 0
	s_waitcnt lgkmcnt(0)
; DI bfr f2bf(float a) { return (bfr)(pack2(a, 0.f) & 0xffffu); }
; DI int crow(int reg, int h) { return (reg & 3) + 8 * (reg >> 2) + 4 * h; }
; template <bool FIRST, bool HAS_H>
; DI void phase_gemm_resid(const Params& p, const bfr* A, const bfr* Wt, const float* gnext, float* ss, char* smem) {
;     ...
;     const float* xsrc = FIRST ? p.x_prompt : X;
;     const int rbase = m0 + wr * 64 + 4 * hl, cbase = n0 + wc * 128 + r;
; #pragma unroll
;     for (int i = 0; i < 2; ++i) {
; #pragma unroll
;       for (int qh = 0; qh < 2; ++qh) {
;         float rs[8];
; #pragma unroll
;         for (int q = 0; q < 8; ++q) rs[q] = 0.f;
; #pragma unroll
;         for (int jh = 0; jh < 2; ++jh) {
;           float xo[2][8];
; #pragma unroll
;           for (int jj = 0; jj < 2; ++jj)
; #pragma unroll
;             for (int q = 0; q < 8; ++q)
;               xo[jj][q] = xsrc[(rbase + i * 32 + crow(qh * 8 + q, 0)) * 1024 + cbase + (jh * 2 + jj) * 32];
; #pragma unroll
;           for (int q = 0; q < 8; ++q) {
;             const int o = (rbase + i * 32 + crow(qh * 8 + q, 0)) * 1024 + cbase;
; #pragma unroll
;             for (int jj = 0; jj < 2; ++jj) {
;               const int j = jh * 2 + jj;
;               const float xn = xo[jj][q] + acc[i][j][qh * 8 + q];
;               X[o + j * 32] = xn;
;               if (HAS_H) Hn[o + j * 32] = f2bf(xn * gnext[cbase + j * 32]);
;               rs[q] += xn * xn;
;             }
;           }
;         }
; #pragma unroll
;         for (int q = 0; q < 8; ++q) rs[q] = half32_sum_hi(rs[q]);
;         if (r == 31) {
; #pragma unroll
;           for (int q = 0; q < 8; ++q) unsafeAtomicAdd(ss + rbase + i * 32 + crow(qh * 8 + q, 0), rs[q]);
;         }
	global_store_dwordx4 v193, v[200:203], s[74:75]
	global_load_dwordx4 v[160:163], v198, s[70:71]
	global_load_dwordx4 v[164:167], v198, s[70:71] offset:32
	global_load_dwordx4 v[168:171], v198, s[70:71] offset:64
	global_load_dwordx4 v[172:175], v198, s[70:71] offset:96
	global_load_dwordx4 v[176:179], v198, s[70:71] offset:128
	global_load_dwordx4 v[180:183], v198, s[70:71] offset:160
	global_load_dwordx4 v[184:187], v198, s[70:71] offset:192
	global_load_dwordx4 v[200:203], v198, s[70:71] offset:224
	s_waitcnt vmcnt(7)
	v_mul_f32_e32 v48, v160, v48
	v_mul_f32_e32 v49, v161, v49
	v_mul_f32_e32 v50, v162, v50
	v_mul_f32_e32 v51, v163, v51
	v_cvt_pk_bf16_f32 v48, v48, v49
	v_cvt_pk_bf16_f32 v49, v50, v51
	ds_write_b64 v190, v[48:49]
	s_waitcnt vmcnt(6)
	v_mul_f32_e32 v52, v164, v52
	v_mul_f32_e32 v53, v165, v53
	v_mul_f32_e32 v54, v166, v54
	v_mul_f32_e32 v55, v167, v55
	v_cvt_pk_bf16_f32 v52, v52, v53
	v_cvt_pk_bf16_f32 v53, v54, v55
	ds_write_b64 v190, v[52:53] offset:16
	s_waitcnt vmcnt(5)
	v_mul_f32_e32 v56, v168, v56
	v_mul_f32_e32 v57, v169, v57
	v_mul_f32_e32 v58, v170, v58
	v_mul_f32_e32 v59, v171, v59
	v_cvt_pk_bf16_f32 v56, v56, v57
	v_cvt_pk_bf16_f32 v57, v58, v59
	ds_write_b64 v190, v[56:57] offset:32
	s_waitcnt vmcnt(4)
	v_mul_f32_e32 v60, v172, v60
	v_mul_f32_e32 v61, v173, v61
	v_mul_f32_e32 v62, v174, v62
	v_mul_f32_e32 v63, v175, v63
	v_cvt_pk_bf16_f32 v60, v60, v61
	v_cvt_pk_bf16_f32 v61, v62, v63
	ds_write_b64 v190, v[60:61] offset:48
	s_waitcnt vmcnt(3)
	v_mul_f32_e32 v32, v176, v32
	v_mul_f32_e32 v33, v177, v33
	v_mul_f32_e32 v34, v178, v34
	v_mul_f32_e32 v35, v179, v35
	v_cvt_pk_bf16_f32 v32, v32, v33
	v_cvt_pk_bf16_f32 v33, v34, v35
	ds_write_b64 v190, v[32:33] offset:64
	s_waitcnt vmcnt(2)
	v_mul_f32_e32 v36, v180, v36
	v_mul_f32_e32 v37, v181, v37
	v_mul_f32_e32 v38, v182, v38
	v_mul_f32_e32 v39, v183, v39
	v_cvt_pk_bf16_f32 v36, v36, v37
	v_cvt_pk_bf16_f32 v37, v38, v39
	ds_write_b64 v190, v[36:37] offset:80
	s_waitcnt vmcnt(1)
	v_mul_f32_e32 v40, v184, v40
	v_mul_f32_e32 v41, v185, v41
	v_mul_f32_e32 v42, v186, v42
	v_mul_f32_e32 v43, v187, v43
	v_cvt_pk_bf16_f32 v40, v40, v41
	v_cvt_pk_bf16_f32 v41, v42, v43
	ds_write_b64 v190, v[40:41] offset:96
	s_waitcnt vmcnt(0)
	v_mul_f32_e32 v44, v200, v44
	v_mul_f32_e32 v45, v201, v45
	v_mul_f32_e32 v46, v202, v46
	v_mul_f32_e32 v47, v203, v47
	v_cvt_pk_bf16_f32 v44, v44, v45
	v_cvt_pk_bf16_f32 v45, v46, v47
	ds_write_b64 v190, v[44:45] offset:112
	ds_read_b128 v[160:163], v192
	ds_read_b128 v[164:167], v192 offset:2176
	ds_read_b128 v[168:171], v192 offset:4352
	ds_read_b128 v[172:175], v192 offset:6528
	s_add_u32 s74, s68, 0x10000
	s_addc_u32 s75, s69, 0
	s_waitcnt lgkmcnt(3)
	global_store_dwordx4 v194, v[160:163], s[74:75]
	s_add_u32 s74, s68, 0x14000
	s_addc_u32 s75, s69, 0
	s_waitcnt lgkmcnt(2)
	global_store_dwordx4 v194, v[164:167], s[74:75]
	s_add_u32 s74, s68, 0x18000
	s_addc_u32 s75, s69, 0
	s_waitcnt lgkmcnt(1)
	global_store_dwordx4 v194, v[168:171], s[74:75]
	s_add_u32 s74, s68, 0x1c000
	s_addc_u32 s75, s69, 0
	s_waitcnt lgkmcnt(0)
	global_store_dwordx4 v194, v[172:175], s[74:75]
	s_waitcnt vmcnt(4)
	ds_write_b128 v191, v[128:131]
	s_waitcnt vmcnt(4)
	ds_write_b128 v191, v[132:135] offset:1088
	s_waitcnt vmcnt(4)
	ds_write_b128 v191, v[136:139] offset:2176
	s_waitcnt vmcnt(4)
	ds_write_b128 v191, v[140:143] offset:3264
	s_waitcnt vmcnt(4)
	ds_write_b128 v191, v[144:147] offset:4352
	s_waitcnt vmcnt(4)
	ds_write_b128 v191, v[148:151] offset:5440
	s_waitcnt vmcnt(4)
	ds_write_b128 v191, v[152:155] offset:6528
	s_waitcnt vmcnt(4)
	ds_write_b128 v191, v[156:159] offset:7616
	ds_read_b128 v[160:163], v188
	ds_read_b128 v[164:167], v188 offset:32
	ds_read_b128 v[168:171], v188 offset:64
	ds_read_b128 v[172:175], v188 offset:96
	ds_read_b128 v[176:179], v188 offset:128
	ds_read_b128 v[180:183], v188 offset:160
	ds_read_b128 v[184:187], v188 offset:192
	ds_read_b128 v[200:203], v188 offset:224
	s_waitcnt lgkmcnt(7)
	v_add_f32_e32 v16, v160, v16
	v_add_f32_e32 v17, v161, v17
	v_add_f32_e32 v18, v162, v18
	v_add_f32_e32 v19, v163, v19
	v_fmac_f32_e32 v204, v16, v16
	v_fmac_f32_e32 v204, v17, v17
	v_fmac_f32_e32 v204, v18, v18
	v_fmac_f32_e32 v204, v19, v19
	ds_write_b128 v188, v[16:19]
	s_waitcnt lgkmcnt(7)
	v_add_f32_e32 v20, v164, v20
	v_add_f32_e32 v21, v165, v21
	v_add_f32_e32 v22, v166, v22
	v_add_f32_e32 v23, v167, v23
	v_fmac_f32_e32 v204, v20, v20
	v_fmac_f32_e32 v204, v21, v21
	v_fmac_f32_e32 v204, v22, v22
	v_fmac_f32_e32 v204, v23, v23
	ds_write_b128 v188, v[20:23] offset:32
	s_waitcnt lgkmcnt(7)
	v_add_f32_e32 v24, v168, v24
	v_add_f32_e32 v25, v169, v25
	v_add_f32_e32 v26, v170, v26
	v_add_f32_e32 v27, v171, v27
	v_fmac_f32_e32 v204, v24, v24
	v_fmac_f32_e32 v204, v25, v25
	v_fmac_f32_e32 v204, v26, v26
	v_fmac_f32_e32 v204, v27, v27
	ds_write_b128 v188, v[24:27] offset:64
	s_waitcnt lgkmcnt(7)
	v_add_f32_e32 v28, v172, v28
	v_add_f32_e32 v29, v173, v29
	v_add_f32_e32 v30, v174, v30
	v_add_f32_e32 v31, v175, v31
	v_fmac_f32_e32 v204, v28, v28
	v_fmac_f32_e32 v204, v29, v29
	v_fmac_f32_e32 v204, v30, v30
	v_fmac_f32_e32 v204, v31, v31
	ds_write_b128 v188, v[28:31] offset:96
	s_waitcnt lgkmcnt(7)
	v_add_f32_e32 v0, v176, v0
	v_add_f32_e32 v1, v177, v1
	v_add_f32_e32 v2, v178, v2
	v_add_f32_e32 v3, v179, v3
	v_fmac_f32_e32 v204, v0, v0
	v_fmac_f32_e32 v204, v1, v1
	v_fmac_f32_e32 v204, v2, v2
	v_fmac_f32_e32 v204, v3, v3
	ds_write_b128 v188, v[0:3] offset:128
	s_waitcnt lgkmcnt(7)
	v_add_f32_e32 v4, v180, v4
	v_add_f32_e32 v5, v181, v5
	v_add_f32_e32 v6, v182, v6
	v_add_f32_e32 v7, v183, v7
	v_fmac_f32_e32 v204, v4, v4
	v_fmac_f32_e32 v204, v5, v5
	v_fmac_f32_e32 v204, v6, v6
	v_fmac_f32_e32 v204, v7, v7
	ds_write_b128 v188, v[4:7] offset:160
	s_waitcnt lgkmcnt(7)
; DI bfr f2bf(float a) { return (bfr)(pack2(a, 0.f) & 0xffffu); }
; DI int crow(int reg, int h) { return (reg & 3) + 8 * (reg >> 2) + 4 * h; }
; template <bool FIRST, bool HAS_H>
; DI void phase_gemm_resid(const Params& p, const bfr* A, const bfr* Wt, const float* gnext, float* ss, char* smem) {
;     ...
;     const float* xsrc = FIRST ? p.x_prompt : X;
;     const int rbase = m0 + wr * 64 + 4 * hl, cbase = n0 + wc * 128 + r;
; #pragma unroll
;     for (int i = 0; i < 2; ++i) {
; #pragma unroll
;       for (int qh = 0; qh < 2; ++qh) {
;         float rs[8];
; #pragma unroll
;         for (int q = 0; q < 8; ++q) rs[q] = 0.f;
; #pragma unroll
;         for (int jh = 0; jh < 2; ++jh) {
;           float xo[2][8];
; #pragma unroll
;           for (int jj = 0; jj < 2; ++jj)
; #pragma unroll
;             for (int q = 0; q < 8; ++q)
;               xo[jj][q] = xsrc[(rbase + i * 32 + crow(qh * 8 + q, 0)) * 1024 + cbase + (jh * 2 + jj) * 32];
; #pragma unroll
;           for (int q = 0; q < 8; ++q) {
;             const int o = (rbase + i * 32 + crow(qh * 8 + q, 0)) * 1024 + cbase;
; #pragma unroll
;             for (int jj = 0; jj < 2; ++jj) {
;               const int j = jh * 2 + jj;
;               const float xn = xo[jj][q] + acc[i][j][qh * 8 + q];
;               X[o + j * 32] = xn;
;               if (HAS_H) Hn[o + j * 32] = f2bf(xn * gnext[cbase + j * 32]);
;               rs[q] += xn * xn;
;             }
;           }
;         }
; #pragma unroll
;         for (int q = 0; q < 8; ++q) rs[q] = half32_sum_hi(rs[q]);
;         if (r == 31) {
; #pragma unroll
;           for (int q = 0; q < 8; ++q) unsafeAtomicAdd(ss + rbase + i * 32 + crow(qh * 8 + q, 0), rs[q]);
;         }
	v_add_f32_e32 v8, v184, v8
	v_add_f32_e32 v9, v185, v9
	v_add_f32_e32 v10, v186, v10
	v_add_f32_e32 v11, v187, v11
	v_fmac_f32_e32 v204, v8, v8
	v_fmac_f32_e32 v204, v9, v9
	v_fmac_f32_e32 v204, v10, v10
	v_fmac_f32_e32 v204, v11, v11
	ds_write_b128 v188, v[8:11] offset:192
	s_waitcnt lgkmcnt(7)
	v_add_f32_e32 v12, v200, v12
	v_add_f32_e32 v13, v201, v13
	v_add_f32_e32 v14, v202, v14
	v_add_f32_e32 v15, v203, v15
	v_fmac_f32_e32 v204, v12, v12
	v_fmac_f32_e32 v204, v13, v13
	v_fmac_f32_e32 v204, v14, v14
	v_fmac_f32_e32 v204, v15, v15
	ds_write_b128 v188, v[12:15] offset:224
	ds_read_b128 v[160:163], v191
	ds_read_b128 v[164:167], v191 offset:1088
	ds_read_b128 v[168:171], v191 offset:2176
	ds_read_b128 v[172:175], v191 offset:3264
	ds_read_b128 v[176:179], v191 offset:4352
	ds_read_b128 v[180:183], v191 offset:5440
	ds_read_b128 v[184:187], v191 offset:6528
	ds_read_b128 v[200:203], v191 offset:7616
	s_add_u32 s74, s66, 0x20100
	s_addc_u32 s75, s67, 0
	s_waitcnt lgkmcnt(7)
	global_store_dwordx4 v193, v[160:163], s[74:75]
	s_add_u32 s74, s66, 0x24100
	s_addc_u32 s75, s67, 0
	s_waitcnt lgkmcnt(6)
	global_store_dwordx4 v193, v[164:167], s[74:75]
	s_add_u32 s74, s66, 0x28100
	s_addc_u32 s75, s67, 0
	s_waitcnt lgkmcnt(5)
	global_store_dwordx4 v193, v[168:171], s[74:75]
	s_add_u32 s74, s66, 0x2c100
	s_addc_u32 s75, s67, 0
	s_waitcnt lgkmcnt(4)
	global_store_dwordx4 v193, v[172:175], s[74:75]
	s_add_u32 s74, s66, 0x30100
	s_addc_u32 s75, s67, 0
	s_waitcnt lgkmcnt(3)
	global_store_dwordx4 v193, v[176:179], s[74:75]
	s_add_u32 s74, s66, 0x34100
	s_addc_u32 s75, s67, 0
	s_waitcnt lgkmcnt(2)
	global_store_dwordx4 v193, v[180:183], s[74:75]
	s_add_u32 s74, s66, 0x38100
	s_addc_u32 s75, s67, 0
	s_waitcnt lgkmcnt(1)
	global_store_dwordx4 v193, v[184:187], s[74:75]
	s_add_u32 s74, s66, 0x3c100
	s_addc_u32 s75, s67, 0
	s_waitcnt lgkmcnt(0)
	global_store_dwordx4 v193, v[200:203], s[74:75]
	global_load_dwordx4 v[160:163], v198, s[70:71] offset:256
	global_load_dwordx4 v[164:167], v198, s[70:71] offset:288
	global_load_dwordx4 v[168:171], v198, s[70:71] offset:320
	global_load_dwordx4 v[172:175], v198, s[70:71] offset:352
	global_load_dwordx4 v[176:179], v198, s[70:71] offset:384
	global_load_dwordx4 v[180:183], v198, s[70:71] offset:416
	global_load_dwordx4 v[184:187], v198, s[70:71] offset:448
	global_load_dwordx4 v[200:203], v198, s[70:71] offset:480
	s_waitcnt vmcnt(7)
	v_mul_f32_e32 v16, v160, v16
	v_mul_f32_e32 v17, v161, v17
	v_mul_f32_e32 v18, v162, v18
	v_mul_f32_e32 v19, v163, v19
	v_cvt_pk_bf16_f32 v16, v16, v17
	v_cvt_pk_bf16_f32 v17, v18, v19
	ds_write_b64 v190, v[16:17]
	s_waitcnt vmcnt(6)
	v_mul_f32_e32 v20, v164, v20
	v_mul_f32_e32 v21, v165, v21
	v_mul_f32_e32 v22, v166, v22
	v_mul_f32_e32 v23, v167, v23
	v_cvt_pk_bf16_f32 v20, v20, v21
	v_cvt_pk_bf16_f32 v21, v22, v23
	ds_write_b64 v190, v[20:21] offset:16
	s_waitcnt vmcnt(5)
	v_mul_f32_e32 v24, v168, v24
	v_mul_f32_e32 v25, v169, v25
	v_mul_f32_e32 v26, v170, v26
	v_mul_f32_e32 v27, v171, v27
	v_cvt_pk_bf16_f32 v24, v24, v25
	v_cvt_pk_bf16_f32 v25, v26, v27
	ds_write_b64 v190, v[24:25] offset:32
	s_waitcnt vmcnt(4)
	v_mul_f32_e32 v28, v172, v28
	v_mul_f32_e32 v29, v173, v29
	v_mul_f32_e32 v30, v174, v30
	v_mul_f32_e32 v31, v175, v31
	v_cvt_pk_bf16_f32 v28, v28, v29
	v_cvt_pk_bf16_f32 v29, v30, v31
	ds_write_b64 v190, v[28:29] offset:48
	s_waitcnt vmcnt(3)
	v_mul_f32_e32 v0, v176, v0
	v_mul_f32_e32 v1, v177, v1
	v_mul_f32_e32 v2, v178, v2
	v_mul_f32_e32 v3, v179, v3
	v_cvt_pk_bf16_f32 v0, v0, v1
	v_cvt_pk_bf16_f32 v1, v2, v3
	ds_write_b64 v190, v[0:1] offset:64
	s_waitcnt vmcnt(2)
	v_mul_f32_e32 v4, v180, v4
	v_mul_f32_e32 v5, v181, v5
	v_mul_f32_e32 v6, v182, v6
	v_mul_f32_e32 v7, v183, v7
	v_cvt_pk_bf16_f32 v4, v4, v5
	v_cvt_pk_bf16_f32 v5, v6, v7
	ds_write_b64 v190, v[4:5] offset:80
	s_waitcnt vmcnt(1)
	v_mul_f32_e32 v8, v184, v8
	v_mul_f32_e32 v9, v185, v9
	v_mul_f32_e32 v10, v186, v10
	v_mul_f32_e32 v11, v187, v11
	v_cvt_pk_bf16_f32 v8, v8, v9
	v_cvt_pk_bf16_f32 v9, v10, v11
	ds_write_b64 v190, v[8:9] offset:96
	s_waitcnt vmcnt(0)
	v_mul_f32_e32 v12, v200, v12
	v_mul_f32_e32 v13, v201, v13
	v_mul_f32_e32 v14, v202, v14
	v_mul_f32_e32 v15, v203, v15
	v_cvt_pk_bf16_f32 v12, v12, v13
	v_cvt_pk_bf16_f32 v13, v14, v15
	ds_write_b64 v190, v[12:13] offset:112
	ds_read_b128 v[160:163], v192
	ds_read_b128 v[164:167], v192 offset:2176
	ds_read_b128 v[168:171], v192 offset:4352
	ds_read_b128 v[172:175], v192 offset:6528
	s_add_u32 s74, s68, 0x10080
	s_addc_u32 s75, s69, 0
	s_waitcnt lgkmcnt(3)
	global_store_dwordx4 v194, v[160:163], s[74:75]
	s_add_u32 s74, s68, 0x14080
	s_addc_u32 s75, s69, 0
	s_waitcnt lgkmcnt(2)
	global_store_dwordx4 v194, v[164:167], s[74:75]
	s_add_u32 s74, s68, 0x18080
	s_addc_u32 s75, s69, 0
	s_waitcnt lgkmcnt(1)
	global_store_dwordx4 v194, v[168:171], s[74:75]
	s_add_u32 s74, s68, 0x1c080
	s_addc_u32 s75, s69, 0
	s_waitcnt lgkmcnt(0)
	global_store_dwordx4 v194, v[172:175], s[74:75]
	s_load_dwordx2 s[64:65], s[92:93], 0x140
	ds_bpermute_b32 v208, v206, v199
	ds_bpermute_b32 v209, v206, v204
	s_waitcnt lgkmcnt(0)
	v_add_f32_e32 v208, v208, v199
	v_add_f32_e32 v209, v209, v204
	s_mov_b32 exec_hi, 0
	s_nop 1
	global_atomic_add_f32 v205, v208, s[64:65]
	global_atomic_add_f32 v205, v209, s[64:65] offset:128
	s_mov_b64 exec, -1
	v_readlane_b32 s64, v207, 0
	v_readlane_b32 s65, v207, 1
	v_readlane_b32 s66, v207, 2
	v_readlane_b32 s67, v207, 3
	v_readlane_b32 s68, v207, 4
	v_readlane_b32 s69, v207, 5
	v_readlane_b32 s70, v207, 6
	v_readlane_b32 s71, v207, 7
	v_readlane_b32 s72, v207, 8
	v_readlane_b32 s73, v207, 9
	v_readlane_b32 s74, v207, 10
	v_readlane_b32 s75, v207, 11
	v_readlane_b32 s76, v207, 12
	v_readlane_b32 s77, v207, 13
	v_readlane_b32 s78, v207, 14
	v_readlane_b32 s79, v207, 15
	s_nop 7
	s_branch .LBB0_840

; #define MFMA32(a, b, c) __builtin_amdgcn_mfma_f32_32x32x16_bf16((a), (b), (c), 0, 0, 0)
; #define GA_LOAD(pr_) do { _Pragma("unroll") for (int i = 0; i < 4; ++i) ra[i] = *(const u32x4*)(Ab + (i * 32) * lda + (pr_) * 64); } while (0)
; #define GB_LOAD(kt_) do { const bfr* bk_ = Bb + (kt_) * NB * 32; \
;     _Pragma("unroll") for (int i = 0; i < 4; ++i) rb[i] = *(const u32x4*)(bk_ + (i * 64) * 32); } while (0)
; #define G_STORE(kt_) do { bfr* as_ = S0 + ((kt_) & 1) * GSTAGE; bfr* bs_ = as_ + 128 * 40; \
;     if (apar == ((kt_) & 1)) { _Pragma("unroll") for (int i = 0; i < 4; ++i) *(u32x4*)(as_ + asoff + i * 32 * 40) = ra[i]; } \
;     _Pragma("unroll") for (int i = 0; i < 4; ++i) *(u32x4*)(bs_ + bsoff + i * 64 * 40) = rb[i]; } while (0)
; template <int lda>
; DI void gemm_mainloop(const bfr* __restrict__ A, const bfr* __restrict__ Bt, int NB, int K, int m0, int n0, char* smem, f32x16 (&acc)[2][4]) {
;     ...
; #pragma unroll
;   for (int i = 0; i < 2; ++i)
; #pragma unroll
;     for (int j = 0; j < 4; ++j)
; #pragma unroll
;       for (int q = 0; q < 16; ++q) acc[i][j][q] = 0.f;
;   u32x4 ra[4], rb[4];
;   const int nk = K >> 5;
;   const int arow = tid >> 3, ac8 = tid & 7, apar = ac8 >> 2;
;   const bfr* Ab = A + (m0 + arow) * lda + ac8 * 8;
;   const int asoff = arow * 40 + (ac8 & 3) * 8;
;   const int brow = tid >> 2, bc4 = tid & 3;
;   const bfr* Bb = Bt + (n0 + brow) * 32 + bc4 * 8;
;   const int bsoff = brow * 40 + bc4 * 8;
;     ...
;   GA_LOAD(0);
;   GB_LOAD(0);
;   G_STORE(0);
;   GB_LOAD(1);
;   __syncthreads();
;   for (int kt = 0; kt < nk; ++kt) {
;     if (kt + 1 < nk) G_STORE(kt + 1);
;     if (kt + 2 < nk) {
;       GB_LOAD(kt + 2);
;       if ((kt & 1) == 0) GA_LOAD((kt >> 1) + 1);
;     }
;     const bfr* As = S0 + (kt & 1) * GSTAGE;
;     const bfr* Bs = As + 128 * 40;
; #pragma unroll
;     for (int ks = 0; ks < 2; ++ks) {
;       bf16x8 af[2], bfg[4];
; #pragma unroll
;       for (int i = 0; i < 2; ++i) af[i] = *(const bf16x8*)(As + (wr * 64 + i * 32 + r) * 40 + ks * 16 + hl * 8);
; #pragma unroll
;       for (int j = 0; j < 4; ++j) bfg[j] = *(const bf16x8*)(Bs + (wc * 128 + j * 32 + r) * 40 + ks * 16 + hl * 8);
; #pragma unroll
;       for (int i = 0; i < 2; ++i)
; #pragma unroll
;         for (int j = 0; j < 4; ++j) acc[i][j] = MFMA32(af[i], bfg[j], acc[i][j]);
;     }
.Lp8_nostag:
	v_mov_b32_e32 v112, 0
	v_mov_b32_e32 v113, 0
	v_mov_b32_e32 v114, 0
	v_mov_b32_e32 v115, 0
	v_mov_b32_e32 v116, 0
	v_mov_b32_e32 v117, 0
	v_mov_b32_e32 v118, 0
	v_mov_b32_e32 v119, 0
	v_mov_b32_e32 v120, 0
	v_mov_b32_e32 v121, 0
	v_mov_b32_e32 v122, 0
	v_mov_b32_e32 v123, 0
	v_mov_b32_e32 v124, 0
	v_mov_b32_e32 v125, 0
	v_mov_b32_e32 v126, 0
	v_mov_b32_e32 v127, 0
	v_mov_b32_e32 v96, 0
	v_mov_b32_e32 v97, 0
	v_mov_b32_e32 v98, 0
	v_mov_b32_e32 v99, 0
	v_mov_b32_e32 v100, 0
	v_mov_b32_e32 v101, 0
	v_mov_b32_e32 v102, 0
	v_mov_b32_e32 v103, 0
	v_mov_b32_e32 v104, 0
	v_mov_b32_e32 v105, 0
	v_mov_b32_e32 v106, 0
	v_mov_b32_e32 v107, 0
	v_mov_b32_e32 v108, 0
	v_mov_b32_e32 v109, 0
	v_mov_b32_e32 v110, 0
	v_mov_b32_e32 v111, 0
	v_mov_b32_e32 v80, 0
	v_mov_b32_e32 v81, 0
	v_mov_b32_e32 v82, 0
	v_mov_b32_e32 v83, 0
	v_mov_b32_e32 v84, 0
	v_mov_b32_e32 v85, 0
	v_mov_b32_e32 v86, 0
	v_mov_b32_e32 v87, 0
	v_mov_b32_e32 v88, 0
	v_mov_b32_e32 v89, 0
	v_mov_b32_e32 v90, 0
	v_mov_b32_e32 v91, 0
	v_mov_b32_e32 v92, 0
	v_mov_b32_e32 v93, 0
	v_mov_b32_e32 v94, 0
	v_mov_b32_e32 v95, 0
	v_mov_b32_e32 v64, 0
	v_mov_b32_e32 v65, 0
	v_mov_b32_e32 v66, 0
	v_mov_b32_e32 v67, 0
	v_mov_b32_e32 v68, 0
	v_mov_b32_e32 v69, 0
	v_mov_b32_e32 v70, 0
	v_mov_b32_e32 v71, 0
	v_mov_b32_e32 v72, 0
	v_mov_b32_e32 v73, 0
	v_mov_b32_e32 v74, 0
	v_mov_b32_e32 v75, 0
	v_mov_b32_e32 v76, 0
	v_mov_b32_e32 v77, 0
	v_mov_b32_e32 v78, 0
	v_mov_b32_e32 v79, 0
	v_mov_b32_e32 v48, 0
	v_mov_b32_e32 v49, 0
	v_mov_b32_e32 v50, 0
	v_mov_b32_e32 v51, 0
	v_mov_b32_e32 v52, 0
	v_mov_b32_e32 v53, 0
	v_mov_b32_e32 v54, 0
	v_mov_b32_e32 v55, 0
	v_mov_b32_e32 v56, 0
	v_mov_b32_e32 v57, 0
	v_mov_b32_e32 v58, 0
	v_mov_b32_e32 v59, 0
	v_mov_b32_e32 v60, 0
	v_mov_b32_e32 v61, 0
	v_mov_b32_e32 v62, 0
	v_mov_b32_e32 v63, 0
	v_mov_b32_e32 v32, 0
	v_mov_b32_e32 v33, 0
	v_mov_b32_e32 v34, 0
	v_mov_b32_e32 v35, 0
	v_mov_b32_e32 v36, 0
	v_mov_b32_e32 v37, 0
	v_mov_b32_e32 v38, 0
	v_mov_b32_e32 v39, 0
	v_mov_b32_e32 v40, 0
	v_mov_b32_e32 v41, 0
	v_mov_b32_e32 v42, 0
	v_mov_b32_e32 v43, 0
	v_mov_b32_e32 v44, 0
	v_mov_b32_e32 v45, 0
	v_mov_b32_e32 v46, 0
	v_mov_b32_e32 v47, 0
	v_mov_b32_e32 v16, 0
	v_mov_b32_e32 v17, 0
	v_mov_b32_e32 v18, 0
	v_mov_b32_e32 v19, 0
	v_mov_b32_e32 v20, 0
	v_mov_b32_e32 v21, 0
	v_mov_b32_e32 v22, 0
	v_mov_b32_e32 v23, 0
	v_mov_b32_e32 v24, 0
	v_mov_b32_e32 v25, 0
	v_mov_b32_e32 v26, 0
	v_mov_b32_e32 v27, 0
	v_mov_b32_e32 v28, 0
	v_mov_b32_e32 v29, 0
	v_mov_b32_e32 v30, 0
	v_mov_b32_e32 v31, 0
	v_mov_b32_e32 v0, 0
	v_mov_b32_e32 v1, 0
	v_mov_b32_e32 v2, 0
	v_mov_b32_e32 v3, 0
	v_mov_b32_e32 v4, 0
	v_mov_b32_e32 v5, 0
	v_mov_b32_e32 v6, 0
	v_mov_b32_e32 v7, 0
	v_mov_b32_e32 v8, 0
	v_mov_b32_e32 v9, 0
	v_mov_b32_e32 v10, 0
	v_mov_b32_e32 v11, 0
	v_mov_b32_e32 v12, 0
	v_mov_b32_e32 v13, 0
	v_mov_b32_e32 v14, 0
	v_mov_b32_e32 v15, 0
	s_waitcnt vmcnt(6)
	s_barrier
	s_mul_i32 s74, s71, 0x6000
	s_add_u32 s75, s74, 0x2000
	s_cmp_eq_u32 s71, 2
	s_cselect_b32 s75, 0x10000, s75
	v_add_u32_e32 v183, s74, v179
	v_add_u32_e32 v185, s75, v181
	v_add_u32_e32 v184, s74, v180
	v_add_u32_e32 v186, s75, v182
	s_add_u32 s71, s71, 1
	s_cmp_eq_u32 s71, 3
	s_cselect_b32 s71, 0, s71
	ds_read_b128 v[128:131], v183
	ds_read_b128 v[144:147], v185
	ds_read_b128 v[148:151], v185 offset:2048
	ds_read_b128 v[152:155], v185 offset:4096
	ds_read_b128 v[156:159], v185 offset:6144
	ds_read_b128 v[132:135], v183 offset:2048
	ds_read_b128 v[136:139], v184
	ds_read_b128 v[160:163], v186
	ds_read_b128 v[164:167], v186 offset:2048
	ds_read_b128 v[168:171], v186 offset:4096
	ds_read_b128 v[172:175], v186 offset:6144
	ds_read_b128 v[140:143], v184 offset:2048
	s_waitcnt lgkmcnt(10)
	v_mfma_f32_32x32x16_bf16 v[112:127], v[144:147], v[128:131], v[112:127]
	s_mul_i32 s74, s70, 0x6000
	s_add_u32 s75, s74, s68
	s_mov_b32 m0, s75
	s_add_u32 s76, s74, 0x2000
	s_cmp_eq_u32 s70, 2
	s_cselect_b32 s76, 0x10000, s76
	global_load_lds_dwordx4 v176, s[64:65]
	s_waitcnt lgkmcnt(9)
	v_mfma_f32_32x32x16_bf16 v[96:111], v[148:151], v[128:131], v[96:111]
	s_add_u32 m0, s75, 0x400
	s_add_u32 s76, s76, s69
	global_load_lds_dwordx4 v177, s[64:65]
	s_waitcnt lgkmcnt(8)
	v_mfma_f32_32x32x16_bf16 v[80:95], v[152:155], v[128:131], v[80:95]
	s_mov_b32 m0, s76
	s_add_u32 s64, s64, 64
	s_addc_u32 s65, s65, 0
	global_load_lds_dwordx4 v178, s[66:67]
	s_waitcnt lgkmcnt(7)
	v_mfma_f32_32x32x16_bf16 v[64:79], v[156:159], v[128:131], v[64:79]
	global_load_lds_dwordx4 v178, s[66:67] offset:1024
	s_waitcnt lgkmcnt(6)
	v_mfma_f32_32x32x16_bf16 v[48:63], v[144:147], v[132:135], v[48:63]
	global_load_lds_dwordx4 v178, s[66:67] offset:2048
	v_mfma_f32_32x32x16_bf16 v[32:47], v[148:151], v[132:135], v[32:47]
	global_load_lds_dwordx4 v178, s[66:67] offset:3072
	s_add_u32 s66, s66, 0x10000
	s_addc_u32 s67, s67, 0
	v_mfma_f32_32x32x16_bf16 v[16:31], v[152:155], v[132:135], v[16:31]
	s_add_u32 s70, s70, 1
	s_cmp_eq_u32 s70, 3
	s_cselect_b32 s70, 0, s70
	v_mfma_f32_32x32x16_bf16 v[0:15], v[156:159], v[132:135], v[0:15]
; #define MFMA32(a, b, c) __builtin_amdgcn_mfma_f32_32x32x16_bf16((a), (b), (c), 0, 0, 0)
; #define GA_LOAD(pr_) do { _Pragma("unroll") for (int i = 0; i < 4; ++i) ra[i] = *(const u32x4*)(Ab + (i * 32) * lda + (pr_) * 64); } while (0)
; #define GB_LOAD(kt_) do { const bfr* bk_ = Bb + (kt_) * NB * 32; \
;     _Pragma("unroll") for (int i = 0; i < 4; ++i) rb[i] = *(const u32x4*)(bk_ + (i * 64) * 32); } while (0)
; #define G_STORE(kt_) do { bfr* as_ = S0 + ((kt_) & 1) * GSTAGE; bfr* bs_ = as_ + 128 * 40; \
;     if (apar == ((kt_) & 1)) { _Pragma("unroll") for (int i = 0; i < 4; ++i) *(u32x4*)(as_ + asoff + i * 32 * 40) = ra[i]; } \
;     _Pragma("unroll") for (int i = 0; i < 4; ++i) *(u32x4*)(bs_ + bsoff + i * 64 * 40) = rb[i]; } while (0)
; template <int lda>
; DI void gemm_mainloop(const bfr* __restrict__ A, const bfr* __restrict__ Bt, int NB, int K, int m0, int n0, char* smem, f32x16 (&acc)[2][4]) {
;     ...
;   for (int kt = 0; kt < nk; ++kt) {
;     if (kt + 1 < nk) G_STORE(kt + 1);
;     if (kt + 2 < nk) {
;       GB_LOAD(kt + 2);
;       if ((kt & 1) == 0) GA_LOAD((kt >> 1) + 1);
;     }
;     const bfr* As = S0 + (kt & 1) * GSTAGE;
;     const bfr* Bs = As + 128 * 40;
; #pragma unroll
;     for (int ks = 0; ks < 2; ++ks) {
;       bf16x8 af[2], bfg[4];
; #pragma unroll
;       for (int i = 0; i < 2; ++i) af[i] = *(const bf16x8*)(As + (wr * 64 + i * 32 + r) * 40 + ks * 16 + hl * 8);
; #pragma unroll
;       for (int j = 0; j < 4; ++j) bfg[j] = *(const bf16x8*)(Bs + (wc * 128 + j * 32 + r) * 40 + ks * 16 + hl * 8);
; #pragma unroll
;       for (int i = 0; i < 2; ++i)
; #pragma unroll
;         for (int j = 0; j < 4; ++j) acc[i][j] = MFMA32(af[i], bfg[j], acc[i][j]);
;     }
;     __syncthreads();
;   }
.Lp8_loop:
	s_waitcnt vmcnt(6) lgkmcnt(0)
	s_barrier
	s_mul_i32 s74, s71, 0x6000
	s_add_u32 s75, s74, 0x2000
	s_cmp_eq_u32 s71, 2
	s_cselect_b32 s75, 0x10000, s75
	v_add_u32_e32 v183, s74, v179
	v_add_u32_e32 v185, s75, v181
	v_add_u32_e32 v184, s74, v180
	v_add_u32_e32 v186, s75, v182
	s_add_u32 s71, s71, 1
	s_cmp_eq_u32 s71, 3
	s_cselect_b32 s71, 0, s71
	ds_read_b128 v[128:131], v183
	ds_read_b128 v[144:147], v185
	ds_read_b128 v[148:151], v185 offset:2048
	ds_read_b128 v[152:155], v185 offset:4096
	ds_read_b128 v[156:159], v185 offset:6144
	ds_read_b128 v[132:135], v183 offset:2048
	v_mfma_f32_32x32x16_bf16 v[112:127], v[160:163], v[136:139], v[112:127]
	s_mul_i32 s74, s70, 0x6000
	s_add_u32 s75, s74, s68
	s_mov_b32 m0, s75
	s_add_u32 s76, s74, 0x2000
	s_cmp_eq_u32 s70, 2
	s_cselect_b32 s76, 0x10000, s76
	global_load_lds_dwordx4 v176, s[64:65]
	v_mfma_f32_32x32x16_bf16 v[96:111], v[164:167], v[136:139], v[96:111]
	s_add_u32 m0, s75, 0x400
	s_add_u32 s76, s76, s69
	global_load_lds_dwordx4 v177, s[64:65]
	v_mfma_f32_32x32x16_bf16 v[80:95], v[168:171], v[136:139], v[80:95]
	s_mov_b32 m0, s76
	s_add_u32 s64, s64, 64
	s_addc_u32 s65, s65, 0
	global_load_lds_dwordx4 v178, s[66:67]
	v_mfma_f32_32x32x16_bf16 v[64:79], v[172:175], v[136:139], v[64:79]
	global_load_lds_dwordx4 v178, s[66:67] offset:1024
	v_mfma_f32_32x32x16_bf16 v[48:63], v[160:163], v[140:143], v[48:63]
	global_load_lds_dwordx4 v178, s[66:67] offset:2048
	v_mfma_f32_32x32x16_bf16 v[32:47], v[164:167], v[140:143], v[32:47]
	global_load_lds_dwordx4 v178, s[66:67] offset:3072
	s_add_u32 s66, s66, 0x10000
	s_addc_u32 s67, s67, 0
	v_mfma_f32_32x32x16_bf16 v[16:31], v[168:171], v[140:143], v[16:31]
	s_add_u32 s70, s70, 1
	s_cmp_eq_u32 s70, 3
	s_cselect_b32 s70, 0, s70
	v_mfma_f32_32x32x16_bf16 v[0:15], v[172:175], v[140:143], v[0:15]
	ds_read_b128 v[136:139], v184
	ds_read_b128 v[160:163], v186
	ds_read_b128 v[164:167], v186 offset:2048
	ds_read_b128 v[168:171], v186 offset:4096
	ds_read_b128 v[172:175], v186 offset:6144
	ds_read_b128 v[140:143], v184 offset:2048
	s_waitcnt lgkmcnt(10)
	v_mfma_f32_32x32x16_bf16 v[112:127], v[144:147], v[128:131], v[112:127]
	s_waitcnt lgkmcnt(9)
	v_mfma_f32_32x32x16_bf16 v[96:111], v[148:151], v[128:131], v[96:111]
	s_waitcnt lgkmcnt(8)
	v_mfma_f32_32x32x16_bf16 v[80:95], v[152:155], v[128:131], v[80:95]
	s_waitcnt lgkmcnt(7)
	v_mfma_f32_32x32x16_bf16 v[64:79], v[156:159], v[128:131], v[64:79]
	s_waitcnt lgkmcnt(6)
	v_mfma_f32_32x32x16_bf16 v[48:63], v[144:147], v[132:135], v[48:63]
	v_mfma_f32_32x32x16_bf16 v[32:47], v[148:151], v[132:135], v[32:47]
	v_mfma_f32_32x32x16_bf16 v[16:31], v[152:155], v[132:135], v[16:31]
	v_mfma_f32_32x32x16_bf16 v[0:15], v[156:159], v[132:135], v[0:15]
	s_add_u32 s72, s72, 1
	s_cmp_lt_u32 s72, 29
	s_cbranch_scc1 .Lp8_loop
	s_waitcnt vmcnt(6) lgkmcnt(0)
	s_barrier
	s_mul_i32 s74, s71, 0x6000
	s_add_u32 s75, s74, 0x2000
	s_cmp_eq_u32 s71, 2
	s_cselect_b32 s75, 0x10000, s75
	v_add_u32_e32 v183, s74, v179
	v_add_u32_e32 v185, s75, v181
	v_add_u32_e32 v184, s74, v180
	v_add_u32_e32 v186, s75, v182
	s_add_u32 s71, s71, 1
	s_cmp_eq_u32 s71, 3
	s_cselect_b32 s71, 0, s71
	ds_read_b128 v[128:131], v183
	ds_read_b128 v[144:147], v185
	ds_read_b128 v[148:151], v185 offset:2048
	ds_read_b128 v[152:155], v185 offset:4096
	ds_read_b128 v[156:159], v185 offset:6144
	ds_read_b128 v[132:135], v183 offset:2048
	v_mfma_f32_32x32x16_bf16 v[112:127], v[160:163], v[136:139], v[112:127]
	v_mfma_f32_32x32x16_bf16 v[96:111], v[164:167], v[136:139], v[96:111]
	v_mfma_f32_32x32x16_bf16 v[80:95], v[168:171], v[136:139], v[80:95]
	v_mfma_f32_32x32x16_bf16 v[64:79], v[172:175], v[136:139], v[64:79]
	v_mfma_f32_32x32x16_bf16 v[48:63], v[160:163], v[140:143], v[48:63]
	v_mfma_f32_32x32x16_bf16 v[32:47], v[164:167], v[140:143], v[32:47]
	v_mfma_f32_32x32x16_bf16 v[16:31], v[168:171], v[140:143], v[16:31]
	v_mfma_f32_32x32x16_bf16 v[0:15], v[172:175], v[140:143], v[0:15]
	ds_read_b128 v[136:139], v184
	ds_read_b128 v[160:163], v186
	ds_read_b128 v[164:167], v186 offset:2048
	ds_read_b128 v[168:171], v186 offset:4096
	ds_read_b128 v[172:175], v186 offset:6144
	ds_read_b128 v[140:143], v184 offset:2048
	s_waitcnt lgkmcnt(10)
	v_mfma_f32_32x32x16_bf16 v[112:127], v[144:147], v[128:131], v[112:127]
	s_waitcnt lgkmcnt(9)
	v_mfma_f32_32x32x16_bf16 v[96:111], v[148:151], v[128:131], v[96:111]
	s_waitcnt lgkmcnt(8)
	v_mfma_f32_32x32x16_bf16 v[80:95], v[152:155], v[128:131], v[80:95]
	s_waitcnt lgkmcnt(7)
	v_mfma_f32_32x32x16_bf16 v[64:79], v[156:159], v[128:131], v[64:79]
	s_waitcnt lgkmcnt(6)
	v_mfma_f32_32x32x16_bf16 v[48:63], v[144:147], v[132:135], v[48:63]
	v_mfma_f32_32x32x16_bf16 v[32:47], v[148:151], v[132:135], v[32:47]
	v_mfma_f32_32x32x16_bf16 v[16:31], v[152:155], v[132:135], v[16:31]
	v_mfma_f32_32x32x16_bf16 v[0:15], v[156:159], v[132:135], v[0:15]
	s_waitcnt vmcnt(0) lgkmcnt(0)
	s_barrier
; #define MFMA32(a, b, c) __builtin_amdgcn_mfma_f32_32x32x16_bf16((a), (b), (c), 0, 0, 0)
; DI bfr f2bf(float a) { return (bfr)(pack2(a, 0.f) & 0xffffu); }
; template <int lda>
; DI void gemm_mainloop(const bfr* __restrict__ A, const bfr* __restrict__ Bt, int NB, int K, int m0, int n0, char* smem, f32x16 (&acc)[2][4]) {
;     ...
;     const bfr* As = S0 + (kt & 1) * GSTAGE;
;     const bfr* Bs = As + 128 * 40;
; #pragma unroll
;     for (int ks = 0; ks < 2; ++ks) {
;       bf16x8 af[2], bfg[4];
; #pragma unroll
;       for (int i = 0; i < 2; ++i) af[i] = *(const bf16x8*)(As + (wr * 64 + i * 32 + r) * 40 + ks * 16 + hl * 8);
; #pragma unroll
;       for (int j = 0; j < 4; ++j) bfg[j] = *(const bf16x8*)(Bs + (wc * 128 + j * 32 + r) * 40 + ks * 16 + hl * 8);
; #pragma unroll
;       for (int i = 0; i < 2; ++i)
; #pragma unroll
;         for (int j = 0; j < 4; ++j) acc[i][j] = MFMA32(af[i], bfg[j], acc[i][j]);
;     }
;     __syncthreads();
; DI void phase_gemm_bf16out(const Params& p, const bfr* A, const bfr* Wt, bfr* C, int N, const float* ss, char* smem) {
;     ...
;     gemm_tile<1024>(A, Wt, N, 1024, mt * 128, nt * 256, smem,
;               [=](int row, int col, float v) {
;                 float inv = rsqrtf(ss[row] * (1.0f / 1024.0f) + EPSF);
;                 C[(size_t)row * N + col] = f2bf(v * inv);
;               });
	s_mul_i32 s74, s71, 0x6000
	s_add_u32 s75, s74, 0x2000
	s_cmp_eq_u32 s71, 2
	s_cselect_b32 s75, 0x10000, s75
	v_add_u32_e32 v183, s74, v179
	v_add_u32_e32 v185, s75, v181
	v_add_u32_e32 v184, s74, v180
	v_add_u32_e32 v186, s75, v182
	s_add_u32 s71, s71, 1
	s_cmp_eq_u32 s71, 3
	s_cselect_b32 s71, 0, s71
	ds_read_b128 v[128:131], v183
	ds_read_b128 v[144:147], v185
	ds_read_b128 v[148:151], v185 offset:2048
	ds_read_b128 v[152:155], v185 offset:4096
	ds_read_b128 v[156:159], v185 offset:6144
	ds_read_b128 v[132:135], v183 offset:2048
	v_mfma_f32_32x32x16_bf16 v[112:127], v[160:163], v[136:139], v[112:127]
	v_mfma_f32_32x32x16_bf16 v[96:111], v[164:167], v[136:139], v[96:111]
	v_mfma_f32_32x32x16_bf16 v[80:95], v[168:171], v[136:139], v[80:95]
	v_mfma_f32_32x32x16_bf16 v[64:79], v[172:175], v[136:139], v[64:79]
	v_mfma_f32_32x32x16_bf16 v[48:63], v[160:163], v[140:143], v[48:63]
	v_mfma_f32_32x32x16_bf16 v[32:47], v[164:167], v[140:143], v[32:47]
	v_mfma_f32_32x32x16_bf16 v[16:31], v[168:171], v[140:143], v[16:31]
	v_mfma_f32_32x32x16_bf16 v[0:15], v[172:175], v[140:143], v[0:15]
	ds_read_b128 v[136:139], v184
	ds_read_b128 v[160:163], v186
	ds_read_b128 v[164:167], v186 offset:2048
	ds_read_b128 v[168:171], v186 offset:4096
	ds_read_b128 v[172:175], v186 offset:6144
	ds_read_b128 v[140:143], v184 offset:2048
	s_waitcnt lgkmcnt(10)
	v_mfma_f32_32x32x16_bf16 v[112:127], v[144:147], v[128:131], v[112:127]
	s_waitcnt lgkmcnt(9)
	v_mfma_f32_32x32x16_bf16 v[96:111], v[148:151], v[128:131], v[96:111]
	s_waitcnt lgkmcnt(8)
	v_mfma_f32_32x32x16_bf16 v[80:95], v[152:155], v[128:131], v[80:95]
	s_waitcnt lgkmcnt(7)
	v_mfma_f32_32x32x16_bf16 v[64:79], v[156:159], v[128:131], v[64:79]
	s_waitcnt lgkmcnt(6)
	v_mfma_f32_32x32x16_bf16 v[48:63], v[144:147], v[132:135], v[48:63]
	v_mfma_f32_32x32x16_bf16 v[32:47], v[148:151], v[132:135], v[32:47]
	v_mfma_f32_32x32x16_bf16 v[16:31], v[152:155], v[132:135], v[16:31]
	v_mfma_f32_32x32x16_bf16 v[0:15], v[156:159], v[132:135], v[0:15]
	s_waitcnt lgkmcnt(0)
	v_mfma_f32_32x32x16_bf16 v[112:127], v[160:163], v[136:139], v[112:127]
	v_mfma_f32_32x32x16_bf16 v[96:111], v[164:167], v[136:139], v[96:111]
	v_mfma_f32_32x32x16_bf16 v[80:95], v[168:171], v[136:139], v[80:95]
	v_mfma_f32_32x32x16_bf16 v[64:79], v[172:175], v[136:139], v[64:79]
	v_mfma_f32_32x32x16_bf16 v[48:63], v[160:163], v[140:143], v[48:63]
	v_mfma_f32_32x32x16_bf16 v[32:47], v[164:167], v[140:143], v[32:47]
	v_mfma_f32_32x32x16_bf16 v[16:31], v[168:171], v[140:143], v[16:31]
	v_mfma_f32_32x32x16_bf16 v[0:15], v[172:175], v[140:143], v[0:15]
	s_nop 7
	s_nop 3
	s_barrier
	s_load_dwordx2 s[64:65], s[92:93], 0x160
	s_load_dwordx2 s[66:67], s[92:93], 0x140
	v_and_b32_e32 v176, 31, v196
	v_bfe_u32 v177, v196, 5, 1
	s_lshr_b32 s74, s73, 1
	s_lshl_b32 s74, s74, 6
	s_add_u32 s74, s74, s77
	v_add_u32_e32 v178, s74, v176
	s_mul_i32 s76, s73, 8704
	v_mul_u32_u24_e32 v180, 272, v176
	v_lshl_add_u32 v180, v177, 3, v180
	v_add_u32_e32 v180, s76, v180
	v_bfe_u32 v185, v196, 4, 2
	v_and_b32_e32 v186, 15, v196
	v_mul_u32_u24_e32 v181, 272, v185
	v_lshl_add_u32 v181, v186, 4, v181
	v_add_u32_e32 v181, s76, v181
	s_and_b32 s75, s73, 1
	s_lshl_b32 s75, s75, 7
	s_add_u32 s75, s75, s78
	v_add_u32_e32 v179, s74, v185
	v_mul_u32_u24_e32 v179, 0x400, v179
	v_lshl_add_u32 v179, v186, 3, v179
	v_add_lshl_u32 v182, v179, s75, 1
	s_waitcnt lgkmcnt(0)
	v_lshlrev_b32_e32 v179, 2, v178
	global_load_dword v183, v179, s[66:67]
	global_load_dword v184, v179, s[66:67] offset:128
	s_waitcnt vmcnt(0)
	v_mul_f32_e32 v183, 0x3a800000, v183
	v_mul_f32_e32 v184, 0x3a800000, v184
	v_add_f32_e32 v183, 0x358637bd, v183
	v_add_f32_e32 v184, 0x358637bd, v184
	v_rsq_f32_e32 v183, v183
	v_rsq_f32_e32 v184, v184
	s_nop 1
	v_mul_f32_e32 v112, v183, v112
	v_mul_f32_e32 v113, v183, v113
	v_mul_f32_e32 v114, v183, v114
	v_mul_f32_e32 v115, v183, v115
	v_cvt_pk_bf16_f32 v112, v112, v113
	v_cvt_pk_bf16_f32 v113, v114, v115
	ds_write_b64 v180, v[112:113]
	v_mul_f32_e32 v116, v183, v116
	v_mul_f32_e32 v117, v183, v117
	v_mul_f32_e32 v118, v183, v118
	v_mul_f32_e32 v119, v183, v119
	v_cvt_pk_bf16_f32 v116, v116, v117
	v_cvt_pk_bf16_f32 v117, v118, v119
	ds_write_b64 v180, v[116:117] offset:16
	v_mul_f32_e32 v120, v183, v120
	v_mul_f32_e32 v121, v183, v121
	v_mul_f32_e32 v122, v183, v122
	v_mul_f32_e32 v123, v183, v123
	v_cvt_pk_bf16_f32 v120, v120, v121
	v_cvt_pk_bf16_f32 v121, v122, v123
	ds_write_b64 v180, v[120:121] offset:32
	v_mul_f32_e32 v124, v183, v124
	v_mul_f32_e32 v125, v183, v125
	v_mul_f32_e32 v126, v183, v126
	v_mul_f32_e32 v127, v183, v127
	v_cvt_pk_bf16_f32 v124, v124, v125
	v_cvt_pk_bf16_f32 v125, v126, v127
	ds_write_b64 v180, v[124:125] offset:48
	v_mul_f32_e32 v96, v183, v96
	v_mul_f32_e32 v97, v183, v97
	v_mul_f32_e32 v98, v183, v98
	v_mul_f32_e32 v99, v183, v99
	v_cvt_pk_bf16_f32 v96, v96, v97
	v_cvt_pk_bf16_f32 v97, v98, v99
	ds_write_b64 v180, v[96:97] offset:64
	v_mul_f32_e32 v100, v183, v100
	v_mul_f32_e32 v101, v183, v101
	v_mul_f32_e32 v102, v183, v102
	v_mul_f32_e32 v103, v183, v103
	v_cvt_pk_bf16_f32 v100, v100, v101
	v_cvt_pk_bf16_f32 v101, v102, v103
	ds_write_b64 v180, v[100:101] offset:80
	v_mul_f32_e32 v104, v183, v104
	v_mul_f32_e32 v105, v183, v105
	v_mul_f32_e32 v106, v183, v106
	v_mul_f32_e32 v107, v183, v107
	v_cvt_pk_bf16_f32 v104, v104, v105
	v_cvt_pk_bf16_f32 v105, v106, v107
	ds_write_b64 v180, v[104:105] offset:96
	v_mul_f32_e32 v108, v183, v108
	v_mul_f32_e32 v109, v183, v109
	v_mul_f32_e32 v110, v183, v110
	v_mul_f32_e32 v111, v183, v111
	v_cvt_pk_bf16_f32 v108, v108, v109
	v_cvt_pk_bf16_f32 v109, v110, v111
	ds_write_b64 v180, v[108:109] offset:112
; DI bfr f2bf(float a) { return (bfr)(pack2(a, 0.f) & 0xffffu); }
; DI void phase_gemm_bf16out(const Params& p, const bfr* A, const bfr* Wt, bfr* C, int N, const float* ss, char* smem) {
;     ...
;   for (int t0 = blockIdx.x; t0 < 128 * ntn; t0 += gridDim.x) {
;     const int t = ((gridDim.x & 7) == 0) ? xcd_tile(t0, ntn) : t0;
;     int mt = t / ntn, nt = t % ntn;
;     gemm_tile<1024>(A, Wt, N, 1024, mt * 128, nt * 256, smem,
;               [=](int row, int col, float v) {
;                 float inv = rsqrtf(ss[row] * (1.0f / 1024.0f) + EPSF);
;                 C[(size_t)row * N + col] = f2bf(v * inv);
;               });
	v_mul_f32_e32 v80, v183, v80
	v_mul_f32_e32 v81, v183, v81
	v_mul_f32_e32 v82, v183, v82
	v_mul_f32_e32 v83, v183, v83
	v_cvt_pk_bf16_f32 v80, v80, v81
	v_cvt_pk_bf16_f32 v81, v82, v83
	ds_write_b64 v180, v[80:81] offset:128
	v_mul_f32_e32 v84, v183, v84
	v_mul_f32_e32 v85, v183, v85
	v_mul_f32_e32 v86, v183, v86
	v_mul_f32_e32 v87, v183, v87
	v_cvt_pk_bf16_f32 v84, v84, v85
	v_cvt_pk_bf16_f32 v85, v86, v87
	ds_write_b64 v180, v[84:85] offset:144
	v_mul_f32_e32 v88, v183, v88
	v_mul_f32_e32 v89, v183, v89
	v_mul_f32_e32 v90, v183, v90
	v_mul_f32_e32 v91, v183, v91
	v_cvt_pk_bf16_f32 v88, v88, v89
	v_cvt_pk_bf16_f32 v89, v90, v91
	ds_write_b64 v180, v[88:89] offset:160
	v_mul_f32_e32 v92, v183, v92
	v_mul_f32_e32 v93, v183, v93
	v_mul_f32_e32 v94, v183, v94
	v_mul_f32_e32 v95, v183, v95
	v_cvt_pk_bf16_f32 v92, v92, v93
	v_cvt_pk_bf16_f32 v93, v94, v95
	ds_write_b64 v180, v[92:93] offset:176
	v_mul_f32_e32 v64, v183, v64
	v_mul_f32_e32 v65, v183, v65
	v_mul_f32_e32 v66, v183, v66
	v_mul_f32_e32 v67, v183, v67
	v_cvt_pk_bf16_f32 v64, v64, v65
	v_cvt_pk_bf16_f32 v65, v66, v67
	ds_write_b64 v180, v[64:65] offset:192
	v_mul_f32_e32 v68, v183, v68
	v_mul_f32_e32 v69, v183, v69
	v_mul_f32_e32 v70, v183, v70
	v_mul_f32_e32 v71, v183, v71
	v_cvt_pk_bf16_f32 v68, v68, v69
	v_cvt_pk_bf16_f32 v69, v70, v71
	ds_write_b64 v180, v[68:69] offset:208
	v_mul_f32_e32 v72, v183, v72
	v_mul_f32_e32 v73, v183, v73
	v_mul_f32_e32 v74, v183, v74
	v_mul_f32_e32 v75, v183, v75
	v_cvt_pk_bf16_f32 v72, v72, v73
	v_cvt_pk_bf16_f32 v73, v74, v75
	ds_write_b64 v180, v[72:73] offset:224
	v_mul_f32_e32 v76, v183, v76
	v_mul_f32_e32 v77, v183, v77
	v_mul_f32_e32 v78, v183, v78
	v_mul_f32_e32 v79, v183, v79
	v_cvt_pk_bf16_f32 v76, v76, v77
	v_cvt_pk_bf16_f32 v77, v78, v79
	ds_write_b64 v180, v[76:77] offset:240
	s_waitcnt lgkmcnt(0)
	ds_read_b128 v[112:115], v181
	ds_read_b128 v[116:119], v181 offset:1088
	ds_read_b128 v[120:123], v181 offset:2176
	ds_read_b128 v[124:127], v181 offset:3264
	ds_read_b128 v[96:99], v181 offset:4352
	ds_read_b128 v[100:103], v181 offset:5440
	ds_read_b128 v[104:107], v181 offset:6528
	ds_read_b128 v[108:111], v181 offset:7616
	s_add_u32 s66, s64, 0x0
	s_addc_u32 s67, s65, 0
	s_waitcnt lgkmcnt(7)
	global_store_dwordx4 v182, v[112:115], s[66:67]
	s_add_u32 s66, s64, 0x2000
	s_addc_u32 s67, s65, 0
	s_waitcnt lgkmcnt(6)
	global_store_dwordx4 v182, v[116:119], s[66:67]
	s_add_u32 s66, s64, 0x4000
	s_addc_u32 s67, s65, 0
	s_waitcnt lgkmcnt(5)
	global_store_dwordx4 v182, v[120:123], s[66:67]
	s_add_u32 s66, s64, 0x6000
	s_addc_u32 s67, s65, 0
	s_waitcnt lgkmcnt(4)
	global_store_dwordx4 v182, v[124:127], s[66:67]
	s_add_u32 s66, s64, 0x8000
	s_addc_u32 s67, s65, 0
	s_waitcnt lgkmcnt(3)
	global_store_dwordx4 v182, v[96:99], s[66:67]
	s_add_u32 s66, s64, 0xa000
	s_addc_u32 s67, s65, 0
	s_waitcnt lgkmcnt(2)
	global_store_dwordx4 v182, v[100:103], s[66:67]
	s_add_u32 s66, s64, 0xc000
	s_addc_u32 s67, s65, 0
	s_waitcnt lgkmcnt(1)
	global_store_dwordx4 v182, v[104:107], s[66:67]
	s_add_u32 s66, s64, 0xe000
	s_addc_u32 s67, s65, 0
	s_waitcnt lgkmcnt(0)
; DI bfr f2bf(float a) { return (bfr)(pack2(a, 0.f) & 0xffffu); }
; DI void phase_gemm_bf16out(const Params& p, const bfr* A, const bfr* Wt, bfr* C, int N, const float* ss, char* smem) {
;     ...
;   for (int t0 = blockIdx.x; t0 < 128 * ntn; t0 += gridDim.x) {
;     const int t = ((gridDim.x & 7) == 0) ? xcd_tile(t0, ntn) : t0;
;     int mt = t / ntn, nt = t % ntn;
;     gemm_tile<1024>(A, Wt, N, 1024, mt * 128, nt * 256, smem,
;               [=](int row, int col, float v) {
;                 float inv = rsqrtf(ss[row] * (1.0f / 1024.0f) + EPSF);
;                 C[(size_t)row * N + col] = f2bf(v * inv);
;               });
	global_store_dwordx4 v182, v[108:111], s[66:67]
	v_mul_f32_e32 v48, v184, v48
	v_mul_f32_e32 v49, v184, v49
	v_mul_f32_e32 v50, v184, v50
	v_mul_f32_e32 v51, v184, v51
	v_cvt_pk_bf16_f32 v48, v48, v49
	v_cvt_pk_bf16_f32 v49, v50, v51
	ds_write_b64 v180, v[48:49]
	v_mul_f32_e32 v52, v184, v52
	v_mul_f32_e32 v53, v184, v53
	v_mul_f32_e32 v54, v184, v54
	v_mul_f32_e32 v55, v184, v55
	v_cvt_pk_bf16_f32 v52, v52, v53
	v_cvt_pk_bf16_f32 v53, v54, v55
	ds_write_b64 v180, v[52:53] offset:16
	v_mul_f32_e32 v56, v184, v56
	v_mul_f32_e32 v57, v184, v57
	v_mul_f32_e32 v58, v184, v58
	v_mul_f32_e32 v59, v184, v59
	v_cvt_pk_bf16_f32 v56, v56, v57
	v_cvt_pk_bf16_f32 v57, v58, v59
	ds_write_b64 v180, v[56:57] offset:32
	v_mul_f32_e32 v60, v184, v60
	v_mul_f32_e32 v61, v184, v61
	v_mul_f32_e32 v62, v184, v62
	v_mul_f32_e32 v63, v184, v63
	v_cvt_pk_bf16_f32 v60, v60, v61
	v_cvt_pk_bf16_f32 v61, v62, v63
	ds_write_b64 v180, v[60:61] offset:48
	v_mul_f32_e32 v32, v184, v32
	v_mul_f32_e32 v33, v184, v33
	v_mul_f32_e32 v34, v184, v34
	v_mul_f32_e32 v35, v184, v35
	v_cvt_pk_bf16_f32 v32, v32, v33
	v_cvt_pk_bf16_f32 v33, v34, v35
	ds_write_b64 v180, v[32:33] offset:64
	v_mul_f32_e32 v36, v184, v36
	v_mul_f32_e32 v37, v184, v37
	v_mul_f32_e32 v38, v184, v38
	v_mul_f32_e32 v39, v184, v39
	v_cvt_pk_bf16_f32 v36, v36, v37
	v_cvt_pk_bf16_f32 v37, v38, v39
	ds_write_b64 v180, v[36:37] offset:80
	v_mul_f32_e32 v40, v184, v40
	v_mul_f32_e32 v41, v184, v41
	v_mul_f32_e32 v42, v184, v42
	v_mul_f32_e32 v43, v184, v43
	v_cvt_pk_bf16_f32 v40, v40, v41
	v_cvt_pk_bf16_f32 v41, v42, v43
	ds_write_b64 v180, v[40:41] offset:96
	v_mul_f32_e32 v44, v184, v44
	v_mul_f32_e32 v45, v184, v45
	v_mul_f32_e32 v46, v184, v46
	v_mul_f32_e32 v47, v184, v47
	v_cvt_pk_bf16_f32 v44, v44, v45
	v_cvt_pk_bf16_f32 v45, v46, v47
	ds_write_b64 v180, v[44:45] offset:112
	v_mul_f32_e32 v16, v184, v16
	v_mul_f32_e32 v17, v184, v17
	v_mul_f32_e32 v18, v184, v18
	v_mul_f32_e32 v19, v184, v19
	v_cvt_pk_bf16_f32 v16, v16, v17
	v_cvt_pk_bf16_f32 v17, v18, v19
	ds_write_b64 v180, v[16:17] offset:128
	v_mul_f32_e32 v20, v184, v20
	v_mul_f32_e32 v21, v184, v21
	v_mul_f32_e32 v22, v184, v22
	v_mul_f32_e32 v23, v184, v23
	v_cvt_pk_bf16_f32 v20, v20, v21
	v_cvt_pk_bf16_f32 v21, v22, v23
	ds_write_b64 v180, v[20:21] offset:144
	v_mul_f32_e32 v24, v184, v24
	v_mul_f32_e32 v25, v184, v25
	v_mul_f32_e32 v26, v184, v26
	v_mul_f32_e32 v27, v184, v27
	v_cvt_pk_bf16_f32 v24, v24, v25
	v_cvt_pk_bf16_f32 v25, v26, v27
	ds_write_b64 v180, v[24:25] offset:160
	v_mul_f32_e32 v28, v184, v28
	v_mul_f32_e32 v29, v184, v29
	v_mul_f32_e32 v30, v184, v30
	v_mul_f32_e32 v31, v184, v31
	v_cvt_pk_bf16_f32 v28, v28, v29
	v_cvt_pk_bf16_f32 v29, v30, v31
	ds_write_b64 v180, v[28:29] offset:176
	v_mul_f32_e32 v0, v184, v0
	v_mul_f32_e32 v1, v184, v1
	v_mul_f32_e32 v2, v184, v2
	v_mul_f32_e32 v3, v184, v3
	v_cvt_pk_bf16_f32 v0, v0, v1
	v_cvt_pk_bf16_f32 v1, v2, v3
	ds_write_b64 v180, v[0:1] offset:192
	v_mul_f32_e32 v4, v184, v4
	v_mul_f32_e32 v5, v184, v5
	v_mul_f32_e32 v6, v184, v6
	v_mul_f32_e32 v7, v184, v7
	v_cvt_pk_bf16_f32 v4, v4, v5
	v_cvt_pk_bf16_f32 v5, v6, v7
	ds_write_b64 v180, v[4:5] offset:208
	v_mul_f32_e32 v8, v184, v8
	v_mul_f32_e32 v9, v184, v9
	v_mul_f32_e32 v10, v184, v10
	v_mul_f32_e32 v11, v184, v11
	v_cvt_pk_bf16_f32 v8, v8, v9
	v_cvt_pk_bf16_f32 v9, v10, v11
	ds_write_b64 v180, v[8:9] offset:224
	v_mul_f32_e32 v12, v184, v12
	v_mul_f32_e32 v13, v184, v13
	v_mul_f32_e32 v14, v184, v14
	v_mul_f32_e32 v15, v184, v15
	v_cvt_pk_bf16_f32 v12, v12, v13
	v_cvt_pk_bf16_f32 v13, v14, v15
	ds_write_b64 v180, v[12:13] offset:240
	s_waitcnt lgkmcnt(0)
	ds_read_b128 v[48:51], v181
	ds_read_b128 v[52:55], v181 offset:1088
	ds_read_b128 v[56:59], v181 offset:2176
	ds_read_b128 v[60:63], v181 offset:3264
	ds_read_b128 v[32:35], v181 offset:4352
	ds_read_b128 v[36:39], v181 offset:5440
	ds_read_b128 v[40:43], v181 offset:6528
	ds_read_b128 v[44:47], v181 offset:7616
	s_add_u32 s66, s64, 0x10000
	s_addc_u32 s67, s65, 0
	s_waitcnt lgkmcnt(7)
	global_store_dwordx4 v182, v[48:51], s[66:67]
	s_add_u32 s66, s64, 0x12000
	s_addc_u32 s67, s65, 0
	s_waitcnt lgkmcnt(6)
	global_store_dwordx4 v182, v[52:55], s[66:67]
	s_add_u32 s66, s64, 0x14000
	s_addc_u32 s67, s65, 0
	s_waitcnt lgkmcnt(5)
	global_store_dwordx4 v182, v[56:59], s[66:67]
	s_add_u32 s66, s64, 0x16000
	s_addc_u32 s67, s65, 0
	s_waitcnt lgkmcnt(4)
	global_store_dwordx4 v182, v[60:63], s[66:67]
	s_add_u32 s66, s64, 0x18000
	s_addc_u32 s67, s65, 0
	s_waitcnt lgkmcnt(3)
	global_store_dwordx4 v182, v[32:35], s[66:67]
	s_add_u32 s66, s64, 0x1a000
	s_addc_u32 s67, s65, 0
	s_waitcnt lgkmcnt(2)
	global_store_dwordx4 v182, v[36:39], s[66:67]
	s_add_u32 s66, s64, 0x1c000
	s_addc_u32 s67, s65, 0
	s_waitcnt lgkmcnt(1)
	global_store_dwordx4 v182, v[40:43], s[66:67]
	s_add_u32 s66, s64, 0x1e000
	s_addc_u32 s67, s65, 0
	s_waitcnt lgkmcnt(0)
	global_store_dwordx4 v182, v[44:47], s[66:67]
	v_readlane_b32 s64, v187, 0
	v_readlane_b32 s65, v187, 1
	v_readlane_b32 s66, v187, 2
	v_readlane_b32 s67, v187, 3
	v_readlane_b32 s68, v187, 4
	v_readlane_b32 s69, v187, 5
	v_readlane_b32 s70, v187, 6
	v_readlane_b32 s71, v187, 7
	v_readlane_b32 s72, v187, 8
	v_readlane_b32 s73, v187, 9
	v_readlane_b32 s74, v187, 10
	v_readlane_b32 s75, v187, 11
	v_readlane_b32 s76, v187, 12
	v_readlane_b32 s77, v187, 13
	v_readlane_b32 s78, v187, 14
	v_readlane_b32 s79, v187, 15
	s_nop 7
	s_add_i32 s28, s28, s34
	s_cmpk_lt_i32 s28, 0x200
	s_cbranch_scc0 .LBB0_936
	s_branch .LBB0_923

; #define MFMA32(a, b, c) __builtin_amdgcn_mfma_f32_32x32x16_bf16((a), (b), (c), 0, 0, 0)
; #define GA_LOAD(pr_) do { _Pragma("unroll") for (int i = 0; i < 4; ++i) ra[i] = *(const u32x4*)(Ab + (i * 32) * lda + (pr_) * 64); } while (0)
; #define GB_LOAD(kt_) do { const bfr* bk_ = Bb + (kt_) * NB * 32; \
;     _Pragma("unroll") for (int i = 0; i < 4; ++i) rb[i] = *(const u32x4*)(bk_ + (i * 64) * 32); } while (0)
; #define G_STORE(kt_) do { bfr* as_ = S0 + ((kt_) & 1) * GSTAGE; bfr* bs_ = as_ + 128 * 40; \
;     if (apar == ((kt_) & 1)) { _Pragma("unroll") for (int i = 0; i < 4; ++i) *(u32x4*)(as_ + asoff + i * 32 * 40) = ra[i]; } \
;     _Pragma("unroll") for (int i = 0; i < 4; ++i) *(u32x4*)(bs_ + bsoff + i * 64 * 40) = rb[i]; } while (0)
; template <int lda>
; DI void gemm_mainloop(const bfr* __restrict__ A, const bfr* __restrict__ Bt, int NB, int K, int m0, int n0, char* smem, f32x16 (&acc)[2][4]) {
;     ...
; #pragma unroll
;   for (int i = 0; i < 2; ++i)
; #pragma unroll
;     for (int j = 0; j < 4; ++j)
; #pragma unroll
;       for (int q = 0; q < 16; ++q) acc[i][j][q] = 0.f;
;   u32x4 ra[4], rb[4];
;   const int nk = K >> 5;
;   const int arow = tid >> 3, ac8 = tid & 7, apar = ac8 >> 2;
;   const bfr* Ab = A + (m0 + arow) * lda + ac8 * 8;
;   const int asoff = arow * 40 + (ac8 & 3) * 8;
;   const int brow = tid >> 2, bc4 = tid & 3;
;   const bfr* Bb = Bt + (n0 + brow) * 32 + bc4 * 8;
;   const int bsoff = brow * 40 + bc4 * 8;
;     ...
;   GA_LOAD(0);
;   GB_LOAD(0);
;   G_STORE(0);
;   GB_LOAD(1);
;   __syncthreads();
;   for (int kt = 0; kt < nk; ++kt) {
;     if (kt + 1 < nk) G_STORE(kt + 1);
;     if (kt + 2 < nk) {
;       GB_LOAD(kt + 2);
;       if ((kt & 1) == 0) GA_LOAD((kt >> 1) + 1);
;     }
;     const bfr* As = S0 + (kt & 1) * GSTAGE;
;     const bfr* Bs = As + 128 * 40;
; #pragma unroll
;     for (int ks = 0; ks < 2; ++ks) {
;       bf16x8 af[2], bfg[4];
; #pragma unroll
;       for (int i = 0; i < 2; ++i) af[i] = *(const bf16x8*)(As + (wr * 64 + i * 32 + r) * 40 + ks * 16 + hl * 8);
; #pragma unroll
;       for (int j = 0; j < 4; ++j) bfg[j] = *(const bf16x8*)(Bs + (wc * 128 + j * 32 + r) * 40 + ks * 16 + hl * 8);
; #pragma unroll
;       for (int i = 0; i < 2; ++i)
; #pragma unroll
;         for (int j = 0; j < 4; ++j) acc[i][j] = MFMA32(af[i], bfg[j], acc[i][j]);
;     }
.Lp10_nostag:
	v_mov_b32_e32 v112, 0
	v_mov_b32_e32 v113, 0
	v_mov_b32_e32 v114, 0
	v_mov_b32_e32 v115, 0
	v_mov_b32_e32 v116, 0
	v_mov_b32_e32 v117, 0
	v_mov_b32_e32 v118, 0
	v_mov_b32_e32 v119, 0
	v_mov_b32_e32 v120, 0
	v_mov_b32_e32 v121, 0
	v_mov_b32_e32 v122, 0
	v_mov_b32_e32 v123, 0
	v_mov_b32_e32 v124, 0
	v_mov_b32_e32 v125, 0
	v_mov_b32_e32 v126, 0
	v_mov_b32_e32 v127, 0
	v_mov_b32_e32 v96, 0
	v_mov_b32_e32 v97, 0
	v_mov_b32_e32 v98, 0
	v_mov_b32_e32 v99, 0
	v_mov_b32_e32 v100, 0
	v_mov_b32_e32 v101, 0
	v_mov_b32_e32 v102, 0
	v_mov_b32_e32 v103, 0
	v_mov_b32_e32 v104, 0
	v_mov_b32_e32 v105, 0
	v_mov_b32_e32 v106, 0
	v_mov_b32_e32 v107, 0
	v_mov_b32_e32 v108, 0
	v_mov_b32_e32 v109, 0
	v_mov_b32_e32 v110, 0
	v_mov_b32_e32 v111, 0
	v_mov_b32_e32 v80, 0
	v_mov_b32_e32 v81, 0
	v_mov_b32_e32 v82, 0
	v_mov_b32_e32 v83, 0
	v_mov_b32_e32 v84, 0
	v_mov_b32_e32 v85, 0
	v_mov_b32_e32 v86, 0
	v_mov_b32_e32 v87, 0
	v_mov_b32_e32 v88, 0
	v_mov_b32_e32 v89, 0
	v_mov_b32_e32 v90, 0
	v_mov_b32_e32 v91, 0
	v_mov_b32_e32 v92, 0
	v_mov_b32_e32 v93, 0
	v_mov_b32_e32 v94, 0
	v_mov_b32_e32 v95, 0
	v_mov_b32_e32 v64, 0
	v_mov_b32_e32 v65, 0
	v_mov_b32_e32 v66, 0
	v_mov_b32_e32 v67, 0
	v_mov_b32_e32 v68, 0
	v_mov_b32_e32 v69, 0
	v_mov_b32_e32 v70, 0
	v_mov_b32_e32 v71, 0
	v_mov_b32_e32 v72, 0
	v_mov_b32_e32 v73, 0
	v_mov_b32_e32 v74, 0
	v_mov_b32_e32 v75, 0
	v_mov_b32_e32 v76, 0
	v_mov_b32_e32 v77, 0
	v_mov_b32_e32 v78, 0
	v_mov_b32_e32 v79, 0
	v_mov_b32_e32 v48, 0
	v_mov_b32_e32 v49, 0
	v_mov_b32_e32 v50, 0
	v_mov_b32_e32 v51, 0
	v_mov_b32_e32 v52, 0
	v_mov_b32_e32 v53, 0
	v_mov_b32_e32 v54, 0
	v_mov_b32_e32 v55, 0
	v_mov_b32_e32 v56, 0
	v_mov_b32_e32 v57, 0
	v_mov_b32_e32 v58, 0
	v_mov_b32_e32 v59, 0
	v_mov_b32_e32 v60, 0
	v_mov_b32_e32 v61, 0
	v_mov_b32_e32 v62, 0
	v_mov_b32_e32 v63, 0
	v_mov_b32_e32 v32, 0
	v_mov_b32_e32 v33, 0
	v_mov_b32_e32 v34, 0
	v_mov_b32_e32 v35, 0
	v_mov_b32_e32 v36, 0
	v_mov_b32_e32 v37, 0
	v_mov_b32_e32 v38, 0
	v_mov_b32_e32 v39, 0
	v_mov_b32_e32 v40, 0
	v_mov_b32_e32 v41, 0
	v_mov_b32_e32 v42, 0
	v_mov_b32_e32 v43, 0
	v_mov_b32_e32 v44, 0
	v_mov_b32_e32 v45, 0
	v_mov_b32_e32 v46, 0
	v_mov_b32_e32 v47, 0
	v_mov_b32_e32 v16, 0
	v_mov_b32_e32 v17, 0
	v_mov_b32_e32 v18, 0
	v_mov_b32_e32 v19, 0
	v_mov_b32_e32 v20, 0
	v_mov_b32_e32 v21, 0
	v_mov_b32_e32 v22, 0
	v_mov_b32_e32 v23, 0
	v_mov_b32_e32 v24, 0
	v_mov_b32_e32 v25, 0
	v_mov_b32_e32 v26, 0
	v_mov_b32_e32 v27, 0
	v_mov_b32_e32 v28, 0
	v_mov_b32_e32 v29, 0
	v_mov_b32_e32 v30, 0
	v_mov_b32_e32 v31, 0
	v_mov_b32_e32 v0, 0
	v_mov_b32_e32 v1, 0
	v_mov_b32_e32 v2, 0
	v_mov_b32_e32 v3, 0
	v_mov_b32_e32 v4, 0
	v_mov_b32_e32 v5, 0
	v_mov_b32_e32 v6, 0
	v_mov_b32_e32 v7, 0
	v_mov_b32_e32 v8, 0
	v_mov_b32_e32 v9, 0
	v_mov_b32_e32 v10, 0
	v_mov_b32_e32 v11, 0
	v_mov_b32_e32 v12, 0
	v_mov_b32_e32 v13, 0
	v_mov_b32_e32 v14, 0
	v_mov_b32_e32 v15, 0
	s_waitcnt vmcnt(6)
	s_barrier
	s_mul_i32 s74, s71, 0x6000
	s_add_u32 s75, s74, 0x2000
	s_cmp_eq_u32 s71, 2
	s_cselect_b32 s75, 0x10000, s75
	v_add_u32_e32 v203, s74, v199
	v_add_u32_e32 v205, s75, v201
	v_add_u32_e32 v204, s74, v200
	v_add_u32_e32 v206, s75, v202
	s_add_u32 s71, s71, 1
	s_cmp_eq_u32 s71, 3
	s_cselect_b32 s71, 0, s71
	ds_read_b128 v[128:131], v203
	ds_read_b128 v[144:147], v205
	ds_read_b128 v[148:151], v205 offset:2048
	ds_read_b128 v[152:155], v205 offset:4096
	ds_read_b128 v[156:159], v205 offset:6144
	ds_read_b128 v[132:135], v203 offset:2048
	ds_read_b128 v[136:139], v204
	ds_read_b128 v[160:163], v206
	ds_read_b128 v[164:167], v206 offset:2048
	ds_read_b128 v[168:171], v206 offset:4096
	ds_read_b128 v[172:175], v206 offset:6144
	ds_read_b128 v[140:143], v204 offset:2048
	s_waitcnt lgkmcnt(10)
	v_mfma_f32_32x32x16_bf16 v[112:127], v[144:147], v[128:131], v[112:127]
	s_mul_i32 s74, s70, 0x6000
	s_add_u32 s75, s74, s68
	s_mov_b32 m0, s75
	s_add_u32 s76, s74, 0x2000
	s_cmp_eq_u32 s70, 2
	s_cselect_b32 s76, 0x10000, s76
	global_load_lds_dwordx4 v192, s[64:65]
	s_waitcnt lgkmcnt(9)
	v_mfma_f32_32x32x16_bf16 v[96:111], v[148:151], v[128:131], v[96:111]
	s_add_u32 m0, s75, 0x400
	s_add_u32 s76, s76, s69
	global_load_lds_dwordx4 v194, s[64:65]
	s_waitcnt lgkmcnt(8)
	v_mfma_f32_32x32x16_bf16 v[80:95], v[152:155], v[128:131], v[80:95]
	s_mov_b32 m0, s76
	s_add_u32 s64, s64, 64
	s_addc_u32 s65, s65, 0
	global_load_lds_dwordx4 v198, s[66:67]
	s_waitcnt lgkmcnt(7)
	v_mfma_f32_32x32x16_bf16 v[64:79], v[156:159], v[128:131], v[64:79]
	global_load_lds_dwordx4 v198, s[66:67] offset:1024
	s_waitcnt lgkmcnt(6)
	v_mfma_f32_32x32x16_bf16 v[48:63], v[144:147], v[132:135], v[48:63]
	global_load_lds_dwordx4 v198, s[66:67] offset:2048
	v_mfma_f32_32x32x16_bf16 v[32:47], v[148:151], v[132:135], v[32:47]
	global_load_lds_dwordx4 v198, s[66:67] offset:3072
	s_add_u32 s66, s66, 0x10000
	s_addc_u32 s67, s67, 0
	v_mfma_f32_32x32x16_bf16 v[16:31], v[152:155], v[132:135], v[16:31]
	s_add_u32 s70, s70, 1
	s_cmp_eq_u32 s70, 3
	s_cselect_b32 s70, 0, s70
	v_mfma_f32_32x32x16_bf16 v[0:15], v[156:159], v[132:135], v[0:15]
; #define MFMA32(a, b, c) __builtin_amdgcn_mfma_f32_32x32x16_bf16((a), (b), (c), 0, 0, 0)
; #define GA_LOAD(pr_) do { _Pragma("unroll") for (int i = 0; i < 4; ++i) ra[i] = *(const u32x4*)(Ab + (i * 32) * lda + (pr_) * 64); } while (0)
; #define GB_LOAD(kt_) do { const bfr* bk_ = Bb + (kt_) * NB * 32; \
;     _Pragma("unroll") for (int i = 0; i < 4; ++i) rb[i] = *(const u32x4*)(bk_ + (i * 64) * 32); } while (0)
; #define G_STORE(kt_) do { bfr* as_ = S0 + ((kt_) & 1) * GSTAGE; bfr* bs_ = as_ + 128 * 40; \
;     if (apar == ((kt_) & 1)) { _Pragma("unroll") for (int i = 0; i < 4; ++i) *(u32x4*)(as_ + asoff + i * 32 * 40) = ra[i]; } \
;     _Pragma("unroll") for (int i = 0; i < 4; ++i) *(u32x4*)(bs_ + bsoff + i * 64 * 40) = rb[i]; } while (0)
; template <int lda>
; DI void gemm_mainloop(const bfr* __restrict__ A, const bfr* __restrict__ Bt, int NB, int K, int m0, int n0, char* smem, f32x16 (&acc)[2][4]) {
;     ...
;   for (int kt = 0; kt < nk; ++kt) {
;     if (kt + 1 < nk) G_STORE(kt + 1);
;     if (kt + 2 < nk) {
;       GB_LOAD(kt + 2);
;       if ((kt & 1) == 0) GA_LOAD((kt >> 1) + 1);
;     }
;     const bfr* As = S0 + (kt & 1) * GSTAGE;
;     const bfr* Bs = As + 128 * 40;
; #pragma unroll
;     for (int ks = 0; ks < 2; ++ks) {
;       bf16x8 af[2], bfg[4];
; #pragma unroll
;       for (int i = 0; i < 2; ++i) af[i] = *(const bf16x8*)(As + (wr * 64 + i * 32 + r) * 40 + ks * 16 + hl * 8);
; #pragma unroll
;       for (int j = 0; j < 4; ++j) bfg[j] = *(const bf16x8*)(Bs + (wc * 128 + j * 32 + r) * 40 + ks * 16 + hl * 8);
; #pragma unroll
;       for (int i = 0; i < 2; ++i)
; #pragma unroll
;         for (int j = 0; j < 4; ++j) acc[i][j] = MFMA32(af[i], bfg[j], acc[i][j]);
;     }
;     __syncthreads();
;   }
.Lp10_loop:
	s_waitcnt vmcnt(6) lgkmcnt(0)
	s_barrier
	s_mul_i32 s74, s71, 0x6000
	s_add_u32 s75, s74, 0x2000
	s_cmp_eq_u32 s71, 2
	s_cselect_b32 s75, 0x10000, s75
	v_add_u32_e32 v203, s74, v199
	v_add_u32_e32 v205, s75, v201
	v_add_u32_e32 v204, s74, v200
	v_add_u32_e32 v206, s75, v202
	s_add_u32 s71, s71, 1
	s_cmp_eq_u32 s71, 3
	s_cselect_b32 s71, 0, s71
	ds_read_b128 v[128:131], v203
	ds_read_b128 v[144:147], v205
	ds_read_b128 v[148:151], v205 offset:2048
	ds_read_b128 v[152:155], v205 offset:4096
	ds_read_b128 v[156:159], v205 offset:6144
	ds_read_b128 v[132:135], v203 offset:2048
	v_mfma_f32_32x32x16_bf16 v[112:127], v[160:163], v[136:139], v[112:127]
	s_mul_i32 s74, s70, 0x6000
	s_add_u32 s75, s74, s68
	s_mov_b32 m0, s75
	s_add_u32 s76, s74, 0x2000
	s_cmp_eq_u32 s70, 2
	s_cselect_b32 s76, 0x10000, s76
	global_load_lds_dwordx4 v192, s[64:65]
	v_mfma_f32_32x32x16_bf16 v[96:111], v[164:167], v[136:139], v[96:111]
	s_add_u32 m0, s75, 0x400
	s_add_u32 s76, s76, s69
	global_load_lds_dwordx4 v194, s[64:65]
	v_mfma_f32_32x32x16_bf16 v[80:95], v[168:171], v[136:139], v[80:95]
	s_mov_b32 m0, s76
	s_add_u32 s64, s64, 64
	s_addc_u32 s65, s65, 0
	global_load_lds_dwordx4 v198, s[66:67]
	v_mfma_f32_32x32x16_bf16 v[64:79], v[172:175], v[136:139], v[64:79]
	global_load_lds_dwordx4 v198, s[66:67] offset:1024
	v_mfma_f32_32x32x16_bf16 v[48:63], v[160:163], v[140:143], v[48:63]
	global_load_lds_dwordx4 v198, s[66:67] offset:2048
	v_mfma_f32_32x32x16_bf16 v[32:47], v[164:167], v[140:143], v[32:47]
	global_load_lds_dwordx4 v198, s[66:67] offset:3072
	s_add_u32 s66, s66, 0x10000
	s_addc_u32 s67, s67, 0
	v_mfma_f32_32x32x16_bf16 v[16:31], v[168:171], v[140:143], v[16:31]
	s_add_u32 s70, s70, 1
	s_cmp_eq_u32 s70, 3
	s_cselect_b32 s70, 0, s70
	v_mfma_f32_32x32x16_bf16 v[0:15], v[172:175], v[140:143], v[0:15]
	ds_read_b128 v[136:139], v204
	ds_read_b128 v[160:163], v206
	ds_read_b128 v[164:167], v206 offset:2048
	ds_read_b128 v[168:171], v206 offset:4096
	ds_read_b128 v[172:175], v206 offset:6144
	ds_read_b128 v[140:143], v204 offset:2048
	s_waitcnt lgkmcnt(10)
	v_mfma_f32_32x32x16_bf16 v[112:127], v[144:147], v[128:131], v[112:127]
	s_waitcnt lgkmcnt(9)
	v_mfma_f32_32x32x16_bf16 v[96:111], v[148:151], v[128:131], v[96:111]
	s_waitcnt lgkmcnt(8)
	v_mfma_f32_32x32x16_bf16 v[80:95], v[152:155], v[128:131], v[80:95]
	s_waitcnt lgkmcnt(7)
	v_mfma_f32_32x32x16_bf16 v[64:79], v[156:159], v[128:131], v[64:79]
	s_waitcnt lgkmcnt(6)
	v_mfma_f32_32x32x16_bf16 v[48:63], v[144:147], v[132:135], v[48:63]
	v_mfma_f32_32x32x16_bf16 v[32:47], v[148:151], v[132:135], v[32:47]
	v_mfma_f32_32x32x16_bf16 v[16:31], v[152:155], v[132:135], v[16:31]
	v_mfma_f32_32x32x16_bf16 v[0:15], v[156:159], v[132:135], v[0:15]
	s_add_u32 s72, s72, 1
	s_cmp_lt_u32 s72, 29
	s_cbranch_scc1 .Lp10_loop
	s_waitcnt vmcnt(6) lgkmcnt(0)
	s_barrier
	s_mul_i32 s74, s71, 0x6000
	s_add_u32 s75, s74, 0x2000
	s_cmp_eq_u32 s71, 2
	s_cselect_b32 s75, 0x10000, s75
	v_add_u32_e32 v203, s74, v199
	v_add_u32_e32 v205, s75, v201
	v_add_u32_e32 v204, s74, v200
	v_add_u32_e32 v206, s75, v202
	s_add_u32 s71, s71, 1
	s_cmp_eq_u32 s71, 3
	s_cselect_b32 s71, 0, s71
	ds_read_b128 v[128:131], v203
	ds_read_b128 v[144:147], v205
	ds_read_b128 v[148:151], v205 offset:2048
	ds_read_b128 v[152:155], v205 offset:4096
	ds_read_b128 v[156:159], v205 offset:6144
	ds_read_b128 v[132:135], v203 offset:2048
	v_mfma_f32_32x32x16_bf16 v[112:127], v[160:163], v[136:139], v[112:127]
	v_mfma_f32_32x32x16_bf16 v[96:111], v[164:167], v[136:139], v[96:111]
	v_mfma_f32_32x32x16_bf16 v[80:95], v[168:171], v[136:139], v[80:95]
	v_mfma_f32_32x32x16_bf16 v[64:79], v[172:175], v[136:139], v[64:79]
	v_mfma_f32_32x32x16_bf16 v[48:63], v[160:163], v[140:143], v[48:63]
	v_mfma_f32_32x32x16_bf16 v[32:47], v[164:167], v[140:143], v[32:47]
	v_mfma_f32_32x32x16_bf16 v[16:31], v[168:171], v[140:143], v[16:31]
	v_mfma_f32_32x32x16_bf16 v[0:15], v[172:175], v[140:143], v[0:15]
	ds_read_b128 v[136:139], v204
	ds_read_b128 v[160:163], v206
	ds_read_b128 v[164:167], v206 offset:2048
	ds_read_b128 v[168:171], v206 offset:4096
	ds_read_b128 v[172:175], v206 offset:6144
	ds_read_b128 v[140:143], v204 offset:2048
	s_waitcnt lgkmcnt(10)
	v_mfma_f32_32x32x16_bf16 v[112:127], v[144:147], v[128:131], v[112:127]
	s_waitcnt lgkmcnt(9)
	v_mfma_f32_32x32x16_bf16 v[96:111], v[148:151], v[128:131], v[96:111]
	s_waitcnt lgkmcnt(8)
	v_mfma_f32_32x32x16_bf16 v[80:95], v[152:155], v[128:131], v[80:95]
	s_waitcnt lgkmcnt(7)
	v_mfma_f32_32x32x16_bf16 v[64:79], v[156:159], v[128:131], v[64:79]
	s_waitcnt lgkmcnt(6)
	v_mfma_f32_32x32x16_bf16 v[48:63], v[144:147], v[132:135], v[48:63]
	v_mfma_f32_32x32x16_bf16 v[32:47], v[148:151], v[132:135], v[32:47]
	v_mfma_f32_32x32x16_bf16 v[16:31], v[152:155], v[132:135], v[16:31]
	v_mfma_f32_32x32x16_bf16 v[0:15], v[156:159], v[132:135], v[0:15]
	s_waitcnt vmcnt(0) lgkmcnt(0)
	s_barrier
; #define MFMA32(a, b, c) __builtin_amdgcn_mfma_f32_32x32x16_bf16((a), (b), (c), 0, 0, 0)
; DI int crow(int reg, int h) { return (reg & 3) + 8 * (reg >> 2) + 4 * h; }
; template <int lda>
; DI void gemm_mainloop(const bfr* __restrict__ A, const bfr* __restrict__ Bt, int NB, int K, int m0, int n0, char* smem, f32x16 (&acc)[2][4]) {
;     ...
; #pragma unroll
;     for (int ks = 0; ks < 2; ++ks) {
;       bf16x8 af[2], bfg[4];
; #pragma unroll
;       for (int i = 0; i < 2; ++i) af[i] = *(const bf16x8*)(As + (wr * 64 + i * 32 + r) * 40 + ks * 16 + hl * 8);
; #pragma unroll
;       for (int j = 0; j < 4; ++j) bfg[j] = *(const bf16x8*)(Bs + (wc * 128 + j * 32 + r) * 40 + ks * 16 + hl * 8);
; #pragma unroll
;       for (int i = 0; i < 2; ++i)
; #pragma unroll
;         for (int j = 0; j < 4; ++j) acc[i][j] = MFMA32(af[i], bfg[j], acc[i][j]);
;     }
;     __syncthreads();
; template <bool FIRST, bool HAS_H>
; DI void phase_gemm_resid(const Params& p, const bfr* A, const bfr* Wt, const float* gnext, float* ss, char* smem) {
;     ...
;   for (int t0 = blockIdx.x; t0 < 128 * 4; t0 += gridDim.x) {
;     const int t = ((gridDim.x & 7) == 0) ? xcd_tile(t0, 4) : t0;
;     const int mt = t >> 2, nt = t & 3, m0 = mt * 128, n0 = nt * 256;
;     f32x16 acc[2][4];
;     gemm_mainloop<1024>(A, Wt, 1024, 1024, m0, n0, smem, acc);
;     int tid2 = threadIdx.x;
;     asm volatile("" : "+v"(tid2));
;     const int lane = tid2 & 63, wid = tid2 >> 6, wr = wid >> 1, wc = wid & 1, r = lane & 31, hl = lane >> 5;
;     const float* xsrc = FIRST ? p.x_prompt : X;
;     const int rbase = m0 + wr * 64 + 4 * hl, cbase = n0 + wc * 128 + r;
; #pragma unroll
;     for (int i = 0; i < 2; ++i) {
; #pragma unroll
;       for (int qh = 0; qh < 2; ++qh) {
;         float rs[8];
; #pragma unroll
;         for (int q = 0; q < 8; ++q) rs[q] = 0.f;
; #pragma unroll
;         for (int jh = 0; jh < 2; ++jh) {
;           float xo[2][8];
; #pragma unroll
;           for (int jj = 0; jj < 2; ++jj)
; #pragma unroll
;             for (int q = 0; q < 8; ++q)
;               xo[jj][q] = xsrc[(rbase + i * 32 + crow(qh * 8 + q, 0)) * 1024 + cbase + (jh * 2 + jj) * 32];
	s_mul_i32 s74, s71, 0x6000
	s_add_u32 s75, s74, 0x2000
	s_cmp_eq_u32 s71, 2
	s_cselect_b32 s75, 0x10000, s75
	v_add_u32_e32 v203, s74, v199
	v_add_u32_e32 v205, s75, v201
	v_add_u32_e32 v204, s74, v200
	v_add_u32_e32 v206, s75, v202
	s_add_u32 s71, s71, 1
	s_cmp_eq_u32 s71, 3
	s_cselect_b32 s71, 0, s71
	ds_read_b128 v[128:131], v203
	ds_read_b128 v[144:147], v205
	ds_read_b128 v[148:151], v205 offset:2048
	ds_read_b128 v[152:155], v205 offset:4096
	ds_read_b128 v[156:159], v205 offset:6144
	ds_read_b128 v[132:135], v203 offset:2048
	v_mfma_f32_32x32x16_bf16 v[112:127], v[160:163], v[136:139], v[112:127]
	v_mfma_f32_32x32x16_bf16 v[96:111], v[164:167], v[136:139], v[96:111]
	v_mfma_f32_32x32x16_bf16 v[80:95], v[168:171], v[136:139], v[80:95]
	v_mfma_f32_32x32x16_bf16 v[64:79], v[172:175], v[136:139], v[64:79]
	v_mfma_f32_32x32x16_bf16 v[48:63], v[160:163], v[140:143], v[48:63]
	v_mfma_f32_32x32x16_bf16 v[32:47], v[164:167], v[140:143], v[32:47]
	v_mfma_f32_32x32x16_bf16 v[16:31], v[168:171], v[140:143], v[16:31]
	v_mfma_f32_32x32x16_bf16 v[0:15], v[172:175], v[140:143], v[0:15]
	ds_read_b128 v[136:139], v204
	ds_read_b128 v[160:163], v206
	ds_read_b128 v[164:167], v206 offset:2048
	ds_read_b128 v[168:171], v206 offset:4096
	ds_read_b128 v[172:175], v206 offset:6144
	ds_read_b128 v[140:143], v204 offset:2048
	s_waitcnt lgkmcnt(10)
	v_mfma_f32_32x32x16_bf16 v[112:127], v[144:147], v[128:131], v[112:127]
	s_waitcnt lgkmcnt(9)
	v_mfma_f32_32x32x16_bf16 v[96:111], v[148:151], v[128:131], v[96:111]
	s_waitcnt lgkmcnt(8)
	v_mfma_f32_32x32x16_bf16 v[80:95], v[152:155], v[128:131], v[80:95]
	s_waitcnt lgkmcnt(7)
	v_mfma_f32_32x32x16_bf16 v[64:79], v[156:159], v[128:131], v[64:79]
	s_waitcnt lgkmcnt(6)
	v_mfma_f32_32x32x16_bf16 v[48:63], v[144:147], v[132:135], v[48:63]
	v_mfma_f32_32x32x16_bf16 v[32:47], v[148:151], v[132:135], v[32:47]
	v_mfma_f32_32x32x16_bf16 v[16:31], v[152:155], v[132:135], v[16:31]
	v_mfma_f32_32x32x16_bf16 v[0:15], v[156:159], v[132:135], v[0:15]
	s_waitcnt lgkmcnt(0)
	v_mfma_f32_32x32x16_bf16 v[112:127], v[160:163], v[136:139], v[112:127]
	v_mfma_f32_32x32x16_bf16 v[96:111], v[164:167], v[136:139], v[96:111]
	v_mfma_f32_32x32x16_bf16 v[80:95], v[168:171], v[136:139], v[80:95]
	v_mfma_f32_32x32x16_bf16 v[64:79], v[172:175], v[136:139], v[64:79]
	v_mfma_f32_32x32x16_bf16 v[48:63], v[160:163], v[140:143], v[48:63]
	v_mfma_f32_32x32x16_bf16 v[32:47], v[164:167], v[140:143], v[32:47]
	v_mfma_f32_32x32x16_bf16 v[16:31], v[168:171], v[140:143], v[16:31]
	v_mfma_f32_32x32x16_bf16 v[0:15], v[172:175], v[140:143], v[0:15]
	s_nop 7
	s_nop 3
	s_load_dwordx2 s[64:65], s[92:93], 0x100
	s_load_dwordx2 s[66:67], s[92:93], 0x100
	s_load_dwordx2 s[68:69], s[92:93], 0x148
	s_load_dwordx2 s[70:71], s[92:93], 0x48
	s_mul_i32 s76, s73, 8704
	s_lshr_b32 s74, s73, 1
	s_lshl_b32 s74, s74, 6
	s_add_u32 s74, s74, s77
	s_and_b32 s75, s73, 1
	s_lshl_b32 s75, s75, 7
	s_add_u32 s75, s75, s78
	v_and_b32_e32 v208, 31, v196
	v_bfe_u32 v209, v196, 5, 1
	v_mul_u32_u24_e32 v210, 272, v208
	v_add_u32_e32 v210, s76, v210
	v_lshl_add_u32 v192, v209, 4, v210
	v_lshl_add_u32 v194, v209, 3, v210
	v_lshlrev_b32_e32 v210, 2, v209
	v_add_lshl_u32 v202, v210, s75, 2
	v_add_lshl_u32 v205, v208, s74, 2
	v_and_b32_e32 v210, 63, v196
	v_xor_b32_e32 v210, 32, v210
	v_lshlrev_b32_e32 v206, 2, v210
	v_bfe_u32 v208, v196, 4, 2
	v_and_b32_e32 v209, 15, v196
	v_mul_u32_u24_e32 v210, 272, v208
	v_lshl_add_u32 v210, v209, 4, v210
	v_add_u32_e32 v198, s76, v210
	v_add_u32_e32 v210, s74, v208
	v_lshlrev_b32_e32 v210, 10, v210
	v_lshl_add_u32 v210, v209, 2, v210
	v_add_lshl_u32 v200, v210, s75, 2
	s_mov_b32 s79, s74
	s_mov_b32 s72, s75
	s_waitcnt lgkmcnt(0)
	s_add_u32 s74, s64, 0x0
	s_addc_u32 s75, s65, 0
	global_load_dwordx4 v[128:131], v200, s[74:75]
	s_add_u32 s74, s64, 0x4000
	s_addc_u32 s75, s65, 0
	global_load_dwordx4 v[132:135], v200, s[74:75]
	s_add_u32 s74, s64, 0x8000
	s_addc_u32 s75, s65, 0
	global_load_dwordx4 v[136:139], v200, s[74:75]
	s_add_u32 s74, s64, 0xc000
	s_addc_u32 s75, s65, 0
	global_load_dwordx4 v[140:143], v200, s[74:75]
	s_add_u32 s74, s64, 0x10000
	s_addc_u32 s75, s65, 0
	global_load_dwordx4 v[144:147], v200, s[74:75]
	s_add_u32 s74, s64, 0x14000
	s_addc_u32 s75, s65, 0
	global_load_dwordx4 v[148:151], v200, s[74:75]
	s_add_u32 s74, s64, 0x18000
	s_addc_u32 s75, s65, 0
	global_load_dwordx4 v[152:155], v200, s[74:75]
	s_add_u32 s74, s64, 0x1c000
	s_addc_u32 s75, s65, 0
	global_load_dwordx4 v[156:159], v200, s[74:75]
	s_mov_b32 s74, s79
	s_mov_b32 s75, s72
	v_bfe_u32 v208, v196, 3, 3
	v_and_b32_e32 v209, 7, v196
	v_mul_u32_u24_e32 v210, 272, v208
	v_lshl_add_u32 v210, v209, 4, v210
	v_add_u32_e32 v199, s76, v210
	v_add_u32_e32 v210, s74, v208
	v_lshlrev_b32_e32 v210, 10, v210
	v_lshl_add_u32 v210, v209, 3, v210
	v_add_lshl_u32 v201, v210, s75, 1
	v_mov_b32_e32 v203, 0
	v_mov_b32_e32 v204, 0
	s_waitcnt lgkmcnt(0)
	s_barrier
; DI bfr f2bf(float a) { return (bfr)(pack2(a, 0.f) & 0xffffu); }
; DI int crow(int reg, int h) { return (reg & 3) + 8 * (reg >> 2) + 4 * h; }
; template <bool FIRST, bool HAS_H>
; DI void phase_gemm_resid(const Params& p, const bfr* A, const bfr* Wt, const float* gnext, float* ss, char* smem) {
;     ...
;         for (int jh = 0; jh < 2; ++jh) {
;           float xo[2][8];
; #pragma unroll
;           for (int jj = 0; jj < 2; ++jj)
; #pragma unroll
;             for (int q = 0; q < 8; ++q)
;               xo[jj][q] = xsrc[(rbase + i * 32 + crow(qh * 8 + q, 0)) * 1024 + cbase + (jh * 2 + jj) * 32];
; #pragma unroll
;           for (int q = 0; q < 8; ++q) {
;             const int o = (rbase + i * 32 + crow(qh * 8 + q, 0)) * 1024 + cbase;
; #pragma unroll
;             for (int jj = 0; jj < 2; ++jj) {
;               const int j = jh * 2 + jj;
;               const float xn = xo[jj][q] + acc[i][j][qh * 8 + q];
;               X[o + j * 32] = xn;
;               if (HAS_H) Hn[o + j * 32] = f2bf(xn * gnext[cbase + j * 32]);
;               rs[q] += xn * xn;
;             }
;           }
	s_add_u32 s70, s70, 0x1000
	s_addc_u32 s71, s71, 0
	s_waitcnt vmcnt(7)
	ds_write_b128 v198, v[128:131]
	s_waitcnt vmcnt(6)
	ds_write_b128 v198, v[132:135] offset:1088
	s_waitcnt vmcnt(5)
	ds_write_b128 v198, v[136:139] offset:2176
	s_waitcnt vmcnt(4)
	ds_write_b128 v198, v[140:143] offset:3264
	s_waitcnt vmcnt(3)
	ds_write_b128 v198, v[144:147] offset:4352
	s_waitcnt vmcnt(2)
	ds_write_b128 v198, v[148:151] offset:5440
	s_waitcnt vmcnt(1)
	ds_write_b128 v198, v[152:155] offset:6528
	s_waitcnt vmcnt(0)
	ds_write_b128 v198, v[156:159] offset:7616
	s_add_u32 s74, s64, 0x100
	s_addc_u32 s75, s65, 0
	global_load_dwordx4 v[128:131], v200, s[74:75]
	s_add_u32 s74, s64, 0x4100
	s_addc_u32 s75, s65, 0
	global_load_dwordx4 v[132:135], v200, s[74:75]
	s_add_u32 s74, s64, 0x8100
	s_addc_u32 s75, s65, 0
	global_load_dwordx4 v[136:139], v200, s[74:75]
	s_add_u32 s74, s64, 0xc100
	s_addc_u32 s75, s65, 0
	global_load_dwordx4 v[140:143], v200, s[74:75]
	s_add_u32 s74, s64, 0x10100
	s_addc_u32 s75, s65, 0
	global_load_dwordx4 v[144:147], v200, s[74:75]
	s_add_u32 s74, s64, 0x14100
	s_addc_u32 s75, s65, 0
	global_load_dwordx4 v[148:151], v200, s[74:75]
	s_add_u32 s74, s64, 0x18100
	s_addc_u32 s75, s65, 0
	global_load_dwordx4 v[152:155], v200, s[74:75]
	s_add_u32 s74, s64, 0x1c100
	s_addc_u32 s75, s65, 0
	global_load_dwordx4 v[156:159], v200, s[74:75]
	ds_read_b128 v[160:163], v192
	ds_read_b128 v[164:167], v192 offset:32
	ds_read_b128 v[168:171], v192 offset:64
	ds_read_b128 v[172:175], v192 offset:96
	ds_read_b128 v[176:179], v192 offset:128
	ds_read_b128 v[180:183], v192 offset:160
	ds_read_b128 v[184:187], v192 offset:192
	ds_read_b128 v[188:191], v192 offset:224
	s_waitcnt lgkmcnt(7)
	v_add_f32_e32 v112, v160, v112
	v_add_f32_e32 v113, v161, v113
	v_add_f32_e32 v114, v162, v114
	v_add_f32_e32 v115, v163, v115
	v_fmac_f32_e32 v203, v112, v112
	v_fmac_f32_e32 v203, v113, v113
	v_fmac_f32_e32 v203, v114, v114
	v_fmac_f32_e32 v203, v115, v115
	ds_write_b128 v192, v[112:115]
	s_waitcnt lgkmcnt(7)
	v_add_f32_e32 v116, v164, v116
	v_add_f32_e32 v117, v165, v117
	v_add_f32_e32 v118, v166, v118
	v_add_f32_e32 v119, v167, v119
	v_fmac_f32_e32 v203, v116, v116
	v_fmac_f32_e32 v203, v117, v117
	v_fmac_f32_e32 v203, v118, v118
	v_fmac_f32_e32 v203, v119, v119
	ds_write_b128 v192, v[116:119] offset:32
	s_waitcnt lgkmcnt(7)
	v_add_f32_e32 v120, v168, v120
	v_add_f32_e32 v121, v169, v121
	v_add_f32_e32 v122, v170, v122
	v_add_f32_e32 v123, v171, v123
	v_fmac_f32_e32 v203, v120, v120
	v_fmac_f32_e32 v203, v121, v121
	v_fmac_f32_e32 v203, v122, v122
	v_fmac_f32_e32 v203, v123, v123
	ds_write_b128 v192, v[120:123] offset:64
	s_waitcnt lgkmcnt(7)
	v_add_f32_e32 v124, v172, v124
	v_add_f32_e32 v125, v173, v125
	v_add_f32_e32 v126, v174, v126
	v_add_f32_e32 v127, v175, v127
	v_fmac_f32_e32 v203, v124, v124
	v_fmac_f32_e32 v203, v125, v125
	v_fmac_f32_e32 v203, v126, v126
	v_fmac_f32_e32 v203, v127, v127
	ds_write_b128 v192, v[124:127] offset:96
	s_waitcnt lgkmcnt(7)
	v_add_f32_e32 v96, v176, v96
	v_add_f32_e32 v97, v177, v97
	v_add_f32_e32 v98, v178, v98
	v_add_f32_e32 v99, v179, v99
	v_fmac_f32_e32 v203, v96, v96
	v_fmac_f32_e32 v203, v97, v97
	v_fmac_f32_e32 v203, v98, v98
	v_fmac_f32_e32 v203, v99, v99
	ds_write_b128 v192, v[96:99] offset:128
	s_waitcnt lgkmcnt(7)
	v_add_f32_e32 v100, v180, v100
	v_add_f32_e32 v101, v181, v101
	v_add_f32_e32 v102, v182, v102
	v_add_f32_e32 v103, v183, v103
	v_fmac_f32_e32 v203, v100, v100
	v_fmac_f32_e32 v203, v101, v101
	v_fmac_f32_e32 v203, v102, v102
	v_fmac_f32_e32 v203, v103, v103
	ds_write_b128 v192, v[100:103] offset:160
	s_waitcnt lgkmcnt(7)
	v_add_f32_e32 v104, v184, v104
	v_add_f32_e32 v105, v185, v105
	v_add_f32_e32 v106, v186, v106
	v_add_f32_e32 v107, v187, v107
	v_fmac_f32_e32 v203, v104, v104
	v_fmac_f32_e32 v203, v105, v105
	v_fmac_f32_e32 v203, v106, v106
	v_fmac_f32_e32 v203, v107, v107
	ds_write_b128 v192, v[104:107] offset:192
	s_waitcnt lgkmcnt(7)
	v_add_f32_e32 v108, v188, v108
	v_add_f32_e32 v109, v189, v109
	v_add_f32_e32 v110, v190, v110
	v_add_f32_e32 v111, v191, v111
	v_fmac_f32_e32 v203, v108, v108
	v_fmac_f32_e32 v203, v109, v109
	v_fmac_f32_e32 v203, v110, v110
	v_fmac_f32_e32 v203, v111, v111
	ds_write_b128 v192, v[108:111] offset:224
	ds_read_b128 v[160:163], v198
	ds_read_b128 v[164:167], v198 offset:1088
	ds_read_b128 v[168:171], v198 offset:2176
	ds_read_b128 v[172:175], v198 offset:3264
	ds_read_b128 v[176:179], v198 offset:4352
	ds_read_b128 v[180:183], v198 offset:5440
	ds_read_b128 v[184:187], v198 offset:6528
	ds_read_b128 v[188:191], v198 offset:7616
	s_add_u32 s74, s66, 0x0
	s_addc_u32 s75, s67, 0
	s_waitcnt lgkmcnt(7)
	global_store_dwordx4 v200, v[160:163], s[74:75]
	s_add_u32 s74, s66, 0x4000
	s_addc_u32 s75, s67, 0
	s_waitcnt lgkmcnt(6)
	global_store_dwordx4 v200, v[164:167], s[74:75]
	s_add_u32 s74, s66, 0x8000
	s_addc_u32 s75, s67, 0
	s_waitcnt lgkmcnt(5)
	global_store_dwordx4 v200, v[168:171], s[74:75]
	s_add_u32 s74, s66, 0xc000
	s_addc_u32 s75, s67, 0
	s_waitcnt lgkmcnt(4)
	global_store_dwordx4 v200, v[172:175], s[74:75]
	s_add_u32 s74, s66, 0x10000
	s_addc_u32 s75, s67, 0
	s_waitcnt lgkmcnt(3)
	global_store_dwordx4 v200, v[176:179], s[74:75]
	s_add_u32 s74, s66, 0x14000
	s_addc_u32 s75, s67, 0
	s_waitcnt lgkmcnt(2)
	global_store_dwordx4 v200, v[180:183], s[74:75]
	s_add_u32 s74, s66, 0x18000
	s_addc_u32 s75, s67, 0
	s_waitcnt lgkmcnt(1)
	global_store_dwordx4 v200, v[184:187], s[74:75]
	s_add_u32 s74, s66, 0x1c000
	s_addc_u32 s75, s67, 0
	s_waitcnt lgkmcnt(0)
; DI bfr f2bf(float a) { return (bfr)(pack2(a, 0.f) & 0xffffu); }
; DI int crow(int reg, int h) { return (reg & 3) + 8 * (reg >> 2) + 4 * h; }
; template <bool FIRST, bool HAS_H>
; DI void phase_gemm_resid(const Params& p, const bfr* A, const bfr* Wt, const float* gnext, float* ss, char* smem) {
;     ...
;           for (int jj = 0; jj < 2; ++jj)
; #pragma unroll
;             for (int q = 0; q < 8; ++q)
;               xo[jj][q] = xsrc[(rbase + i * 32 + crow(qh * 8 + q, 0)) * 1024 + cbase + (jh * 2 + jj) * 32];
; #pragma unroll
;           for (int q = 0; q < 8; ++q) {
;             const int o = (rbase + i * 32 + crow(qh * 8 + q, 0)) * 1024 + cbase;
; #pragma unroll
;             for (int jj = 0; jj < 2; ++jj) {
;               const int j = jh * 2 + jj;
;               const float xn = xo[jj][q] + acc[i][j][qh * 8 + q];
;               X[o + j * 32] = xn;
;               if (HAS_H) Hn[o + j * 32] = f2bf(xn * gnext[cbase + j * 32]);
;               rs[q] += xn * xn;
;             }
	global_store_dwordx4 v200, v[188:191], s[74:75]
	global_load_dwordx4 v[160:163], v202, s[70:71]
	global_load_dwordx4 v[164:167], v202, s[70:71] offset:32
	global_load_dwordx4 v[168:171], v202, s[70:71] offset:64
	global_load_dwordx4 v[172:175], v202, s[70:71] offset:96
	global_load_dwordx4 v[176:179], v202, s[70:71] offset:128
	global_load_dwordx4 v[180:183], v202, s[70:71] offset:160
	global_load_dwordx4 v[184:187], v202, s[70:71] offset:192
	global_load_dwordx4 v[188:191], v202, s[70:71] offset:224
	s_waitcnt vmcnt(7)
	v_mul_f32_e32 v112, v160, v112
	v_mul_f32_e32 v113, v161, v113
	v_mul_f32_e32 v114, v162, v114
	v_mul_f32_e32 v115, v163, v115
	v_cvt_pk_bf16_f32 v112, v112, v113
	v_cvt_pk_bf16_f32 v113, v114, v115
	ds_write_b64 v194, v[112:113]
	s_waitcnt vmcnt(6)
	v_mul_f32_e32 v116, v164, v116
	v_mul_f32_e32 v117, v165, v117
	v_mul_f32_e32 v118, v166, v118
	v_mul_f32_e32 v119, v167, v119
	v_cvt_pk_bf16_f32 v116, v116, v117
	v_cvt_pk_bf16_f32 v117, v118, v119
	ds_write_b64 v194, v[116:117] offset:16
	s_waitcnt vmcnt(5)
	v_mul_f32_e32 v120, v168, v120
	v_mul_f32_e32 v121, v169, v121
	v_mul_f32_e32 v122, v170, v122
	v_mul_f32_e32 v123, v171, v123
	v_cvt_pk_bf16_f32 v120, v120, v121
	v_cvt_pk_bf16_f32 v121, v122, v123
	ds_write_b64 v194, v[120:121] offset:32
	s_waitcnt vmcnt(4)
	v_mul_f32_e32 v124, v172, v124
	v_mul_f32_e32 v125, v173, v125
	v_mul_f32_e32 v126, v174, v126
	v_mul_f32_e32 v127, v175, v127
	v_cvt_pk_bf16_f32 v124, v124, v125
	v_cvt_pk_bf16_f32 v125, v126, v127
	ds_write_b64 v194, v[124:125] offset:48
	s_waitcnt vmcnt(3)
	v_mul_f32_e32 v96, v176, v96
	v_mul_f32_e32 v97, v177, v97
	v_mul_f32_e32 v98, v178, v98
	v_mul_f32_e32 v99, v179, v99
	v_cvt_pk_bf16_f32 v96, v96, v97
	v_cvt_pk_bf16_f32 v97, v98, v99
	ds_write_b64 v194, v[96:97] offset:64
	s_waitcnt vmcnt(2)
	v_mul_f32_e32 v100, v180, v100
	v_mul_f32_e32 v101, v181, v101
	v_mul_f32_e32 v102, v182, v102
	v_mul_f32_e32 v103, v183, v103
	v_cvt_pk_bf16_f32 v100, v100, v101
	v_cvt_pk_bf16_f32 v101, v102, v103
	ds_write_b64 v194, v[100:101] offset:80
	s_waitcnt vmcnt(1)
	v_mul_f32_e32 v104, v184, v104
	v_mul_f32_e32 v105, v185, v105
	v_mul_f32_e32 v106, v186, v106
	v_mul_f32_e32 v107, v187, v107
	v_cvt_pk_bf16_f32 v104, v104, v105
	v_cvt_pk_bf16_f32 v105, v106, v107
	ds_write_b64 v194, v[104:105] offset:96
	s_waitcnt vmcnt(0)
	v_mul_f32_e32 v108, v188, v108
	v_mul_f32_e32 v109, v189, v109
	v_mul_f32_e32 v110, v190, v110
	v_mul_f32_e32 v111, v191, v111
	v_cvt_pk_bf16_f32 v108, v108, v109
	v_cvt_pk_bf16_f32 v109, v110, v111
	ds_write_b64 v194, v[108:109] offset:112
	ds_read_b128 v[160:163], v199
	ds_read_b128 v[164:167], v199 offset:2176
	ds_read_b128 v[168:171], v199 offset:4352
	ds_read_b128 v[172:175], v199 offset:6528
	s_add_u32 s74, s68, 0x0
	s_addc_u32 s75, s69, 0
	s_waitcnt lgkmcnt(3)
	global_store_dwordx4 v201, v[160:163], s[74:75]
	s_add_u32 s74, s68, 0x4000
	s_addc_u32 s75, s69, 0
	s_waitcnt lgkmcnt(2)
	global_store_dwordx4 v201, v[164:167], s[74:75]
	s_add_u32 s74, s68, 0x8000
	s_addc_u32 s75, s69, 0
	s_waitcnt lgkmcnt(1)
	global_store_dwordx4 v201, v[168:171], s[74:75]
	s_add_u32 s74, s68, 0xc000
	s_addc_u32 s75, s69, 0
	s_waitcnt lgkmcnt(0)
	global_store_dwordx4 v201, v[172:175], s[74:75]
	s_waitcnt vmcnt(4)
	ds_write_b128 v198, v[128:131]
	s_waitcnt vmcnt(4)
	ds_write_b128 v198, v[132:135] offset:1088
	s_waitcnt vmcnt(4)
	ds_write_b128 v198, v[136:139] offset:2176
	s_waitcnt vmcnt(4)
	ds_write_b128 v198, v[140:143] offset:3264
	s_waitcnt vmcnt(4)
	ds_write_b128 v198, v[144:147] offset:4352
	s_waitcnt vmcnt(4)
	ds_write_b128 v198, v[148:151] offset:5440
	s_waitcnt vmcnt(4)
	ds_write_b128 v198, v[152:155] offset:6528
	s_waitcnt vmcnt(4)
	ds_write_b128 v198, v[156:159] offset:7616
	s_add_u32 s74, s64, 0x20000
	s_addc_u32 s75, s65, 0
	global_load_dwordx4 v[128:131], v200, s[74:75]
	s_add_u32 s74, s64, 0x24000
	s_addc_u32 s75, s65, 0
	global_load_dwordx4 v[132:135], v200, s[74:75]
	s_add_u32 s74, s64, 0x28000
	s_addc_u32 s75, s65, 0
	global_load_dwordx4 v[136:139], v200, s[74:75]
	s_add_u32 s74, s64, 0x2c000
	s_addc_u32 s75, s65, 0
	global_load_dwordx4 v[140:143], v200, s[74:75]
	s_add_u32 s74, s64, 0x30000
	s_addc_u32 s75, s65, 0
	global_load_dwordx4 v[144:147], v200, s[74:75]
	s_add_u32 s74, s64, 0x34000
	s_addc_u32 s75, s65, 0
	global_load_dwordx4 v[148:151], v200, s[74:75]
	s_add_u32 s74, s64, 0x38000
	s_addc_u32 s75, s65, 0
	global_load_dwordx4 v[152:155], v200, s[74:75]
	s_add_u32 s74, s64, 0x3c000
	s_addc_u32 s75, s65, 0
	global_load_dwordx4 v[156:159], v200, s[74:75]
	ds_read_b128 v[160:163], v192
	ds_read_b128 v[164:167], v192 offset:32
	ds_read_b128 v[168:171], v192 offset:64
	ds_read_b128 v[172:175], v192 offset:96
	ds_read_b128 v[176:179], v192 offset:128
	ds_read_b128 v[180:183], v192 offset:160
	ds_read_b128 v[184:187], v192 offset:192
	ds_read_b128 v[188:191], v192 offset:224
	s_waitcnt lgkmcnt(7)
	v_add_f32_e32 v80, v160, v80
	v_add_f32_e32 v81, v161, v81
	v_add_f32_e32 v82, v162, v82
	v_add_f32_e32 v83, v163, v83
	v_fmac_f32_e32 v203, v80, v80
	v_fmac_f32_e32 v203, v81, v81
	v_fmac_f32_e32 v203, v82, v82
	v_fmac_f32_e32 v203, v83, v83
	ds_write_b128 v192, v[80:83]
	s_waitcnt lgkmcnt(7)
	v_add_f32_e32 v84, v164, v84
	v_add_f32_e32 v85, v165, v85
	v_add_f32_e32 v86, v166, v86
	v_add_f32_e32 v87, v167, v87
	v_fmac_f32_e32 v203, v84, v84
	v_fmac_f32_e32 v203, v85, v85
	v_fmac_f32_e32 v203, v86, v86
	v_fmac_f32_e32 v203, v87, v87
	ds_write_b128 v192, v[84:87] offset:32
	s_waitcnt lgkmcnt(7)
	v_add_f32_e32 v88, v168, v88
	v_add_f32_e32 v89, v169, v89
	v_add_f32_e32 v90, v170, v90
	v_add_f32_e32 v91, v171, v91
	v_fmac_f32_e32 v203, v88, v88
	v_fmac_f32_e32 v203, v89, v89
	v_fmac_f32_e32 v203, v90, v90
	v_fmac_f32_e32 v203, v91, v91
	ds_write_b128 v192, v[88:91] offset:64
	s_waitcnt lgkmcnt(7)
; DI bfr f2bf(float a) { return (bfr)(pack2(a, 0.f) & 0xffffu); }
; DI int crow(int reg, int h) { return (reg & 3) + 8 * (reg >> 2) + 4 * h; }
; template <bool FIRST, bool HAS_H>
; DI void phase_gemm_resid(const Params& p, const bfr* A, const bfr* Wt, const float* gnext, float* ss, char* smem) {
;     ...
;         for (int jh = 0; jh < 2; ++jh) {
;           float xo[2][8];
; #pragma unroll
;           for (int jj = 0; jj < 2; ++jj)
; #pragma unroll
;             for (int q = 0; q < 8; ++q)
;               xo[jj][q] = xsrc[(rbase + i * 32 + crow(qh * 8 + q, 0)) * 1024 + cbase + (jh * 2 + jj) * 32];
; #pragma unroll
;           for (int q = 0; q < 8; ++q) {
;             const int o = (rbase + i * 32 + crow(qh * 8 + q, 0)) * 1024 + cbase;
; #pragma unroll
;             for (int jj = 0; jj < 2; ++jj) {
;               const int j = jh * 2 + jj;
;               const float xn = xo[jj][q] + acc[i][j][qh * 8 + q];
;               X[o + j * 32] = xn;
;               if (HAS_H) Hn[o + j * 32] = f2bf(xn * gnext[cbase + j * 32]);
;               rs[q] += xn * xn;
;             }
	v_add_f32_e32 v92, v172, v92
	v_add_f32_e32 v93, v173, v93
	v_add_f32_e32 v94, v174, v94
	v_add_f32_e32 v95, v175, v95
	v_fmac_f32_e32 v203, v92, v92
	v_fmac_f32_e32 v203, v93, v93
	v_fmac_f32_e32 v203, v94, v94
	v_fmac_f32_e32 v203, v95, v95
	ds_write_b128 v192, v[92:95] offset:96
	s_waitcnt lgkmcnt(7)
	v_add_f32_e32 v64, v176, v64
	v_add_f32_e32 v65, v177, v65
	v_add_f32_e32 v66, v178, v66
	v_add_f32_e32 v67, v179, v67
	v_fmac_f32_e32 v203, v64, v64
	v_fmac_f32_e32 v203, v65, v65
	v_fmac_f32_e32 v203, v66, v66
	v_fmac_f32_e32 v203, v67, v67
	ds_write_b128 v192, v[64:67] offset:128
	s_waitcnt lgkmcnt(7)
	v_add_f32_e32 v68, v180, v68
	v_add_f32_e32 v69, v181, v69
	v_add_f32_e32 v70, v182, v70
	v_add_f32_e32 v71, v183, v71
	v_fmac_f32_e32 v203, v68, v68
	v_fmac_f32_e32 v203, v69, v69
	v_fmac_f32_e32 v203, v70, v70
	v_fmac_f32_e32 v203, v71, v71
	ds_write_b128 v192, v[68:71] offset:160
	s_waitcnt lgkmcnt(7)
	v_add_f32_e32 v72, v184, v72
	v_add_f32_e32 v73, v185, v73
	v_add_f32_e32 v74, v186, v74
	v_add_f32_e32 v75, v187, v75
	v_fmac_f32_e32 v203, v72, v72
	v_fmac_f32_e32 v203, v73, v73
	v_fmac_f32_e32 v203, v74, v74
	v_fmac_f32_e32 v203, v75, v75
	ds_write_b128 v192, v[72:75] offset:192
	s_waitcnt lgkmcnt(7)
	v_add_f32_e32 v76, v188, v76
	v_add_f32_e32 v77, v189, v77
	v_add_f32_e32 v78, v190, v78
	v_add_f32_e32 v79, v191, v79
	v_fmac_f32_e32 v203, v76, v76
	v_fmac_f32_e32 v203, v77, v77
	v_fmac_f32_e32 v203, v78, v78
	v_fmac_f32_e32 v203, v79, v79
	ds_write_b128 v192, v[76:79] offset:224
	ds_read_b128 v[160:163], v198
	ds_read_b128 v[164:167], v198 offset:1088
	ds_read_b128 v[168:171], v198 offset:2176
	ds_read_b128 v[172:175], v198 offset:3264
	ds_read_b128 v[176:179], v198 offset:4352
	ds_read_b128 v[180:183], v198 offset:5440
	ds_read_b128 v[184:187], v198 offset:6528
	ds_read_b128 v[188:191], v198 offset:7616
	s_add_u32 s74, s66, 0x100
	s_addc_u32 s75, s67, 0
	s_waitcnt lgkmcnt(7)
	global_store_dwordx4 v200, v[160:163], s[74:75]
	s_add_u32 s74, s66, 0x4100
	s_addc_u32 s75, s67, 0
	s_waitcnt lgkmcnt(6)
	global_store_dwordx4 v200, v[164:167], s[74:75]
	s_add_u32 s74, s66, 0x8100
	s_addc_u32 s75, s67, 0
	s_waitcnt lgkmcnt(5)
	global_store_dwordx4 v200, v[168:171], s[74:75]
	s_add_u32 s74, s66, 0xc100
	s_addc_u32 s75, s67, 0
	s_waitcnt lgkmcnt(4)
	global_store_dwordx4 v200, v[172:175], s[74:75]
	s_add_u32 s74, s66, 0x10100
	s_addc_u32 s75, s67, 0
	s_waitcnt lgkmcnt(3)
	global_store_dwordx4 v200, v[176:179], s[74:75]
	s_add_u32 s74, s66, 0x14100
	s_addc_u32 s75, s67, 0
	s_waitcnt lgkmcnt(2)
	global_store_dwordx4 v200, v[180:183], s[74:75]
	s_add_u32 s74, s66, 0x18100
	s_addc_u32 s75, s67, 0
	s_waitcnt lgkmcnt(1)
	global_store_dwordx4 v200, v[184:187], s[74:75]
	s_add_u32 s74, s66, 0x1c100
	s_addc_u32 s75, s67, 0
	s_waitcnt lgkmcnt(0)
	global_store_dwordx4 v200, v[188:191], s[74:75]
	global_load_dwordx4 v[160:163], v202, s[70:71] offset:256
	global_load_dwordx4 v[164:167], v202, s[70:71] offset:288
	global_load_dwordx4 v[168:171], v202, s[70:71] offset:320
	global_load_dwordx4 v[172:175], v202, s[70:71] offset:352
	global_load_dwordx4 v[176:179], v202, s[70:71] offset:384
	global_load_dwordx4 v[180:183], v202, s[70:71] offset:416
	global_load_dwordx4 v[184:187], v202, s[70:71] offset:448
	global_load_dwordx4 v[188:191], v202, s[70:71] offset:480
	s_waitcnt vmcnt(7)
	v_mul_f32_e32 v80, v160, v80
	v_mul_f32_e32 v81, v161, v81
	v_mul_f32_e32 v82, v162, v82
	v_mul_f32_e32 v83, v163, v83
	v_cvt_pk_bf16_f32 v80, v80, v81
	v_cvt_pk_bf16_f32 v81, v82, v83
	ds_write_b64 v194, v[80:81]
	s_waitcnt vmcnt(6)
	v_mul_f32_e32 v84, v164, v84
	v_mul_f32_e32 v85, v165, v85
	v_mul_f32_e32 v86, v166, v86
	v_mul_f32_e32 v87, v167, v87
	v_cvt_pk_bf16_f32 v84, v84, v85
	v_cvt_pk_bf16_f32 v85, v86, v87
	ds_write_b64 v194, v[84:85] offset:16
	s_waitcnt vmcnt(5)
	v_mul_f32_e32 v88, v168, v88
	v_mul_f32_e32 v89, v169, v89
	v_mul_f32_e32 v90, v170, v90
	v_mul_f32_e32 v91, v171, v91
	v_cvt_pk_bf16_f32 v88, v88, v89
	v_cvt_pk_bf16_f32 v89, v90, v91
	ds_write_b64 v194, v[88:89] offset:32
	s_waitcnt vmcnt(4)
	v_mul_f32_e32 v92, v172, v92
	v_mul_f32_e32 v93, v173, v93
	v_mul_f32_e32 v94, v174, v94
	v_mul_f32_e32 v95, v175, v95
	v_cvt_pk_bf16_f32 v92, v92, v93
	v_cvt_pk_bf16_f32 v93, v94, v95
	ds_write_b64 v194, v[92:93] offset:48
	s_waitcnt vmcnt(3)
	v_mul_f32_e32 v64, v176, v64
	v_mul_f32_e32 v65, v177, v65
	v_mul_f32_e32 v66, v178, v66
	v_mul_f32_e32 v67, v179, v67
	v_cvt_pk_bf16_f32 v64, v64, v65
	v_cvt_pk_bf16_f32 v65, v66, v67
	ds_write_b64 v194, v[64:65] offset:64
	s_waitcnt vmcnt(2)
	v_mul_f32_e32 v68, v180, v68
	v_mul_f32_e32 v69, v181, v69
	v_mul_f32_e32 v70, v182, v70
	v_mul_f32_e32 v71, v183, v71
	v_cvt_pk_bf16_f32 v68, v68, v69
	v_cvt_pk_bf16_f32 v69, v70, v71
	ds_write_b64 v194, v[68:69] offset:80
	s_waitcnt vmcnt(1)
	v_mul_f32_e32 v72, v184, v72
	v_mul_f32_e32 v73, v185, v73
	v_mul_f32_e32 v74, v186, v74
	v_mul_f32_e32 v75, v187, v75
	v_cvt_pk_bf16_f32 v72, v72, v73
	v_cvt_pk_bf16_f32 v73, v74, v75
	ds_write_b64 v194, v[72:73] offset:96
	s_waitcnt vmcnt(0)
	v_mul_f32_e32 v76, v188, v76
	v_mul_f32_e32 v77, v189, v77
	v_mul_f32_e32 v78, v190, v78
	v_mul_f32_e32 v79, v191, v79
	v_cvt_pk_bf16_f32 v76, v76, v77
	v_cvt_pk_bf16_f32 v77, v78, v79
	ds_write_b64 v194, v[76:77] offset:112
	ds_read_b128 v[160:163], v199
	ds_read_b128 v[164:167], v199 offset:2176
	ds_read_b128 v[168:171], v199 offset:4352
	ds_read_b128 v[172:175], v199 offset:6528
	s_add_u32 s74, s68, 0x80
	s_addc_u32 s75, s69, 0
	s_waitcnt lgkmcnt(3)
	global_store_dwordx4 v201, v[160:163], s[74:75]
	s_add_u32 s74, s68, 0x4080
	s_addc_u32 s75, s69, 0
	s_waitcnt lgkmcnt(2)
; DI bfr f2bf(float a) { return (bfr)(pack2(a, 0.f) & 0xffffu); }
; DI int crow(int reg, int h) { return (reg & 3) + 8 * (reg >> 2) + 4 * h; }
; template <bool FIRST, bool HAS_H>
; DI void phase_gemm_resid(const Params& p, const bfr* A, const bfr* Wt, const float* gnext, float* ss, char* smem) {
;     ...
;         for (int jh = 0; jh < 2; ++jh) {
;           float xo[2][8];
; #pragma unroll
;           for (int jj = 0; jj < 2; ++jj)
; #pragma unroll
;             for (int q = 0; q < 8; ++q)
;               xo[jj][q] = xsrc[(rbase + i * 32 + crow(qh * 8 + q, 0)) * 1024 + cbase + (jh * 2 + jj) * 32];
; #pragma unroll
;           for (int q = 0; q < 8; ++q) {
;             const int o = (rbase + i * 32 + crow(qh * 8 + q, 0)) * 1024 + cbase;
; #pragma unroll
;             for (int jj = 0; jj < 2; ++jj) {
;               const int j = jh * 2 + jj;
;               const float xn = xo[jj][q] + acc[i][j][qh * 8 + q];
;               X[o + j * 32] = xn;
;               if (HAS_H) Hn[o + j * 32] = f2bf(xn * gnext[cbase + j * 32]);
;               rs[q] += xn * xn;
;             }
;           }
	global_store_dwordx4 v201, v[164:167], s[74:75]
	s_add_u32 s74, s68, 0x8080
	s_addc_u32 s75, s69, 0
	s_waitcnt lgkmcnt(1)
	global_store_dwordx4 v201, v[168:171], s[74:75]
	s_add_u32 s74, s68, 0xc080
	s_addc_u32 s75, s69, 0
	s_waitcnt lgkmcnt(0)
	global_store_dwordx4 v201, v[172:175], s[74:75]
	s_waitcnt vmcnt(4)
	ds_write_b128 v198, v[128:131]
	s_waitcnt vmcnt(4)
	ds_write_b128 v198, v[132:135] offset:1088
	s_waitcnt vmcnt(4)
	ds_write_b128 v198, v[136:139] offset:2176
	s_waitcnt vmcnt(4)
	ds_write_b128 v198, v[140:143] offset:3264
	s_waitcnt vmcnt(4)
	ds_write_b128 v198, v[144:147] offset:4352
	s_waitcnt vmcnt(4)
	ds_write_b128 v198, v[148:151] offset:5440
	s_waitcnt vmcnt(4)
	ds_write_b128 v198, v[152:155] offset:6528
	s_waitcnt vmcnt(4)
	ds_write_b128 v198, v[156:159] offset:7616
	s_add_u32 s74, s64, 0x20100
	s_addc_u32 s75, s65, 0
	global_load_dwordx4 v[128:131], v200, s[74:75]
	s_add_u32 s74, s64, 0x24100
	s_addc_u32 s75, s65, 0
	global_load_dwordx4 v[132:135], v200, s[74:75]
	s_add_u32 s74, s64, 0x28100
	s_addc_u32 s75, s65, 0
	global_load_dwordx4 v[136:139], v200, s[74:75]
	s_add_u32 s74, s64, 0x2c100
	s_addc_u32 s75, s65, 0
	global_load_dwordx4 v[140:143], v200, s[74:75]
	s_add_u32 s74, s64, 0x30100
	s_addc_u32 s75, s65, 0
	global_load_dwordx4 v[144:147], v200, s[74:75]
	s_add_u32 s74, s64, 0x34100
	s_addc_u32 s75, s65, 0
	global_load_dwordx4 v[148:151], v200, s[74:75]
	s_add_u32 s74, s64, 0x38100
	s_addc_u32 s75, s65, 0
	global_load_dwordx4 v[152:155], v200, s[74:75]
	s_add_u32 s74, s64, 0x3c100
	s_addc_u32 s75, s65, 0
	global_load_dwordx4 v[156:159], v200, s[74:75]
	ds_read_b128 v[160:163], v192
	ds_read_b128 v[164:167], v192 offset:32
	ds_read_b128 v[168:171], v192 offset:64
	ds_read_b128 v[172:175], v192 offset:96
	ds_read_b128 v[176:179], v192 offset:128
	ds_read_b128 v[180:183], v192 offset:160
	ds_read_b128 v[184:187], v192 offset:192
	ds_read_b128 v[188:191], v192 offset:224
	s_waitcnt lgkmcnt(7)
	v_add_f32_e32 v48, v160, v48
	v_add_f32_e32 v49, v161, v49
	v_add_f32_e32 v50, v162, v50
	v_add_f32_e32 v51, v163, v51
	v_fmac_f32_e32 v204, v48, v48
	v_fmac_f32_e32 v204, v49, v49
	v_fmac_f32_e32 v204, v50, v50
	v_fmac_f32_e32 v204, v51, v51
	ds_write_b128 v192, v[48:51]
	s_waitcnt lgkmcnt(7)
	v_add_f32_e32 v52, v164, v52
	v_add_f32_e32 v53, v165, v53
	v_add_f32_e32 v54, v166, v54
	v_add_f32_e32 v55, v167, v55
	v_fmac_f32_e32 v204, v52, v52
	v_fmac_f32_e32 v204, v53, v53
	v_fmac_f32_e32 v204, v54, v54
	v_fmac_f32_e32 v204, v55, v55
	ds_write_b128 v192, v[52:55] offset:32
	s_waitcnt lgkmcnt(7)
	v_add_f32_e32 v56, v168, v56
	v_add_f32_e32 v57, v169, v57
	v_add_f32_e32 v58, v170, v58
	v_add_f32_e32 v59, v171, v59
	v_fmac_f32_e32 v204, v56, v56
	v_fmac_f32_e32 v204, v57, v57
	v_fmac_f32_e32 v204, v58, v58
	v_fmac_f32_e32 v204, v59, v59
	ds_write_b128 v192, v[56:59] offset:64
	s_waitcnt lgkmcnt(7)
	v_add_f32_e32 v60, v172, v60
	v_add_f32_e32 v61, v173, v61
	v_add_f32_e32 v62, v174, v62
	v_add_f32_e32 v63, v175, v63
	v_fmac_f32_e32 v204, v60, v60
	v_fmac_f32_e32 v204, v61, v61
	v_fmac_f32_e32 v204, v62, v62
	v_fmac_f32_e32 v204, v63, v63
	ds_write_b128 v192, v[60:63] offset:96
	s_waitcnt lgkmcnt(7)
	v_add_f32_e32 v32, v176, v32
	v_add_f32_e32 v33, v177, v33
	v_add_f32_e32 v34, v178, v34
	v_add_f32_e32 v35, v179, v35
	v_fmac_f32_e32 v204, v32, v32
	v_fmac_f32_e32 v204, v33, v33
	v_fmac_f32_e32 v204, v34, v34
	v_fmac_f32_e32 v204, v35, v35
	ds_write_b128 v192, v[32:35] offset:128
	s_waitcnt lgkmcnt(7)
	v_add_f32_e32 v36, v180, v36
	v_add_f32_e32 v37, v181, v37
	v_add_f32_e32 v38, v182, v38
	v_add_f32_e32 v39, v183, v39
	v_fmac_f32_e32 v204, v36, v36
	v_fmac_f32_e32 v204, v37, v37
	v_fmac_f32_e32 v204, v38, v38
	v_fmac_f32_e32 v204, v39, v39
	ds_write_b128 v192, v[36:39] offset:160
	s_waitcnt lgkmcnt(7)
	v_add_f32_e32 v40, v184, v40
	v_add_f32_e32 v41, v185, v41
	v_add_f32_e32 v42, v186, v42
	v_add_f32_e32 v43, v187, v43
	v_fmac_f32_e32 v204, v40, v40
	v_fmac_f32_e32 v204, v41, v41
	v_fmac_f32_e32 v204, v42, v42
	v_fmac_f32_e32 v204, v43, v43
	ds_write_b128 v192, v[40:43] offset:192
	s_waitcnt lgkmcnt(7)
	v_add_f32_e32 v44, v188, v44
	v_add_f32_e32 v45, v189, v45
	v_add_f32_e32 v46, v190, v46
	v_add_f32_e32 v47, v191, v47
	v_fmac_f32_e32 v204, v44, v44
	v_fmac_f32_e32 v204, v45, v45
	v_fmac_f32_e32 v204, v46, v46
	v_fmac_f32_e32 v204, v47, v47
	ds_write_b128 v192, v[44:47] offset:224
	ds_read_b128 v[160:163], v198
	ds_read_b128 v[164:167], v198 offset:1088
	ds_read_b128 v[168:171], v198 offset:2176
	ds_read_b128 v[172:175], v198 offset:3264
	ds_read_b128 v[176:179], v198 offset:4352
	ds_read_b128 v[180:183], v198 offset:5440
	ds_read_b128 v[184:187], v198 offset:6528
	ds_read_b128 v[188:191], v198 offset:7616
	s_add_u32 s74, s66, 0x20000
	s_addc_u32 s75, s67, 0
	s_waitcnt lgkmcnt(7)
	global_store_dwordx4 v200, v[160:163], s[74:75]
	s_add_u32 s74, s66, 0x24000
	s_addc_u32 s75, s67, 0
	s_waitcnt lgkmcnt(6)
	global_store_dwordx4 v200, v[164:167], s[74:75]
	s_add_u32 s74, s66, 0x28000
	s_addc_u32 s75, s67, 0
	s_waitcnt lgkmcnt(5)
	global_store_dwordx4 v200, v[168:171], s[74:75]
	s_add_u32 s74, s66, 0x2c000
	s_addc_u32 s75, s67, 0
	s_waitcnt lgkmcnt(4)
	global_store_dwordx4 v200, v[172:175], s[74:75]
	s_add_u32 s74, s66, 0x30000
	s_addc_u32 s75, s67, 0
	s_waitcnt lgkmcnt(3)
	global_store_dwordx4 v200, v[176:179], s[74:75]
	s_add_u32 s74, s66, 0x34000
	s_addc_u32 s75, s67, 0
	s_waitcnt lgkmcnt(2)
	global_store_dwordx4 v200, v[180:183], s[74:75]
	s_add_u32 s74, s66, 0x38000
	s_addc_u32 s75, s67, 0
	s_waitcnt lgkmcnt(1)
	global_store_dwordx4 v200, v[184:187], s[74:75]
	s_add_u32 s74, s66, 0x3c000
	s_addc_u32 s75, s67, 0
	s_waitcnt lgkmcnt(0)
; DI bfr f2bf(float a) { return (bfr)(pack2(a, 0.f) & 0xffffu); }
; DI int crow(int reg, int h) { return (reg & 3) + 8 * (reg >> 2) + 4 * h; }
; template <bool FIRST, bool HAS_H>
; DI void phase_gemm_resid(const Params& p, const bfr* A, const bfr* Wt, const float* gnext, float* ss, char* smem) {
;     ...
;           for (int jj = 0; jj < 2; ++jj)
; #pragma unroll
;             for (int q = 0; q < 8; ++q)
;               xo[jj][q] = xsrc[(rbase + i * 32 + crow(qh * 8 + q, 0)) * 1024 + cbase + (jh * 2 + jj) * 32];
; #pragma unroll
;           for (int q = 0; q < 8; ++q) {
;             const int o = (rbase + i * 32 + crow(qh * 8 + q, 0)) * 1024 + cbase;
; #pragma unroll
;             for (int jj = 0; jj < 2; ++jj) {
;               const int j = jh * 2 + jj;
;               const float xn = xo[jj][q] + acc[i][j][qh * 8 + q];
;               X[o + j * 32] = xn;
;               if (HAS_H) Hn[o + j * 32] = f2bf(xn * gnext[cbase + j * 32]);
;               rs[q] += xn * xn;
;             }
;           }
	global_store_dwordx4 v200, v[188:191], s[74:75]
	global_load_dwordx4 v[160:163], v202, s[70:71]
	global_load_dwordx4 v[164:167], v202, s[70:71] offset:32
	global_load_dwordx4 v[168:171], v202, s[70:71] offset:64
	global_load_dwordx4 v[172:175], v202, s[70:71] offset:96
	global_load_dwordx4 v[176:179], v202, s[70:71] offset:128
	global_load_dwordx4 v[180:183], v202, s[70:71] offset:160
	global_load_dwordx4 v[184:187], v202, s[70:71] offset:192
	global_load_dwordx4 v[188:191], v202, s[70:71] offset:224
	s_waitcnt vmcnt(7)
	v_mul_f32_e32 v48, v160, v48
	v_mul_f32_e32 v49, v161, v49
	v_mul_f32_e32 v50, v162, v50
	v_mul_f32_e32 v51, v163, v51
	v_cvt_pk_bf16_f32 v48, v48, v49
	v_cvt_pk_bf16_f32 v49, v50, v51
	ds_write_b64 v194, v[48:49]
	s_waitcnt vmcnt(6)
	v_mul_f32_e32 v52, v164, v52
	v_mul_f32_e32 v53, v165, v53
	v_mul_f32_e32 v54, v166, v54
	v_mul_f32_e32 v55, v167, v55
	v_cvt_pk_bf16_f32 v52, v52, v53
	v_cvt_pk_bf16_f32 v53, v54, v55
	ds_write_b64 v194, v[52:53] offset:16
	s_waitcnt vmcnt(5)
	v_mul_f32_e32 v56, v168, v56
	v_mul_f32_e32 v57, v169, v57
	v_mul_f32_e32 v58, v170, v58
	v_mul_f32_e32 v59, v171, v59
	v_cvt_pk_bf16_f32 v56, v56, v57
	v_cvt_pk_bf16_f32 v57, v58, v59
	ds_write_b64 v194, v[56:57] offset:32
	s_waitcnt vmcnt(4)
	v_mul_f32_e32 v60, v172, v60
	v_mul_f32_e32 v61, v173, v61
	v_mul_f32_e32 v62, v174, v62
	v_mul_f32_e32 v63, v175, v63
	v_cvt_pk_bf16_f32 v60, v60, v61
	v_cvt_pk_bf16_f32 v61, v62, v63
	ds_write_b64 v194, v[60:61] offset:48
	s_waitcnt vmcnt(3)
	v_mul_f32_e32 v32, v176, v32
	v_mul_f32_e32 v33, v177, v33
	v_mul_f32_e32 v34, v178, v34
	v_mul_f32_e32 v35, v179, v35
	v_cvt_pk_bf16_f32 v32, v32, v33
	v_cvt_pk_bf16_f32 v33, v34, v35
	ds_write_b64 v194, v[32:33] offset:64
	s_waitcnt vmcnt(2)
	v_mul_f32_e32 v36, v180, v36
	v_mul_f32_e32 v37, v181, v37
	v_mul_f32_e32 v38, v182, v38
	v_mul_f32_e32 v39, v183, v39
	v_cvt_pk_bf16_f32 v36, v36, v37
	v_cvt_pk_bf16_f32 v37, v38, v39
	ds_write_b64 v194, v[36:37] offset:80
	s_waitcnt vmcnt(1)
	v_mul_f32_e32 v40, v184, v40
	v_mul_f32_e32 v41, v185, v41
	v_mul_f32_e32 v42, v186, v42
	v_mul_f32_e32 v43, v187, v43
	v_cvt_pk_bf16_f32 v40, v40, v41
	v_cvt_pk_bf16_f32 v41, v42, v43
	ds_write_b64 v194, v[40:41] offset:96
	s_waitcnt vmcnt(0)
	v_mul_f32_e32 v44, v188, v44
	v_mul_f32_e32 v45, v189, v45
	v_mul_f32_e32 v46, v190, v46
	v_mul_f32_e32 v47, v191, v47
	v_cvt_pk_bf16_f32 v44, v44, v45
	v_cvt_pk_bf16_f32 v45, v46, v47
	ds_write_b64 v194, v[44:45] offset:112
	ds_read_b128 v[160:163], v199
	ds_read_b128 v[164:167], v199 offset:2176
	ds_read_b128 v[168:171], v199 offset:4352
	ds_read_b128 v[172:175], v199 offset:6528
	s_add_u32 s74, s68, 0x10000
	s_addc_u32 s75, s69, 0
	s_waitcnt lgkmcnt(3)
	global_store_dwordx4 v201, v[160:163], s[74:75]
	s_add_u32 s74, s68, 0x14000
	s_addc_u32 s75, s69, 0
	s_waitcnt lgkmcnt(2)
	global_store_dwordx4 v201, v[164:167], s[74:75]
	s_add_u32 s74, s68, 0x18000
	s_addc_u32 s75, s69, 0
	s_waitcnt lgkmcnt(1)
	global_store_dwordx4 v201, v[168:171], s[74:75]
	s_add_u32 s74, s68, 0x1c000
	s_addc_u32 s75, s69, 0
	s_waitcnt lgkmcnt(0)
	global_store_dwordx4 v201, v[172:175], s[74:75]
	s_waitcnt vmcnt(4)
	ds_write_b128 v198, v[128:131]
	s_waitcnt vmcnt(4)
	ds_write_b128 v198, v[132:135] offset:1088
	s_waitcnt vmcnt(4)
	ds_write_b128 v198, v[136:139] offset:2176
	s_waitcnt vmcnt(4)
	ds_write_b128 v198, v[140:143] offset:3264
	s_waitcnt vmcnt(4)
	ds_write_b128 v198, v[144:147] offset:4352
	s_waitcnt vmcnt(4)
	ds_write_b128 v198, v[148:151] offset:5440
	s_waitcnt vmcnt(4)
	ds_write_b128 v198, v[152:155] offset:6528
	s_waitcnt vmcnt(4)
	ds_write_b128 v198, v[156:159] offset:7616
	ds_read_b128 v[160:163], v192
	ds_read_b128 v[164:167], v192 offset:32
	ds_read_b128 v[168:171], v192 offset:64
	ds_read_b128 v[172:175], v192 offset:96
	ds_read_b128 v[176:179], v192 offset:128
	ds_read_b128 v[180:183], v192 offset:160
	ds_read_b128 v[184:187], v192 offset:192
	ds_read_b128 v[188:191], v192 offset:224
	s_waitcnt lgkmcnt(7)
	v_add_f32_e32 v16, v160, v16
	v_add_f32_e32 v17, v161, v17
	v_add_f32_e32 v18, v162, v18
	v_add_f32_e32 v19, v163, v19
	v_fmac_f32_e32 v204, v16, v16
	v_fmac_f32_e32 v204, v17, v17
	v_fmac_f32_e32 v204, v18, v18
	v_fmac_f32_e32 v204, v19, v19
	ds_write_b128 v192, v[16:19]
	s_waitcnt lgkmcnt(7)
	v_add_f32_e32 v20, v164, v20
	v_add_f32_e32 v21, v165, v21
	v_add_f32_e32 v22, v166, v22
	v_add_f32_e32 v23, v167, v23
	v_fmac_f32_e32 v204, v20, v20
	v_fmac_f32_e32 v204, v21, v21
	v_fmac_f32_e32 v204, v22, v22
	v_fmac_f32_e32 v204, v23, v23
	ds_write_b128 v192, v[20:23] offset:32
	s_waitcnt lgkmcnt(7)
	v_add_f32_e32 v24, v168, v24
	v_add_f32_e32 v25, v169, v25
	v_add_f32_e32 v26, v170, v26
	v_add_f32_e32 v27, v171, v27
	v_fmac_f32_e32 v204, v24, v24
	v_fmac_f32_e32 v204, v25, v25
	v_fmac_f32_e32 v204, v26, v26
	v_fmac_f32_e32 v204, v27, v27
	ds_write_b128 v192, v[24:27] offset:64
	s_waitcnt lgkmcnt(7)
	v_add_f32_e32 v28, v172, v28
	v_add_f32_e32 v29, v173, v29
	v_add_f32_e32 v30, v174, v30
	v_add_f32_e32 v31, v175, v31
	v_fmac_f32_e32 v204, v28, v28
	v_fmac_f32_e32 v204, v29, v29
	v_fmac_f32_e32 v204, v30, v30
	v_fmac_f32_e32 v204, v31, v31
	ds_write_b128 v192, v[28:31] offset:96
	s_waitcnt lgkmcnt(7)
	v_add_f32_e32 v0, v176, v0
	v_add_f32_e32 v1, v177, v1
	v_add_f32_e32 v2, v178, v2
	v_add_f32_e32 v3, v179, v3
	v_fmac_f32_e32 v204, v0, v0
	v_fmac_f32_e32 v204, v1, v1
	v_fmac_f32_e32 v204, v2, v2
	v_fmac_f32_e32 v204, v3, v3
	ds_write_b128 v192, v[0:3] offset:128
	s_waitcnt lgkmcnt(7)
	v_add_f32_e32 v4, v180, v4
	v_add_f32_e32 v5, v181, v5
	v_add_f32_e32 v6, v182, v6
	v_add_f32_e32 v7, v183, v7
	v_fmac_f32_e32 v204, v4, v4
	v_fmac_f32_e32 v204, v5, v5
	v_fmac_f32_e32 v204, v6, v6
	v_fmac_f32_e32 v204, v7, v7
	ds_write_b128 v192, v[4:7] offset:160
	s_waitcnt lgkmcnt(7)
; DI bfr f2bf(float a) { return (bfr)(pack2(a, 0.f) & 0xffffu); }
; DI int crow(int reg, int h) { return (reg & 3) + 8 * (reg >> 2) + 4 * h; }
; template <bool FIRST, bool HAS_H>
; DI void phase_gemm_resid(const Params& p, const bfr* A, const bfr* Wt, const float* gnext, float* ss, char* smem) {
;     ...
;           for (int q = 0; q < 8; ++q) {
;             const int o = (rbase + i * 32 + crow(qh * 8 + q, 0)) * 1024 + cbase;
; #pragma unroll
;             for (int jj = 0; jj < 2; ++jj) {
;               const int j = jh * 2 + jj;
;               const float xn = xo[jj][q] + acc[i][j][qh * 8 + q];
;               X[o + j * 32] = xn;
;               if (HAS_H) Hn[o + j * 32] = f2bf(xn * gnext[cbase + j * 32]);
;               rs[q] += xn * xn;
;             }
;           }
;         }
; #pragma unroll
;         for (int q = 0; q < 8; ++q) rs[q] = half32_sum_hi(rs[q]);
;         if (r == 31) {
; #pragma unroll
;           for (int q = 0; q < 8; ++q) unsafeAtomicAdd(ss + rbase + i * 32 + crow(qh * 8 + q, 0), rs[q]);
;         }
	v_add_f32_e32 v8, v184, v8
	v_add_f32_e32 v9, v185, v9
	v_add_f32_e32 v10, v186, v10
	v_add_f32_e32 v11, v187, v11
	v_fmac_f32_e32 v204, v8, v8
	v_fmac_f32_e32 v204, v9, v9
	v_fmac_f32_e32 v204, v10, v10
	v_fmac_f32_e32 v204, v11, v11
	ds_write_b128 v192, v[8:11] offset:192
	s_waitcnt lgkmcnt(7)
	v_add_f32_e32 v12, v188, v12
	v_add_f32_e32 v13, v189, v13
	v_add_f32_e32 v14, v190, v14
	v_add_f32_e32 v15, v191, v15
	v_fmac_f32_e32 v204, v12, v12
	v_fmac_f32_e32 v204, v13, v13
	v_fmac_f32_e32 v204, v14, v14
	v_fmac_f32_e32 v204, v15, v15
	ds_write_b128 v192, v[12:15] offset:224
	ds_read_b128 v[160:163], v198
	ds_read_b128 v[164:167], v198 offset:1088
	ds_read_b128 v[168:171], v198 offset:2176
	ds_read_b128 v[172:175], v198 offset:3264
	ds_read_b128 v[176:179], v198 offset:4352
	ds_read_b128 v[180:183], v198 offset:5440
	ds_read_b128 v[184:187], v198 offset:6528
	ds_read_b128 v[188:191], v198 offset:7616
	s_add_u32 s74, s66, 0x20100
	s_addc_u32 s75, s67, 0
	s_waitcnt lgkmcnt(7)
	global_store_dwordx4 v200, v[160:163], s[74:75]
	s_add_u32 s74, s66, 0x24100
	s_addc_u32 s75, s67, 0
	s_waitcnt lgkmcnt(6)
	global_store_dwordx4 v200, v[164:167], s[74:75]
	s_add_u32 s74, s66, 0x28100
	s_addc_u32 s75, s67, 0
	s_waitcnt lgkmcnt(5)
	global_store_dwordx4 v200, v[168:171], s[74:75]
	s_add_u32 s74, s66, 0x2c100
	s_addc_u32 s75, s67, 0
	s_waitcnt lgkmcnt(4)
	global_store_dwordx4 v200, v[172:175], s[74:75]
	s_add_u32 s74, s66, 0x30100
	s_addc_u32 s75, s67, 0
	s_waitcnt lgkmcnt(3)
	global_store_dwordx4 v200, v[176:179], s[74:75]
	s_add_u32 s74, s66, 0x34100
	s_addc_u32 s75, s67, 0
	s_waitcnt lgkmcnt(2)
	global_store_dwordx4 v200, v[180:183], s[74:75]
	s_add_u32 s74, s66, 0x38100
	s_addc_u32 s75, s67, 0
	s_waitcnt lgkmcnt(1)
	global_store_dwordx4 v200, v[184:187], s[74:75]
	s_add_u32 s74, s66, 0x3c100
	s_addc_u32 s75, s67, 0
	s_waitcnt lgkmcnt(0)
	global_store_dwordx4 v200, v[188:191], s[74:75]
	global_load_dwordx4 v[160:163], v202, s[70:71] offset:256
	global_load_dwordx4 v[164:167], v202, s[70:71] offset:288
	global_load_dwordx4 v[168:171], v202, s[70:71] offset:320
	global_load_dwordx4 v[172:175], v202, s[70:71] offset:352
	global_load_dwordx4 v[176:179], v202, s[70:71] offset:384
	global_load_dwordx4 v[180:183], v202, s[70:71] offset:416
	global_load_dwordx4 v[184:187], v202, s[70:71] offset:448
	global_load_dwordx4 v[188:191], v202, s[70:71] offset:480
	s_waitcnt vmcnt(7)
	v_mul_f32_e32 v16, v160, v16
	v_mul_f32_e32 v17, v161, v17
	v_mul_f32_e32 v18, v162, v18
	v_mul_f32_e32 v19, v163, v19
	v_cvt_pk_bf16_f32 v16, v16, v17
	v_cvt_pk_bf16_f32 v17, v18, v19
	ds_write_b64 v194, v[16:17]
	s_waitcnt vmcnt(6)
	v_mul_f32_e32 v20, v164, v20
	v_mul_f32_e32 v21, v165, v21
	v_mul_f32_e32 v22, v166, v22
	v_mul_f32_e32 v23, v167, v23
	v_cvt_pk_bf16_f32 v20, v20, v21
	v_cvt_pk_bf16_f32 v21, v22, v23
	ds_write_b64 v194, v[20:21] offset:16
	s_waitcnt vmcnt(5)
	v_mul_f32_e32 v24, v168, v24
	v_mul_f32_e32 v25, v169, v25
	v_mul_f32_e32 v26, v170, v26
	v_mul_f32_e32 v27, v171, v27
	v_cvt_pk_bf16_f32 v24, v24, v25
	v_cvt_pk_bf16_f32 v25, v26, v27
	ds_write_b64 v194, v[24:25] offset:32
	s_waitcnt vmcnt(4)
	v_mul_f32_e32 v28, v172, v28
	v_mul_f32_e32 v29, v173, v29
	v_mul_f32_e32 v30, v174, v30
	v_mul_f32_e32 v31, v175, v31
	v_cvt_pk_bf16_f32 v28, v28, v29
	v_cvt_pk_bf16_f32 v29, v30, v31
	ds_write_b64 v194, v[28:29] offset:48
	s_waitcnt vmcnt(3)
	v_mul_f32_e32 v0, v176, v0
	v_mul_f32_e32 v1, v177, v1
	v_mul_f32_e32 v2, v178, v2
	v_mul_f32_e32 v3, v179, v3
	v_cvt_pk_bf16_f32 v0, v0, v1
	v_cvt_pk_bf16_f32 v1, v2, v3
	ds_write_b64 v194, v[0:1] offset:64
	s_waitcnt vmcnt(2)
	v_mul_f32_e32 v4, v180, v4
	v_mul_f32_e32 v5, v181, v5
	v_mul_f32_e32 v6, v182, v6
	v_mul_f32_e32 v7, v183, v7
	v_cvt_pk_bf16_f32 v4, v4, v5
	v_cvt_pk_bf16_f32 v5, v6, v7
	ds_write_b64 v194, v[4:5] offset:80
	s_waitcnt vmcnt(1)
	v_mul_f32_e32 v8, v184, v8
	v_mul_f32_e32 v9, v185, v9
	v_mul_f32_e32 v10, v186, v10
	v_mul_f32_e32 v11, v187, v11
	v_cvt_pk_bf16_f32 v8, v8, v9
	v_cvt_pk_bf16_f32 v9, v10, v11
	ds_write_b64 v194, v[8:9] offset:96
	s_waitcnt vmcnt(0)
	v_mul_f32_e32 v12, v188, v12
	v_mul_f32_e32 v13, v189, v13
	v_mul_f32_e32 v14, v190, v14
	v_mul_f32_e32 v15, v191, v15
	v_cvt_pk_bf16_f32 v12, v12, v13
	v_cvt_pk_bf16_f32 v13, v14, v15
	ds_write_b64 v194, v[12:13] offset:112
	ds_read_b128 v[160:163], v199
	ds_read_b128 v[164:167], v199 offset:2176
	ds_read_b128 v[168:171], v199 offset:4352
	ds_read_b128 v[172:175], v199 offset:6528
	s_add_u32 s74, s68, 0x10080
	s_addc_u32 s75, s69, 0
	s_waitcnt lgkmcnt(3)
	global_store_dwordx4 v201, v[160:163], s[74:75]
	s_add_u32 s74, s68, 0x14080
	s_addc_u32 s75, s69, 0
	s_waitcnt lgkmcnt(2)
	global_store_dwordx4 v201, v[164:167], s[74:75]
	s_add_u32 s74, s68, 0x18080
	s_addc_u32 s75, s69, 0
	s_waitcnt lgkmcnt(1)
	global_store_dwordx4 v201, v[168:171], s[74:75]
	s_add_u32 s74, s68, 0x1c080
	s_addc_u32 s75, s69, 0
	s_waitcnt lgkmcnt(0)
	global_store_dwordx4 v201, v[172:175], s[74:75]
	s_load_dwordx2 s[64:65], s[92:93], 0x140
	ds_bpermute_b32 v208, v206, v203
	ds_bpermute_b32 v209, v206, v204
	s_waitcnt lgkmcnt(0)
	s_add_u32 s64, s64, 0x10200
	s_addc_u32 s65, s65, 0
	v_add_f32_e32 v208, v208, v203
	v_add_f32_e32 v209, v209, v204
	s_mov_b32 exec_hi, 0
	s_nop 1
	global_atomic_add_f32 v205, v208, s[64:65]
	global_atomic_add_f32 v205, v209, s[64:65] offset:128
	s_mov_b64 exec, -1
	v_readlane_b32 s64, v207, 0
	v_readlane_b32 s65, v207, 1
	v_readlane_b32 s66, v207, 2
	v_readlane_b32 s67, v207, 3
	v_readlane_b32 s68, v207, 4
	v_readlane_b32 s69, v207, 5
	v_readlane_b32 s70, v207, 6
	v_readlane_b32 s71, v207, 7
	v_readlane_b32 s72, v207, 8
	v_readlane_b32 s73, v207, 9
	v_readlane_b32 s74, v207, 10
	v_readlane_b32 s75, v207, 11
	v_readlane_b32 s76, v207, 12
	v_readlane_b32 s77, v207, 13
	v_readlane_b32 s78, v207, 14
	v_readlane_b32 s79, v207, 15
	s_nop 7
	s_branch .LBB0_1096

; #define MFMA32(a, b, c) __builtin_amdgcn_mfma_f32_32x32x16_bf16((a), (b), (c), 0, 0, 0)
; #define GA_LOAD(pr_) do { _Pragma("unroll") for (int i = 0; i < 4; ++i) ra[i] = *(const u32x4*)(Ab + (i * 32) * lda + (pr_) * 64); } while (0)
; #define GB_LOAD(kt_) do { const bfr* bk_ = Bb + (kt_) * NB * 32; \
;     _Pragma("unroll") for (int i = 0; i < 4; ++i) rb[i] = *(const u32x4*)(bk_ + (i * 64) * 32); } while (0)
; #define G_STORE(kt_) do { bfr* as_ = S0 + ((kt_) & 1) * GSTAGE; bfr* bs_ = as_ + 128 * 40; \
;     if (apar == ((kt_) & 1)) { _Pragma("unroll") for (int i = 0; i < 4; ++i) *(u32x4*)(as_ + asoff + i * 32 * 40) = ra[i]; } \
;     _Pragma("unroll") for (int i = 0; i < 4; ++i) *(u32x4*)(bs_ + bsoff + i * 64 * 40) = rb[i]; } while (0)
; template <int lda>
; DI void gemm_mainloop(const bfr* __restrict__ A, const bfr* __restrict__ Bt, int NB, int K, int m0, int n0, char* smem, f32x16 (&acc)[2][4]) {
;     ...
; #pragma unroll
;   for (int i = 0; i < 2; ++i)
; #pragma unroll
;     for (int j = 0; j < 4; ++j)
; #pragma unroll
;       for (int q = 0; q < 16; ++q) acc[i][j][q] = 0.f;
;   u32x4 ra[4], rb[4];
;   const int nk = K >> 5;
;   const int arow = tid >> 3, ac8 = tid & 7, apar = ac8 >> 2;
;   const bfr* Ab = A + (m0 + arow) * lda + ac8 * 8;
;   const int asoff = arow * 40 + (ac8 & 3) * 8;
;   const int brow = tid >> 2, bc4 = tid & 3;
;   const bfr* Bb = Bt + (n0 + brow) * 32 + bc4 * 8;
;   const int bsoff = brow * 40 + bc4 * 8;
;     ...
;   GA_LOAD(0);
;   GB_LOAD(0);
;   G_STORE(0);
;   GB_LOAD(1);
;   __syncthreads();
;   for (int kt = 0; kt < nk; ++kt) {
;     if (kt + 1 < nk) G_STORE(kt + 1);
;     if (kt + 2 < nk) {
;       GB_LOAD(kt + 2);
;       if ((kt & 1) == 0) GA_LOAD((kt >> 1) + 1);
;     }
;     const bfr* As = S0 + (kt & 1) * GSTAGE;
;     const bfr* Bs = As + 128 * 40;
; #pragma unroll
;     for (int ks = 0; ks < 2; ++ks) {
;       bf16x8 af[2], bfg[4];
; #pragma unroll
;       for (int i = 0; i < 2; ++i) af[i] = *(const bf16x8*)(As + (wr * 64 + i * 32 + r) * 40 + ks * 16 + hl * 8);
; #pragma unroll
;       for (int j = 0; j < 4; ++j) bfg[j] = *(const bf16x8*)(Bs + (wc * 128 + j * 32 + r) * 40 + ks * 16 + hl * 8);
; #pragma unroll
;       for (int i = 0; i < 2; ++i)
; #pragma unroll
;         for (int j = 0; j < 4; ++j) acc[i][j] = MFMA32(af[i], bfg[j], acc[i][j]);
.Lp12_nostag:
	v_mov_b32_e32 v112, 0
	v_mov_b32_e32 v113, 0
	v_mov_b32_e32 v114, 0
	v_mov_b32_e32 v115, 0
	v_mov_b32_e32 v116, 0
	v_mov_b32_e32 v117, 0
	v_mov_b32_e32 v118, 0
	v_mov_b32_e32 v119, 0
	v_mov_b32_e32 v120, 0
	v_mov_b32_e32 v121, 0
	v_mov_b32_e32 v122, 0
	v_mov_b32_e32 v123, 0
	v_mov_b32_e32 v124, 0
	v_mov_b32_e32 v125, 0
	v_mov_b32_e32 v126, 0
	v_mov_b32_e32 v127, 0
	v_mov_b32_e32 v96, 0
	v_mov_b32_e32 v97, 0
	v_mov_b32_e32 v98, 0
	v_mov_b32_e32 v99, 0
	v_mov_b32_e32 v100, 0
	v_mov_b32_e32 v101, 0
	v_mov_b32_e32 v102, 0
	v_mov_b32_e32 v103, 0
	v_mov_b32_e32 v104, 0
	v_mov_b32_e32 v105, 0
	v_mov_b32_e32 v106, 0
	v_mov_b32_e32 v107, 0
	v_mov_b32_e32 v108, 0
	v_mov_b32_e32 v109, 0
	v_mov_b32_e32 v110, 0
	v_mov_b32_e32 v111, 0
	v_mov_b32_e32 v80, 0
	v_mov_b32_e32 v81, 0
	v_mov_b32_e32 v82, 0
	v_mov_b32_e32 v83, 0
	v_mov_b32_e32 v84, 0
	v_mov_b32_e32 v85, 0
	v_mov_b32_e32 v86, 0
	v_mov_b32_e32 v87, 0
	v_mov_b32_e32 v88, 0
	v_mov_b32_e32 v89, 0
	v_mov_b32_e32 v90, 0
	v_mov_b32_e32 v91, 0
	v_mov_b32_e32 v92, 0
	v_mov_b32_e32 v93, 0
	v_mov_b32_e32 v94, 0
	v_mov_b32_e32 v95, 0
	v_mov_b32_e32 v64, 0
	v_mov_b32_e32 v65, 0
	v_mov_b32_e32 v66, 0
	v_mov_b32_e32 v67, 0
	v_mov_b32_e32 v68, 0
	v_mov_b32_e32 v69, 0
	v_mov_b32_e32 v70, 0
	v_mov_b32_e32 v71, 0
	v_mov_b32_e32 v72, 0
	v_mov_b32_e32 v73, 0
	v_mov_b32_e32 v74, 0
	v_mov_b32_e32 v75, 0
	v_mov_b32_e32 v76, 0
	v_mov_b32_e32 v77, 0
	v_mov_b32_e32 v78, 0
	v_mov_b32_e32 v79, 0
	v_mov_b32_e32 v48, 0
	v_mov_b32_e32 v49, 0
	v_mov_b32_e32 v50, 0
	v_mov_b32_e32 v51, 0
	v_mov_b32_e32 v52, 0
	v_mov_b32_e32 v53, 0
	v_mov_b32_e32 v54, 0
	v_mov_b32_e32 v55, 0
	v_mov_b32_e32 v56, 0
	v_mov_b32_e32 v57, 0
	v_mov_b32_e32 v58, 0
	v_mov_b32_e32 v59, 0
	v_mov_b32_e32 v60, 0
	v_mov_b32_e32 v61, 0
	v_mov_b32_e32 v62, 0
	v_mov_b32_e32 v63, 0
	v_mov_b32_e32 v32, 0
	v_mov_b32_e32 v33, 0
	v_mov_b32_e32 v34, 0
	v_mov_b32_e32 v35, 0
	v_mov_b32_e32 v36, 0
	v_mov_b32_e32 v37, 0
	v_mov_b32_e32 v38, 0
	v_mov_b32_e32 v39, 0
	v_mov_b32_e32 v40, 0
	v_mov_b32_e32 v41, 0
	v_mov_b32_e32 v42, 0
	v_mov_b32_e32 v43, 0
	v_mov_b32_e32 v44, 0
	v_mov_b32_e32 v45, 0
	v_mov_b32_e32 v46, 0
	v_mov_b32_e32 v47, 0
	v_mov_b32_e32 v16, 0
	v_mov_b32_e32 v17, 0
	v_mov_b32_e32 v18, 0
	v_mov_b32_e32 v19, 0
	v_mov_b32_e32 v20, 0
	v_mov_b32_e32 v21, 0
	v_mov_b32_e32 v22, 0
	v_mov_b32_e32 v23, 0
	v_mov_b32_e32 v24, 0
	v_mov_b32_e32 v25, 0
	v_mov_b32_e32 v26, 0
	v_mov_b32_e32 v27, 0
	v_mov_b32_e32 v28, 0
	v_mov_b32_e32 v29, 0
	v_mov_b32_e32 v30, 0
	v_mov_b32_e32 v31, 0
	v_mov_b32_e32 v0, 0
	v_mov_b32_e32 v1, 0
	v_mov_b32_e32 v2, 0
	v_mov_b32_e32 v3, 0
	v_mov_b32_e32 v4, 0
	v_mov_b32_e32 v5, 0
	v_mov_b32_e32 v6, 0
	v_mov_b32_e32 v7, 0
	v_mov_b32_e32 v8, 0
	v_mov_b32_e32 v9, 0
	v_mov_b32_e32 v10, 0
	v_mov_b32_e32 v11, 0
	v_mov_b32_e32 v12, 0
	v_mov_b32_e32 v13, 0
	v_mov_b32_e32 v14, 0
	v_mov_b32_e32 v15, 0
	s_waitcnt vmcnt(6)
	s_barrier
	s_mul_i32 s74, s71, 0x6000
	s_add_u32 s75, s74, 0x2000
	s_cmp_eq_u32 s71, 2
	s_cselect_b32 s75, 0x10000, s75
	v_add_u32_e32 v183, s74, v179
	v_add_u32_e32 v185, s75, v181
	v_add_u32_e32 v184, s74, v180
	v_add_u32_e32 v186, s75, v182
	s_add_u32 s71, s71, 1
	s_cmp_eq_u32 s71, 3
	s_cselect_b32 s71, 0, s71
	ds_read_b128 v[128:131], v183
	ds_read_b128 v[144:147], v185
	ds_read_b128 v[148:151], v185 offset:2048
	ds_read_b128 v[152:155], v185 offset:4096
	ds_read_b128 v[156:159], v185 offset:6144
	ds_read_b128 v[132:135], v183 offset:2048
	ds_read_b128 v[136:139], v184
	ds_read_b128 v[160:163], v186
	ds_read_b128 v[164:167], v186 offset:2048
	ds_read_b128 v[168:171], v186 offset:4096
	ds_read_b128 v[172:175], v186 offset:6144
	ds_read_b128 v[140:143], v184 offset:2048
	s_waitcnt lgkmcnt(10)
	v_mfma_f32_32x32x16_bf16 v[112:127], v[144:147], v[128:131], v[112:127]
	s_mul_i32 s74, s70, 0x6000
	s_add_u32 s75, s74, s68
	s_mov_b32 m0, s75
	s_add_u32 s76, s74, 0x2000
	s_cmp_eq_u32 s70, 2
	s_cselect_b32 s76, 0x10000, s76
	global_load_lds_dwordx4 v176, s[64:65]
	s_waitcnt lgkmcnt(9)
	v_mfma_f32_32x32x16_bf16 v[96:111], v[148:151], v[128:131], v[96:111]
	s_add_u32 m0, s75, 0x400
	s_add_u32 s76, s76, s69
	global_load_lds_dwordx4 v177, s[64:65]
	s_waitcnt lgkmcnt(8)
	v_mfma_f32_32x32x16_bf16 v[80:95], v[152:155], v[128:131], v[80:95]
	s_mov_b32 m0, s76
	s_add_u32 s64, s64, 64
	s_addc_u32 s65, s65, 0
	global_load_lds_dwordx4 v178, s[66:67]
	s_waitcnt lgkmcnt(7)
	v_mfma_f32_32x32x16_bf16 v[64:79], v[156:159], v[128:131], v[64:79]
	global_load_lds_dwordx4 v178, s[66:67] offset:1024
	s_waitcnt lgkmcnt(6)
	v_mfma_f32_32x32x16_bf16 v[48:63], v[144:147], v[132:135], v[48:63]
	global_load_lds_dwordx4 v178, s[66:67] offset:2048
	v_mfma_f32_32x32x16_bf16 v[32:47], v[148:151], v[132:135], v[32:47]
	global_load_lds_dwordx4 v178, s[66:67] offset:3072
	s_add_u32 s66, s66, 0x20000
	s_addc_u32 s67, s67, 0
	v_mfma_f32_32x32x16_bf16 v[16:31], v[152:155], v[132:135], v[16:31]
	s_add_u32 s70, s70, 1
	s_cmp_eq_u32 s70, 3
	s_cselect_b32 s70, 0, s70
	v_mfma_f32_32x32x16_bf16 v[0:15], v[156:159], v[132:135], v[0:15]
; #define MFMA32(a, b, c) __builtin_amdgcn_mfma_f32_32x32x16_bf16((a), (b), (c), 0, 0, 0)
; #define GA_LOAD(pr_) do { _Pragma("unroll") for (int i = 0; i < 4; ++i) ra[i] = *(const u32x4*)(Ab + (i * 32) * lda + (pr_) * 64); } while (0)
; #define GB_LOAD(kt_) do { const bfr* bk_ = Bb + (kt_) * NB * 32; \
;     _Pragma("unroll") for (int i = 0; i < 4; ++i) rb[i] = *(const u32x4*)(bk_ + (i * 64) * 32); } while (0)
; #define G_STORE(kt_) do { bfr* as_ = S0 + ((kt_) & 1) * GSTAGE; bfr* bs_ = as_ + 128 * 40; \
;     if (apar == ((kt_) & 1)) { _Pragma("unroll") for (int i = 0; i < 4; ++i) *(u32x4*)(as_ + asoff + i * 32 * 40) = ra[i]; } \
;     _Pragma("unroll") for (int i = 0; i < 4; ++i) *(u32x4*)(bs_ + bsoff + i * 64 * 40) = rb[i]; } while (0)
; template <int lda>
; DI void gemm_mainloop(const bfr* __restrict__ A, const bfr* __restrict__ Bt, int NB, int K, int m0, int n0, char* smem, f32x16 (&acc)[2][4]) {
;     ...
;   for (int kt = 0; kt < nk; ++kt) {
;     if (kt + 1 < nk) G_STORE(kt + 1);
;     if (kt + 2 < nk) {
;       GB_LOAD(kt + 2);
;       if ((kt & 1) == 0) GA_LOAD((kt >> 1) + 1);
;     }
;     const bfr* As = S0 + (kt & 1) * GSTAGE;
;     const bfr* Bs = As + 128 * 40;
; #pragma unroll
;     for (int ks = 0; ks < 2; ++ks) {
;       bf16x8 af[2], bfg[4];
; #pragma unroll
;       for (int i = 0; i < 2; ++i) af[i] = *(const bf16x8*)(As + (wr * 64 + i * 32 + r) * 40 + ks * 16 + hl * 8);
; #pragma unroll
;       for (int j = 0; j < 4; ++j) bfg[j] = *(const bf16x8*)(Bs + (wc * 128 + j * 32 + r) * 40 + ks * 16 + hl * 8);
; #pragma unroll
;       for (int i = 0; i < 2; ++i)
; #pragma unroll
;         for (int j = 0; j < 4; ++j) acc[i][j] = MFMA32(af[i], bfg[j], acc[i][j]);
;     }
;     __syncthreads();
;   }
.Lp12_loop:
	s_waitcnt vmcnt(6) lgkmcnt(0)
	s_barrier
	s_mul_i32 s74, s71, 0x6000
	s_add_u32 s75, s74, 0x2000
	s_cmp_eq_u32 s71, 2
	s_cselect_b32 s75, 0x10000, s75
	v_add_u32_e32 v183, s74, v179
	v_add_u32_e32 v185, s75, v181
	v_add_u32_e32 v184, s74, v180
	v_add_u32_e32 v186, s75, v182
	s_add_u32 s71, s71, 1
	s_cmp_eq_u32 s71, 3
	s_cselect_b32 s71, 0, s71
	ds_read_b128 v[128:131], v183
	ds_read_b128 v[144:147], v185
	ds_read_b128 v[148:151], v185 offset:2048
	ds_read_b128 v[152:155], v185 offset:4096
	ds_read_b128 v[156:159], v185 offset:6144
	ds_read_b128 v[132:135], v183 offset:2048
	v_mfma_f32_32x32x16_bf16 v[112:127], v[160:163], v[136:139], v[112:127]
	s_mul_i32 s74, s70, 0x6000
	s_add_u32 s75, s74, s68
	s_mov_b32 m0, s75
	s_add_u32 s76, s74, 0x2000
	s_cmp_eq_u32 s70, 2
	s_cselect_b32 s76, 0x10000, s76
	global_load_lds_dwordx4 v176, s[64:65]
	v_mfma_f32_32x32x16_bf16 v[96:111], v[164:167], v[136:139], v[96:111]
	s_add_u32 m0, s75, 0x400
	s_add_u32 s76, s76, s69
	global_load_lds_dwordx4 v177, s[64:65]
	v_mfma_f32_32x32x16_bf16 v[80:95], v[168:171], v[136:139], v[80:95]
	s_mov_b32 m0, s76
	s_add_u32 s64, s64, 64
	s_addc_u32 s65, s65, 0
	global_load_lds_dwordx4 v178, s[66:67]
	v_mfma_f32_32x32x16_bf16 v[64:79], v[172:175], v[136:139], v[64:79]
	global_load_lds_dwordx4 v178, s[66:67] offset:1024
	v_mfma_f32_32x32x16_bf16 v[48:63], v[160:163], v[140:143], v[48:63]
	global_load_lds_dwordx4 v178, s[66:67] offset:2048
	v_mfma_f32_32x32x16_bf16 v[32:47], v[164:167], v[140:143], v[32:47]
	global_load_lds_dwordx4 v178, s[66:67] offset:3072
	s_add_u32 s66, s66, 0x20000
	s_addc_u32 s67, s67, 0
	v_mfma_f32_32x32x16_bf16 v[16:31], v[168:171], v[140:143], v[16:31]
	s_add_u32 s70, s70, 1
	s_cmp_eq_u32 s70, 3
	s_cselect_b32 s70, 0, s70
	v_mfma_f32_32x32x16_bf16 v[0:15], v[172:175], v[140:143], v[0:15]
	ds_read_b128 v[136:139], v184
	ds_read_b128 v[160:163], v186
	ds_read_b128 v[164:167], v186 offset:2048
	ds_read_b128 v[168:171], v186 offset:4096
	ds_read_b128 v[172:175], v186 offset:6144
	ds_read_b128 v[140:143], v184 offset:2048
	s_waitcnt lgkmcnt(10)
	v_mfma_f32_32x32x16_bf16 v[112:127], v[144:147], v[128:131], v[112:127]
	s_waitcnt lgkmcnt(9)
	v_mfma_f32_32x32x16_bf16 v[96:111], v[148:151], v[128:131], v[96:111]
	s_waitcnt lgkmcnt(8)
	v_mfma_f32_32x32x16_bf16 v[80:95], v[152:155], v[128:131], v[80:95]
	s_waitcnt lgkmcnt(7)
	v_mfma_f32_32x32x16_bf16 v[64:79], v[156:159], v[128:131], v[64:79]
	s_waitcnt lgkmcnt(6)
	v_mfma_f32_32x32x16_bf16 v[48:63], v[144:147], v[132:135], v[48:63]
	v_mfma_f32_32x32x16_bf16 v[32:47], v[148:151], v[132:135], v[32:47]
	v_mfma_f32_32x32x16_bf16 v[16:31], v[152:155], v[132:135], v[16:31]
	v_mfma_f32_32x32x16_bf16 v[0:15], v[156:159], v[132:135], v[0:15]
	s_add_u32 s72, s72, 1
	s_cmp_lt_u32 s72, 29
	s_cbranch_scc1 .Lp12_loop
	s_waitcnt vmcnt(6) lgkmcnt(0)
	s_barrier
	s_mul_i32 s74, s71, 0x6000
	s_add_u32 s75, s74, 0x2000
	s_cmp_eq_u32 s71, 2
	s_cselect_b32 s75, 0x10000, s75
	v_add_u32_e32 v183, s74, v179
	v_add_u32_e32 v185, s75, v181
	v_add_u32_e32 v184, s74, v180
	v_add_u32_e32 v186, s75, v182
	s_add_u32 s71, s71, 1
	s_cmp_eq_u32 s71, 3
	s_cselect_b32 s71, 0, s71
	ds_read_b128 v[128:131], v183
	ds_read_b128 v[144:147], v185
	ds_read_b128 v[148:151], v185 offset:2048
	ds_read_b128 v[152:155], v185 offset:4096
	ds_read_b128 v[156:159], v185 offset:6144
	ds_read_b128 v[132:135], v183 offset:2048
	v_mfma_f32_32x32x16_bf16 v[112:127], v[160:163], v[136:139], v[112:127]
	v_mfma_f32_32x32x16_bf16 v[96:111], v[164:167], v[136:139], v[96:111]
	v_mfma_f32_32x32x16_bf16 v[80:95], v[168:171], v[136:139], v[80:95]
	v_mfma_f32_32x32x16_bf16 v[64:79], v[172:175], v[136:139], v[64:79]
	v_mfma_f32_32x32x16_bf16 v[48:63], v[160:163], v[140:143], v[48:63]
	v_mfma_f32_32x32x16_bf16 v[32:47], v[164:167], v[140:143], v[32:47]
	v_mfma_f32_32x32x16_bf16 v[16:31], v[168:171], v[140:143], v[16:31]
	v_mfma_f32_32x32x16_bf16 v[0:15], v[172:175], v[140:143], v[0:15]
	ds_read_b128 v[136:139], v184
	ds_read_b128 v[160:163], v186
	ds_read_b128 v[164:167], v186 offset:2048
	ds_read_b128 v[168:171], v186 offset:4096
	ds_read_b128 v[172:175], v186 offset:6144
	ds_read_b128 v[140:143], v184 offset:2048
	s_waitcnt lgkmcnt(10)
	v_mfma_f32_32x32x16_bf16 v[112:127], v[144:147], v[128:131], v[112:127]
	s_waitcnt lgkmcnt(9)
	v_mfma_f32_32x32x16_bf16 v[96:111], v[148:151], v[128:131], v[96:111]
	s_waitcnt lgkmcnt(8)
	v_mfma_f32_32x32x16_bf16 v[80:95], v[152:155], v[128:131], v[80:95]
	s_waitcnt lgkmcnt(7)
	v_mfma_f32_32x32x16_bf16 v[64:79], v[156:159], v[128:131], v[64:79]
	s_waitcnt lgkmcnt(6)
	v_mfma_f32_32x32x16_bf16 v[48:63], v[144:147], v[132:135], v[48:63]
	v_mfma_f32_32x32x16_bf16 v[32:47], v[148:151], v[132:135], v[32:47]
	v_mfma_f32_32x32x16_bf16 v[16:31], v[152:155], v[132:135], v[16:31]
	v_mfma_f32_32x32x16_bf16 v[0:15], v[156:159], v[132:135], v[0:15]
	s_waitcnt vmcnt(0) lgkmcnt(0)
	s_barrier
; #define MFMA32(a, b, c) __builtin_amdgcn_mfma_f32_32x32x16_bf16((a), (b), (c), 0, 0, 0)
; DI bfr f2bf(float a) { return (bfr)(pack2(a, 0.f) & 0xffffu); }
; #define GA_LOAD(pr_) do { _Pragma("unroll") for (int i = 0; i < 4; ++i) ra[i] = *(const u32x4*)(Ab + (i * 32) * lda + (pr_) * 64); } while (0)
; #define GB_LOAD(kt_) do { const bfr* bk_ = Bb + (kt_) * NB * 32; \
;     _Pragma("unroll") for (int i = 0; i < 4; ++i) rb[i] = *(const u32x4*)(bk_ + (i * 64) * 32); } while (0)
; #define G_STORE(kt_) do { bfr* as_ = S0 + ((kt_) & 1) * GSTAGE; bfr* bs_ = as_ + 128 * 40; \
;     if (apar == ((kt_) & 1)) { _Pragma("unroll") for (int i = 0; i < 4; ++i) *(u32x4*)(as_ + asoff + i * 32 * 40) = ra[i]; } \
;     _Pragma("unroll") for (int i = 0; i < 4; ++i) *(u32x4*)(bs_ + bsoff + i * 64 * 40) = rb[i]; } while (0)
; template <int lda>
; DI void gemm_mainloop(const bfr* __restrict__ A, const bfr* __restrict__ Bt, int NB, int K, int m0, int n0, char* smem, f32x16 (&acc)[2][4]) {
;     ...
;   for (int kt = 0; kt < nk; ++kt) {
;     if (kt + 1 < nk) G_STORE(kt + 1);
;     if (kt + 2 < nk) {
;       GB_LOAD(kt + 2);
;       if ((kt & 1) == 0) GA_LOAD((kt >> 1) + 1);
;     }
;     const bfr* As = S0 + (kt & 1) * GSTAGE;
;     const bfr* Bs = As + 128 * 40;
; #pragma unroll
;     for (int ks = 0; ks < 2; ++ks) {
;       bf16x8 af[2], bfg[4];
; #pragma unroll
;       for (int i = 0; i < 2; ++i) af[i] = *(const bf16x8*)(As + (wr * 64 + i * 32 + r) * 40 + ks * 16 + hl * 8);
; #pragma unroll
;       for (int j = 0; j < 4; ++j) bfg[j] = *(const bf16x8*)(Bs + (wc * 128 + j * 32 + r) * 40 + ks * 16 + hl * 8);
; #pragma unroll
;       for (int i = 0; i < 2; ++i)
; #pragma unroll
;         for (int j = 0; j < 4; ++j) acc[i][j] = MFMA32(af[i], bfg[j], acc[i][j]);
;     }
;     __syncthreads();
;   }
; DI void phase_gemm_bf16out(const Params& p, const bfr* A, const bfr* Wt, bfr* C, int N, const float* ss, char* smem) {
;     ...
;                        float inv = rsqrtf(ss[row] * (1.0f / 1024.0f) + EPSF);
;                        C[(size_t)row * N + col] = f2bf(v * inv);
;     ...
;     gemm_tile<1024>(A, Wt, N, 1024, mt * 128, nt * 256, smem,
;               [=](int row, int col, float v) {
;                 float inv = rsqrtf(ss[row] * (1.0f / 1024.0f) + EPSF);
;                 C[(size_t)row * N + col] = f2bf(v * inv);
;               });
	s_mul_i32 s74, s71, 0x6000
	s_add_u32 s75, s74, 0x2000
	s_cmp_eq_u32 s71, 2
	s_cselect_b32 s75, 0x10000, s75
	v_add_u32_e32 v183, s74, v179
	v_add_u32_e32 v185, s75, v181
	v_add_u32_e32 v184, s74, v180
	v_add_u32_e32 v186, s75, v182
	s_add_u32 s71, s71, 1
	s_cmp_eq_u32 s71, 3
	s_cselect_b32 s71, 0, s71
	ds_read_b128 v[128:131], v183
	ds_read_b128 v[144:147], v185
	ds_read_b128 v[148:151], v185 offset:2048
	ds_read_b128 v[152:155], v185 offset:4096
	ds_read_b128 v[156:159], v185 offset:6144
	ds_read_b128 v[132:135], v183 offset:2048
	v_mfma_f32_32x32x16_bf16 v[112:127], v[160:163], v[136:139], v[112:127]
	v_mfma_f32_32x32x16_bf16 v[96:111], v[164:167], v[136:139], v[96:111]
	v_mfma_f32_32x32x16_bf16 v[80:95], v[168:171], v[136:139], v[80:95]
	v_mfma_f32_32x32x16_bf16 v[64:79], v[172:175], v[136:139], v[64:79]
	v_mfma_f32_32x32x16_bf16 v[48:63], v[160:163], v[140:143], v[48:63]
	v_mfma_f32_32x32x16_bf16 v[32:47], v[164:167], v[140:143], v[32:47]
	v_mfma_f32_32x32x16_bf16 v[16:31], v[168:171], v[140:143], v[16:31]
	v_mfma_f32_32x32x16_bf16 v[0:15], v[172:175], v[140:143], v[0:15]
	ds_read_b128 v[136:139], v184
	ds_read_b128 v[160:163], v186
	ds_read_b128 v[164:167], v186 offset:2048
	ds_read_b128 v[168:171], v186 offset:4096
	ds_read_b128 v[172:175], v186 offset:6144
	ds_read_b128 v[140:143], v184 offset:2048
	s_waitcnt lgkmcnt(10)
	v_mfma_f32_32x32x16_bf16 v[112:127], v[144:147], v[128:131], v[112:127]
	s_waitcnt lgkmcnt(9)
	v_mfma_f32_32x32x16_bf16 v[96:111], v[148:151], v[128:131], v[96:111]
	s_waitcnt lgkmcnt(8)
	v_mfma_f32_32x32x16_bf16 v[80:95], v[152:155], v[128:131], v[80:95]
	s_waitcnt lgkmcnt(7)
	v_mfma_f32_32x32x16_bf16 v[64:79], v[156:159], v[128:131], v[64:79]
	s_waitcnt lgkmcnt(6)
	v_mfma_f32_32x32x16_bf16 v[48:63], v[144:147], v[132:135], v[48:63]
	v_mfma_f32_32x32x16_bf16 v[32:47], v[148:151], v[132:135], v[32:47]
	v_mfma_f32_32x32x16_bf16 v[16:31], v[152:155], v[132:135], v[16:31]
	v_mfma_f32_32x32x16_bf16 v[0:15], v[156:159], v[132:135], v[0:15]
	s_waitcnt lgkmcnt(0)
	v_mfma_f32_32x32x16_bf16 v[112:127], v[160:163], v[136:139], v[112:127]
	v_mfma_f32_32x32x16_bf16 v[96:111], v[164:167], v[136:139], v[96:111]
	v_mfma_f32_32x32x16_bf16 v[80:95], v[168:171], v[136:139], v[80:95]
	v_mfma_f32_32x32x16_bf16 v[64:79], v[172:175], v[136:139], v[64:79]
	v_mfma_f32_32x32x16_bf16 v[48:63], v[160:163], v[140:143], v[48:63]
	v_mfma_f32_32x32x16_bf16 v[32:47], v[164:167], v[140:143], v[32:47]
	v_mfma_f32_32x32x16_bf16 v[16:31], v[168:171], v[140:143], v[16:31]
	v_mfma_f32_32x32x16_bf16 v[0:15], v[172:175], v[140:143], v[0:15]
	s_nop 7
	s_nop 3
	s_barrier
	s_load_dwordx2 s[64:65], s[92:93], 0x150
	s_load_dwordx2 s[66:67], s[92:93], 0x140
	v_and_b32_e32 v176, 31, v196
	v_bfe_u32 v177, v196, 5, 1
	s_lshr_b32 s74, s73, 1
	s_lshl_b32 s74, s74, 6
	s_add_u32 s74, s74, s77
	v_add_u32_e32 v178, s74, v176
	s_mul_i32 s76, s73, 8704
	v_mul_u32_u24_e32 v180, 272, v176
	v_lshl_add_u32 v180, v177, 3, v180
	v_add_u32_e32 v180, s76, v180
	v_bfe_u32 v185, v196, 4, 2
	v_and_b32_e32 v186, 15, v196
	v_mul_u32_u24_e32 v181, 272, v185
	v_lshl_add_u32 v181, v186, 4, v181
	v_add_u32_e32 v181, s76, v181
	s_and_b32 s75, s73, 1
	s_lshl_b32 s75, s75, 7
	s_add_u32 s75, s75, s78
	v_add_u32_e32 v179, s74, v185
	v_mul_u32_u24_e32 v179, 0x800, v179
	v_lshl_add_u32 v179, v186, 3, v179
	v_add_lshl_u32 v182, v179, s75, 1
	s_waitcnt lgkmcnt(0)
	s_add_u32 s66, s66, 0x10200
	s_addc_u32 s67, s67, 0
	v_lshlrev_b32_e32 v179, 2, v178
	global_load_dword v183, v179, s[66:67]
	global_load_dword v184, v179, s[66:67] offset:128
	s_waitcnt vmcnt(0)
	v_mul_f32_e32 v183, 0x3a800000, v183
	v_mul_f32_e32 v184, 0x3a800000, v184
	v_add_f32_e32 v183, 0x358637bd, v183
	v_add_f32_e32 v184, 0x358637bd, v184
	v_rsq_f32_e32 v183, v183
	v_rsq_f32_e32 v184, v184
	s_nop 1
	v_mul_f32_e32 v112, v183, v112
	v_mul_f32_e32 v113, v183, v113
	v_mul_f32_e32 v114, v183, v114
	v_mul_f32_e32 v115, v183, v115
	v_cvt_pk_bf16_f32 v112, v112, v113
	v_cvt_pk_bf16_f32 v113, v114, v115
	ds_write_b64 v180, v[112:113]
	v_mul_f32_e32 v116, v183, v116
	v_mul_f32_e32 v117, v183, v117
	v_mul_f32_e32 v118, v183, v118
	v_mul_f32_e32 v119, v183, v119
	v_cvt_pk_bf16_f32 v116, v116, v117
	v_cvt_pk_bf16_f32 v117, v118, v119
	ds_write_b64 v180, v[116:117] offset:16
	v_mul_f32_e32 v120, v183, v120
	v_mul_f32_e32 v121, v183, v121
	v_mul_f32_e32 v122, v183, v122
	v_mul_f32_e32 v123, v183, v123
	v_cvt_pk_bf16_f32 v120, v120, v121
	v_cvt_pk_bf16_f32 v121, v122, v123
	ds_write_b64 v180, v[120:121] offset:32
	v_mul_f32_e32 v124, v183, v124
	v_mul_f32_e32 v125, v183, v125
	v_mul_f32_e32 v126, v183, v126
	v_mul_f32_e32 v127, v183, v127
	v_cvt_pk_bf16_f32 v124, v124, v125
	v_cvt_pk_bf16_f32 v125, v126, v127
	ds_write_b64 v180, v[124:125] offset:48
	v_mul_f32_e32 v96, v183, v96
	v_mul_f32_e32 v97, v183, v97
	v_mul_f32_e32 v98, v183, v98
	v_mul_f32_e32 v99, v183, v99
	v_cvt_pk_bf16_f32 v96, v96, v97
	v_cvt_pk_bf16_f32 v97, v98, v99
	ds_write_b64 v180, v[96:97] offset:64
	v_mul_f32_e32 v100, v183, v100
	v_mul_f32_e32 v101, v183, v101
	v_mul_f32_e32 v102, v183, v102
	v_mul_f32_e32 v103, v183, v103
	v_cvt_pk_bf16_f32 v100, v100, v101
	v_cvt_pk_bf16_f32 v101, v102, v103
	ds_write_b64 v180, v[100:101] offset:80
	v_mul_f32_e32 v104, v183, v104
	v_mul_f32_e32 v105, v183, v105
	v_mul_f32_e32 v106, v183, v106
	v_mul_f32_e32 v107, v183, v107
	v_cvt_pk_bf16_f32 v104, v104, v105
	v_cvt_pk_bf16_f32 v105, v106, v107
	ds_write_b64 v180, v[104:105] offset:96
	v_mul_f32_e32 v108, v183, v108
	v_mul_f32_e32 v109, v183, v109
	v_mul_f32_e32 v110, v183, v110
	v_mul_f32_e32 v111, v183, v111
	v_cvt_pk_bf16_f32 v108, v108, v109
	v_cvt_pk_bf16_f32 v109, v110, v111
; DI bfr f2bf(float a) { return (bfr)(pack2(a, 0.f) & 0xffffu); }
; DI int crow(int reg, int h) { return (reg & 3) + 8 * (reg >> 2) + 4 * h; }
; template <int lda, class Epi>
; DI void gemm_tile(const bfr* __restrict__ A, const bfr* __restrict__ Bt, int NB, int K, int m0, int n0, char* smem, Epi epi) {
;     ...
; #pragma unroll
;   for (int i = 0; i < 2; ++i)
; #pragma unroll
;     for (int j = 0; j < 4; ++j)
; #pragma unroll
;       for (int q = 0; q < 16; ++q) {
;         int row = m0 + wr * 64 + i * 32 + crow(q, hl);
;         int col = n0 + wc * 128 + j * 32 + r;
;         epi(row, col, acc[i][j][q]);
;       }
; DI void phase_gemm_bf16out(const Params& p, const bfr* A, const bfr* Wt, bfr* C, int N, const float* ss, char* smem) {
;     ...
;               [=](int row, int col, float v) {
;                 float inv = rsqrtf(ss[row] * (1.0f / 1024.0f) + EPSF);
;                 C[(size_t)row * N + col] = f2bf(v * inv);
;               });
	ds_write_b64 v180, v[108:109] offset:112
	v_mul_f32_e32 v80, v183, v80
	v_mul_f32_e32 v81, v183, v81
	v_mul_f32_e32 v82, v183, v82
	v_mul_f32_e32 v83, v183, v83
	v_cvt_pk_bf16_f32 v80, v80, v81
	v_cvt_pk_bf16_f32 v81, v82, v83
	ds_write_b64 v180, v[80:81] offset:128
	v_mul_f32_e32 v84, v183, v84
	v_mul_f32_e32 v85, v183, v85
	v_mul_f32_e32 v86, v183, v86
	v_mul_f32_e32 v87, v183, v87
	v_cvt_pk_bf16_f32 v84, v84, v85
	v_cvt_pk_bf16_f32 v85, v86, v87
	ds_write_b64 v180, v[84:85] offset:144
	v_mul_f32_e32 v88, v183, v88
	v_mul_f32_e32 v89, v183, v89
	v_mul_f32_e32 v90, v183, v90
	v_mul_f32_e32 v91, v183, v91
	v_cvt_pk_bf16_f32 v88, v88, v89
	v_cvt_pk_bf16_f32 v89, v90, v91
	ds_write_b64 v180, v[88:89] offset:160
	v_mul_f32_e32 v92, v183, v92
	v_mul_f32_e32 v93, v183, v93
	v_mul_f32_e32 v94, v183, v94
	v_mul_f32_e32 v95, v183, v95
	v_cvt_pk_bf16_f32 v92, v92, v93
	v_cvt_pk_bf16_f32 v93, v94, v95
	ds_write_b64 v180, v[92:93] offset:176
	v_mul_f32_e32 v64, v183, v64
	v_mul_f32_e32 v65, v183, v65
	v_mul_f32_e32 v66, v183, v66
	v_mul_f32_e32 v67, v183, v67
	v_cvt_pk_bf16_f32 v64, v64, v65
	v_cvt_pk_bf16_f32 v65, v66, v67
	ds_write_b64 v180, v[64:65] offset:192
	v_mul_f32_e32 v68, v183, v68
	v_mul_f32_e32 v69, v183, v69
	v_mul_f32_e32 v70, v183, v70
	v_mul_f32_e32 v71, v183, v71
	v_cvt_pk_bf16_f32 v68, v68, v69
	v_cvt_pk_bf16_f32 v69, v70, v71
	ds_write_b64 v180, v[68:69] offset:208
	v_mul_f32_e32 v72, v183, v72
	v_mul_f32_e32 v73, v183, v73
	v_mul_f32_e32 v74, v183, v74
	v_mul_f32_e32 v75, v183, v75
	v_cvt_pk_bf16_f32 v72, v72, v73
	v_cvt_pk_bf16_f32 v73, v74, v75
	ds_write_b64 v180, v[72:73] offset:224
	v_mul_f32_e32 v76, v183, v76
	v_mul_f32_e32 v77, v183, v77
	v_mul_f32_e32 v78, v183, v78
	v_mul_f32_e32 v79, v183, v79
	v_cvt_pk_bf16_f32 v76, v76, v77
	v_cvt_pk_bf16_f32 v77, v78, v79
	ds_write_b64 v180, v[76:77] offset:240
	s_waitcnt lgkmcnt(0)
	ds_read_b128 v[112:115], v181
	ds_read_b128 v[116:119], v181 offset:1088
	ds_read_b128 v[120:123], v181 offset:2176
	ds_read_b128 v[124:127], v181 offset:3264
	ds_read_b128 v[96:99], v181 offset:4352
	ds_read_b128 v[100:103], v181 offset:5440
	ds_read_b128 v[104:107], v181 offset:6528
	ds_read_b128 v[108:111], v181 offset:7616
	s_add_u32 s66, s64, 0x0
	s_addc_u32 s67, s65, 0
	s_waitcnt lgkmcnt(7)
	global_store_dwordx4 v182, v[112:115], s[66:67]
	s_add_u32 s66, s64, 0x4000
	s_addc_u32 s67, s65, 0
	s_waitcnt lgkmcnt(6)
	global_store_dwordx4 v182, v[116:119], s[66:67]
	s_add_u32 s66, s64, 0x8000
	s_addc_u32 s67, s65, 0
	s_waitcnt lgkmcnt(5)
	global_store_dwordx4 v182, v[120:123], s[66:67]
	s_add_u32 s66, s64, 0xc000
	s_addc_u32 s67, s65, 0
	s_waitcnt lgkmcnt(4)
	global_store_dwordx4 v182, v[124:127], s[66:67]
	s_add_u32 s66, s64, 0x10000
	s_addc_u32 s67, s65, 0
	s_waitcnt lgkmcnt(3)
	global_store_dwordx4 v182, v[96:99], s[66:67]
	s_add_u32 s66, s64, 0x14000
	s_addc_u32 s67, s65, 0
	s_waitcnt lgkmcnt(2)
	global_store_dwordx4 v182, v[100:103], s[66:67]
	s_add_u32 s66, s64, 0x18000
	s_addc_u32 s67, s65, 0
	s_waitcnt lgkmcnt(1)
	global_store_dwordx4 v182, v[104:107], s[66:67]
	s_add_u32 s66, s64, 0x1c000
	s_addc_u32 s67, s65, 0
	s_waitcnt lgkmcnt(0)
; DI bfr f2bf(float a) { return (bfr)(pack2(a, 0.f) & 0xffffu); }
; DI int crow(int reg, int h) { return (reg & 3) + 8 * (reg >> 2) + 4 * h; }
; template <int lda, class Epi>
; DI void gemm_tile(const bfr* __restrict__ A, const bfr* __restrict__ Bt, int NB, int K, int m0, int n0, char* smem, Epi epi) {
;     ...
; #pragma unroll
;   for (int i = 0; i < 2; ++i)
; #pragma unroll
;     for (int j = 0; j < 4; ++j)
; #pragma unroll
;       for (int q = 0; q < 16; ++q) {
;         int row = m0 + wr * 64 + i * 32 + crow(q, hl);
;         int col = n0 + wc * 128 + j * 32 + r;
;         epi(row, col, acc[i][j][q]);
;       }
; DI void phase_gemm_bf16out(const Params& p, const bfr* A, const bfr* Wt, bfr* C, int N, const float* ss, char* smem) {
;     ...
;   for (int t0 = blockIdx.x; t0 < 128 * ntn; t0 += gridDim.x) {
;     const int t = ((gridDim.x & 7) == 0) ? xcd_tile(t0, ntn) : t0;
;     int mt = t / ntn, nt = t % ntn;
;     gemm_tile<1024>(A, Wt, N, 1024, mt * 128, nt * 256, smem,
;               [=](int row, int col, float v) {
;                 float inv = rsqrtf(ss[row] * (1.0f / 1024.0f) + EPSF);
;                 C[(size_t)row * N + col] = f2bf(v * inv);
;               });
	global_store_dwordx4 v182, v[108:111], s[66:67]
	v_mul_f32_e32 v48, v184, v48
	v_mul_f32_e32 v49, v184, v49
	v_mul_f32_e32 v50, v184, v50
	v_mul_f32_e32 v51, v184, v51
	v_cvt_pk_bf16_f32 v48, v48, v49
	v_cvt_pk_bf16_f32 v49, v50, v51
	ds_write_b64 v180, v[48:49]
	v_mul_f32_e32 v52, v184, v52
	v_mul_f32_e32 v53, v184, v53
	v_mul_f32_e32 v54, v184, v54
	v_mul_f32_e32 v55, v184, v55
	v_cvt_pk_bf16_f32 v52, v52, v53
	v_cvt_pk_bf16_f32 v53, v54, v55
	ds_write_b64 v180, v[52:53] offset:16
	v_mul_f32_e32 v56, v184, v56
	v_mul_f32_e32 v57, v184, v57
	v_mul_f32_e32 v58, v184, v58
	v_mul_f32_e32 v59, v184, v59
	v_cvt_pk_bf16_f32 v56, v56, v57
	v_cvt_pk_bf16_f32 v57, v58, v59
	ds_write_b64 v180, v[56:57] offset:32
	v_mul_f32_e32 v60, v184, v60
	v_mul_f32_e32 v61, v184, v61
	v_mul_f32_e32 v62, v184, v62
	v_mul_f32_e32 v63, v184, v63
	v_cvt_pk_bf16_f32 v60, v60, v61
	v_cvt_pk_bf16_f32 v61, v62, v63
	ds_write_b64 v180, v[60:61] offset:48
	v_mul_f32_e32 v32, v184, v32
	v_mul_f32_e32 v33, v184, v33
	v_mul_f32_e32 v34, v184, v34
	v_mul_f32_e32 v35, v184, v35
	v_cvt_pk_bf16_f32 v32, v32, v33
	v_cvt_pk_bf16_f32 v33, v34, v35
	ds_write_b64 v180, v[32:33] offset:64
	v_mul_f32_e32 v36, v184, v36
	v_mul_f32_e32 v37, v184, v37
	v_mul_f32_e32 v38, v184, v38
	v_mul_f32_e32 v39, v184, v39
	v_cvt_pk_bf16_f32 v36, v36, v37
	v_cvt_pk_bf16_f32 v37, v38, v39
	ds_write_b64 v180, v[36:37] offset:80
	v_mul_f32_e32 v40, v184, v40
	v_mul_f32_e32 v41, v184, v41
	v_mul_f32_e32 v42, v184, v42
	v_mul_f32_e32 v43, v184, v43
	v_cvt_pk_bf16_f32 v40, v40, v41
	v_cvt_pk_bf16_f32 v41, v42, v43
	ds_write_b64 v180, v[40:41] offset:96
	v_mul_f32_e32 v44, v184, v44
	v_mul_f32_e32 v45, v184, v45
	v_mul_f32_e32 v46, v184, v46
	v_mul_f32_e32 v47, v184, v47
	v_cvt_pk_bf16_f32 v44, v44, v45
	v_cvt_pk_bf16_f32 v45, v46, v47
	ds_write_b64 v180, v[44:45] offset:112
	v_mul_f32_e32 v16, v184, v16
	v_mul_f32_e32 v17, v184, v17
	v_mul_f32_e32 v18, v184, v18
	v_mul_f32_e32 v19, v184, v19
	v_cvt_pk_bf16_f32 v16, v16, v17
	v_cvt_pk_bf16_f32 v17, v18, v19
	ds_write_b64 v180, v[16:17] offset:128
	v_mul_f32_e32 v20, v184, v20
	v_mul_f32_e32 v21, v184, v21
	v_mul_f32_e32 v22, v184, v22
	v_mul_f32_e32 v23, v184, v23
	v_cvt_pk_bf16_f32 v20, v20, v21
	v_cvt_pk_bf16_f32 v21, v22, v23
	ds_write_b64 v180, v[20:21] offset:144
	v_mul_f32_e32 v24, v184, v24
	v_mul_f32_e32 v25, v184, v25
	v_mul_f32_e32 v26, v184, v26
	v_mul_f32_e32 v27, v184, v27
	v_cvt_pk_bf16_f32 v24, v24, v25
	v_cvt_pk_bf16_f32 v25, v26, v27
	ds_write_b64 v180, v[24:25] offset:160
	v_mul_f32_e32 v28, v184, v28
	v_mul_f32_e32 v29, v184, v29
	v_mul_f32_e32 v30, v184, v30
	v_mul_f32_e32 v31, v184, v31
	v_cvt_pk_bf16_f32 v28, v28, v29
	v_cvt_pk_bf16_f32 v29, v30, v31
	ds_write_b64 v180, v[28:29] offset:176
	v_mul_f32_e32 v0, v184, v0
	v_mul_f32_e32 v1, v184, v1
	v_mul_f32_e32 v2, v184, v2
	v_mul_f32_e32 v3, v184, v3
	v_cvt_pk_bf16_f32 v0, v0, v1
	v_cvt_pk_bf16_f32 v1, v2, v3
	ds_write_b64 v180, v[0:1] offset:192
	v_mul_f32_e32 v4, v184, v4
	v_mul_f32_e32 v5, v184, v5
	v_mul_f32_e32 v6, v184, v6
	v_mul_f32_e32 v7, v184, v7
	v_cvt_pk_bf16_f32 v4, v4, v5
	v_cvt_pk_bf16_f32 v5, v6, v7
	ds_write_b64 v180, v[4:5] offset:208
	v_mul_f32_e32 v8, v184, v8
	v_mul_f32_e32 v9, v184, v9
	v_mul_f32_e32 v10, v184, v10
	v_mul_f32_e32 v11, v184, v11
	v_cvt_pk_bf16_f32 v8, v8, v9
	v_cvt_pk_bf16_f32 v9, v10, v11
	ds_write_b64 v180, v[8:9] offset:224
	v_mul_f32_e32 v12, v184, v12
	v_mul_f32_e32 v13, v184, v13
	v_mul_f32_e32 v14, v184, v14
	v_mul_f32_e32 v15, v184, v15
	v_cvt_pk_bf16_f32 v12, v12, v13
	v_cvt_pk_bf16_f32 v13, v14, v15
	ds_write_b64 v180, v[12:13] offset:240
	s_waitcnt lgkmcnt(0)
	ds_read_b128 v[48:51], v181
	ds_read_b128 v[52:55], v181 offset:1088
	ds_read_b128 v[56:59], v181 offset:2176
	ds_read_b128 v[60:63], v181 offset:3264
	ds_read_b128 v[32:35], v181 offset:4352
	ds_read_b128 v[36:39], v181 offset:5440
	ds_read_b128 v[40:43], v181 offset:6528
	ds_read_b128 v[44:47], v181 offset:7616
	s_add_u32 s66, s64, 0x20000
	s_addc_u32 s67, s65, 0
	s_waitcnt lgkmcnt(7)
	global_store_dwordx4 v182, v[48:51], s[66:67]
	s_add_u32 s66, s64, 0x24000
	s_addc_u32 s67, s65, 0
	s_waitcnt lgkmcnt(6)
	global_store_dwordx4 v182, v[52:55], s[66:67]
	s_add_u32 s66, s64, 0x28000
	s_addc_u32 s67, s65, 0
	s_waitcnt lgkmcnt(5)
	global_store_dwordx4 v182, v[56:59], s[66:67]
	s_add_u32 s66, s64, 0x2c000
	s_addc_u32 s67, s65, 0
	s_waitcnt lgkmcnt(4)
	global_store_dwordx4 v182, v[60:63], s[66:67]
	s_add_u32 s66, s64, 0x30000
	s_addc_u32 s67, s65, 0
	s_waitcnt lgkmcnt(3)
	global_store_dwordx4 v182, v[32:35], s[66:67]
	s_add_u32 s66, s64, 0x34000
	s_addc_u32 s67, s65, 0
	s_waitcnt lgkmcnt(2)
	global_store_dwordx4 v182, v[36:39], s[66:67]
	s_add_u32 s66, s64, 0x38000
	s_addc_u32 s67, s65, 0
	s_waitcnt lgkmcnt(1)
	global_store_dwordx4 v182, v[40:43], s[66:67]
	s_add_u32 s66, s64, 0x3c000
	s_addc_u32 s67, s65, 0
	s_waitcnt lgkmcnt(0)
	global_store_dwordx4 v182, v[44:47], s[66:67]
	v_readlane_b32 s64, v187, 0
	v_readlane_b32 s65, v187, 1
	v_readlane_b32 s66, v187, 2
	v_readlane_b32 s67, v187, 3
	v_readlane_b32 s68, v187, 4
	v_readlane_b32 s69, v187, 5
	v_readlane_b32 s70, v187, 6
	v_readlane_b32 s71, v187, 7
	v_readlane_b32 s72, v187, 8
	v_readlane_b32 s73, v187, 9
	v_readlane_b32 s74, v187, 10
	v_readlane_b32 s75, v187, 11
	v_readlane_b32 s76, v187, 12
	v_readlane_b32 s77, v187, 13
	v_readlane_b32 s78, v187, 14
	v_readlane_b32 s79, v187, 15
	s_nop 7
	s_add_i32 s28, s28, s34
	s_cmpk_lt_i32 s28, 0x400
	s_cbranch_scc0 .LBB0_1192
	s_branch .LBB0_1179

; #define MFMA32(a, b, c) __builtin_amdgcn_mfma_f32_32x32x16_bf16((a), (b), (c), 0, 0, 0)
; #define GA_LOAD(pr_) do { _Pragma("unroll") for (int i = 0; i < 4; ++i) ra[i] = *(const u32x4*)(Ab + (i * 32) * lda + (pr_) * 64); } while (0)
; #define GB_LOAD(kt_) do { const bfr* bk_ = Bb + (kt_) * NB * 32; \
;     _Pragma("unroll") for (int i = 0; i < 4; ++i) rb[i] = *(const u32x4*)(bk_ + (i * 64) * 32); } while (0)
; #define G_STORE(kt_) do { bfr* as_ = S0 + ((kt_) & 1) * GSTAGE; bfr* bs_ = as_ + 128 * 40; \
;     if (apar == ((kt_) & 1)) { _Pragma("unroll") for (int i = 0; i < 4; ++i) *(u32x4*)(as_ + asoff + i * 32 * 40) = ra[i]; } \
;     _Pragma("unroll") for (int i = 0; i < 4; ++i) *(u32x4*)(bs_ + bsoff + i * 64 * 40) = rb[i]; } while (0)
; template <int lda>
; DI void gemm_mainloop(const bfr* __restrict__ A, const bfr* __restrict__ Bt, int NB, int K, int m0, int n0, char* smem, f32x16 (&acc)[2][4]) {
;     ...
; #pragma unroll
;   for (int i = 0; i < 2; ++i)
; #pragma unroll
;     for (int j = 0; j < 4; ++j)
; #pragma unroll
;       for (int q = 0; q < 16; ++q) acc[i][j][q] = 0.f;
;   u32x4 ra[4], rb[4];
;   const int nk = K >> 5;
;   const int arow = tid >> 3, ac8 = tid & 7, apar = ac8 >> 2;
;   const bfr* Ab = A + (m0 + arow) * lda + ac8 * 8;
;   const int asoff = arow * 40 + (ac8 & 3) * 8;
;   const int brow = tid >> 2, bc4 = tid & 3;
;   const bfr* Bb = Bt + (n0 + brow) * 32 + bc4 * 8;
;   const int bsoff = brow * 40 + bc4 * 8;
;     ...
;   GA_LOAD(0);
;   GB_LOAD(0);
;   G_STORE(0);
;   GB_LOAD(1);
;   __syncthreads();
;   for (int kt = 0; kt < nk; ++kt) {
;     if (kt + 1 < nk) G_STORE(kt + 1);
;     if (kt + 2 < nk) {
;       GB_LOAD(kt + 2);
;       if ((kt & 1) == 0) GA_LOAD((kt >> 1) + 1);
;     }
;     const bfr* As = S0 + (kt & 1) * GSTAGE;
;     const bfr* Bs = As + 128 * 40;
; #pragma unroll
;     for (int ks = 0; ks < 2; ++ks) {
;       bf16x8 af[2], bfg[4];
; #pragma unroll
;       for (int i = 0; i < 2; ++i) af[i] = *(const bf16x8*)(As + (wr * 64 + i * 32 + r) * 40 + ks * 16 + hl * 8);
; #pragma unroll
;       for (int j = 0; j < 4; ++j) bfg[j] = *(const bf16x8*)(Bs + (wc * 128 + j * 32 + r) * 40 + ks * 16 + hl * 8);
; #pragma unroll
;       for (int i = 0; i < 2; ++i)
; #pragma unroll
;         for (int j = 0; j < 4; ++j) acc[i][j] = MFMA32(af[i], bfg[j], acc[i][j]);
.Lp14_nostag:
	v_mov_b32_e32 v112, 0
	v_mov_b32_e32 v113, 0
	v_mov_b32_e32 v114, 0
	v_mov_b32_e32 v115, 0
	v_mov_b32_e32 v116, 0
	v_mov_b32_e32 v117, 0
	v_mov_b32_e32 v118, 0
	v_mov_b32_e32 v119, 0
	v_mov_b32_e32 v120, 0
	v_mov_b32_e32 v121, 0
	v_mov_b32_e32 v122, 0
	v_mov_b32_e32 v123, 0
	v_mov_b32_e32 v124, 0
	v_mov_b32_e32 v125, 0
	v_mov_b32_e32 v126, 0
	v_mov_b32_e32 v127, 0
	v_mov_b32_e32 v96, 0
	v_mov_b32_e32 v97, 0
	v_mov_b32_e32 v98, 0
	v_mov_b32_e32 v99, 0
	v_mov_b32_e32 v100, 0
	v_mov_b32_e32 v101, 0
	v_mov_b32_e32 v102, 0
	v_mov_b32_e32 v103, 0
	v_mov_b32_e32 v104, 0
	v_mov_b32_e32 v105, 0
	v_mov_b32_e32 v106, 0
	v_mov_b32_e32 v107, 0
	v_mov_b32_e32 v108, 0
	v_mov_b32_e32 v109, 0
	v_mov_b32_e32 v110, 0
	v_mov_b32_e32 v111, 0
	v_mov_b32_e32 v80, 0
	v_mov_b32_e32 v81, 0
	v_mov_b32_e32 v82, 0
	v_mov_b32_e32 v83, 0
	v_mov_b32_e32 v84, 0
	v_mov_b32_e32 v85, 0
	v_mov_b32_e32 v86, 0
	v_mov_b32_e32 v87, 0
	v_mov_b32_e32 v88, 0
	v_mov_b32_e32 v89, 0
	v_mov_b32_e32 v90, 0
	v_mov_b32_e32 v91, 0
	v_mov_b32_e32 v92, 0
	v_mov_b32_e32 v93, 0
	v_mov_b32_e32 v94, 0
	v_mov_b32_e32 v95, 0
	v_mov_b32_e32 v64, 0
	v_mov_b32_e32 v65, 0
	v_mov_b32_e32 v66, 0
	v_mov_b32_e32 v67, 0
	v_mov_b32_e32 v68, 0
	v_mov_b32_e32 v69, 0
	v_mov_b32_e32 v70, 0
	v_mov_b32_e32 v71, 0
	v_mov_b32_e32 v72, 0
	v_mov_b32_e32 v73, 0
	v_mov_b32_e32 v74, 0
	v_mov_b32_e32 v75, 0
	v_mov_b32_e32 v76, 0
	v_mov_b32_e32 v77, 0
	v_mov_b32_e32 v78, 0
	v_mov_b32_e32 v79, 0
	v_mov_b32_e32 v48, 0
	v_mov_b32_e32 v49, 0
	v_mov_b32_e32 v50, 0
	v_mov_b32_e32 v51, 0
	v_mov_b32_e32 v52, 0
	v_mov_b32_e32 v53, 0
	v_mov_b32_e32 v54, 0
	v_mov_b32_e32 v55, 0
	v_mov_b32_e32 v56, 0
	v_mov_b32_e32 v57, 0
	v_mov_b32_e32 v58, 0
	v_mov_b32_e32 v59, 0
	v_mov_b32_e32 v60, 0
	v_mov_b32_e32 v61, 0
	v_mov_b32_e32 v62, 0
	v_mov_b32_e32 v63, 0
	v_mov_b32_e32 v32, 0
	v_mov_b32_e32 v33, 0
	v_mov_b32_e32 v34, 0
	v_mov_b32_e32 v35, 0
	v_mov_b32_e32 v36, 0
	v_mov_b32_e32 v37, 0
	v_mov_b32_e32 v38, 0
	v_mov_b32_e32 v39, 0
	v_mov_b32_e32 v40, 0
	v_mov_b32_e32 v41, 0
	v_mov_b32_e32 v42, 0
	v_mov_b32_e32 v43, 0
	v_mov_b32_e32 v44, 0
	v_mov_b32_e32 v45, 0
	v_mov_b32_e32 v46, 0
	v_mov_b32_e32 v47, 0
	v_mov_b32_e32 v16, 0
	v_mov_b32_e32 v17, 0
	v_mov_b32_e32 v18, 0
	v_mov_b32_e32 v19, 0
	v_mov_b32_e32 v20, 0
	v_mov_b32_e32 v21, 0
	v_mov_b32_e32 v22, 0
	v_mov_b32_e32 v23, 0
	v_mov_b32_e32 v24, 0
	v_mov_b32_e32 v25, 0
	v_mov_b32_e32 v26, 0
	v_mov_b32_e32 v27, 0
	v_mov_b32_e32 v28, 0
	v_mov_b32_e32 v29, 0
	v_mov_b32_e32 v30, 0
	v_mov_b32_e32 v31, 0
	v_mov_b32_e32 v0, 0
	v_mov_b32_e32 v1, 0
	v_mov_b32_e32 v2, 0
	v_mov_b32_e32 v3, 0
	v_mov_b32_e32 v4, 0
	v_mov_b32_e32 v5, 0
	v_mov_b32_e32 v6, 0
	v_mov_b32_e32 v7, 0
	v_mov_b32_e32 v8, 0
	v_mov_b32_e32 v9, 0
	v_mov_b32_e32 v10, 0
	v_mov_b32_e32 v11, 0
	v_mov_b32_e32 v12, 0
	v_mov_b32_e32 v13, 0
	v_mov_b32_e32 v14, 0
	v_mov_b32_e32 v15, 0
	s_waitcnt vmcnt(6)
	s_barrier
	s_mul_i32 s74, s71, 0x6000
	s_add_u32 s75, s74, 0x2000
	s_cmp_eq_u32 s71, 2
	s_cselect_b32 s75, 0x10000, s75
	v_add_u32_e32 v184, s74, v180
	v_add_u32_e32 v186, s75, v182
	v_add_u32_e32 v185, s74, v181
	v_add_u32_e32 v187, s75, v183
	s_add_u32 s71, s71, 1
	s_cmp_eq_u32 s71, 3
	s_cselect_b32 s71, 0, s71
	ds_read_b128 v[128:131], v184
	ds_read_b128 v[144:147], v186
	ds_read_b128 v[148:151], v186 offset:2048
	ds_read_b128 v[152:155], v186 offset:4096
	ds_read_b128 v[156:159], v186 offset:6144
	ds_read_b128 v[132:135], v184 offset:2048
	ds_read_b128 v[136:139], v185
	ds_read_b128 v[164:167], v187
	ds_read_b128 v[168:171], v187 offset:2048
	ds_read_b128 v[172:175], v187 offset:4096
	ds_read_b128 v[176:179], v187 offset:6144
	ds_read_b128 v[140:143], v185 offset:2048
	s_waitcnt lgkmcnt(10)
	v_mfma_f32_32x32x16_bf16 v[112:127], v[144:147], v[128:131], v[112:127]
	s_mul_i32 s74, s70, 0x6000
	s_add_u32 s75, s74, s68
	s_mov_b32 m0, s75
	s_add_u32 s76, s74, 0x2000
	s_cmp_eq_u32 s70, 2
	s_cselect_b32 s76, 0x10000, s76
	global_load_lds_dwordx4 v160, s[64:65]
	s_waitcnt lgkmcnt(9)
	v_mfma_f32_32x32x16_bf16 v[96:111], v[148:151], v[128:131], v[96:111]
	s_add_u32 m0, s75, 0x400
	s_add_u32 s76, s76, s69
	global_load_lds_dwordx4 v162, s[64:65]
	s_waitcnt lgkmcnt(8)
	v_mfma_f32_32x32x16_bf16 v[80:95], v[152:155], v[128:131], v[80:95]
	s_mov_b32 m0, s76
	s_add_u32 s64, s64, 64
	s_addc_u32 s65, s65, 0
	global_load_lds_dwordx4 v163, s[66:67]
	s_waitcnt lgkmcnt(7)
	v_mfma_f32_32x32x16_bf16 v[64:79], v[156:159], v[128:131], v[64:79]
	global_load_lds_dwordx4 v163, s[66:67] offset:1024
	s_waitcnt lgkmcnt(6)
	v_mfma_f32_32x32x16_bf16 v[48:63], v[144:147], v[132:135], v[48:63]
	global_load_lds_dwordx4 v163, s[66:67] offset:2048
	v_mfma_f32_32x32x16_bf16 v[32:47], v[148:151], v[132:135], v[32:47]
	global_load_lds_dwordx4 v163, s[66:67] offset:3072
	s_add_u32 s66, s66, 0x4000
	s_addc_u32 s67, s67, 0
	v_mfma_f32_32x32x16_bf16 v[16:31], v[152:155], v[132:135], v[16:31]
	s_add_u32 s70, s70, 1
	s_cmp_eq_u32 s70, 3
	s_cselect_b32 s70, 0, s70
	v_mfma_f32_32x32x16_bf16 v[0:15], v[156:159], v[132:135], v[0:15]
; #define MFMA32(a, b, c) __builtin_amdgcn_mfma_f32_32x32x16_bf16((a), (b), (c), 0, 0, 0)
; #define GA_LOAD(pr_) do { _Pragma("unroll") for (int i = 0; i < 4; ++i) ra[i] = *(const u32x4*)(Ab + (i * 32) * lda + (pr_) * 64); } while (0)
; #define GB_LOAD(kt_) do { const bfr* bk_ = Bb + (kt_) * NB * 32; \
;     _Pragma("unroll") for (int i = 0; i < 4; ++i) rb[i] = *(const u32x4*)(bk_ + (i * 64) * 32); } while (0)
; #define G_STORE(kt_) do { bfr* as_ = S0 + ((kt_) & 1) * GSTAGE; bfr* bs_ = as_ + 128 * 40; \
;     if (apar == ((kt_) & 1)) { _Pragma("unroll") for (int i = 0; i < 4; ++i) *(u32x4*)(as_ + asoff + i * 32 * 40) = ra[i]; } \
;     _Pragma("unroll") for (int i = 0; i < 4; ++i) *(u32x4*)(bs_ + bsoff + i * 64 * 40) = rb[i]; } while (0)
; template <int lda>
; DI void gemm_mainloop(const bfr* __restrict__ A, const bfr* __restrict__ Bt, int NB, int K, int m0, int n0, char* smem, f32x16 (&acc)[2][4]) {
;     ...
;   for (int kt = 0; kt < nk; ++kt) {
;     if (kt + 1 < nk) G_STORE(kt + 1);
;     if (kt + 2 < nk) {
;       GB_LOAD(kt + 2);
;       if ((kt & 1) == 0) GA_LOAD((kt >> 1) + 1);
;     }
;     const bfr* As = S0 + (kt & 1) * GSTAGE;
;     const bfr* Bs = As + 128 * 40;
; #pragma unroll
;     for (int ks = 0; ks < 2; ++ks) {
;       bf16x8 af[2], bfg[4];
; #pragma unroll
;       for (int i = 0; i < 2; ++i) af[i] = *(const bf16x8*)(As + (wr * 64 + i * 32 + r) * 40 + ks * 16 + hl * 8);
; #pragma unroll
;       for (int j = 0; j < 4; ++j) bfg[j] = *(const bf16x8*)(Bs + (wc * 128 + j * 32 + r) * 40 + ks * 16 + hl * 8);
; #pragma unroll
;       for (int i = 0; i < 2; ++i)
; #pragma unroll
;         for (int j = 0; j < 4; ++j) acc[i][j] = MFMA32(af[i], bfg[j], acc[i][j]);
;     }
;     __syncthreads();
;   }
.Lp14_loop:
	s_waitcnt vmcnt(6) lgkmcnt(0)
	s_barrier
	s_mul_i32 s74, s71, 0x6000
	s_add_u32 s75, s74, 0x2000
	s_cmp_eq_u32 s71, 2
	s_cselect_b32 s75, 0x10000, s75
	v_add_u32_e32 v184, s74, v180
	v_add_u32_e32 v186, s75, v182
	v_add_u32_e32 v185, s74, v181
	v_add_u32_e32 v187, s75, v183
	s_add_u32 s71, s71, 1
	s_cmp_eq_u32 s71, 3
	s_cselect_b32 s71, 0, s71
	ds_read_b128 v[128:131], v184
	ds_read_b128 v[144:147], v186
	ds_read_b128 v[148:151], v186 offset:2048
	ds_read_b128 v[152:155], v186 offset:4096
	ds_read_b128 v[156:159], v186 offset:6144
	ds_read_b128 v[132:135], v184 offset:2048
	v_mfma_f32_32x32x16_bf16 v[112:127], v[164:167], v[136:139], v[112:127]
	s_mul_i32 s74, s70, 0x6000
	s_add_u32 s75, s74, s68
	s_mov_b32 m0, s75
	s_add_u32 s76, s74, 0x2000
	s_cmp_eq_u32 s70, 2
	s_cselect_b32 s76, 0x10000, s76
	global_load_lds_dwordx4 v160, s[64:65]
	v_mfma_f32_32x32x16_bf16 v[96:111], v[168:171], v[136:139], v[96:111]
	s_add_u32 m0, s75, 0x400
	s_add_u32 s76, s76, s69
	global_load_lds_dwordx4 v162, s[64:65]
	v_mfma_f32_32x32x16_bf16 v[80:95], v[172:175], v[136:139], v[80:95]
	s_mov_b32 m0, s76
	s_add_u32 s64, s64, 64
	s_addc_u32 s65, s65, 0
	global_load_lds_dwordx4 v163, s[66:67]
	v_mfma_f32_32x32x16_bf16 v[64:79], v[176:179], v[136:139], v[64:79]
	global_load_lds_dwordx4 v163, s[66:67] offset:1024
	v_mfma_f32_32x32x16_bf16 v[48:63], v[164:167], v[140:143], v[48:63]
	global_load_lds_dwordx4 v163, s[66:67] offset:2048
	v_mfma_f32_32x32x16_bf16 v[32:47], v[168:171], v[140:143], v[32:47]
	global_load_lds_dwordx4 v163, s[66:67] offset:3072
	s_add_u32 s66, s66, 0x4000
	s_addc_u32 s67, s67, 0
	v_mfma_f32_32x32x16_bf16 v[16:31], v[172:175], v[140:143], v[16:31]
	s_add_u32 s70, s70, 1
	s_cmp_eq_u32 s70, 3
	s_cselect_b32 s70, 0, s70
	v_mfma_f32_32x32x16_bf16 v[0:15], v[176:179], v[140:143], v[0:15]
	ds_read_b128 v[136:139], v185
	ds_read_b128 v[164:167], v187
	ds_read_b128 v[168:171], v187 offset:2048
	ds_read_b128 v[172:175], v187 offset:4096
	ds_read_b128 v[176:179], v187 offset:6144
	ds_read_b128 v[140:143], v185 offset:2048
	s_waitcnt lgkmcnt(10)
	v_mfma_f32_32x32x16_bf16 v[112:127], v[144:147], v[128:131], v[112:127]
	s_waitcnt lgkmcnt(9)
	v_mfma_f32_32x32x16_bf16 v[96:111], v[148:151], v[128:131], v[96:111]
	s_waitcnt lgkmcnt(8)
	v_mfma_f32_32x32x16_bf16 v[80:95], v[152:155], v[128:131], v[80:95]
	s_waitcnt lgkmcnt(7)
	v_mfma_f32_32x32x16_bf16 v[64:79], v[156:159], v[128:131], v[64:79]
	s_waitcnt lgkmcnt(6)
	v_mfma_f32_32x32x16_bf16 v[48:63], v[144:147], v[132:135], v[48:63]
	v_mfma_f32_32x32x16_bf16 v[32:47], v[148:151], v[132:135], v[32:47]
	v_mfma_f32_32x32x16_bf16 v[16:31], v[152:155], v[132:135], v[16:31]
	v_mfma_f32_32x32x16_bf16 v[0:15], v[156:159], v[132:135], v[0:15]
	s_add_u32 s72, s72, 1
	s_cmp_lt_u32 s72, 5
	s_cbranch_scc1 .Lp14_loop
	s_waitcnt vmcnt(6) lgkmcnt(0)
	s_barrier
	s_mul_i32 s74, s71, 0x6000
	s_add_u32 s75, s74, 0x2000
	s_cmp_eq_u32 s71, 2
	s_cselect_b32 s75, 0x10000, s75
	v_add_u32_e32 v184, s74, v180
	v_add_u32_e32 v186, s75, v182
	v_add_u32_e32 v185, s74, v181
	v_add_u32_e32 v187, s75, v183
	s_add_u32 s71, s71, 1
	s_cmp_eq_u32 s71, 3
	s_cselect_b32 s71, 0, s71
	ds_read_b128 v[128:131], v184
	ds_read_b128 v[144:147], v186
	ds_read_b128 v[148:151], v186 offset:2048
	ds_read_b128 v[152:155], v186 offset:4096
	ds_read_b128 v[156:159], v186 offset:6144
	ds_read_b128 v[132:135], v184 offset:2048
	v_mfma_f32_32x32x16_bf16 v[112:127], v[164:167], v[136:139], v[112:127]
	v_mfma_f32_32x32x16_bf16 v[96:111], v[168:171], v[136:139], v[96:111]
	v_mfma_f32_32x32x16_bf16 v[80:95], v[172:175], v[136:139], v[80:95]
	v_mfma_f32_32x32x16_bf16 v[64:79], v[176:179], v[136:139], v[64:79]
	v_mfma_f32_32x32x16_bf16 v[48:63], v[164:167], v[140:143], v[48:63]
	v_mfma_f32_32x32x16_bf16 v[32:47], v[168:171], v[140:143], v[32:47]
	v_mfma_f32_32x32x16_bf16 v[16:31], v[172:175], v[140:143], v[16:31]
	v_mfma_f32_32x32x16_bf16 v[0:15], v[176:179], v[140:143], v[0:15]
	ds_read_b128 v[136:139], v185
	ds_read_b128 v[164:167], v187
	ds_read_b128 v[168:171], v187 offset:2048
	ds_read_b128 v[172:175], v187 offset:4096
	ds_read_b128 v[176:179], v187 offset:6144
	ds_read_b128 v[140:143], v185 offset:2048
	s_waitcnt lgkmcnt(10)
	v_mfma_f32_32x32x16_bf16 v[112:127], v[144:147], v[128:131], v[112:127]
	s_waitcnt lgkmcnt(9)
	v_mfma_f32_32x32x16_bf16 v[96:111], v[148:151], v[128:131], v[96:111]
	s_waitcnt lgkmcnt(8)
	v_mfma_f32_32x32x16_bf16 v[80:95], v[152:155], v[128:131], v[80:95]
	s_waitcnt lgkmcnt(7)
	v_mfma_f32_32x32x16_bf16 v[64:79], v[156:159], v[128:131], v[64:79]
	s_waitcnt lgkmcnt(6)
	v_mfma_f32_32x32x16_bf16 v[48:63], v[144:147], v[132:135], v[48:63]
	v_mfma_f32_32x32x16_bf16 v[32:47], v[148:151], v[132:135], v[32:47]
	v_mfma_f32_32x32x16_bf16 v[16:31], v[152:155], v[132:135], v[16:31]
	v_mfma_f32_32x32x16_bf16 v[0:15], v[156:159], v[132:135], v[0:15]
	s_waitcnt vmcnt(0) lgkmcnt(0)
	s_barrier
; #define MFMA32(a, b, c) __builtin_amdgcn_mfma_f32_32x32x16_bf16((a), (b), (c), 0, 0, 0)
; DI bfr f2bf(float a) { return (bfr)(pack2(a, 0.f) & 0xffffu); }
; DI float bf2f(bfr u) { return __uint_as_float(((unsigned)u) << 16); }
; DI float siluf_(float x) { return x / (1.0f + __expf(-x)); }
; #define GA_LOAD(pr_) do { _Pragma("unroll") for (int i = 0; i < 4; ++i) ra[i] = *(const u32x4*)(Ab + (i * 32) * lda + (pr_) * 64); } while (0)
; #define GB_LOAD(kt_) do { const bfr* bk_ = Bb + (kt_) * NB * 32; \
;     _Pragma("unroll") for (int i = 0; i < 4; ++i) rb[i] = *(const u32x4*)(bk_ + (i * 64) * 32); } while (0)
; #define G_STORE(kt_) do { bfr* as_ = S0 + ((kt_) & 1) * GSTAGE; bfr* bs_ = as_ + 128 * 40; \
;     if (apar == ((kt_) & 1)) { _Pragma("unroll") for (int i = 0; i < 4; ++i) *(u32x4*)(as_ + asoff + i * 32 * 40) = ra[i]; } \
;     _Pragma("unroll") for (int i = 0; i < 4; ++i) *(u32x4*)(bs_ + bsoff + i * 64 * 40) = rb[i]; } while (0)
; template <int lda>
; DI void gemm_mainloop(const bfr* __restrict__ A, const bfr* __restrict__ Bt, int NB, int K, int m0, int n0, char* smem, f32x16 (&acc)[2][4]) {
;     ...
;   for (int kt = 0; kt < nk; ++kt) {
;     if (kt + 1 < nk) G_STORE(kt + 1);
;     if (kt + 2 < nk) {
;       GB_LOAD(kt + 2);
;       if ((kt & 1) == 0) GA_LOAD((kt >> 1) + 1);
;     }
;     const bfr* As = S0 + (kt & 1) * GSTAGE;
;     const bfr* Bs = As + 128 * 40;
; #pragma unroll
;     for (int ks = 0; ks < 2; ++ks) {
;       bf16x8 af[2], bfg[4];
; #pragma unroll
;       for (int i = 0; i < 2; ++i) af[i] = *(const bf16x8*)(As + (wr * 64 + i * 32 + r) * 40 + ks * 16 + hl * 8);
; #pragma unroll
;       for (int j = 0; j < 4; ++j) bfg[j] = *(const bf16x8*)(Bs + (wc * 128 + j * 32 + r) * 40 + ks * 16 + hl * 8);
; #pragma unroll
;       for (int i = 0; i < 2; ++i)
; #pragma unroll
;         for (int j = 0; j < 4; ++j) acc[i][j] = MFMA32(af[i], bfg[j], acc[i][j]);
;     }
;     __syncthreads();
;   }
; DI void phase_gemm_pool(const Params& p, char* smem) {
;     ...
;     gemm_tile<1024>(p.MIX + g * 256, p.WtPool + (size_t)g * 65536, 256, 256, mt * 128, nt * 256, smem,
;               [=](int row, int col, float v) {
;                 float gate = bf2f(P2[(size_t)row * 2048 + 1024 + g * 256 + col]);
;                 float z = (v + bp[col]) * sc[col] * siluf_(gate);
;                 Z[(size_t)row * 1024 + g * 256 + col] = f2bf(z);
;               });
	s_mul_i32 s74, s71, 0x6000
	s_add_u32 s75, s74, 0x2000
	s_cmp_eq_u32 s71, 2
	s_cselect_b32 s75, 0x10000, s75
	v_add_u32_e32 v184, s74, v180
	v_add_u32_e32 v186, s75, v182
	v_add_u32_e32 v185, s74, v181
	v_add_u32_e32 v187, s75, v183
	s_add_u32 s71, s71, 1
	s_cmp_eq_u32 s71, 3
	s_cselect_b32 s71, 0, s71
	ds_read_b128 v[128:131], v184
	ds_read_b128 v[144:147], v186
	ds_read_b128 v[148:151], v186 offset:2048
	ds_read_b128 v[152:155], v186 offset:4096
	ds_read_b128 v[156:159], v186 offset:6144
	ds_read_b128 v[132:135], v184 offset:2048
	v_mfma_f32_32x32x16_bf16 v[112:127], v[164:167], v[136:139], v[112:127]
	v_mfma_f32_32x32x16_bf16 v[96:111], v[168:171], v[136:139], v[96:111]
	v_mfma_f32_32x32x16_bf16 v[80:95], v[172:175], v[136:139], v[80:95]
	v_mfma_f32_32x32x16_bf16 v[64:79], v[176:179], v[136:139], v[64:79]
	v_mfma_f32_32x32x16_bf16 v[48:63], v[164:167], v[140:143], v[48:63]
	v_mfma_f32_32x32x16_bf16 v[32:47], v[168:171], v[140:143], v[32:47]
	v_mfma_f32_32x32x16_bf16 v[16:31], v[172:175], v[140:143], v[16:31]
	v_mfma_f32_32x32x16_bf16 v[0:15], v[176:179], v[140:143], v[0:15]
	ds_read_b128 v[136:139], v185
	ds_read_b128 v[164:167], v187
	ds_read_b128 v[168:171], v187 offset:2048
	ds_read_b128 v[172:175], v187 offset:4096
	ds_read_b128 v[176:179], v187 offset:6144
	ds_read_b128 v[140:143], v185 offset:2048
	s_waitcnt lgkmcnt(10)
	v_mfma_f32_32x32x16_bf16 v[112:127], v[144:147], v[128:131], v[112:127]
	s_waitcnt lgkmcnt(9)
	v_mfma_f32_32x32x16_bf16 v[96:111], v[148:151], v[128:131], v[96:111]
	s_waitcnt lgkmcnt(8)
	v_mfma_f32_32x32x16_bf16 v[80:95], v[152:155], v[128:131], v[80:95]
	s_waitcnt lgkmcnt(7)
	v_mfma_f32_32x32x16_bf16 v[64:79], v[156:159], v[128:131], v[64:79]
	s_waitcnt lgkmcnt(6)
	v_mfma_f32_32x32x16_bf16 v[48:63], v[144:147], v[132:135], v[48:63]
	v_mfma_f32_32x32x16_bf16 v[32:47], v[148:151], v[132:135], v[32:47]
	v_mfma_f32_32x32x16_bf16 v[16:31], v[152:155], v[132:135], v[16:31]
	v_mfma_f32_32x32x16_bf16 v[0:15], v[156:159], v[132:135], v[0:15]
	s_waitcnt lgkmcnt(0)
	v_mfma_f32_32x32x16_bf16 v[112:127], v[164:167], v[136:139], v[112:127]
	v_mfma_f32_32x32x16_bf16 v[96:111], v[168:171], v[136:139], v[96:111]
	v_mfma_f32_32x32x16_bf16 v[80:95], v[172:175], v[136:139], v[80:95]
	v_mfma_f32_32x32x16_bf16 v[64:79], v[176:179], v[136:139], v[64:79]
	v_mfma_f32_32x32x16_bf16 v[48:63], v[164:167], v[140:143], v[48:63]
	v_mfma_f32_32x32x16_bf16 v[32:47], v[168:171], v[140:143], v[32:47]
	v_mfma_f32_32x32x16_bf16 v[16:31], v[172:175], v[140:143], v[16:31]
	v_mfma_f32_32x32x16_bf16 v[0:15], v[176:179], v[140:143], v[0:15]
	s_nop 7
	s_nop 3
	s_load_dwordx2 s[64:65], s[92:93], 0x150
	s_load_dwordx2 s[66:67], s[92:93], 0x168
	s_load_dwordx4 s[68:71], s[92:93], 0xc0
	s_mul_i32 s76, s73, 8704
	s_lshr_b32 s74, s73, 1
	s_lshl_b32 s74, s74, 6
	s_add_u32 s74, s74, s77
	s_and_b32 s75, s73, 1
	s_lshl_b32 s75, s75, 7
	s_add_u32 s75, s75, s78
	v_and_b32_e32 v189, 31, v196
	v_bfe_u32 v190, v196, 5, 1
	v_mul_u32_u24_e32 v191, 272, v189
	v_add_u32_e32 v191, s76, v191
	v_lshl_add_u32 v160, v190, 3, v191
	v_lshlrev_b32_e32 v191, 2, v190
	v_add_lshl_u32 v181, v191, s75, 2
	v_bfe_u32 v189, v196, 4, 2
	v_and_b32_e32 v190, 15, v196
	v_mul_u32_u24_e32 v191, 272, v189
	v_lshl_add_u32 v191, v190, 4, v191
	v_add_u32_e32 v162, s76, v191
	v_add_u32_e32 v191, s74, v189
	v_lshlrev_b32_e32 v192, 3, v190
	v_add_u32_e32 v192, s75, v192
	v_lshl_add_u32 v189, v191, 10, v192
	v_lshlrev_b32_e32 v180, 1, v189
	v_add_u32_e32 v192, 0x400, v192
	v_lshl_add_u32 v189, v191, 11, v192
	v_lshlrev_b32_e32 v163, 1, v189
	s_waitcnt lgkmcnt(0)
	s_barrier
	s_add_u32 s74, s64, 0x0
	s_addc_u32 s75, s65, 0
	global_load_dwordx4 v[128:131], v163, s[74:75]
	s_add_u32 s74, s64, 0x4000
	s_addc_u32 s75, s65, 0
	global_load_dwordx4 v[132:135], v163, s[74:75]
	s_add_u32 s74, s64, 0x8000
	s_addc_u32 s75, s65, 0
	global_load_dwordx4 v[136:139], v163, s[74:75]
	s_add_u32 s74, s64, 0xc000
	s_addc_u32 s75, s65, 0
	global_load_dwordx4 v[140:143], v163, s[74:75]
	s_add_u32 s74, s64, 0x10000
	s_addc_u32 s75, s65, 0
	global_load_dwordx4 v[144:147], v163, s[74:75]
	s_add_u32 s74, s64, 0x14000
	s_addc_u32 s75, s65, 0
	global_load_dwordx4 v[148:151], v163, s[74:75]
	s_add_u32 s74, s64, 0x18000
	s_addc_u32 s75, s65, 0
	global_load_dwordx4 v[152:155], v163, s[74:75]
	s_add_u32 s74, s64, 0x1c000
	s_addc_u32 s75, s65, 0
	global_load_dwordx4 v[156:159], v163, s[74:75]
	s_waitcnt vmcnt(7)
	ds_write_b128 v162, v[128:131]
	s_waitcnt vmcnt(6)
	ds_write_b128 v162, v[132:135] offset:1088
	s_waitcnt vmcnt(5)
	ds_write_b128 v162, v[136:139] offset:2176
	s_waitcnt vmcnt(4)
	ds_write_b128 v162, v[140:143] offset:3264
	s_waitcnt vmcnt(3)
	ds_write_b128 v162, v[144:147] offset:4352
	s_waitcnt vmcnt(2)
	ds_write_b128 v162, v[148:151] offset:5440
	s_waitcnt vmcnt(1)
	ds_write_b128 v162, v[152:155] offset:6528
	s_waitcnt vmcnt(0)
	ds_write_b128 v162, v[156:159] offset:7616
	global_load_dwordx4 v[128:131], v181, s[68:69]
	global_load_dwordx4 v[132:135], v181, s[68:69] offset:32
	global_load_dwordx4 v[136:139], v181, s[68:69] offset:64
	global_load_dwordx4 v[140:143], v181, s[68:69] offset:96
	global_load_dwordx4 v[144:147], v181, s[70:71]
	global_load_dwordx4 v[148:151], v181, s[70:71] offset:32
	global_load_dwordx4 v[152:155], v181, s[70:71] offset:64
	global_load_dwordx4 v[156:159], v181, s[70:71] offset:96
	ds_read_b64 v[164:165], v160
	s_waitcnt vmcnt(3) lgkmcnt(0)
; DI bfr f2bf(float a) { return (bfr)(pack2(a, 0.f) & 0xffffu); }
; DI float bf2f(bfr u) { return __uint_as_float(((unsigned)u) << 16); }
; DI float siluf_(float x) { return x / (1.0f + __expf(-x)); }
; DI void phase_gemm_pool(const Params& p, char* smem) {
;     ...
;               [=](int row, int col, float v) {
;                 float gate = bf2f(P2[(size_t)row * 2048 + 1024 + g * 256 + col]);
;                 float z = (v + bp[col]) * sc[col] * siluf_(gate);
;                 Z[(size_t)row * 1024 + g * 256 + col] = f2bf(z);
;               });
	v_lshlrev_b32_e32 v182, 16, v164
	v_and_b32_e32 v183, 0xffff0000, v164
	v_lshlrev_b32_e32 v184, 16, v165
	v_and_b32_e32 v185, 0xffff0000, v165
	v_add_f32_e32 v112, v128, v112
	v_mul_f32_e32 v112, v144, v112
	v_add_f32_e32 v113, v129, v113
	v_mul_f32_e32 v113, v145, v113
	v_add_f32_e32 v114, v130, v114
	v_mul_f32_e32 v114, v146, v114
	v_add_f32_e32 v115, v131, v115
	v_mul_f32_e32 v115, v147, v115
	v_mul_f32_e32 v189, 0xbfb8aa3b, v182
	v_mul_f32_e32 v190, 0xbfb8aa3b, v183
	v_mul_f32_e32 v191, 0xbfb8aa3b, v184
	v_mul_f32_e32 v192, 0xbfb8aa3b, v185
	v_exp_f32_e32 v189, v189
	v_exp_f32_e32 v190, v190
	v_exp_f32_e32 v191, v191
	v_exp_f32_e32 v192, v192
	s_nop 0
	v_add_f32_e32 v189, 1.0, v189
	v_add_f32_e32 v190, 1.0, v190
	v_add_f32_e32 v191, 1.0, v191
	v_add_f32_e32 v192, 1.0, v192
	v_rcp_f32_e32 v166, v189
	v_rcp_f32_e32 v167, v190
	s_nop 0
	v_fma_f32 v189, -v189, v166, 2.0
	v_fma_f32 v190, -v190, v167, 2.0
	v_mul_f32_e32 v166, v166, v189
	v_mul_f32_e32 v167, v167, v190
	v_mul_f32_e32 v182, v182, v166
	v_mul_f32_e32 v183, v183, v167
	v_rcp_f32_e32 v166, v191
	v_rcp_f32_e32 v167, v192
	s_nop 0
	v_fma_f32 v191, -v191, v166, 2.0
	v_fma_f32 v192, -v192, v167, 2.0
	v_mul_f32_e32 v166, v166, v191
	v_mul_f32_e32 v167, v167, v192
	v_mul_f32_e32 v184, v184, v166
	v_mul_f32_e32 v185, v185, v167
	v_mul_f32_e32 v112, v182, v112
	v_mul_f32_e32 v113, v183, v113
	v_mul_f32_e32 v114, v184, v114
	v_mul_f32_e32 v115, v185, v115
	v_cvt_pk_bf16_f32 v112, v112, v113
	v_cvt_pk_bf16_f32 v113, v114, v115
	ds_write_b64 v160, v[112:113]
	ds_read_b64 v[164:165], v160 offset:16
	s_waitcnt vmcnt(2) lgkmcnt(0)
	v_lshlrev_b32_e32 v182, 16, v164
	v_and_b32_e32 v183, 0xffff0000, v164
	v_lshlrev_b32_e32 v184, 16, v165
	v_and_b32_e32 v185, 0xffff0000, v165
	v_add_f32_e32 v116, v132, v116
	v_mul_f32_e32 v116, v148, v116
	v_add_f32_e32 v117, v133, v117
	v_mul_f32_e32 v117, v149, v117
	v_add_f32_e32 v118, v134, v118
	v_mul_f32_e32 v118, v150, v118
	v_add_f32_e32 v119, v135, v119
	v_mul_f32_e32 v119, v151, v119
	v_mul_f32_e32 v189, 0xbfb8aa3b, v182
	v_mul_f32_e32 v190, 0xbfb8aa3b, v183
	v_mul_f32_e32 v191, 0xbfb8aa3b, v184
	v_mul_f32_e32 v192, 0xbfb8aa3b, v185
	v_exp_f32_e32 v189, v189
	v_exp_f32_e32 v190, v190
	v_exp_f32_e32 v191, v191
	v_exp_f32_e32 v192, v192
	s_nop 0
	v_add_f32_e32 v189, 1.0, v189
	v_add_f32_e32 v190, 1.0, v190
	v_add_f32_e32 v191, 1.0, v191
	v_add_f32_e32 v192, 1.0, v192
	v_rcp_f32_e32 v166, v189
	v_rcp_f32_e32 v167, v190
	s_nop 0
	v_fma_f32 v189, -v189, v166, 2.0
	v_fma_f32 v190, -v190, v167, 2.0
	v_mul_f32_e32 v166, v166, v189
	v_mul_f32_e32 v167, v167, v190
	v_mul_f32_e32 v182, v182, v166
	v_mul_f32_e32 v183, v183, v167
	v_rcp_f32_e32 v166, v191
	v_rcp_f32_e32 v167, v192
	s_nop 0
	v_fma_f32 v191, -v191, v166, 2.0
	v_fma_f32 v192, -v192, v167, 2.0
	v_mul_f32_e32 v166, v166, v191
	v_mul_f32_e32 v167, v167, v192
	v_mul_f32_e32 v184, v184, v166
	v_mul_f32_e32 v185, v185, v167
	v_mul_f32_e32 v116, v182, v116
	v_mul_f32_e32 v117, v183, v117
	v_mul_f32_e32 v118, v184, v118
	v_mul_f32_e32 v119, v185, v119
	v_cvt_pk_bf16_f32 v116, v116, v117
	v_cvt_pk_bf16_f32 v117, v118, v119
	ds_write_b64 v160, v[116:117] offset:16
	ds_read_b64 v[164:165], v160 offset:32
	s_waitcnt vmcnt(1) lgkmcnt(0)
	v_lshlrev_b32_e32 v182, 16, v164
	v_and_b32_e32 v183, 0xffff0000, v164
	v_lshlrev_b32_e32 v184, 16, v165
	v_and_b32_e32 v185, 0xffff0000, v165
	v_add_f32_e32 v120, v136, v120
	v_mul_f32_e32 v120, v152, v120
	v_add_f32_e32 v121, v137, v121
	v_mul_f32_e32 v121, v153, v121
	v_add_f32_e32 v122, v138, v122
	v_mul_f32_e32 v122, v154, v122
	v_add_f32_e32 v123, v139, v123
	v_mul_f32_e32 v123, v155, v123
	v_mul_f32_e32 v189, 0xbfb8aa3b, v182
	v_mul_f32_e32 v190, 0xbfb8aa3b, v183
	v_mul_f32_e32 v191, 0xbfb8aa3b, v184
	v_mul_f32_e32 v192, 0xbfb8aa3b, v185
	v_exp_f32_e32 v189, v189
	v_exp_f32_e32 v190, v190
	v_exp_f32_e32 v191, v191
	v_exp_f32_e32 v192, v192
	s_nop 0
	v_add_f32_e32 v189, 1.0, v189
	v_add_f32_e32 v190, 1.0, v190
	v_add_f32_e32 v191, 1.0, v191
	v_add_f32_e32 v192, 1.0, v192
	v_rcp_f32_e32 v166, v189
	v_rcp_f32_e32 v167, v190
	s_nop 0
	v_fma_f32 v189, -v189, v166, 2.0
	v_fma_f32 v190, -v190, v167, 2.0
	v_mul_f32_e32 v166, v166, v189
	v_mul_f32_e32 v167, v167, v190
	v_mul_f32_e32 v182, v182, v166
	v_mul_f32_e32 v183, v183, v167
	v_rcp_f32_e32 v166, v191
	v_rcp_f32_e32 v167, v192
	s_nop 0
	v_fma_f32 v191, -v191, v166, 2.0
	v_fma_f32 v192, -v192, v167, 2.0
	v_mul_f32_e32 v166, v166, v191
	v_mul_f32_e32 v167, v167, v192
	v_mul_f32_e32 v184, v184, v166
	v_mul_f32_e32 v185, v185, v167
	v_mul_f32_e32 v120, v182, v120
	v_mul_f32_e32 v121, v183, v121
	v_mul_f32_e32 v122, v184, v122
	v_mul_f32_e32 v123, v185, v123
	v_cvt_pk_bf16_f32 v120, v120, v121
	v_cvt_pk_bf16_f32 v121, v122, v123
	ds_write_b64 v160, v[120:121] offset:32
	ds_read_b64 v[164:165], v160 offset:48
	s_waitcnt vmcnt(0) lgkmcnt(0)
; DI bfr f2bf(float a) { return (bfr)(pack2(a, 0.f) & 0xffffu); }
; DI float bf2f(bfr u) { return __uint_as_float(((unsigned)u) << 16); }
; DI float siluf_(float x) { return x / (1.0f + __expf(-x)); }
; DI void phase_gemm_pool(const Params& p, char* smem) {
;     ...
;               [=](int row, int col, float v) {
;                 float gate = bf2f(P2[(size_t)row * 2048 + 1024 + g * 256 + col]);
;                 float z = (v + bp[col]) * sc[col] * siluf_(gate);
;                 Z[(size_t)row * 1024 + g * 256 + col] = f2bf(z);
;               });
	v_lshlrev_b32_e32 v182, 16, v164
	v_and_b32_e32 v183, 0xffff0000, v164
	v_lshlrev_b32_e32 v184, 16, v165
	v_and_b32_e32 v185, 0xffff0000, v165
	v_add_f32_e32 v124, v140, v124
	v_mul_f32_e32 v124, v156, v124
	v_add_f32_e32 v125, v141, v125
	v_mul_f32_e32 v125, v157, v125
	v_add_f32_e32 v126, v142, v126
	v_mul_f32_e32 v126, v158, v126
	v_add_f32_e32 v127, v143, v127
	v_mul_f32_e32 v127, v159, v127
	v_mul_f32_e32 v189, 0xbfb8aa3b, v182
	v_mul_f32_e32 v190, 0xbfb8aa3b, v183
	v_mul_f32_e32 v191, 0xbfb8aa3b, v184
	v_mul_f32_e32 v192, 0xbfb8aa3b, v185
	v_exp_f32_e32 v189, v189
	v_exp_f32_e32 v190, v190
	v_exp_f32_e32 v191, v191
	v_exp_f32_e32 v192, v192
	s_nop 0
	v_add_f32_e32 v189, 1.0, v189
	v_add_f32_e32 v190, 1.0, v190
	v_add_f32_e32 v191, 1.0, v191
	v_add_f32_e32 v192, 1.0, v192
	v_rcp_f32_e32 v166, v189
	v_rcp_f32_e32 v167, v190
	s_nop 0
	v_fma_f32 v189, -v189, v166, 2.0
	v_fma_f32 v190, -v190, v167, 2.0
	v_mul_f32_e32 v166, v166, v189
	v_mul_f32_e32 v167, v167, v190
	v_mul_f32_e32 v182, v182, v166
	v_mul_f32_e32 v183, v183, v167
	v_rcp_f32_e32 v166, v191
	v_rcp_f32_e32 v167, v192
	s_nop 0
	v_fma_f32 v191, -v191, v166, 2.0
	v_fma_f32 v192, -v192, v167, 2.0
	v_mul_f32_e32 v166, v166, v191
	v_mul_f32_e32 v167, v167, v192
	v_mul_f32_e32 v184, v184, v166
	v_mul_f32_e32 v185, v185, v167
	v_mul_f32_e32 v124, v182, v124
	v_mul_f32_e32 v125, v183, v125
	v_mul_f32_e32 v126, v184, v126
	v_mul_f32_e32 v127, v185, v127
	v_cvt_pk_bf16_f32 v124, v124, v125
	v_cvt_pk_bf16_f32 v125, v126, v127
	ds_write_b64 v160, v[124:125] offset:48
	global_load_dwordx4 v[128:131], v181, s[68:69] offset:128
	global_load_dwordx4 v[132:135], v181, s[68:69] offset:160
	global_load_dwordx4 v[136:139], v181, s[68:69] offset:192
	global_load_dwordx4 v[140:143], v181, s[68:69] offset:224
	global_load_dwordx4 v[144:147], v181, s[70:71] offset:128
	global_load_dwordx4 v[148:151], v181, s[70:71] offset:160
	global_load_dwordx4 v[152:155], v181, s[70:71] offset:192
	global_load_dwordx4 v[156:159], v181, s[70:71] offset:224
	ds_read_b64 v[164:165], v160 offset:64
	s_waitcnt vmcnt(3) lgkmcnt(0)
	v_lshlrev_b32_e32 v182, 16, v164
	v_and_b32_e32 v183, 0xffff0000, v164
	v_lshlrev_b32_e32 v184, 16, v165
	v_and_b32_e32 v185, 0xffff0000, v165
	v_add_f32_e32 v96, v128, v96
	v_mul_f32_e32 v96, v144, v96
	v_add_f32_e32 v97, v129, v97
	v_mul_f32_e32 v97, v145, v97
	v_add_f32_e32 v98, v130, v98
	v_mul_f32_e32 v98, v146, v98
	v_add_f32_e32 v99, v131, v99
	v_mul_f32_e32 v99, v147, v99
	v_mul_f32_e32 v189, 0xbfb8aa3b, v182
	v_mul_f32_e32 v190, 0xbfb8aa3b, v183
	v_mul_f32_e32 v191, 0xbfb8aa3b, v184
	v_mul_f32_e32 v192, 0xbfb8aa3b, v185
	v_exp_f32_e32 v189, v189
	v_exp_f32_e32 v190, v190
	v_exp_f32_e32 v191, v191
	v_exp_f32_e32 v192, v192
	s_nop 0
	v_add_f32_e32 v189, 1.0, v189
	v_add_f32_e32 v190, 1.0, v190
	v_add_f32_e32 v191, 1.0, v191
	v_add_f32_e32 v192, 1.0, v192
	v_rcp_f32_e32 v166, v189
	v_rcp_f32_e32 v167, v190
	s_nop 0
	v_fma_f32 v189, -v189, v166, 2.0
	v_fma_f32 v190, -v190, v167, 2.0
	v_mul_f32_e32 v166, v166, v189
	v_mul_f32_e32 v167, v167, v190
	v_mul_f32_e32 v182, v182, v166
	v_mul_f32_e32 v183, v183, v167
	v_rcp_f32_e32 v166, v191
	v_rcp_f32_e32 v167, v192
	s_nop 0
	v_fma_f32 v191, -v191, v166, 2.0
	v_fma_f32 v192, -v192, v167, 2.0
	v_mul_f32_e32 v166, v166, v191
	v_mul_f32_e32 v167, v167, v192
	v_mul_f32_e32 v184, v184, v166
	v_mul_f32_e32 v185, v185, v167
	v_mul_f32_e32 v96, v182, v96
	v_mul_f32_e32 v97, v183, v97
	v_mul_f32_e32 v98, v184, v98
	v_mul_f32_e32 v99, v185, v99
	v_cvt_pk_bf16_f32 v96, v96, v97
	v_cvt_pk_bf16_f32 v97, v98, v99
	ds_write_b64 v160, v[96:97] offset:64
	ds_read_b64 v[164:165], v160 offset:80
	s_waitcnt vmcnt(2) lgkmcnt(0)
	v_lshlrev_b32_e32 v182, 16, v164
	v_and_b32_e32 v183, 0xffff0000, v164
	v_lshlrev_b32_e32 v184, 16, v165
	v_and_b32_e32 v185, 0xffff0000, v165
	v_add_f32_e32 v100, v132, v100
	v_mul_f32_e32 v100, v148, v100
	v_add_f32_e32 v101, v133, v101
	v_mul_f32_e32 v101, v149, v101
	v_add_f32_e32 v102, v134, v102
	v_mul_f32_e32 v102, v150, v102
	v_add_f32_e32 v103, v135, v103
	v_mul_f32_e32 v103, v151, v103
	v_mul_f32_e32 v189, 0xbfb8aa3b, v182
	v_mul_f32_e32 v190, 0xbfb8aa3b, v183
	v_mul_f32_e32 v191, 0xbfb8aa3b, v184
	v_mul_f32_e32 v192, 0xbfb8aa3b, v185
	v_exp_f32_e32 v189, v189
	v_exp_f32_e32 v190, v190
	v_exp_f32_e32 v191, v191
	v_exp_f32_e32 v192, v192
	s_nop 0
	v_add_f32_e32 v189, 1.0, v189
	v_add_f32_e32 v190, 1.0, v190
	v_add_f32_e32 v191, 1.0, v191
	v_add_f32_e32 v192, 1.0, v192
	v_rcp_f32_e32 v166, v189
	v_rcp_f32_e32 v167, v190
	s_nop 0
	v_fma_f32 v189, -v189, v166, 2.0
	v_fma_f32 v190, -v190, v167, 2.0
	v_mul_f32_e32 v166, v166, v189
	v_mul_f32_e32 v167, v167, v190
	v_mul_f32_e32 v182, v182, v166
	v_mul_f32_e32 v183, v183, v167
	v_rcp_f32_e32 v166, v191
	v_rcp_f32_e32 v167, v192
	s_nop 0
	v_fma_f32 v191, -v191, v166, 2.0
	v_fma_f32 v192, -v192, v167, 2.0
	v_mul_f32_e32 v166, v166, v191
	v_mul_f32_e32 v167, v167, v192
	v_mul_f32_e32 v184, v184, v166
	v_mul_f32_e32 v185, v185, v167
	v_mul_f32_e32 v100, v182, v100
	v_mul_f32_e32 v101, v183, v101
	v_mul_f32_e32 v102, v184, v102
	v_mul_f32_e32 v103, v185, v103
	v_cvt_pk_bf16_f32 v100, v100, v101
	v_cvt_pk_bf16_f32 v101, v102, v103
	ds_write_b64 v160, v[100:101] offset:80
	ds_read_b64 v[164:165], v160 offset:96
	s_waitcnt vmcnt(1) lgkmcnt(0)
; DI bfr f2bf(float a) { return (bfr)(pack2(a, 0.f) & 0xffffu); }
; DI float bf2f(bfr u) { return __uint_as_float(((unsigned)u) << 16); }
; DI float siluf_(float x) { return x / (1.0f + __expf(-x)); }
; DI void phase_gemm_pool(const Params& p, char* smem) {
;     ...
;               [=](int row, int col, float v) {
;                 float gate = bf2f(P2[(size_t)row * 2048 + 1024 + g * 256 + col]);
;                 float z = (v + bp[col]) * sc[col] * siluf_(gate);
;                 Z[(size_t)row * 1024 + g * 256 + col] = f2bf(z);
;               });
	v_lshlrev_b32_e32 v182, 16, v164
	v_and_b32_e32 v183, 0xffff0000, v164
	v_lshlrev_b32_e32 v184, 16, v165
	v_and_b32_e32 v185, 0xffff0000, v165
	v_add_f32_e32 v104, v136, v104
	v_mul_f32_e32 v104, v152, v104
	v_add_f32_e32 v105, v137, v105
	v_mul_f32_e32 v105, v153, v105
	v_add_f32_e32 v106, v138, v106
	v_mul_f32_e32 v106, v154, v106
	v_add_f32_e32 v107, v139, v107
	v_mul_f32_e32 v107, v155, v107
	v_mul_f32_e32 v189, 0xbfb8aa3b, v182
	v_mul_f32_e32 v190, 0xbfb8aa3b, v183
	v_mul_f32_e32 v191, 0xbfb8aa3b, v184
	v_mul_f32_e32 v192, 0xbfb8aa3b, v185
	v_exp_f32_e32 v189, v189
	v_exp_f32_e32 v190, v190
	v_exp_f32_e32 v191, v191
	v_exp_f32_e32 v192, v192
	s_nop 0
	v_add_f32_e32 v189, 1.0, v189
	v_add_f32_e32 v190, 1.0, v190
	v_add_f32_e32 v191, 1.0, v191
	v_add_f32_e32 v192, 1.0, v192
	v_rcp_f32_e32 v166, v189
	v_rcp_f32_e32 v167, v190
	s_nop 0
	v_fma_f32 v189, -v189, v166, 2.0
	v_fma_f32 v190, -v190, v167, 2.0
	v_mul_f32_e32 v166, v166, v189
	v_mul_f32_e32 v167, v167, v190
	v_mul_f32_e32 v182, v182, v166
	v_mul_f32_e32 v183, v183, v167
	v_rcp_f32_e32 v166, v191
	v_rcp_f32_e32 v167, v192
	s_nop 0
	v_fma_f32 v191, -v191, v166, 2.0
	v_fma_f32 v192, -v192, v167, 2.0
	v_mul_f32_e32 v166, v166, v191
	v_mul_f32_e32 v167, v167, v192
	v_mul_f32_e32 v184, v184, v166
	v_mul_f32_e32 v185, v185, v167
	v_mul_f32_e32 v104, v182, v104
	v_mul_f32_e32 v105, v183, v105
	v_mul_f32_e32 v106, v184, v106
	v_mul_f32_e32 v107, v185, v107
	v_cvt_pk_bf16_f32 v104, v104, v105
	v_cvt_pk_bf16_f32 v105, v106, v107
	ds_write_b64 v160, v[104:105] offset:96
	ds_read_b64 v[164:165], v160 offset:112
	s_waitcnt vmcnt(0) lgkmcnt(0)
	v_lshlrev_b32_e32 v182, 16, v164
	v_and_b32_e32 v183, 0xffff0000, v164
	v_lshlrev_b32_e32 v184, 16, v165
	v_and_b32_e32 v185, 0xffff0000, v165
	v_add_f32_e32 v108, v140, v108
	v_mul_f32_e32 v108, v156, v108
	v_add_f32_e32 v109, v141, v109
	v_mul_f32_e32 v109, v157, v109
	v_add_f32_e32 v110, v142, v110
	v_mul_f32_e32 v110, v158, v110
	v_add_f32_e32 v111, v143, v111
	v_mul_f32_e32 v111, v159, v111
	v_mul_f32_e32 v189, 0xbfb8aa3b, v182
	v_mul_f32_e32 v190, 0xbfb8aa3b, v183
	v_mul_f32_e32 v191, 0xbfb8aa3b, v184
	v_mul_f32_e32 v192, 0xbfb8aa3b, v185
	v_exp_f32_e32 v189, v189
	v_exp_f32_e32 v190, v190
	v_exp_f32_e32 v191, v191
	v_exp_f32_e32 v192, v192
	s_nop 0
	v_add_f32_e32 v189, 1.0, v189
	v_add_f32_e32 v190, 1.0, v190
	v_add_f32_e32 v191, 1.0, v191
	v_add_f32_e32 v192, 1.0, v192
	v_rcp_f32_e32 v166, v189
	v_rcp_f32_e32 v167, v190
	s_nop 0
	v_fma_f32 v189, -v189, v166, 2.0
	v_fma_f32 v190, -v190, v167, 2.0
	v_mul_f32_e32 v166, v166, v189
	v_mul_f32_e32 v167, v167, v190
	v_mul_f32_e32 v182, v182, v166
	v_mul_f32_e32 v183, v183, v167
	v_rcp_f32_e32 v166, v191
	v_rcp_f32_e32 v167, v192
	s_nop 0
	v_fma_f32 v191, -v191, v166, 2.0
	v_fma_f32 v192, -v192, v167, 2.0
	v_mul_f32_e32 v166, v166, v191
	v_mul_f32_e32 v167, v167, v192
	v_mul_f32_e32 v184, v184, v166
	v_mul_f32_e32 v185, v185, v167
	v_mul_f32_e32 v108, v182, v108
	v_mul_f32_e32 v109, v183, v109
	v_mul_f32_e32 v110, v184, v110
	v_mul_f32_e32 v111, v185, v111
	v_cvt_pk_bf16_f32 v108, v108, v109
	v_cvt_pk_bf16_f32 v109, v110, v111
	ds_write_b64 v160, v[108:109] offset:112
	global_load_dwordx4 v[128:131], v181, s[68:69] offset:256
	global_load_dwordx4 v[132:135], v181, s[68:69] offset:288
	global_load_dwordx4 v[136:139], v181, s[68:69] offset:320
	global_load_dwordx4 v[140:143], v181, s[68:69] offset:352
	global_load_dwordx4 v[144:147], v181, s[70:71] offset:256
	global_load_dwordx4 v[148:151], v181, s[70:71] offset:288
	global_load_dwordx4 v[152:155], v181, s[70:71] offset:320
	global_load_dwordx4 v[156:159], v181, s[70:71] offset:352
	ds_read_b64 v[164:165], v160 offset:128
	s_waitcnt vmcnt(3) lgkmcnt(0)
	v_lshlrev_b32_e32 v182, 16, v164
	v_and_b32_e32 v183, 0xffff0000, v164
	v_lshlrev_b32_e32 v184, 16, v165
	v_and_b32_e32 v185, 0xffff0000, v165
	v_add_f32_e32 v80, v128, v80
	v_mul_f32_e32 v80, v144, v80
	v_add_f32_e32 v81, v129, v81
	v_mul_f32_e32 v81, v145, v81
	v_add_f32_e32 v82, v130, v82
	v_mul_f32_e32 v82, v146, v82
	v_add_f32_e32 v83, v131, v83
	v_mul_f32_e32 v83, v147, v83
	v_mul_f32_e32 v189, 0xbfb8aa3b, v182
	v_mul_f32_e32 v190, 0xbfb8aa3b, v183
	v_mul_f32_e32 v191, 0xbfb8aa3b, v184
	v_mul_f32_e32 v192, 0xbfb8aa3b, v185
	v_exp_f32_e32 v189, v189
	v_exp_f32_e32 v190, v190
	v_exp_f32_e32 v191, v191
	v_exp_f32_e32 v192, v192
	s_nop 0
	v_add_f32_e32 v189, 1.0, v189
	v_add_f32_e32 v190, 1.0, v190
	v_add_f32_e32 v191, 1.0, v191
	v_add_f32_e32 v192, 1.0, v192
	v_rcp_f32_e32 v166, v189
	v_rcp_f32_e32 v167, v190
	s_nop 0
	v_fma_f32 v189, -v189, v166, 2.0
	v_fma_f32 v190, -v190, v167, 2.0
	v_mul_f32_e32 v166, v166, v189
	v_mul_f32_e32 v167, v167, v190
	v_mul_f32_e32 v182, v182, v166
	v_mul_f32_e32 v183, v183, v167
	v_rcp_f32_e32 v166, v191
	v_rcp_f32_e32 v167, v192
	s_nop 0
	v_fma_f32 v191, -v191, v166, 2.0
	v_fma_f32 v192, -v192, v167, 2.0
	v_mul_f32_e32 v166, v166, v191
	v_mul_f32_e32 v167, v167, v192
	v_mul_f32_e32 v184, v184, v166
	v_mul_f32_e32 v185, v185, v167
	v_mul_f32_e32 v80, v182, v80
	v_mul_f32_e32 v81, v183, v81
	v_mul_f32_e32 v82, v184, v82
	v_mul_f32_e32 v83, v185, v83
	v_cvt_pk_bf16_f32 v80, v80, v81
	v_cvt_pk_bf16_f32 v81, v82, v83
	ds_write_b64 v160, v[80:81] offset:128
	ds_read_b64 v[164:165], v160 offset:144
	s_waitcnt vmcnt(2) lgkmcnt(0)
; DI bfr f2bf(float a) { return (bfr)(pack2(a, 0.f) & 0xffffu); }
; DI float bf2f(bfr u) { return __uint_as_float(((unsigned)u) << 16); }
; DI float siluf_(float x) { return x / (1.0f + __expf(-x)); }
; DI void phase_gemm_pool(const Params& p, char* smem) {
;     ...
;               [=](int row, int col, float v) {
;                 float gate = bf2f(P2[(size_t)row * 2048 + 1024 + g * 256 + col]);
;                 float z = (v + bp[col]) * sc[col] * siluf_(gate);
;                 Z[(size_t)row * 1024 + g * 256 + col] = f2bf(z);
;               });
	v_lshlrev_b32_e32 v182, 16, v164
	v_and_b32_e32 v183, 0xffff0000, v164
	v_lshlrev_b32_e32 v184, 16, v165
	v_and_b32_e32 v185, 0xffff0000, v165
	v_add_f32_e32 v84, v132, v84
	v_mul_f32_e32 v84, v148, v84
	v_add_f32_e32 v85, v133, v85
	v_mul_f32_e32 v85, v149, v85
	v_add_f32_e32 v86, v134, v86
	v_mul_f32_e32 v86, v150, v86
	v_add_f32_e32 v87, v135, v87
	v_mul_f32_e32 v87, v151, v87
	v_mul_f32_e32 v189, 0xbfb8aa3b, v182
	v_mul_f32_e32 v190, 0xbfb8aa3b, v183
	v_mul_f32_e32 v191, 0xbfb8aa3b, v184
	v_mul_f32_e32 v192, 0xbfb8aa3b, v185
	v_exp_f32_e32 v189, v189
	v_exp_f32_e32 v190, v190
	v_exp_f32_e32 v191, v191
	v_exp_f32_e32 v192, v192
	s_nop 0
	v_add_f32_e32 v189, 1.0, v189
	v_add_f32_e32 v190, 1.0, v190
	v_add_f32_e32 v191, 1.0, v191
	v_add_f32_e32 v192, 1.0, v192
	v_rcp_f32_e32 v166, v189
	v_rcp_f32_e32 v167, v190
	s_nop 0
	v_fma_f32 v189, -v189, v166, 2.0
	v_fma_f32 v190, -v190, v167, 2.0
	v_mul_f32_e32 v166, v166, v189
	v_mul_f32_e32 v167, v167, v190
	v_mul_f32_e32 v182, v182, v166
	v_mul_f32_e32 v183, v183, v167
	v_rcp_f32_e32 v166, v191
	v_rcp_f32_e32 v167, v192
	s_nop 0
	v_fma_f32 v191, -v191, v166, 2.0
	v_fma_f32 v192, -v192, v167, 2.0
	v_mul_f32_e32 v166, v166, v191
	v_mul_f32_e32 v167, v167, v192
	v_mul_f32_e32 v184, v184, v166
	v_mul_f32_e32 v185, v185, v167
	v_mul_f32_e32 v84, v182, v84
	v_mul_f32_e32 v85, v183, v85
	v_mul_f32_e32 v86, v184, v86
	v_mul_f32_e32 v87, v185, v87
	v_cvt_pk_bf16_f32 v84, v84, v85
	v_cvt_pk_bf16_f32 v85, v86, v87
	ds_write_b64 v160, v[84:85] offset:144
	ds_read_b64 v[164:165], v160 offset:160
	s_waitcnt vmcnt(1) lgkmcnt(0)
	v_lshlrev_b32_e32 v182, 16, v164
	v_and_b32_e32 v183, 0xffff0000, v164
	v_lshlrev_b32_e32 v184, 16, v165
	v_and_b32_e32 v185, 0xffff0000, v165
	v_add_f32_e32 v88, v136, v88
	v_mul_f32_e32 v88, v152, v88
	v_add_f32_e32 v89, v137, v89
	v_mul_f32_e32 v89, v153, v89
	v_add_f32_e32 v90, v138, v90
	v_mul_f32_e32 v90, v154, v90
	v_add_f32_e32 v91, v139, v91
	v_mul_f32_e32 v91, v155, v91
	v_mul_f32_e32 v189, 0xbfb8aa3b, v182
	v_mul_f32_e32 v190, 0xbfb8aa3b, v183
	v_mul_f32_e32 v191, 0xbfb8aa3b, v184
	v_mul_f32_e32 v192, 0xbfb8aa3b, v185
	v_exp_f32_e32 v189, v189
	v_exp_f32_e32 v190, v190
	v_exp_f32_e32 v191, v191
	v_exp_f32_e32 v192, v192
	s_nop 0
	v_add_f32_e32 v189, 1.0, v189
	v_add_f32_e32 v190, 1.0, v190
	v_add_f32_e32 v191, 1.0, v191
	v_add_f32_e32 v192, 1.0, v192
	v_rcp_f32_e32 v166, v189
	v_rcp_f32_e32 v167, v190
	s_nop 0
	v_fma_f32 v189, -v189, v166, 2.0
	v_fma_f32 v190, -v190, v167, 2.0
	v_mul_f32_e32 v166, v166, v189
	v_mul_f32_e32 v167, v167, v190
	v_mul_f32_e32 v182, v182, v166
	v_mul_f32_e32 v183, v183, v167
	v_rcp_f32_e32 v166, v191
	v_rcp_f32_e32 v167, v192
	s_nop 0
	v_fma_f32 v191, -v191, v166, 2.0
	v_fma_f32 v192, -v192, v167, 2.0
	v_mul_f32_e32 v166, v166, v191
	v_mul_f32_e32 v167, v167, v192
	v_mul_f32_e32 v184, v184, v166
	v_mul_f32_e32 v185, v185, v167
	v_mul_f32_e32 v88, v182, v88
	v_mul_f32_e32 v89, v183, v89
	v_mul_f32_e32 v90, v184, v90
	v_mul_f32_e32 v91, v185, v91
	v_cvt_pk_bf16_f32 v88, v88, v89
	v_cvt_pk_bf16_f32 v89, v90, v91
	ds_write_b64 v160, v[88:89] offset:160
	ds_read_b64 v[164:165], v160 offset:176
	s_waitcnt vmcnt(0) lgkmcnt(0)
	v_lshlrev_b32_e32 v182, 16, v164
	v_and_b32_e32 v183, 0xffff0000, v164
	v_lshlrev_b32_e32 v184, 16, v165
	v_and_b32_e32 v185, 0xffff0000, v165
	v_add_f32_e32 v92, v140, v92
	v_mul_f32_e32 v92, v156, v92
	v_add_f32_e32 v93, v141, v93
	v_mul_f32_e32 v93, v157, v93
	v_add_f32_e32 v94, v142, v94
	v_mul_f32_e32 v94, v158, v94
	v_add_f32_e32 v95, v143, v95
	v_mul_f32_e32 v95, v159, v95
	v_mul_f32_e32 v189, 0xbfb8aa3b, v182
	v_mul_f32_e32 v190, 0xbfb8aa3b, v183
	v_mul_f32_e32 v191, 0xbfb8aa3b, v184
	v_mul_f32_e32 v192, 0xbfb8aa3b, v185
	v_exp_f32_e32 v189, v189
	v_exp_f32_e32 v190, v190
	v_exp_f32_e32 v191, v191
	v_exp_f32_e32 v192, v192
	s_nop 0
	v_add_f32_e32 v189, 1.0, v189
	v_add_f32_e32 v190, 1.0, v190
	v_add_f32_e32 v191, 1.0, v191
	v_add_f32_e32 v192, 1.0, v192
	v_rcp_f32_e32 v166, v189
	v_rcp_f32_e32 v167, v190
	s_nop 0
	v_fma_f32 v189, -v189, v166, 2.0
	v_fma_f32 v190, -v190, v167, 2.0
	v_mul_f32_e32 v166, v166, v189
	v_mul_f32_e32 v167, v167, v190
	v_mul_f32_e32 v182, v182, v166
	v_mul_f32_e32 v183, v183, v167
	v_rcp_f32_e32 v166, v191
	v_rcp_f32_e32 v167, v192
	s_nop 0
	v_fma_f32 v191, -v191, v166, 2.0
	v_fma_f32 v192, -v192, v167, 2.0
	v_mul_f32_e32 v166, v166, v191
	v_mul_f32_e32 v167, v167, v192
	v_mul_f32_e32 v184, v184, v166
	v_mul_f32_e32 v185, v185, v167
	v_mul_f32_e32 v92, v182, v92
	v_mul_f32_e32 v93, v183, v93
	v_mul_f32_e32 v94, v184, v94
	v_mul_f32_e32 v95, v185, v95
	v_cvt_pk_bf16_f32 v92, v92, v93
	v_cvt_pk_bf16_f32 v93, v94, v95
	ds_write_b64 v160, v[92:93] offset:176
	global_load_dwordx4 v[128:131], v181, s[68:69] offset:384
	global_load_dwordx4 v[132:135], v181, s[68:69] offset:416
	global_load_dwordx4 v[136:139], v181, s[68:69] offset:448
	global_load_dwordx4 v[140:143], v181, s[68:69] offset:480
	global_load_dwordx4 v[144:147], v181, s[70:71] offset:384
	global_load_dwordx4 v[148:151], v181, s[70:71] offset:416
	global_load_dwordx4 v[152:155], v181, s[70:71] offset:448
	global_load_dwordx4 v[156:159], v181, s[70:71] offset:480
	ds_read_b64 v[164:165], v160 offset:192
	s_waitcnt vmcnt(3) lgkmcnt(0)
; DI bfr f2bf(float a) { return (bfr)(pack2(a, 0.f) & 0xffffu); }
; DI float bf2f(bfr u) { return __uint_as_float(((unsigned)u) << 16); }
; DI float siluf_(float x) { return x / (1.0f + __expf(-x)); }
; DI void phase_gemm_pool(const Params& p, char* smem) {
;     ...
;               [=](int row, int col, float v) {
;                 float gate = bf2f(P2[(size_t)row * 2048 + 1024 + g * 256 + col]);
;                 float z = (v + bp[col]) * sc[col] * siluf_(gate);
;                 Z[(size_t)row * 1024 + g * 256 + col] = f2bf(z);
;               });
	v_lshlrev_b32_e32 v182, 16, v164
	v_and_b32_e32 v183, 0xffff0000, v164
	v_lshlrev_b32_e32 v184, 16, v165
	v_and_b32_e32 v185, 0xffff0000, v165
	v_add_f32_e32 v64, v128, v64
	v_mul_f32_e32 v64, v144, v64
	v_add_f32_e32 v65, v129, v65
	v_mul_f32_e32 v65, v145, v65
	v_add_f32_e32 v66, v130, v66
	v_mul_f32_e32 v66, v146, v66
	v_add_f32_e32 v67, v131, v67
	v_mul_f32_e32 v67, v147, v67
	v_mul_f32_e32 v189, 0xbfb8aa3b, v182
	v_mul_f32_e32 v190, 0xbfb8aa3b, v183
	v_mul_f32_e32 v191, 0xbfb8aa3b, v184
	v_mul_f32_e32 v192, 0xbfb8aa3b, v185
	v_exp_f32_e32 v189, v189
	v_exp_f32_e32 v190, v190
	v_exp_f32_e32 v191, v191
	v_exp_f32_e32 v192, v192
	s_nop 0
	v_add_f32_e32 v189, 1.0, v189
	v_add_f32_e32 v190, 1.0, v190
	v_add_f32_e32 v191, 1.0, v191
	v_add_f32_e32 v192, 1.0, v192
	v_rcp_f32_e32 v166, v189
	v_rcp_f32_e32 v167, v190
	s_nop 0
	v_fma_f32 v189, -v189, v166, 2.0
	v_fma_f32 v190, -v190, v167, 2.0
	v_mul_f32_e32 v166, v166, v189
	v_mul_f32_e32 v167, v167, v190
	v_mul_f32_e32 v182, v182, v166
	v_mul_f32_e32 v183, v183, v167
	v_rcp_f32_e32 v166, v191
	v_rcp_f32_e32 v167, v192
	s_nop 0
	v_fma_f32 v191, -v191, v166, 2.0
	v_fma_f32 v192, -v192, v167, 2.0
	v_mul_f32_e32 v166, v166, v191
	v_mul_f32_e32 v167, v167, v192
	v_mul_f32_e32 v184, v184, v166
	v_mul_f32_e32 v185, v185, v167
	v_mul_f32_e32 v64, v182, v64
	v_mul_f32_e32 v65, v183, v65
	v_mul_f32_e32 v66, v184, v66
	v_mul_f32_e32 v67, v185, v67
	v_cvt_pk_bf16_f32 v64, v64, v65
	v_cvt_pk_bf16_f32 v65, v66, v67
	ds_write_b64 v160, v[64:65] offset:192
	ds_read_b64 v[164:165], v160 offset:208
	s_waitcnt vmcnt(2) lgkmcnt(0)
	v_lshlrev_b32_e32 v182, 16, v164
	v_and_b32_e32 v183, 0xffff0000, v164
	v_lshlrev_b32_e32 v184, 16, v165
	v_and_b32_e32 v185, 0xffff0000, v165
	v_add_f32_e32 v68, v132, v68
	v_mul_f32_e32 v68, v148, v68
	v_add_f32_e32 v69, v133, v69
	v_mul_f32_e32 v69, v149, v69
	v_add_f32_e32 v70, v134, v70
	v_mul_f32_e32 v70, v150, v70
	v_add_f32_e32 v71, v135, v71
	v_mul_f32_e32 v71, v151, v71
	v_mul_f32_e32 v189, 0xbfb8aa3b, v182
	v_mul_f32_e32 v190, 0xbfb8aa3b, v183
	v_mul_f32_e32 v191, 0xbfb8aa3b, v184
	v_mul_f32_e32 v192, 0xbfb8aa3b, v185
	v_exp_f32_e32 v189, v189
	v_exp_f32_e32 v190, v190
	v_exp_f32_e32 v191, v191
	v_exp_f32_e32 v192, v192
	s_nop 0
	v_add_f32_e32 v189, 1.0, v189
	v_add_f32_e32 v190, 1.0, v190
	v_add_f32_e32 v191, 1.0, v191
	v_add_f32_e32 v192, 1.0, v192
	v_rcp_f32_e32 v166, v189
	v_rcp_f32_e32 v167, v190
	s_nop 0
	v_fma_f32 v189, -v189, v166, 2.0
	v_fma_f32 v190, -v190, v167, 2.0
	v_mul_f32_e32 v166, v166, v189
	v_mul_f32_e32 v167, v167, v190
	v_mul_f32_e32 v182, v182, v166
	v_mul_f32_e32 v183, v183, v167
	v_rcp_f32_e32 v166, v191
	v_rcp_f32_e32 v167, v192
	s_nop 0
	v_fma_f32 v191, -v191, v166, 2.0
	v_fma_f32 v192, -v192, v167, 2.0
	v_mul_f32_e32 v166, v166, v191
	v_mul_f32_e32 v167, v167, v192
	v_mul_f32_e32 v184, v184, v166
	v_mul_f32_e32 v185, v185, v167
	v_mul_f32_e32 v68, v182, v68
	v_mul_f32_e32 v69, v183, v69
	v_mul_f32_e32 v70, v184, v70
	v_mul_f32_e32 v71, v185, v71
	v_cvt_pk_bf16_f32 v68, v68, v69
	v_cvt_pk_bf16_f32 v69, v70, v71
	ds_write_b64 v160, v[68:69] offset:208
	ds_read_b64 v[164:165], v160 offset:224
	s_waitcnt vmcnt(1) lgkmcnt(0)
	v_lshlrev_b32_e32 v182, 16, v164
	v_and_b32_e32 v183, 0xffff0000, v164
	v_lshlrev_b32_e32 v184, 16, v165
	v_and_b32_e32 v185, 0xffff0000, v165
	v_add_f32_e32 v72, v136, v72
	v_mul_f32_e32 v72, v152, v72
	v_add_f32_e32 v73, v137, v73
	v_mul_f32_e32 v73, v153, v73
	v_add_f32_e32 v74, v138, v74
	v_mul_f32_e32 v74, v154, v74
	v_add_f32_e32 v75, v139, v75
	v_mul_f32_e32 v75, v155, v75
	v_mul_f32_e32 v189, 0xbfb8aa3b, v182
	v_mul_f32_e32 v190, 0xbfb8aa3b, v183
	v_mul_f32_e32 v191, 0xbfb8aa3b, v184
	v_mul_f32_e32 v192, 0xbfb8aa3b, v185
	v_exp_f32_e32 v189, v189
	v_exp_f32_e32 v190, v190
	v_exp_f32_e32 v191, v191
	v_exp_f32_e32 v192, v192
	s_nop 0
	v_add_f32_e32 v189, 1.0, v189
	v_add_f32_e32 v190, 1.0, v190
	v_add_f32_e32 v191, 1.0, v191
	v_add_f32_e32 v192, 1.0, v192
	v_rcp_f32_e32 v166, v189
	v_rcp_f32_e32 v167, v190
	s_nop 0
	v_fma_f32 v189, -v189, v166, 2.0
	v_fma_f32 v190, -v190, v167, 2.0
	v_mul_f32_e32 v166, v166, v189
	v_mul_f32_e32 v167, v167, v190
	v_mul_f32_e32 v182, v182, v166
	v_mul_f32_e32 v183, v183, v167
	v_rcp_f32_e32 v166, v191
	v_rcp_f32_e32 v167, v192
	s_nop 0
	v_fma_f32 v191, -v191, v166, 2.0
	v_fma_f32 v192, -v192, v167, 2.0
	v_mul_f32_e32 v166, v166, v191
	v_mul_f32_e32 v167, v167, v192
	v_mul_f32_e32 v184, v184, v166
	v_mul_f32_e32 v185, v185, v167
	v_mul_f32_e32 v72, v182, v72
	v_mul_f32_e32 v73, v183, v73
	v_mul_f32_e32 v74, v184, v74
	v_mul_f32_e32 v75, v185, v75
	v_cvt_pk_bf16_f32 v72, v72, v73
	v_cvt_pk_bf16_f32 v73, v74, v75
	ds_write_b64 v160, v[72:73] offset:224
	ds_read_b64 v[164:165], v160 offset:240
	s_waitcnt vmcnt(0) lgkmcnt(0)
	v_lshlrev_b32_e32 v182, 16, v164
	v_and_b32_e32 v183, 0xffff0000, v164
	v_lshlrev_b32_e32 v184, 16, v165
	v_and_b32_e32 v185, 0xffff0000, v165
	v_add_f32_e32 v76, v140, v76
	v_mul_f32_e32 v76, v156, v76
	v_add_f32_e32 v77, v141, v77
	v_mul_f32_e32 v77, v157, v77
	v_add_f32_e32 v78, v142, v78
	v_mul_f32_e32 v78, v158, v78
	v_add_f32_e32 v79, v143, v79
	v_mul_f32_e32 v79, v159, v79
	v_mul_f32_e32 v189, 0xbfb8aa3b, v182
	v_mul_f32_e32 v190, 0xbfb8aa3b, v183
	v_mul_f32_e32 v191, 0xbfb8aa3b, v184
	v_mul_f32_e32 v192, 0xbfb8aa3b, v185
	v_exp_f32_e32 v189, v189
	v_exp_f32_e32 v190, v190
	v_exp_f32_e32 v191, v191
	v_exp_f32_e32 v192, v192
	s_nop 0
	v_add_f32_e32 v189, 1.0, v189
	v_add_f32_e32 v190, 1.0, v190
	v_add_f32_e32 v191, 1.0, v191
	v_add_f32_e32 v192, 1.0, v192
	v_rcp_f32_e32 v166, v189
	v_rcp_f32_e32 v167, v190
	s_nop 0
	v_fma_f32 v189, -v189, v166, 2.0
	v_fma_f32 v190, -v190, v167, 2.0
	v_mul_f32_e32 v166, v166, v189
	v_mul_f32_e32 v167, v167, v190
	v_mul_f32_e32 v182, v182, v166
	v_mul_f32_e32 v183, v183, v167
	v_rcp_f32_e32 v166, v191
	v_rcp_f32_e32 v167, v192
	s_nop 0
	v_fma_f32 v191, -v191, v166, 2.0
	v_fma_f32 v192, -v192, v167, 2.0
	v_mul_f32_e32 v166, v166, v191
	v_mul_f32_e32 v167, v167, v192
	v_mul_f32_e32 v184, v184, v166
	v_mul_f32_e32 v185, v185, v167
	v_mul_f32_e32 v76, v182, v76
	v_mul_f32_e32 v77, v183, v77
	v_mul_f32_e32 v78, v184, v78
	v_mul_f32_e32 v79, v185, v79
	v_cvt_pk_bf16_f32 v76, v76, v77
	v_cvt_pk_bf16_f32 v77, v78, v79
	ds_write_b64 v160, v[76:77] offset:240
	s_waitcnt lgkmcnt(0)
; DI bfr f2bf(float a) { return (bfr)(pack2(a, 0.f) & 0xffffu); }
; DI float bf2f(bfr u) { return __uint_as_float(((unsigned)u) << 16); }
; DI float siluf_(float x) { return x / (1.0f + __expf(-x)); }
; DI void phase_gemm_pool(const Params& p, char* smem) {
;     ...
;     gemm_tile<1024>(p.MIX + g * 256, p.WtPool + (size_t)g * 65536, 256, 256, mt * 128, nt * 256, smem,
;               [=](int row, int col, float v) {
;                 float gate = bf2f(P2[(size_t)row * 2048 + 1024 + g * 256 + col]);
;                 float z = (v + bp[col]) * sc[col] * siluf_(gate);
;                 Z[(size_t)row * 1024 + g * 256 + col] = f2bf(z);
;               });
	ds_read_b128 v[128:131], v162
	ds_read_b128 v[132:135], v162 offset:1088
	ds_read_b128 v[136:139], v162 offset:2176
	ds_read_b128 v[140:143], v162 offset:3264
	ds_read_b128 v[144:147], v162 offset:4352
	ds_read_b128 v[148:151], v162 offset:5440
	ds_read_b128 v[152:155], v162 offset:6528
	ds_read_b128 v[156:159], v162 offset:7616
	s_add_u32 s74, s66, 0x0
	s_addc_u32 s75, s67, 0
	s_waitcnt lgkmcnt(7)
	global_store_dwordx4 v180, v[128:131], s[74:75]
	s_add_u32 s74, s66, 0x2000
	s_addc_u32 s75, s67, 0
	s_waitcnt lgkmcnt(6)
	global_store_dwordx4 v180, v[132:135], s[74:75]
	s_add_u32 s74, s66, 0x4000
	s_addc_u32 s75, s67, 0
	s_waitcnt lgkmcnt(5)
	global_store_dwordx4 v180, v[136:139], s[74:75]
	s_add_u32 s74, s66, 0x6000
	s_addc_u32 s75, s67, 0
	s_waitcnt lgkmcnt(4)
	global_store_dwordx4 v180, v[140:143], s[74:75]
	s_add_u32 s74, s66, 0x8000
	s_addc_u32 s75, s67, 0
	s_waitcnt lgkmcnt(3)
	global_store_dwordx4 v180, v[144:147], s[74:75]
	s_add_u32 s74, s66, 0xa000
	s_addc_u32 s75, s67, 0
	s_waitcnt lgkmcnt(2)
	global_store_dwordx4 v180, v[148:151], s[74:75]
	s_add_u32 s74, s66, 0xc000
	s_addc_u32 s75, s67, 0
	s_waitcnt lgkmcnt(1)
	global_store_dwordx4 v180, v[152:155], s[74:75]
	s_add_u32 s74, s66, 0xe000
	s_addc_u32 s75, s67, 0
	s_waitcnt lgkmcnt(0)
	global_store_dwordx4 v180, v[156:159], s[74:75]
	s_add_u32 s74, s64, 0x20000
	s_addc_u32 s75, s65, 0
	global_load_dwordx4 v[128:131], v163, s[74:75]
	s_add_u32 s74, s64, 0x24000
	s_addc_u32 s75, s65, 0
	global_load_dwordx4 v[132:135], v163, s[74:75]
	s_add_u32 s74, s64, 0x28000
	s_addc_u32 s75, s65, 0
	global_load_dwordx4 v[136:139], v163, s[74:75]
	s_add_u32 s74, s64, 0x2c000
	s_addc_u32 s75, s65, 0
	global_load_dwordx4 v[140:143], v163, s[74:75]
	s_add_u32 s74, s64, 0x30000
	s_addc_u32 s75, s65, 0
	global_load_dwordx4 v[144:147], v163, s[74:75]
	s_add_u32 s74, s64, 0x34000
	s_addc_u32 s75, s65, 0
	global_load_dwordx4 v[148:151], v163, s[74:75]
	s_add_u32 s74, s64, 0x38000
	s_addc_u32 s75, s65, 0
	global_load_dwordx4 v[152:155], v163, s[74:75]
	s_add_u32 s74, s64, 0x3c000
	s_addc_u32 s75, s65, 0
	global_load_dwordx4 v[156:159], v163, s[74:75]
	s_waitcnt vmcnt(7)
	ds_write_b128 v162, v[128:131]
	s_waitcnt vmcnt(6)
	ds_write_b128 v162, v[132:135] offset:1088
	s_waitcnt vmcnt(5)
	ds_write_b128 v162, v[136:139] offset:2176
	s_waitcnt vmcnt(4)
	ds_write_b128 v162, v[140:143] offset:3264
	s_waitcnt vmcnt(3)
	ds_write_b128 v162, v[144:147] offset:4352
	s_waitcnt vmcnt(2)
	ds_write_b128 v162, v[148:151] offset:5440
	s_waitcnt vmcnt(1)
	ds_write_b128 v162, v[152:155] offset:6528
	s_waitcnt vmcnt(0)
	ds_write_b128 v162, v[156:159] offset:7616
	global_load_dwordx4 v[128:131], v181, s[68:69]
	global_load_dwordx4 v[132:135], v181, s[68:69] offset:32
	global_load_dwordx4 v[136:139], v181, s[68:69] offset:64
	global_load_dwordx4 v[140:143], v181, s[68:69] offset:96
	global_load_dwordx4 v[144:147], v181, s[70:71]
	global_load_dwordx4 v[148:151], v181, s[70:71] offset:32
	global_load_dwordx4 v[152:155], v181, s[70:71] offset:64
	global_load_dwordx4 v[156:159], v181, s[70:71] offset:96
	ds_read_b64 v[164:165], v160
	s_waitcnt vmcnt(3) lgkmcnt(0)
	v_lshlrev_b32_e32 v182, 16, v164
	v_and_b32_e32 v183, 0xffff0000, v164
	v_lshlrev_b32_e32 v184, 16, v165
	v_and_b32_e32 v185, 0xffff0000, v165
	v_add_f32_e32 v48, v128, v48
	v_mul_f32_e32 v48, v144, v48
	v_add_f32_e32 v49, v129, v49
	v_mul_f32_e32 v49, v145, v49
	v_add_f32_e32 v50, v130, v50
	v_mul_f32_e32 v50, v146, v50
	v_add_f32_e32 v51, v131, v51
	v_mul_f32_e32 v51, v147, v51
	v_mul_f32_e32 v189, 0xbfb8aa3b, v182
	v_mul_f32_e32 v190, 0xbfb8aa3b, v183
	v_mul_f32_e32 v191, 0xbfb8aa3b, v184
	v_mul_f32_e32 v192, 0xbfb8aa3b, v185
	v_exp_f32_e32 v189, v189
	v_exp_f32_e32 v190, v190
	v_exp_f32_e32 v191, v191
	v_exp_f32_e32 v192, v192
	s_nop 0
	v_add_f32_e32 v189, 1.0, v189
	v_add_f32_e32 v190, 1.0, v190
	v_add_f32_e32 v191, 1.0, v191
	v_add_f32_e32 v192, 1.0, v192
	v_rcp_f32_e32 v166, v189
	v_rcp_f32_e32 v167, v190
	s_nop 0
	v_fma_f32 v189, -v189, v166, 2.0
	v_fma_f32 v190, -v190, v167, 2.0
	v_mul_f32_e32 v166, v166, v189
	v_mul_f32_e32 v167, v167, v190
	v_mul_f32_e32 v182, v182, v166
	v_mul_f32_e32 v183, v183, v167
	v_rcp_f32_e32 v166, v191
	v_rcp_f32_e32 v167, v192
	s_nop 0
	v_fma_f32 v191, -v191, v166, 2.0
	v_fma_f32 v192, -v192, v167, 2.0
	v_mul_f32_e32 v166, v166, v191
	v_mul_f32_e32 v167, v167, v192
	v_mul_f32_e32 v184, v184, v166
	v_mul_f32_e32 v185, v185, v167
	v_mul_f32_e32 v48, v182, v48
	v_mul_f32_e32 v49, v183, v49
	v_mul_f32_e32 v50, v184, v50
	v_mul_f32_e32 v51, v185, v51
	v_cvt_pk_bf16_f32 v48, v48, v49
	v_cvt_pk_bf16_f32 v49, v50, v51
	ds_write_b64 v160, v[48:49]
	ds_read_b64 v[164:165], v160 offset:16
	s_waitcnt vmcnt(2) lgkmcnt(0)
	v_lshlrev_b32_e32 v182, 16, v164
	v_and_b32_e32 v183, 0xffff0000, v164
	v_lshlrev_b32_e32 v184, 16, v165
	v_and_b32_e32 v185, 0xffff0000, v165
	v_add_f32_e32 v52, v132, v52
	v_mul_f32_e32 v52, v148, v52
	v_add_f32_e32 v53, v133, v53
	v_mul_f32_e32 v53, v149, v53
	v_add_f32_e32 v54, v134, v54
	v_mul_f32_e32 v54, v150, v54
	v_add_f32_e32 v55, v135, v55
	v_mul_f32_e32 v55, v151, v55
	v_mul_f32_e32 v189, 0xbfb8aa3b, v182
	v_mul_f32_e32 v190, 0xbfb8aa3b, v183
	v_mul_f32_e32 v191, 0xbfb8aa3b, v184
	v_mul_f32_e32 v192, 0xbfb8aa3b, v185
	v_exp_f32_e32 v189, v189
	v_exp_f32_e32 v190, v190
	v_exp_f32_e32 v191, v191
	v_exp_f32_e32 v192, v192
	s_nop 0
	v_add_f32_e32 v189, 1.0, v189
	v_add_f32_e32 v190, 1.0, v190
	v_add_f32_e32 v191, 1.0, v191
	v_add_f32_e32 v192, 1.0, v192
	v_rcp_f32_e32 v166, v189
	v_rcp_f32_e32 v167, v190
	s_nop 0
	v_fma_f32 v189, -v189, v166, 2.0
	v_fma_f32 v190, -v190, v167, 2.0
	v_mul_f32_e32 v166, v166, v189
	v_mul_f32_e32 v167, v167, v190
	v_mul_f32_e32 v182, v182, v166
	v_mul_f32_e32 v183, v183, v167
	v_rcp_f32_e32 v166, v191
	v_rcp_f32_e32 v167, v192
	s_nop 0
	v_fma_f32 v191, -v191, v166, 2.0
	v_fma_f32 v192, -v192, v167, 2.0
	v_mul_f32_e32 v166, v166, v191
	v_mul_f32_e32 v167, v167, v192
	v_mul_f32_e32 v184, v184, v166
	v_mul_f32_e32 v185, v185, v167
	v_mul_f32_e32 v52, v182, v52
	v_mul_f32_e32 v53, v183, v53
	v_mul_f32_e32 v54, v184, v54
	v_mul_f32_e32 v55, v185, v55
	v_cvt_pk_bf16_f32 v52, v52, v53
	v_cvt_pk_bf16_f32 v53, v54, v55
	ds_write_b64 v160, v[52:53] offset:16
	ds_read_b64 v[164:165], v160 offset:32
	s_waitcnt vmcnt(1) lgkmcnt(0)
; DI bfr f2bf(float a) { return (bfr)(pack2(a, 0.f) & 0xffffu); }
; DI float bf2f(bfr u) { return __uint_as_float(((unsigned)u) << 16); }
; DI float siluf_(float x) { return x / (1.0f + __expf(-x)); }
; DI void phase_gemm_pool(const Params& p, char* smem) {
;     ...
;     gemm_tile<1024>(p.MIX + g * 256, p.WtPool + (size_t)g * 65536, 256, 256, mt * 128, nt * 256, smem,
;               [=](int row, int col, float v) {
;                 float gate = bf2f(P2[(size_t)row * 2048 + 1024 + g * 256 + col]);
;                 float z = (v + bp[col]) * sc[col] * siluf_(gate);
;                 Z[(size_t)row * 1024 + g * 256 + col] = f2bf(z);
;               });
	v_lshlrev_b32_e32 v182, 16, v164
	v_and_b32_e32 v183, 0xffff0000, v164
	v_lshlrev_b32_e32 v184, 16, v165
	v_and_b32_e32 v185, 0xffff0000, v165
	v_add_f32_e32 v56, v136, v56
	v_mul_f32_e32 v56, v152, v56
	v_add_f32_e32 v57, v137, v57
	v_mul_f32_e32 v57, v153, v57
	v_add_f32_e32 v58, v138, v58
	v_mul_f32_e32 v58, v154, v58
	v_add_f32_e32 v59, v139, v59
	v_mul_f32_e32 v59, v155, v59
	v_mul_f32_e32 v189, 0xbfb8aa3b, v182
	v_mul_f32_e32 v190, 0xbfb8aa3b, v183
	v_mul_f32_e32 v191, 0xbfb8aa3b, v184
	v_mul_f32_e32 v192, 0xbfb8aa3b, v185
	v_exp_f32_e32 v189, v189
	v_exp_f32_e32 v190, v190
	v_exp_f32_e32 v191, v191
	v_exp_f32_e32 v192, v192
	s_nop 0
	v_add_f32_e32 v189, 1.0, v189
	v_add_f32_e32 v190, 1.0, v190
	v_add_f32_e32 v191, 1.0, v191
	v_add_f32_e32 v192, 1.0, v192
	v_rcp_f32_e32 v166, v189
	v_rcp_f32_e32 v167, v190
	s_nop 0
	v_fma_f32 v189, -v189, v166, 2.0
	v_fma_f32 v190, -v190, v167, 2.0
	v_mul_f32_e32 v166, v166, v189
	v_mul_f32_e32 v167, v167, v190
	v_mul_f32_e32 v182, v182, v166
	v_mul_f32_e32 v183, v183, v167
	v_rcp_f32_e32 v166, v191
	v_rcp_f32_e32 v167, v192
	s_nop 0
	v_fma_f32 v191, -v191, v166, 2.0
	v_fma_f32 v192, -v192, v167, 2.0
	v_mul_f32_e32 v166, v166, v191
	v_mul_f32_e32 v167, v167, v192
	v_mul_f32_e32 v184, v184, v166
	v_mul_f32_e32 v185, v185, v167
	v_mul_f32_e32 v56, v182, v56
	v_mul_f32_e32 v57, v183, v57
	v_mul_f32_e32 v58, v184, v58
	v_mul_f32_e32 v59, v185, v59
	v_cvt_pk_bf16_f32 v56, v56, v57
	v_cvt_pk_bf16_f32 v57, v58, v59
	ds_write_b64 v160, v[56:57] offset:32
	ds_read_b64 v[164:165], v160 offset:48
	s_waitcnt vmcnt(0) lgkmcnt(0)
	v_lshlrev_b32_e32 v182, 16, v164
	v_and_b32_e32 v183, 0xffff0000, v164
	v_lshlrev_b32_e32 v184, 16, v165
	v_and_b32_e32 v185, 0xffff0000, v165
	v_add_f32_e32 v60, v140, v60
	v_mul_f32_e32 v60, v156, v60
	v_add_f32_e32 v61, v141, v61
	v_mul_f32_e32 v61, v157, v61
	v_add_f32_e32 v62, v142, v62
	v_mul_f32_e32 v62, v158, v62
	v_add_f32_e32 v63, v143, v63
	v_mul_f32_e32 v63, v159, v63
	v_mul_f32_e32 v189, 0xbfb8aa3b, v182
	v_mul_f32_e32 v190, 0xbfb8aa3b, v183
	v_mul_f32_e32 v191, 0xbfb8aa3b, v184
	v_mul_f32_e32 v192, 0xbfb8aa3b, v185
	v_exp_f32_e32 v189, v189
	v_exp_f32_e32 v190, v190
	v_exp_f32_e32 v191, v191
	v_exp_f32_e32 v192, v192
	s_nop 0
	v_add_f32_e32 v189, 1.0, v189
	v_add_f32_e32 v190, 1.0, v190
	v_add_f32_e32 v191, 1.0, v191
	v_add_f32_e32 v192, 1.0, v192
	v_rcp_f32_e32 v166, v189
	v_rcp_f32_e32 v167, v190
	s_nop 0
	v_fma_f32 v189, -v189, v166, 2.0
	v_fma_f32 v190, -v190, v167, 2.0
	v_mul_f32_e32 v166, v166, v189
	v_mul_f32_e32 v167, v167, v190
	v_mul_f32_e32 v182, v182, v166
	v_mul_f32_e32 v183, v183, v167
	v_rcp_f32_e32 v166, v191
	v_rcp_f32_e32 v167, v192
	s_nop 0
	v_fma_f32 v191, -v191, v166, 2.0
	v_fma_f32 v192, -v192, v167, 2.0
	v_mul_f32_e32 v166, v166, v191
	v_mul_f32_e32 v167, v167, v192
	v_mul_f32_e32 v184, v184, v166
	v_mul_f32_e32 v185, v185, v167
	v_mul_f32_e32 v60, v182, v60
	v_mul_f32_e32 v61, v183, v61
	v_mul_f32_e32 v62, v184, v62
	v_mul_f32_e32 v63, v185, v63
	v_cvt_pk_bf16_f32 v60, v60, v61
	v_cvt_pk_bf16_f32 v61, v62, v63
	ds_write_b64 v160, v[60:61] offset:48
	global_load_dwordx4 v[128:131], v181, s[68:69] offset:128
	global_load_dwordx4 v[132:135], v181, s[68:69] offset:160
	global_load_dwordx4 v[136:139], v181, s[68:69] offset:192
	global_load_dwordx4 v[140:143], v181, s[68:69] offset:224
	global_load_dwordx4 v[144:147], v181, s[70:71] offset:128
	global_load_dwordx4 v[148:151], v181, s[70:71] offset:160
	global_load_dwordx4 v[152:155], v181, s[70:71] offset:192
	global_load_dwordx4 v[156:159], v181, s[70:71] offset:224
	ds_read_b64 v[164:165], v160 offset:64
	s_waitcnt vmcnt(3) lgkmcnt(0)
	v_lshlrev_b32_e32 v182, 16, v164
	v_and_b32_e32 v183, 0xffff0000, v164
	v_lshlrev_b32_e32 v184, 16, v165
	v_and_b32_e32 v185, 0xffff0000, v165
	v_add_f32_e32 v32, v128, v32
	v_mul_f32_e32 v32, v144, v32
	v_add_f32_e32 v33, v129, v33
	v_mul_f32_e32 v33, v145, v33
	v_add_f32_e32 v34, v130, v34
	v_mul_f32_e32 v34, v146, v34
	v_add_f32_e32 v35, v131, v35
	v_mul_f32_e32 v35, v147, v35
	v_mul_f32_e32 v189, 0xbfb8aa3b, v182
	v_mul_f32_e32 v190, 0xbfb8aa3b, v183
	v_mul_f32_e32 v191, 0xbfb8aa3b, v184
	v_mul_f32_e32 v192, 0xbfb8aa3b, v185
	v_exp_f32_e32 v189, v189
	v_exp_f32_e32 v190, v190
	v_exp_f32_e32 v191, v191
	v_exp_f32_e32 v192, v192
	s_nop 0
	v_add_f32_e32 v189, 1.0, v189
	v_add_f32_e32 v190, 1.0, v190
	v_add_f32_e32 v191, 1.0, v191
	v_add_f32_e32 v192, 1.0, v192
	v_rcp_f32_e32 v166, v189
	v_rcp_f32_e32 v167, v190
	s_nop 0
	v_fma_f32 v189, -v189, v166, 2.0
	v_fma_f32 v190, -v190, v167, 2.0
	v_mul_f32_e32 v166, v166, v189
	v_mul_f32_e32 v167, v167, v190
	v_mul_f32_e32 v182, v182, v166
	v_mul_f32_e32 v183, v183, v167
	v_rcp_f32_e32 v166, v191
	v_rcp_f32_e32 v167, v192
	s_nop 0
	v_fma_f32 v191, -v191, v166, 2.0
	v_fma_f32 v192, -v192, v167, 2.0
	v_mul_f32_e32 v166, v166, v191
	v_mul_f32_e32 v167, v167, v192
	v_mul_f32_e32 v184, v184, v166
	v_mul_f32_e32 v185, v185, v167
	v_mul_f32_e32 v32, v182, v32
	v_mul_f32_e32 v33, v183, v33
	v_mul_f32_e32 v34, v184, v34
	v_mul_f32_e32 v35, v185, v35
	v_cvt_pk_bf16_f32 v32, v32, v33
	v_cvt_pk_bf16_f32 v33, v34, v35
	ds_write_b64 v160, v[32:33] offset:64
	ds_read_b64 v[164:165], v160 offset:80
	s_waitcnt vmcnt(2) lgkmcnt(0)
; DI bfr f2bf(float a) { return (bfr)(pack2(a, 0.f) & 0xffffu); }
; DI float bf2f(bfr u) { return __uint_as_float(((unsigned)u) << 16); }
; DI float siluf_(float x) { return x / (1.0f + __expf(-x)); }
; DI void phase_gemm_pool(const Params& p, char* smem) {
;     ...
;     gemm_tile<1024>(p.MIX + g * 256, p.WtPool + (size_t)g * 65536, 256, 256, mt * 128, nt * 256, smem,
;               [=](int row, int col, float v) {
;                 float gate = bf2f(P2[(size_t)row * 2048 + 1024 + g * 256 + col]);
;                 float z = (v + bp[col]) * sc[col] * siluf_(gate);
;                 Z[(size_t)row * 1024 + g * 256 + col] = f2bf(z);
;               });
	v_lshlrev_b32_e32 v182, 16, v164
	v_and_b32_e32 v183, 0xffff0000, v164
	v_lshlrev_b32_e32 v184, 16, v165
	v_and_b32_e32 v185, 0xffff0000, v165
	v_add_f32_e32 v36, v132, v36
	v_mul_f32_e32 v36, v148, v36
	v_add_f32_e32 v37, v133, v37
	v_mul_f32_e32 v37, v149, v37
	v_add_f32_e32 v38, v134, v38
	v_mul_f32_e32 v38, v150, v38
	v_add_f32_e32 v39, v135, v39
	v_mul_f32_e32 v39, v151, v39
	v_mul_f32_e32 v189, 0xbfb8aa3b, v182
	v_mul_f32_e32 v190, 0xbfb8aa3b, v183
	v_mul_f32_e32 v191, 0xbfb8aa3b, v184
	v_mul_f32_e32 v192, 0xbfb8aa3b, v185
	v_exp_f32_e32 v189, v189
	v_exp_f32_e32 v190, v190
	v_exp_f32_e32 v191, v191
	v_exp_f32_e32 v192, v192
	s_nop 0
	v_add_f32_e32 v189, 1.0, v189
	v_add_f32_e32 v190, 1.0, v190
	v_add_f32_e32 v191, 1.0, v191
	v_add_f32_e32 v192, 1.0, v192
	v_rcp_f32_e32 v166, v189
	v_rcp_f32_e32 v167, v190
	s_nop 0
	v_fma_f32 v189, -v189, v166, 2.0
	v_fma_f32 v190, -v190, v167, 2.0
	v_mul_f32_e32 v166, v166, v189
	v_mul_f32_e32 v167, v167, v190
	v_mul_f32_e32 v182, v182, v166
	v_mul_f32_e32 v183, v183, v167
	v_rcp_f32_e32 v166, v191
	v_rcp_f32_e32 v167, v192
	s_nop 0
	v_fma_f32 v191, -v191, v166, 2.0
	v_fma_f32 v192, -v192, v167, 2.0
	v_mul_f32_e32 v166, v166, v191
	v_mul_f32_e32 v167, v167, v192
	v_mul_f32_e32 v184, v184, v166
	v_mul_f32_e32 v185, v185, v167
	v_mul_f32_e32 v36, v182, v36
	v_mul_f32_e32 v37, v183, v37
	v_mul_f32_e32 v38, v184, v38
	v_mul_f32_e32 v39, v185, v39
	v_cvt_pk_bf16_f32 v36, v36, v37
	v_cvt_pk_bf16_f32 v37, v38, v39
	ds_write_b64 v160, v[36:37] offset:80
	ds_read_b64 v[164:165], v160 offset:96
	s_waitcnt vmcnt(1) lgkmcnt(0)
	v_lshlrev_b32_e32 v182, 16, v164
	v_and_b32_e32 v183, 0xffff0000, v164
	v_lshlrev_b32_e32 v184, 16, v165
	v_and_b32_e32 v185, 0xffff0000, v165
	v_add_f32_e32 v40, v136, v40
	v_mul_f32_e32 v40, v152, v40
	v_add_f32_e32 v41, v137, v41
	v_mul_f32_e32 v41, v153, v41
	v_add_f32_e32 v42, v138, v42
	v_mul_f32_e32 v42, v154, v42
	v_add_f32_e32 v43, v139, v43
	v_mul_f32_e32 v43, v155, v43
	v_mul_f32_e32 v189, 0xbfb8aa3b, v182
	v_mul_f32_e32 v190, 0xbfb8aa3b, v183
	v_mul_f32_e32 v191, 0xbfb8aa3b, v184
	v_mul_f32_e32 v192, 0xbfb8aa3b, v185
	v_exp_f32_e32 v189, v189
	v_exp_f32_e32 v190, v190
	v_exp_f32_e32 v191, v191
	v_exp_f32_e32 v192, v192
	s_nop 0
	v_add_f32_e32 v189, 1.0, v189
	v_add_f32_e32 v190, 1.0, v190
	v_add_f32_e32 v191, 1.0, v191
	v_add_f32_e32 v192, 1.0, v192
	v_rcp_f32_e32 v166, v189
	v_rcp_f32_e32 v167, v190
	s_nop 0
	v_fma_f32 v189, -v189, v166, 2.0
	v_fma_f32 v190, -v190, v167, 2.0
	v_mul_f32_e32 v166, v166, v189
	v_mul_f32_e32 v167, v167, v190
	v_mul_f32_e32 v182, v182, v166
	v_mul_f32_e32 v183, v183, v167
	v_rcp_f32_e32 v166, v191
	v_rcp_f32_e32 v167, v192
	s_nop 0
	v_fma_f32 v191, -v191, v166, 2.0
	v_fma_f32 v192, -v192, v167, 2.0
	v_mul_f32_e32 v166, v166, v191
	v_mul_f32_e32 v167, v167, v192
	v_mul_f32_e32 v184, v184, v166
	v_mul_f32_e32 v185, v185, v167
	v_mul_f32_e32 v40, v182, v40
	v_mul_f32_e32 v41, v183, v41
	v_mul_f32_e32 v42, v184, v42
	v_mul_f32_e32 v43, v185, v43
	v_cvt_pk_bf16_f32 v40, v40, v41
	v_cvt_pk_bf16_f32 v41, v42, v43
	ds_write_b64 v160, v[40:41] offset:96
	ds_read_b64 v[164:165], v160 offset:112
	s_waitcnt vmcnt(0) lgkmcnt(0)
	v_lshlrev_b32_e32 v182, 16, v164
	v_and_b32_e32 v183, 0xffff0000, v164
	v_lshlrev_b32_e32 v184, 16, v165
	v_and_b32_e32 v185, 0xffff0000, v165
	v_add_f32_e32 v44, v140, v44
	v_mul_f32_e32 v44, v156, v44
	v_add_f32_e32 v45, v141, v45
	v_mul_f32_e32 v45, v157, v45
	v_add_f32_e32 v46, v142, v46
	v_mul_f32_e32 v46, v158, v46
	v_add_f32_e32 v47, v143, v47
	v_mul_f32_e32 v47, v159, v47
	v_mul_f32_e32 v189, 0xbfb8aa3b, v182
	v_mul_f32_e32 v190, 0xbfb8aa3b, v183
	v_mul_f32_e32 v191, 0xbfb8aa3b, v184
	v_mul_f32_e32 v192, 0xbfb8aa3b, v185
	v_exp_f32_e32 v189, v189
	v_exp_f32_e32 v190, v190
	v_exp_f32_e32 v191, v191
	v_exp_f32_e32 v192, v192
	s_nop 0
	v_add_f32_e32 v189, 1.0, v189
	v_add_f32_e32 v190, 1.0, v190
	v_add_f32_e32 v191, 1.0, v191
	v_add_f32_e32 v192, 1.0, v192
	v_rcp_f32_e32 v166, v189
	v_rcp_f32_e32 v167, v190
	s_nop 0
	v_fma_f32 v189, -v189, v166, 2.0
	v_fma_f32 v190, -v190, v167, 2.0
	v_mul_f32_e32 v166, v166, v189
	v_mul_f32_e32 v167, v167, v190
	v_mul_f32_e32 v182, v182, v166
	v_mul_f32_e32 v183, v183, v167
	v_rcp_f32_e32 v166, v191
	v_rcp_f32_e32 v167, v192
	s_nop 0
	v_fma_f32 v191, -v191, v166, 2.0
	v_fma_f32 v192, -v192, v167, 2.0
	v_mul_f32_e32 v166, v166, v191
	v_mul_f32_e32 v167, v167, v192
	v_mul_f32_e32 v184, v184, v166
	v_mul_f32_e32 v185, v185, v167
	v_mul_f32_e32 v44, v182, v44
	v_mul_f32_e32 v45, v183, v45
	v_mul_f32_e32 v46, v184, v46
	v_mul_f32_e32 v47, v185, v47
	v_cvt_pk_bf16_f32 v44, v44, v45
	v_cvt_pk_bf16_f32 v45, v46, v47
	ds_write_b64 v160, v[44:45] offset:112
	global_load_dwordx4 v[128:131], v181, s[68:69] offset:256
	global_load_dwordx4 v[132:135], v181, s[68:69] offset:288
	global_load_dwordx4 v[136:139], v181, s[68:69] offset:320
	global_load_dwordx4 v[140:143], v181, s[68:69] offset:352
	global_load_dwordx4 v[144:147], v181, s[70:71] offset:256
	global_load_dwordx4 v[148:151], v181, s[70:71] offset:288
	global_load_dwordx4 v[152:155], v181, s[70:71] offset:320
	global_load_dwordx4 v[156:159], v181, s[70:71] offset:352
	ds_read_b64 v[164:165], v160 offset:128
	s_waitcnt vmcnt(3) lgkmcnt(0)
; DI bfr f2bf(float a) { return (bfr)(pack2(a, 0.f) & 0xffffu); }
; DI float bf2f(bfr u) { return __uint_as_float(((unsigned)u) << 16); }
; DI float siluf_(float x) { return x / (1.0f + __expf(-x)); }
; DI void phase_gemm_pool(const Params& p, char* smem) {
;     ...
;     gemm_tile<1024>(p.MIX + g * 256, p.WtPool + (size_t)g * 65536, 256, 256, mt * 128, nt * 256, smem,
;               [=](int row, int col, float v) {
;                 float gate = bf2f(P2[(size_t)row * 2048 + 1024 + g * 256 + col]);
;                 float z = (v + bp[col]) * sc[col] * siluf_(gate);
;                 Z[(size_t)row * 1024 + g * 256 + col] = f2bf(z);
;               });
	v_lshlrev_b32_e32 v182, 16, v164
	v_and_b32_e32 v183, 0xffff0000, v164
	v_lshlrev_b32_e32 v184, 16, v165
	v_and_b32_e32 v185, 0xffff0000, v165
	v_add_f32_e32 v16, v128, v16
	v_mul_f32_e32 v16, v144, v16
	v_add_f32_e32 v17, v129, v17
	v_mul_f32_e32 v17, v145, v17
	v_add_f32_e32 v18, v130, v18
	v_mul_f32_e32 v18, v146, v18
	v_add_f32_e32 v19, v131, v19
	v_mul_f32_e32 v19, v147, v19
	v_mul_f32_e32 v189, 0xbfb8aa3b, v182
	v_mul_f32_e32 v190, 0xbfb8aa3b, v183
	v_mul_f32_e32 v191, 0xbfb8aa3b, v184
	v_mul_f32_e32 v192, 0xbfb8aa3b, v185
	v_exp_f32_e32 v189, v189
	v_exp_f32_e32 v190, v190
	v_exp_f32_e32 v191, v191
	v_exp_f32_e32 v192, v192
	s_nop 0
	v_add_f32_e32 v189, 1.0, v189
	v_add_f32_e32 v190, 1.0, v190
	v_add_f32_e32 v191, 1.0, v191
	v_add_f32_e32 v192, 1.0, v192
	v_rcp_f32_e32 v166, v189
	v_rcp_f32_e32 v167, v190
	s_nop 0
	v_fma_f32 v189, -v189, v166, 2.0
	v_fma_f32 v190, -v190, v167, 2.0
	v_mul_f32_e32 v166, v166, v189
	v_mul_f32_e32 v167, v167, v190
	v_mul_f32_e32 v182, v182, v166
	v_mul_f32_e32 v183, v183, v167
	v_rcp_f32_e32 v166, v191
	v_rcp_f32_e32 v167, v192
	s_nop 0
	v_fma_f32 v191, -v191, v166, 2.0
	v_fma_f32 v192, -v192, v167, 2.0
	v_mul_f32_e32 v166, v166, v191
	v_mul_f32_e32 v167, v167, v192
	v_mul_f32_e32 v184, v184, v166
	v_mul_f32_e32 v185, v185, v167
	v_mul_f32_e32 v16, v182, v16
	v_mul_f32_e32 v17, v183, v17
	v_mul_f32_e32 v18, v184, v18
	v_mul_f32_e32 v19, v185, v19
	v_cvt_pk_bf16_f32 v16, v16, v17
	v_cvt_pk_bf16_f32 v17, v18, v19
	ds_write_b64 v160, v[16:17] offset:128
	ds_read_b64 v[164:165], v160 offset:144
	s_waitcnt vmcnt(2) lgkmcnt(0)
	v_lshlrev_b32_e32 v182, 16, v164
	v_and_b32_e32 v183, 0xffff0000, v164
	v_lshlrev_b32_e32 v184, 16, v165
	v_and_b32_e32 v185, 0xffff0000, v165
	v_add_f32_e32 v20, v132, v20
	v_mul_f32_e32 v20, v148, v20
	v_add_f32_e32 v21, v133, v21
	v_mul_f32_e32 v21, v149, v21
	v_add_f32_e32 v22, v134, v22
	v_mul_f32_e32 v22, v150, v22
	v_add_f32_e32 v23, v135, v23
	v_mul_f32_e32 v23, v151, v23
	v_mul_f32_e32 v189, 0xbfb8aa3b, v182
	v_mul_f32_e32 v190, 0xbfb8aa3b, v183
	v_mul_f32_e32 v191, 0xbfb8aa3b, v184
	v_mul_f32_e32 v192, 0xbfb8aa3b, v185
	v_exp_f32_e32 v189, v189
	v_exp_f32_e32 v190, v190
	v_exp_f32_e32 v191, v191
	v_exp_f32_e32 v192, v192
	s_nop 0
	v_add_f32_e32 v189, 1.0, v189
	v_add_f32_e32 v190, 1.0, v190
	v_add_f32_e32 v191, 1.0, v191
	v_add_f32_e32 v192, 1.0, v192
	v_rcp_f32_e32 v166, v189
	v_rcp_f32_e32 v167, v190
	s_nop 0
	v_fma_f32 v189, -v189, v166, 2.0
	v_fma_f32 v190, -v190, v167, 2.0
	v_mul_f32_e32 v166, v166, v189
	v_mul_f32_e32 v167, v167, v190
	v_mul_f32_e32 v182, v182, v166
	v_mul_f32_e32 v183, v183, v167
	v_rcp_f32_e32 v166, v191
	v_rcp_f32_e32 v167, v192
	s_nop 0
	v_fma_f32 v191, -v191, v166, 2.0
	v_fma_f32 v192, -v192, v167, 2.0
	v_mul_f32_e32 v166, v166, v191
	v_mul_f32_e32 v167, v167, v192
	v_mul_f32_e32 v184, v184, v166
	v_mul_f32_e32 v185, v185, v167
	v_mul_f32_e32 v20, v182, v20
	v_mul_f32_e32 v21, v183, v21
	v_mul_f32_e32 v22, v184, v22
	v_mul_f32_e32 v23, v185, v23
	v_cvt_pk_bf16_f32 v20, v20, v21
	v_cvt_pk_bf16_f32 v21, v22, v23
	ds_write_b64 v160, v[20:21] offset:144
	ds_read_b64 v[164:165], v160 offset:160
	s_waitcnt vmcnt(1) lgkmcnt(0)
	v_lshlrev_b32_e32 v182, 16, v164
	v_and_b32_e32 v183, 0xffff0000, v164
	v_lshlrev_b32_e32 v184, 16, v165
	v_and_b32_e32 v185, 0xffff0000, v165
	v_add_f32_e32 v24, v136, v24
	v_mul_f32_e32 v24, v152, v24
	v_add_f32_e32 v25, v137, v25
	v_mul_f32_e32 v25, v153, v25
	v_add_f32_e32 v26, v138, v26
	v_mul_f32_e32 v26, v154, v26
	v_add_f32_e32 v27, v139, v27
	v_mul_f32_e32 v27, v155, v27
	v_mul_f32_e32 v189, 0xbfb8aa3b, v182
	v_mul_f32_e32 v190, 0xbfb8aa3b, v183
	v_mul_f32_e32 v191, 0xbfb8aa3b, v184
	v_mul_f32_e32 v192, 0xbfb8aa3b, v185
	v_exp_f32_e32 v189, v189
	v_exp_f32_e32 v190, v190
	v_exp_f32_e32 v191, v191
	v_exp_f32_e32 v192, v192
	s_nop 0
	v_add_f32_e32 v189, 1.0, v189
	v_add_f32_e32 v190, 1.0, v190
	v_add_f32_e32 v191, 1.0, v191
	v_add_f32_e32 v192, 1.0, v192
	v_rcp_f32_e32 v166, v189
	v_rcp_f32_e32 v167, v190
	s_nop 0
	v_fma_f32 v189, -v189, v166, 2.0
	v_fma_f32 v190, -v190, v167, 2.0
	v_mul_f32_e32 v166, v166, v189
	v_mul_f32_e32 v167, v167, v190
	v_mul_f32_e32 v182, v182, v166
	v_mul_f32_e32 v183, v183, v167
	v_rcp_f32_e32 v166, v191
	v_rcp_f32_e32 v167, v192
	s_nop 0
	v_fma_f32 v191, -v191, v166, 2.0
	v_fma_f32 v192, -v192, v167, 2.0
	v_mul_f32_e32 v166, v166, v191
	v_mul_f32_e32 v167, v167, v192
	v_mul_f32_e32 v184, v184, v166
	v_mul_f32_e32 v185, v185, v167
	v_mul_f32_e32 v24, v182, v24
	v_mul_f32_e32 v25, v183, v25
	v_mul_f32_e32 v26, v184, v26
	v_mul_f32_e32 v27, v185, v27
	v_cvt_pk_bf16_f32 v24, v24, v25
	v_cvt_pk_bf16_f32 v25, v26, v27
	ds_write_b64 v160, v[24:25] offset:160
	ds_read_b64 v[164:165], v160 offset:176
	s_waitcnt vmcnt(0) lgkmcnt(0)
; DI bfr f2bf(float a) { return (bfr)(pack2(a, 0.f) & 0xffffu); }
; DI float bf2f(bfr u) { return __uint_as_float(((unsigned)u) << 16); }
; DI float siluf_(float x) { return x / (1.0f + __expf(-x)); }
; DI void phase_gemm_pool(const Params& p, char* smem) {
;     ...
;     gemm_tile<1024>(p.MIX + g * 256, p.WtPool + (size_t)g * 65536, 256, 256, mt * 128, nt * 256, smem,
;               [=](int row, int col, float v) {
;                 float gate = bf2f(P2[(size_t)row * 2048 + 1024 + g * 256 + col]);
;                 float z = (v + bp[col]) * sc[col] * siluf_(gate);
;                 Z[(size_t)row * 1024 + g * 256 + col] = f2bf(z);
;               });
	v_lshlrev_b32_e32 v182, 16, v164
	v_and_b32_e32 v183, 0xffff0000, v164
	v_lshlrev_b32_e32 v184, 16, v165
	v_and_b32_e32 v185, 0xffff0000, v165
	v_add_f32_e32 v28, v140, v28
	v_mul_f32_e32 v28, v156, v28
	v_add_f32_e32 v29, v141, v29
	v_mul_f32_e32 v29, v157, v29
	v_add_f32_e32 v30, v142, v30
	v_mul_f32_e32 v30, v158, v30
	v_add_f32_e32 v31, v143, v31
	v_mul_f32_e32 v31, v159, v31
	v_mul_f32_e32 v189, 0xbfb8aa3b, v182
	v_mul_f32_e32 v190, 0xbfb8aa3b, v183
	v_mul_f32_e32 v191, 0xbfb8aa3b, v184
	v_mul_f32_e32 v192, 0xbfb8aa3b, v185
	v_exp_f32_e32 v189, v189
	v_exp_f32_e32 v190, v190
	v_exp_f32_e32 v191, v191
	v_exp_f32_e32 v192, v192
	s_nop 0
	v_add_f32_e32 v189, 1.0, v189
	v_add_f32_e32 v190, 1.0, v190
	v_add_f32_e32 v191, 1.0, v191
	v_add_f32_e32 v192, 1.0, v192
	v_rcp_f32_e32 v166, v189
	v_rcp_f32_e32 v167, v190
	s_nop 0
	v_fma_f32 v189, -v189, v166, 2.0
	v_fma_f32 v190, -v190, v167, 2.0
	v_mul_f32_e32 v166, v166, v189
	v_mul_f32_e32 v167, v167, v190
	v_mul_f32_e32 v182, v182, v166
	v_mul_f32_e32 v183, v183, v167
	v_rcp_f32_e32 v166, v191
	v_rcp_f32_e32 v167, v192
	s_nop 0
	v_fma_f32 v191, -v191, v166, 2.0
	v_fma_f32 v192, -v192, v167, 2.0
	v_mul_f32_e32 v166, v166, v191
	v_mul_f32_e32 v167, v167, v192
	v_mul_f32_e32 v184, v184, v166
	v_mul_f32_e32 v185, v185, v167
	v_mul_f32_e32 v28, v182, v28
	v_mul_f32_e32 v29, v183, v29
	v_mul_f32_e32 v30, v184, v30
	v_mul_f32_e32 v31, v185, v31
	v_cvt_pk_bf16_f32 v28, v28, v29
	v_cvt_pk_bf16_f32 v29, v30, v31
	ds_write_b64 v160, v[28:29] offset:176
	global_load_dwordx4 v[128:131], v181, s[68:69] offset:384
	global_load_dwordx4 v[132:135], v181, s[68:69] offset:416
	global_load_dwordx4 v[136:139], v181, s[68:69] offset:448
	global_load_dwordx4 v[140:143], v181, s[68:69] offset:480
	global_load_dwordx4 v[144:147], v181, s[70:71] offset:384
	global_load_dwordx4 v[148:151], v181, s[70:71] offset:416
	global_load_dwordx4 v[152:155], v181, s[70:71] offset:448
	global_load_dwordx4 v[156:159], v181, s[70:71] offset:480
	ds_read_b64 v[164:165], v160 offset:192
	s_waitcnt vmcnt(3) lgkmcnt(0)
	v_lshlrev_b32_e32 v182, 16, v164
	v_and_b32_e32 v183, 0xffff0000, v164
	v_lshlrev_b32_e32 v184, 16, v165
	v_and_b32_e32 v185, 0xffff0000, v165
	v_add_f32_e32 v0, v128, v0
	v_mul_f32_e32 v0, v144, v0
	v_add_f32_e32 v1, v129, v1
	v_mul_f32_e32 v1, v145, v1
	v_add_f32_e32 v2, v130, v2
	v_mul_f32_e32 v2, v146, v2
	v_add_f32_e32 v3, v131, v3
	v_mul_f32_e32 v3, v147, v3
	v_mul_f32_e32 v189, 0xbfb8aa3b, v182
	v_mul_f32_e32 v190, 0xbfb8aa3b, v183
	v_mul_f32_e32 v191, 0xbfb8aa3b, v184
	v_mul_f32_e32 v192, 0xbfb8aa3b, v185
	v_exp_f32_e32 v189, v189
	v_exp_f32_e32 v190, v190
	v_exp_f32_e32 v191, v191
	v_exp_f32_e32 v192, v192
	s_nop 0
	v_add_f32_e32 v189, 1.0, v189
	v_add_f32_e32 v190, 1.0, v190
	v_add_f32_e32 v191, 1.0, v191
	v_add_f32_e32 v192, 1.0, v192
	v_rcp_f32_e32 v166, v189
	v_rcp_f32_e32 v167, v190
	s_nop 0
	v_fma_f32 v189, -v189, v166, 2.0
	v_fma_f32 v190, -v190, v167, 2.0
	v_mul_f32_e32 v166, v166, v189
	v_mul_f32_e32 v167, v167, v190
	v_mul_f32_e32 v182, v182, v166
	v_mul_f32_e32 v183, v183, v167
	v_rcp_f32_e32 v166, v191
	v_rcp_f32_e32 v167, v192
	s_nop 0
	v_fma_f32 v191, -v191, v166, 2.0
	v_fma_f32 v192, -v192, v167, 2.0
	v_mul_f32_e32 v166, v166, v191
	v_mul_f32_e32 v167, v167, v192
	v_mul_f32_e32 v184, v184, v166
	v_mul_f32_e32 v185, v185, v167
	v_mul_f32_e32 v0, v182, v0
	v_mul_f32_e32 v1, v183, v1
	v_mul_f32_e32 v2, v184, v2
	v_mul_f32_e32 v3, v185, v3
	v_cvt_pk_bf16_f32 v0, v0, v1
	v_cvt_pk_bf16_f32 v1, v2, v3
	ds_write_b64 v160, v[0:1] offset:192
	ds_read_b64 v[164:165], v160 offset:208
	s_waitcnt vmcnt(2) lgkmcnt(0)
	v_lshlrev_b32_e32 v182, 16, v164
	v_and_b32_e32 v183, 0xffff0000, v164
	v_lshlrev_b32_e32 v184, 16, v165
	v_and_b32_e32 v185, 0xffff0000, v165
	v_add_f32_e32 v4, v132, v4
	v_mul_f32_e32 v4, v148, v4
	v_add_f32_e32 v5, v133, v5
	v_mul_f32_e32 v5, v149, v5
	v_add_f32_e32 v6, v134, v6
	v_mul_f32_e32 v6, v150, v6
	v_add_f32_e32 v7, v135, v7
	v_mul_f32_e32 v7, v151, v7
	v_mul_f32_e32 v189, 0xbfb8aa3b, v182
	v_mul_f32_e32 v190, 0xbfb8aa3b, v183
	v_mul_f32_e32 v191, 0xbfb8aa3b, v184
	v_mul_f32_e32 v192, 0xbfb8aa3b, v185
	v_exp_f32_e32 v189, v189
	v_exp_f32_e32 v190, v190
	v_exp_f32_e32 v191, v191
	v_exp_f32_e32 v192, v192
	s_nop 0
	v_add_f32_e32 v189, 1.0, v189
	v_add_f32_e32 v190, 1.0, v190
	v_add_f32_e32 v191, 1.0, v191
	v_add_f32_e32 v192, 1.0, v192
	v_rcp_f32_e32 v166, v189
	v_rcp_f32_e32 v167, v190
	s_nop 0
	v_fma_f32 v189, -v189, v166, 2.0
	v_fma_f32 v190, -v190, v167, 2.0
	v_mul_f32_e32 v166, v166, v189
	v_mul_f32_e32 v167, v167, v190
	v_mul_f32_e32 v182, v182, v166
	v_mul_f32_e32 v183, v183, v167
	v_rcp_f32_e32 v166, v191
	v_rcp_f32_e32 v167, v192
	s_nop 0
	v_fma_f32 v191, -v191, v166, 2.0
	v_fma_f32 v192, -v192, v167, 2.0
	v_mul_f32_e32 v166, v166, v191
	v_mul_f32_e32 v167, v167, v192
	v_mul_f32_e32 v184, v184, v166
	v_mul_f32_e32 v185, v185, v167
	v_mul_f32_e32 v4, v182, v4
	v_mul_f32_e32 v5, v183, v5
	v_mul_f32_e32 v6, v184, v6
	v_mul_f32_e32 v7, v185, v7
	v_cvt_pk_bf16_f32 v4, v4, v5
	v_cvt_pk_bf16_f32 v5, v6, v7
	ds_write_b64 v160, v[4:5] offset:208
	ds_read_b64 v[164:165], v160 offset:224
	s_waitcnt vmcnt(1) lgkmcnt(0)
; DI bfr f2bf(float a) { return (bfr)(pack2(a, 0.f) & 0xffffu); }
; DI float bf2f(bfr u) { return __uint_as_float(((unsigned)u) << 16); }
; DI float siluf_(float x) { return x / (1.0f + __expf(-x)); }
; DI void phase_gemm_pool(const Params& p, char* smem) {
;     ...
;   for (int t0 = blockIdx.x; t0 < 128 * 4; t0 += gridDim.x) {
;     const int t = ((gridDim.x & 7) == 0) ? xcd_tile(t0, 4) : t0;
;     int mt = t >> 2, g = t & 3, nt = 0;
;     const float* bp = p.b_pool + g * 256;
;     const float* sc = p.pool_scale + g * 256;
;     gemm_tile<1024>(p.MIX + g * 256, p.WtPool + (size_t)g * 65536, 256, 256, mt * 128, nt * 256, smem,
;               [=](int row, int col, float v) {
;                 float gate = bf2f(P2[(size_t)row * 2048 + 1024 + g * 256 + col]);
;                 float z = (v + bp[col]) * sc[col] * siluf_(gate);
;                 Z[(size_t)row * 1024 + g * 256 + col] = f2bf(z);
;               });
;   }
	v_lshlrev_b32_e32 v182, 16, v164
	v_and_b32_e32 v183, 0xffff0000, v164
	v_lshlrev_b32_e32 v184, 16, v165
	v_and_b32_e32 v185, 0xffff0000, v165
	v_add_f32_e32 v8, v136, v8
	v_mul_f32_e32 v8, v152, v8
	v_add_f32_e32 v9, v137, v9
	v_mul_f32_e32 v9, v153, v9
	v_add_f32_e32 v10, v138, v10
	v_mul_f32_e32 v10, v154, v10
	v_add_f32_e32 v11, v139, v11
	v_mul_f32_e32 v11, v155, v11
	v_mul_f32_e32 v189, 0xbfb8aa3b, v182
	v_mul_f32_e32 v190, 0xbfb8aa3b, v183
	v_mul_f32_e32 v191, 0xbfb8aa3b, v184
	v_mul_f32_e32 v192, 0xbfb8aa3b, v185
	v_exp_f32_e32 v189, v189
	v_exp_f32_e32 v190, v190
	v_exp_f32_e32 v191, v191
	v_exp_f32_e32 v192, v192
	s_nop 0
	v_add_f32_e32 v189, 1.0, v189
	v_add_f32_e32 v190, 1.0, v190
	v_add_f32_e32 v191, 1.0, v191
	v_add_f32_e32 v192, 1.0, v192
	v_rcp_f32_e32 v166, v189
	v_rcp_f32_e32 v167, v190
	s_nop 0
	v_fma_f32 v189, -v189, v166, 2.0
	v_fma_f32 v190, -v190, v167, 2.0
	v_mul_f32_e32 v166, v166, v189
	v_mul_f32_e32 v167, v167, v190
	v_mul_f32_e32 v182, v182, v166
	v_mul_f32_e32 v183, v183, v167
	v_rcp_f32_e32 v166, v191
	v_rcp_f32_e32 v167, v192
	s_nop 0
	v_fma_f32 v191, -v191, v166, 2.0
	v_fma_f32 v192, -v192, v167, 2.0
	v_mul_f32_e32 v166, v166, v191
	v_mul_f32_e32 v167, v167, v192
	v_mul_f32_e32 v184, v184, v166
	v_mul_f32_e32 v185, v185, v167
	v_mul_f32_e32 v8, v182, v8
	v_mul_f32_e32 v9, v183, v9
	v_mul_f32_e32 v10, v184, v10
	v_mul_f32_e32 v11, v185, v11
	v_cvt_pk_bf16_f32 v8, v8, v9
	v_cvt_pk_bf16_f32 v9, v10, v11
	ds_write_b64 v160, v[8:9] offset:224
	ds_read_b64 v[164:165], v160 offset:240
	s_waitcnt vmcnt(0) lgkmcnt(0)
	v_lshlrev_b32_e32 v182, 16, v164
	v_and_b32_e32 v183, 0xffff0000, v164
	v_lshlrev_b32_e32 v184, 16, v165
	v_and_b32_e32 v185, 0xffff0000, v165
	v_add_f32_e32 v12, v140, v12
	v_mul_f32_e32 v12, v156, v12
	v_add_f32_e32 v13, v141, v13
	v_mul_f32_e32 v13, v157, v13
	v_add_f32_e32 v14, v142, v14
	v_mul_f32_e32 v14, v158, v14
	v_add_f32_e32 v15, v143, v15
	v_mul_f32_e32 v15, v159, v15
	v_mul_f32_e32 v189, 0xbfb8aa3b, v182
	v_mul_f32_e32 v190, 0xbfb8aa3b, v183
	v_mul_f32_e32 v191, 0xbfb8aa3b, v184
	v_mul_f32_e32 v192, 0xbfb8aa3b, v185
	v_exp_f32_e32 v189, v189
	v_exp_f32_e32 v190, v190
	v_exp_f32_e32 v191, v191
	v_exp_f32_e32 v192, v192
	s_nop 0
	v_add_f32_e32 v189, 1.0, v189
	v_add_f32_e32 v190, 1.0, v190
	v_add_f32_e32 v191, 1.0, v191
	v_add_f32_e32 v192, 1.0, v192
	v_rcp_f32_e32 v166, v189
	v_rcp_f32_e32 v167, v190
	s_nop 0
	v_fma_f32 v189, -v189, v166, 2.0
	v_fma_f32 v190, -v190, v167, 2.0
	v_mul_f32_e32 v166, v166, v189
	v_mul_f32_e32 v167, v167, v190
	v_mul_f32_e32 v182, v182, v166
	v_mul_f32_e32 v183, v183, v167
	v_rcp_f32_e32 v166, v191
	v_rcp_f32_e32 v167, v192
	s_nop 0
	v_fma_f32 v191, -v191, v166, 2.0
	v_fma_f32 v192, -v192, v167, 2.0
	v_mul_f32_e32 v166, v166, v191
	v_mul_f32_e32 v167, v167, v192
	v_mul_f32_e32 v184, v184, v166
	v_mul_f32_e32 v185, v185, v167
	v_mul_f32_e32 v12, v182, v12
	v_mul_f32_e32 v13, v183, v13
	v_mul_f32_e32 v14, v184, v14
	v_mul_f32_e32 v15, v185, v15
	v_cvt_pk_bf16_f32 v12, v12, v13
	v_cvt_pk_bf16_f32 v13, v14, v15
	ds_write_b64 v160, v[12:13] offset:240
	s_waitcnt lgkmcnt(0)
	ds_read_b128 v[128:131], v162
	ds_read_b128 v[132:135], v162 offset:1088
	ds_read_b128 v[136:139], v162 offset:2176
	ds_read_b128 v[140:143], v162 offset:3264
	ds_read_b128 v[144:147], v162 offset:4352
	ds_read_b128 v[148:151], v162 offset:5440
	ds_read_b128 v[152:155], v162 offset:6528
	ds_read_b128 v[156:159], v162 offset:7616
	s_add_u32 s74, s66, 0x10000
	s_addc_u32 s75, s67, 0
	s_waitcnt lgkmcnt(7)
	global_store_dwordx4 v180, v[128:131], s[74:75]
	s_add_u32 s74, s66, 0x12000
	s_addc_u32 s75, s67, 0
	s_waitcnt lgkmcnt(6)
	global_store_dwordx4 v180, v[132:135], s[74:75]
	s_add_u32 s74, s66, 0x14000
	s_addc_u32 s75, s67, 0
	s_waitcnt lgkmcnt(5)
	global_store_dwordx4 v180, v[136:139], s[74:75]
	s_add_u32 s74, s66, 0x16000
	s_addc_u32 s75, s67, 0
	s_waitcnt lgkmcnt(4)
	global_store_dwordx4 v180, v[140:143], s[74:75]
	s_add_u32 s74, s66, 0x18000
	s_addc_u32 s75, s67, 0
	s_waitcnt lgkmcnt(3)
	global_store_dwordx4 v180, v[144:147], s[74:75]
	s_add_u32 s74, s66, 0x1a000
	s_addc_u32 s75, s67, 0
	s_waitcnt lgkmcnt(2)
	global_store_dwordx4 v180, v[148:151], s[74:75]
	s_add_u32 s74, s66, 0x1c000
	s_addc_u32 s75, s67, 0
	s_waitcnt lgkmcnt(1)
	global_store_dwordx4 v180, v[152:155], s[74:75]
	s_add_u32 s74, s66, 0x1e000
	s_addc_u32 s75, s67, 0
	s_waitcnt lgkmcnt(0)
	global_store_dwordx4 v180, v[156:159], s[74:75]
	v_readlane_b32 s64, v188, 0
	v_readlane_b32 s65, v188, 1
	v_readlane_b32 s66, v188, 2
	v_readlane_b32 s67, v188, 3
	v_readlane_b32 s68, v188, 4
	v_readlane_b32 s69, v188, 5
	v_readlane_b32 s70, v188, 6
	v_readlane_b32 s71, v188, 7
	v_readlane_b32 s72, v188, 8
	v_readlane_b32 s73, v188, 9
	v_readlane_b32 s74, v188, 10
	v_readlane_b32 s75, v188, 11
	v_readlane_b32 s76, v188, 12
	v_readlane_b32 s77, v188, 13
	v_readlane_b32 s78, v188, 14
	v_readlane_b32 s79, v188, 15
	s_nop 7
	s_lshl_b32 s6, s22, 2
	s_add_u32 s4, s12, s6
	s_addc_u32 s5, s13, 0
	s_add_u32 s6, s14, s6
	s_addc_u32 s7, s15, 0
	s_lshl_b32 s10, s22, 1
	s_add_u32 s22, s16, s10
	s_addc_u32 s23, s17, 0
	s_add_i32 s37, s37, s24
	s_add_i32 s25, s25, s26
	s_cmpk_lt_i32 s37, 0x200
	s_cbranch_scc0 .LBB0_1395
	s_branch .LBB0_1377

; #define MFMA32(a, b, c) __builtin_amdgcn_mfma_f32_32x32x16_bf16((a), (b), (c), 0, 0, 0)
; #define GA_LOAD(pr_) do { _Pragma("unroll") for (int i = 0; i < 4; ++i) ra[i] = *(const u32x4*)(Ab + (i * 32) * lda + (pr_) * 64); } while (0)
; #define GB_LOAD(kt_) do { const bfr* bk_ = Bb + (kt_) * NB * 32; \
;     _Pragma("unroll") for (int i = 0; i < 4; ++i) rb[i] = *(const u32x4*)(bk_ + (i * 64) * 32); } while (0)
; #define G_STORE(kt_) do { bfr* as_ = S0 + ((kt_) & 1) * GSTAGE; bfr* bs_ = as_ + 128 * 40; \
;     if (apar == ((kt_) & 1)) { _Pragma("unroll") for (int i = 0; i < 4; ++i) *(u32x4*)(as_ + asoff + i * 32 * 40) = ra[i]; } \
;     _Pragma("unroll") for (int i = 0; i < 4; ++i) *(u32x4*)(bs_ + bsoff + i * 64 * 40) = rb[i]; } while (0)
; template <int lda>
; DI void gemm_mainloop(const bfr* __restrict__ A, const bfr* __restrict__ Bt, int NB, int K, int m0, int n0, char* smem, f32x16 (&acc)[2][4]) {
;     ...
; #pragma unroll
;   for (int i = 0; i < 2; ++i)
; #pragma unroll
;     for (int j = 0; j < 4; ++j)
; #pragma unroll
;       for (int q = 0; q < 16; ++q) acc[i][j][q] = 0.f;
;   u32x4 ra[4], rb[4];
;   const int nk = K >> 5;
;   const int arow = tid >> 3, ac8 = tid & 7, apar = ac8 >> 2;
;   const bfr* Ab = A + (m0 + arow) * lda + ac8 * 8;
;   const int asoff = arow * 40 + (ac8 & 3) * 8;
;   const int brow = tid >> 2, bc4 = tid & 3;
;   const bfr* Bb = Bt + (n0 + brow) * 32 + bc4 * 8;
;   const int bsoff = brow * 40 + bc4 * 8;
;     ...
;   GA_LOAD(0);
;   GB_LOAD(0);
;   G_STORE(0);
;   GB_LOAD(1);
;   __syncthreads();
;   for (int kt = 0; kt < nk; ++kt) {
;     if (kt + 1 < nk) G_STORE(kt + 1);
;     if (kt + 2 < nk) {
;       GB_LOAD(kt + 2);
;       if ((kt & 1) == 0) GA_LOAD((kt >> 1) + 1);
;     }
;     const bfr* As = S0 + (kt & 1) * GSTAGE;
;     const bfr* Bs = As + 128 * 40;
; #pragma unroll
;     for (int ks = 0; ks < 2; ++ks) {
;       bf16x8 af[2], bfg[4];
; #pragma unroll
;       for (int i = 0; i < 2; ++i) af[i] = *(const bf16x8*)(As + (wr * 64 + i * 32 + r) * 40 + ks * 16 + hl * 8);
; #pragma unroll
;       for (int j = 0; j < 4; ++j) bfg[j] = *(const bf16x8*)(Bs + (wc * 128 + j * 32 + r) * 40 + ks * 16 + hl * 8);
; #pragma unroll
;       for (int i = 0; i < 2; ++i)
; #pragma unroll
;         for (int j = 0; j < 4; ++j) acc[i][j] = MFMA32(af[i], bfg[j], acc[i][j]);
;     }
.Lp15_nostag:
	v_mov_b32_e32 v112, 0
	v_mov_b32_e32 v113, 0
	v_mov_b32_e32 v114, 0
	v_mov_b32_e32 v115, 0
	v_mov_b32_e32 v116, 0
	v_mov_b32_e32 v117, 0
	v_mov_b32_e32 v118, 0
	v_mov_b32_e32 v119, 0
	v_mov_b32_e32 v120, 0
	v_mov_b32_e32 v121, 0
	v_mov_b32_e32 v122, 0
	v_mov_b32_e32 v123, 0
	v_mov_b32_e32 v124, 0
	v_mov_b32_e32 v125, 0
	v_mov_b32_e32 v126, 0
	v_mov_b32_e32 v127, 0
	v_mov_b32_e32 v96, 0
	v_mov_b32_e32 v97, 0
	v_mov_b32_e32 v98, 0
	v_mov_b32_e32 v99, 0
	v_mov_b32_e32 v100, 0
	v_mov_b32_e32 v101, 0
	v_mov_b32_e32 v102, 0
	v_mov_b32_e32 v103, 0
	v_mov_b32_e32 v104, 0
	v_mov_b32_e32 v105, 0
	v_mov_b32_e32 v106, 0
	v_mov_b32_e32 v107, 0
	v_mov_b32_e32 v108, 0
	v_mov_b32_e32 v109, 0
	v_mov_b32_e32 v110, 0
	v_mov_b32_e32 v111, 0
	v_mov_b32_e32 v80, 0
	v_mov_b32_e32 v81, 0
	v_mov_b32_e32 v82, 0
	v_mov_b32_e32 v83, 0
	v_mov_b32_e32 v84, 0
	v_mov_b32_e32 v85, 0
	v_mov_b32_e32 v86, 0
	v_mov_b32_e32 v87, 0
	v_mov_b32_e32 v88, 0
	v_mov_b32_e32 v89, 0
	v_mov_b32_e32 v90, 0
	v_mov_b32_e32 v91, 0
	v_mov_b32_e32 v92, 0
	v_mov_b32_e32 v93, 0
	v_mov_b32_e32 v94, 0
	v_mov_b32_e32 v95, 0
	v_mov_b32_e32 v64, 0
	v_mov_b32_e32 v65, 0
	v_mov_b32_e32 v66, 0
	v_mov_b32_e32 v67, 0
	v_mov_b32_e32 v68, 0
	v_mov_b32_e32 v69, 0
	v_mov_b32_e32 v70, 0
	v_mov_b32_e32 v71, 0
	v_mov_b32_e32 v72, 0
	v_mov_b32_e32 v73, 0
	v_mov_b32_e32 v74, 0
	v_mov_b32_e32 v75, 0
	v_mov_b32_e32 v76, 0
	v_mov_b32_e32 v77, 0
	v_mov_b32_e32 v78, 0
	v_mov_b32_e32 v79, 0
	v_mov_b32_e32 v48, 0
	v_mov_b32_e32 v49, 0
	v_mov_b32_e32 v50, 0
	v_mov_b32_e32 v51, 0
	v_mov_b32_e32 v52, 0
	v_mov_b32_e32 v53, 0
	v_mov_b32_e32 v54, 0
	v_mov_b32_e32 v55, 0
	v_mov_b32_e32 v56, 0
	v_mov_b32_e32 v57, 0
	v_mov_b32_e32 v58, 0
	v_mov_b32_e32 v59, 0
	v_mov_b32_e32 v60, 0
	v_mov_b32_e32 v61, 0
	v_mov_b32_e32 v62, 0
	v_mov_b32_e32 v63, 0
	v_mov_b32_e32 v32, 0
	v_mov_b32_e32 v33, 0
	v_mov_b32_e32 v34, 0
	v_mov_b32_e32 v35, 0
	v_mov_b32_e32 v36, 0
	v_mov_b32_e32 v37, 0
	v_mov_b32_e32 v38, 0
	v_mov_b32_e32 v39, 0
	v_mov_b32_e32 v40, 0
	v_mov_b32_e32 v41, 0
	v_mov_b32_e32 v42, 0
	v_mov_b32_e32 v43, 0
	v_mov_b32_e32 v44, 0
	v_mov_b32_e32 v45, 0
	v_mov_b32_e32 v46, 0
	v_mov_b32_e32 v47, 0
	v_mov_b32_e32 v16, 0
	v_mov_b32_e32 v17, 0
	v_mov_b32_e32 v18, 0
	v_mov_b32_e32 v19, 0
	v_mov_b32_e32 v20, 0
	v_mov_b32_e32 v21, 0
	v_mov_b32_e32 v22, 0
	v_mov_b32_e32 v23, 0
	v_mov_b32_e32 v24, 0
	v_mov_b32_e32 v25, 0
	v_mov_b32_e32 v26, 0
	v_mov_b32_e32 v27, 0
	v_mov_b32_e32 v28, 0
	v_mov_b32_e32 v29, 0
	v_mov_b32_e32 v30, 0
	v_mov_b32_e32 v31, 0
	v_mov_b32_e32 v0, 0
	v_mov_b32_e32 v1, 0
	v_mov_b32_e32 v2, 0
	v_mov_b32_e32 v3, 0
	v_mov_b32_e32 v4, 0
	v_mov_b32_e32 v5, 0
	v_mov_b32_e32 v6, 0
	v_mov_b32_e32 v7, 0
	v_mov_b32_e32 v8, 0
	v_mov_b32_e32 v9, 0
	v_mov_b32_e32 v10, 0
	v_mov_b32_e32 v11, 0
	v_mov_b32_e32 v12, 0
	v_mov_b32_e32 v13, 0
	v_mov_b32_e32 v14, 0
	v_mov_b32_e32 v15, 0
	s_waitcnt vmcnt(6)
	s_barrier
	s_mul_i32 s74, s71, 0x6000
	s_add_u32 s75, s74, 0x2000
	s_cmp_eq_u32 s71, 2
	s_cselect_b32 s75, 0x10000, s75
	v_add_u32_e32 v205, s74, v201
	v_add_u32_e32 v207, s75, v203
	v_add_u32_e32 v206, s74, v202
	v_add_u32_e32 v208, s75, v204
	s_add_u32 s71, s71, 1
	s_cmp_eq_u32 s71, 3
	s_cselect_b32 s71, 0, s71
	ds_read_b128 v[128:131], v205
	ds_read_b128 v[144:147], v207
	ds_read_b128 v[148:151], v207 offset:2048
	ds_read_b128 v[152:155], v207 offset:4096
	ds_read_b128 v[156:159], v207 offset:6144
	ds_read_b128 v[132:135], v205 offset:2048
	ds_read_b128 v[136:139], v206
	ds_read_b128 v[160:163], v208
	ds_read_b128 v[164:167], v208 offset:2048
	ds_read_b128 v[168:171], v208 offset:4096
	ds_read_b128 v[172:175], v208 offset:6144
	ds_read_b128 v[140:143], v206 offset:2048
	s_waitcnt lgkmcnt(10)
	v_mfma_f32_32x32x16_bf16 v[112:127], v[144:147], v[128:131], v[112:127]
	s_mul_i32 s74, s70, 0x6000
	s_add_u32 s75, s74, s68
	s_mov_b32 m0, s75
	s_add_u32 s76, s74, 0x2000
	s_cmp_eq_u32 s70, 2
	s_cselect_b32 s76, 0x10000, s76
	global_load_lds_dwordx4 v192, s[64:65]
	s_waitcnt lgkmcnt(9)
	v_mfma_f32_32x32x16_bf16 v[96:111], v[148:151], v[128:131], v[96:111]
	s_add_u32 m0, s75, 0x400
	s_add_u32 s76, s76, s69
	global_load_lds_dwordx4 v194, s[64:65]
	s_waitcnt lgkmcnt(8)
	v_mfma_f32_32x32x16_bf16 v[80:95], v[152:155], v[128:131], v[80:95]
	s_mov_b32 m0, s76
	s_add_u32 s64, s64, 64
	s_addc_u32 s65, s65, 0
	global_load_lds_dwordx4 v200, s[66:67]
	s_waitcnt lgkmcnt(7)
	v_mfma_f32_32x32x16_bf16 v[64:79], v[156:159], v[128:131], v[64:79]
	global_load_lds_dwordx4 v200, s[66:67] offset:1024
	s_waitcnt lgkmcnt(6)
	v_mfma_f32_32x32x16_bf16 v[48:63], v[144:147], v[132:135], v[48:63]
	global_load_lds_dwordx4 v200, s[66:67] offset:2048
	v_mfma_f32_32x32x16_bf16 v[32:47], v[148:151], v[132:135], v[32:47]
	global_load_lds_dwordx4 v200, s[66:67] offset:3072
	s_add_u32 s66, s66, 0x10000
	s_addc_u32 s67, s67, 0
	v_mfma_f32_32x32x16_bf16 v[16:31], v[152:155], v[132:135], v[16:31]
	s_add_u32 s70, s70, 1
	s_cmp_eq_u32 s70, 3
	s_cselect_b32 s70, 0, s70
	v_mfma_f32_32x32x16_bf16 v[0:15], v[156:159], v[132:135], v[0:15]
; #define MFMA32(a, b, c) __builtin_amdgcn_mfma_f32_32x32x16_bf16((a), (b), (c), 0, 0, 0)
; #define GA_LOAD(pr_) do { _Pragma("unroll") for (int i = 0; i < 4; ++i) ra[i] = *(const u32x4*)(Ab + (i * 32) * lda + (pr_) * 64); } while (0)
; #define GB_LOAD(kt_) do { const bfr* bk_ = Bb + (kt_) * NB * 32; \
;     _Pragma("unroll") for (int i = 0; i < 4; ++i) rb[i] = *(const u32x4*)(bk_ + (i * 64) * 32); } while (0)
; #define G_STORE(kt_) do { bfr* as_ = S0 + ((kt_) & 1) * GSTAGE; bfr* bs_ = as_ + 128 * 40; \
;     if (apar == ((kt_) & 1)) { _Pragma("unroll") for (int i = 0; i < 4; ++i) *(u32x4*)(as_ + asoff + i * 32 * 40) = ra[i]; } \
;     _Pragma("unroll") for (int i = 0; i < 4; ++i) *(u32x4*)(bs_ + bsoff + i * 64 * 40) = rb[i]; } while (0)
; template <int lda>
; DI void gemm_mainloop(const bfr* __restrict__ A, const bfr* __restrict__ Bt, int NB, int K, int m0, int n0, char* smem, f32x16 (&acc)[2][4]) {
;     ...
;   for (int kt = 0; kt < nk; ++kt) {
;     if (kt + 1 < nk) G_STORE(kt + 1);
;     if (kt + 2 < nk) {
;       GB_LOAD(kt + 2);
;       if ((kt & 1) == 0) GA_LOAD((kt >> 1) + 1);
;     }
;     const bfr* As = S0 + (kt & 1) * GSTAGE;
;     const bfr* Bs = As + 128 * 40;
; #pragma unroll
;     for (int ks = 0; ks < 2; ++ks) {
;       bf16x8 af[2], bfg[4];
; #pragma unroll
;       for (int i = 0; i < 2; ++i) af[i] = *(const bf16x8*)(As + (wr * 64 + i * 32 + r) * 40 + ks * 16 + hl * 8);
; #pragma unroll
;       for (int j = 0; j < 4; ++j) bfg[j] = *(const bf16x8*)(Bs + (wc * 128 + j * 32 + r) * 40 + ks * 16 + hl * 8);
; #pragma unroll
;       for (int i = 0; i < 2; ++i)
; #pragma unroll
;         for (int j = 0; j < 4; ++j) acc[i][j] = MFMA32(af[i], bfg[j], acc[i][j]);
;     }
;     __syncthreads();
.Lp15_loop:
	s_waitcnt vmcnt(6) lgkmcnt(0)
	s_barrier
	s_mul_i32 s74, s71, 0x6000
	s_add_u32 s75, s74, 0x2000
	s_cmp_eq_u32 s71, 2
	s_cselect_b32 s75, 0x10000, s75
	v_add_u32_e32 v205, s74, v201
	v_add_u32_e32 v207, s75, v203
	v_add_u32_e32 v206, s74, v202
	v_add_u32_e32 v208, s75, v204
	s_add_u32 s71, s71, 1
	s_cmp_eq_u32 s71, 3
	s_cselect_b32 s71, 0, s71
	ds_read_b128 v[128:131], v205
	ds_read_b128 v[144:147], v207
	ds_read_b128 v[148:151], v207 offset:2048
	ds_read_b128 v[152:155], v207 offset:4096
	ds_read_b128 v[156:159], v207 offset:6144
	ds_read_b128 v[132:135], v205 offset:2048
	v_mfma_f32_32x32x16_bf16 v[112:127], v[160:163], v[136:139], v[112:127]
	s_mul_i32 s74, s70, 0x6000
	s_add_u32 s75, s74, s68
	s_mov_b32 m0, s75
	s_add_u32 s76, s74, 0x2000
	s_cmp_eq_u32 s70, 2
	s_cselect_b32 s76, 0x10000, s76
	global_load_lds_dwordx4 v192, s[64:65]
	v_mfma_f32_32x32x16_bf16 v[96:111], v[164:167], v[136:139], v[96:111]
	s_add_u32 m0, s75, 0x400
	s_add_u32 s76, s76, s69
	global_load_lds_dwordx4 v194, s[64:65]
	v_mfma_f32_32x32x16_bf16 v[80:95], v[168:171], v[136:139], v[80:95]
	s_mov_b32 m0, s76
	s_add_u32 s64, s64, 64
	s_addc_u32 s65, s65, 0
	global_load_lds_dwordx4 v200, s[66:67]
	v_mfma_f32_32x32x16_bf16 v[64:79], v[172:175], v[136:139], v[64:79]
	global_load_lds_dwordx4 v200, s[66:67] offset:1024
	v_mfma_f32_32x32x16_bf16 v[48:63], v[160:163], v[140:143], v[48:63]
	global_load_lds_dwordx4 v200, s[66:67] offset:2048
	v_mfma_f32_32x32x16_bf16 v[32:47], v[164:167], v[140:143], v[32:47]
	global_load_lds_dwordx4 v200, s[66:67] offset:3072
	s_add_u32 s66, s66, 0x10000
	s_addc_u32 s67, s67, 0
	v_mfma_f32_32x32x16_bf16 v[16:31], v[168:171], v[140:143], v[16:31]
	s_add_u32 s70, s70, 1
	s_cmp_eq_u32 s70, 3
	s_cselect_b32 s70, 0, s70
	v_mfma_f32_32x32x16_bf16 v[0:15], v[172:175], v[140:143], v[0:15]
	ds_read_b128 v[136:139], v206
	ds_read_b128 v[160:163], v208
	ds_read_b128 v[164:167], v208 offset:2048
	ds_read_b128 v[168:171], v208 offset:4096
	ds_read_b128 v[172:175], v208 offset:6144
	ds_read_b128 v[140:143], v206 offset:2048
	s_waitcnt lgkmcnt(10)
	v_mfma_f32_32x32x16_bf16 v[112:127], v[144:147], v[128:131], v[112:127]
	s_waitcnt lgkmcnt(9)
	v_mfma_f32_32x32x16_bf16 v[96:111], v[148:151], v[128:131], v[96:111]
	s_waitcnt lgkmcnt(8)
	v_mfma_f32_32x32x16_bf16 v[80:95], v[152:155], v[128:131], v[80:95]
	s_waitcnt lgkmcnt(7)
	v_mfma_f32_32x32x16_bf16 v[64:79], v[156:159], v[128:131], v[64:79]
	s_waitcnt lgkmcnt(6)
	v_mfma_f32_32x32x16_bf16 v[48:63], v[144:147], v[132:135], v[48:63]
	v_mfma_f32_32x32x16_bf16 v[32:47], v[148:151], v[132:135], v[32:47]
	v_mfma_f32_32x32x16_bf16 v[16:31], v[152:155], v[132:135], v[16:31]
	v_mfma_f32_32x32x16_bf16 v[0:15], v[156:159], v[132:135], v[0:15]
	s_add_u32 s72, s72, 1
	s_cmp_lt_u32 s72, 29
	s_cbranch_scc1 .Lp15_loop
	s_waitcnt vmcnt(6) lgkmcnt(0)
	s_barrier
	s_mul_i32 s74, s71, 0x6000
	s_add_u32 s75, s74, 0x2000
	s_cmp_eq_u32 s71, 2
	s_cselect_b32 s75, 0x10000, s75
	v_add_u32_e32 v205, s74, v201
	v_add_u32_e32 v207, s75, v203
	v_add_u32_e32 v206, s74, v202
	v_add_u32_e32 v208, s75, v204
	s_add_u32 s71, s71, 1
	s_cmp_eq_u32 s71, 3
	s_cselect_b32 s71, 0, s71
	ds_read_b128 v[128:131], v205
	ds_read_b128 v[144:147], v207
	ds_read_b128 v[148:151], v207 offset:2048
	ds_read_b128 v[152:155], v207 offset:4096
	ds_read_b128 v[156:159], v207 offset:6144
	ds_read_b128 v[132:135], v205 offset:2048
	v_mfma_f32_32x32x16_bf16 v[112:127], v[160:163], v[136:139], v[112:127]
	v_mfma_f32_32x32x16_bf16 v[96:111], v[164:167], v[136:139], v[96:111]
	v_mfma_f32_32x32x16_bf16 v[80:95], v[168:171], v[136:139], v[80:95]
	v_mfma_f32_32x32x16_bf16 v[64:79], v[172:175], v[136:139], v[64:79]
	v_mfma_f32_32x32x16_bf16 v[48:63], v[160:163], v[140:143], v[48:63]
	v_mfma_f32_32x32x16_bf16 v[32:47], v[164:167], v[140:143], v[32:47]
	v_mfma_f32_32x32x16_bf16 v[16:31], v[168:171], v[140:143], v[16:31]
	v_mfma_f32_32x32x16_bf16 v[0:15], v[172:175], v[140:143], v[0:15]
	ds_read_b128 v[136:139], v206
	ds_read_b128 v[160:163], v208
	ds_read_b128 v[164:167], v208 offset:2048
	ds_read_b128 v[168:171], v208 offset:4096
	ds_read_b128 v[172:175], v208 offset:6144
	ds_read_b128 v[140:143], v206 offset:2048
	s_waitcnt lgkmcnt(10)
	v_mfma_f32_32x32x16_bf16 v[112:127], v[144:147], v[128:131], v[112:127]
	s_waitcnt lgkmcnt(9)
	v_mfma_f32_32x32x16_bf16 v[96:111], v[148:151], v[128:131], v[96:111]
	s_waitcnt lgkmcnt(8)
	v_mfma_f32_32x32x16_bf16 v[80:95], v[152:155], v[128:131], v[80:95]
	s_waitcnt lgkmcnt(7)
	v_mfma_f32_32x32x16_bf16 v[64:79], v[156:159], v[128:131], v[64:79]
	s_waitcnt lgkmcnt(6)
	v_mfma_f32_32x32x16_bf16 v[48:63], v[144:147], v[132:135], v[48:63]
	v_mfma_f32_32x32x16_bf16 v[32:47], v[148:151], v[132:135], v[32:47]
	v_mfma_f32_32x32x16_bf16 v[16:31], v[152:155], v[132:135], v[16:31]
	v_mfma_f32_32x32x16_bf16 v[0:15], v[156:159], v[132:135], v[0:15]
	s_waitcnt vmcnt(0) lgkmcnt(0)
	s_barrier
; #define MFMA32(a, b, c) __builtin_amdgcn_mfma_f32_32x32x16_bf16((a), (b), (c), 0, 0, 0)
; DI int crow(int reg, int h) { return (reg & 3) + 8 * (reg >> 2) + 4 * h; }
; #define GA_LOAD(pr_) do { _Pragma("unroll") for (int i = 0; i < 4; ++i) ra[i] = *(const u32x4*)(Ab + (i * 32) * lda + (pr_) * 64); } while (0)
; template <int lda>
; DI void gemm_mainloop(const bfr* __restrict__ A, const bfr* __restrict__ Bt, int NB, int K, int m0, int n0, char* smem, f32x16 (&acc)[2][4]) {
;     ...
;   for (int kt = 0; kt < nk; ++kt) {
;     if (kt + 1 < nk) G_STORE(kt + 1);
;     if (kt + 2 < nk) {
;       GB_LOAD(kt + 2);
;       if ((kt & 1) == 0) GA_LOAD((kt >> 1) + 1);
;     }
;     const bfr* As = S0 + (kt & 1) * GSTAGE;
;     const bfr* Bs = As + 128 * 40;
; #pragma unroll
;     for (int ks = 0; ks < 2; ++ks) {
;       bf16x8 af[2], bfg[4];
; #pragma unroll
;       for (int i = 0; i < 2; ++i) af[i] = *(const bf16x8*)(As + (wr * 64 + i * 32 + r) * 40 + ks * 16 + hl * 8);
; #pragma unroll
;       for (int j = 0; j < 4; ++j) bfg[j] = *(const bf16x8*)(Bs + (wc * 128 + j * 32 + r) * 40 + ks * 16 + hl * 8);
; #pragma unroll
;       for (int i = 0; i < 2; ++i)
; #pragma unroll
;         for (int j = 0; j < 4; ++j) acc[i][j] = MFMA32(af[i], bfg[j], acc[i][j]);
;     }
; template <bool FIRST, bool HAS_H>
; DI void phase_gemm_resid(const Params& p, const bfr* A, const bfr* Wt, const float* gnext, float* ss, char* smem) {
;     ...
;     int tid2 = threadIdx.x;
;     asm volatile("" : "+v"(tid2));
;     const int lane = tid2 & 63, wid = tid2 >> 6, wr = wid >> 1, wc = wid & 1, r = lane & 31, hl = lane >> 5;
;     const float* xsrc = FIRST ? p.x_prompt : X;
;     const int rbase = m0 + wr * 64 + 4 * hl, cbase = n0 + wc * 128 + r;
; #pragma unroll
;     for (int i = 0; i < 2; ++i) {
; #pragma unroll
;       for (int qh = 0; qh < 2; ++qh) {
;         float rs[8];
; #pragma unroll
;         for (int q = 0; q < 8; ++q) rs[q] = 0.f;
; #pragma unroll
;         for (int jh = 0; jh < 2; ++jh) {
;           float xo[2][8];
; #pragma unroll
;           for (int jj = 0; jj < 2; ++jj)
; #pragma unroll
;             for (int q = 0; q < 8; ++q)
;               xo[jj][q] = xsrc[(rbase + i * 32 + crow(qh * 8 + q, 0)) * 1024 + cbase + (jh * 2 + jj) * 32];
	s_mul_i32 s74, s71, 0x6000
	s_add_u32 s75, s74, 0x2000
	s_cmp_eq_u32 s71, 2
	s_cselect_b32 s75, 0x10000, s75
	v_add_u32_e32 v205, s74, v201
	v_add_u32_e32 v207, s75, v203
	v_add_u32_e32 v206, s74, v202
	v_add_u32_e32 v208, s75, v204
	s_add_u32 s71, s71, 1
	s_cmp_eq_u32 s71, 3
	s_cselect_b32 s71, 0, s71
	ds_read_b128 v[128:131], v205
	ds_read_b128 v[144:147], v207
	ds_read_b128 v[148:151], v207 offset:2048
	ds_read_b128 v[152:155], v207 offset:4096
	ds_read_b128 v[156:159], v207 offset:6144
	ds_read_b128 v[132:135], v205 offset:2048
	v_mfma_f32_32x32x16_bf16 v[112:127], v[160:163], v[136:139], v[112:127]
	v_mfma_f32_32x32x16_bf16 v[96:111], v[164:167], v[136:139], v[96:111]
	v_mfma_f32_32x32x16_bf16 v[80:95], v[168:171], v[136:139], v[80:95]
	v_mfma_f32_32x32x16_bf16 v[64:79], v[172:175], v[136:139], v[64:79]
	v_mfma_f32_32x32x16_bf16 v[48:63], v[160:163], v[140:143], v[48:63]
	v_mfma_f32_32x32x16_bf16 v[32:47], v[164:167], v[140:143], v[32:47]
	v_mfma_f32_32x32x16_bf16 v[16:31], v[168:171], v[140:143], v[16:31]
	v_mfma_f32_32x32x16_bf16 v[0:15], v[172:175], v[140:143], v[0:15]
	ds_read_b128 v[136:139], v206
	ds_read_b128 v[160:163], v208
	ds_read_b128 v[164:167], v208 offset:2048
	ds_read_b128 v[168:171], v208 offset:4096
	ds_read_b128 v[172:175], v208 offset:6144
	ds_read_b128 v[140:143], v206 offset:2048
	s_waitcnt lgkmcnt(10)
	v_mfma_f32_32x32x16_bf16 v[112:127], v[144:147], v[128:131], v[112:127]
	s_waitcnt lgkmcnt(9)
	v_mfma_f32_32x32x16_bf16 v[96:111], v[148:151], v[128:131], v[96:111]
	s_waitcnt lgkmcnt(8)
	v_mfma_f32_32x32x16_bf16 v[80:95], v[152:155], v[128:131], v[80:95]
	s_waitcnt lgkmcnt(7)
	v_mfma_f32_32x32x16_bf16 v[64:79], v[156:159], v[128:131], v[64:79]
	s_waitcnt lgkmcnt(6)
	v_mfma_f32_32x32x16_bf16 v[48:63], v[144:147], v[132:135], v[48:63]
	v_mfma_f32_32x32x16_bf16 v[32:47], v[148:151], v[132:135], v[32:47]
	v_mfma_f32_32x32x16_bf16 v[16:31], v[152:155], v[132:135], v[16:31]
	v_mfma_f32_32x32x16_bf16 v[0:15], v[156:159], v[132:135], v[0:15]
	s_waitcnt lgkmcnt(0)
	v_mfma_f32_32x32x16_bf16 v[112:127], v[160:163], v[136:139], v[112:127]
	v_mfma_f32_32x32x16_bf16 v[96:111], v[164:167], v[136:139], v[96:111]
	v_mfma_f32_32x32x16_bf16 v[80:95], v[168:171], v[136:139], v[80:95]
	v_mfma_f32_32x32x16_bf16 v[64:79], v[172:175], v[136:139], v[64:79]
	v_mfma_f32_32x32x16_bf16 v[48:63], v[160:163], v[140:143], v[48:63]
	v_mfma_f32_32x32x16_bf16 v[32:47], v[164:167], v[140:143], v[32:47]
	v_mfma_f32_32x32x16_bf16 v[16:31], v[168:171], v[140:143], v[16:31]
	v_mfma_f32_32x32x16_bf16 v[0:15], v[172:175], v[140:143], v[0:15]
	s_nop 7
	s_nop 3
	s_load_dwordx2 s[64:65], s[92:93], 0x100
	s_load_dwordx2 s[66:67], s[92:93], 0x100
	s_load_dwordx2 s[68:69], s[92:93], 0x148
	s_load_dwordx2 s[70:71], s[92:93], 0x50
	s_mul_i32 s76, s73, 8704
	s_lshr_b32 s74, s73, 1
	s_lshl_b32 s74, s74, 6
	s_add_u32 s74, s74, s77
	s_and_b32 s75, s73, 1
	s_lshl_b32 s75, s75, 7
	s_add_u32 s75, s75, s78
	v_and_b32_e32 v210, 31, v196
	v_bfe_u32 v211, v196, 5, 1
	v_mul_u32_u24_e32 v216, 272, v210
	v_add_u32_e32 v216, s76, v216
	v_lshl_add_u32 v192, v211, 4, v216
	v_lshl_add_u32 v194, v211, 3, v216
	v_lshlrev_b32_e32 v216, 2, v211
	v_add_lshl_u32 v204, v216, s75, 2
	v_add_lshl_u32 v207, v210, s74, 2
	v_and_b32_e32 v216, 63, v196
	v_xor_b32_e32 v216, 32, v216
	v_lshlrev_b32_e32 v208, 2, v216
	v_bfe_u32 v210, v196, 4, 2
	v_and_b32_e32 v211, 15, v196
	v_mul_u32_u24_e32 v216, 272, v210
	v_lshl_add_u32 v216, v211, 4, v216
	v_add_u32_e32 v200, s76, v216
	v_add_u32_e32 v216, s74, v210
	v_lshlrev_b32_e32 v216, 10, v216
	v_lshl_add_u32 v216, v211, 2, v216
	v_add_lshl_u32 v202, v216, s75, 2
	s_mov_b32 s79, s74
	s_mov_b32 s72, s75
	s_waitcnt lgkmcnt(0)
	s_add_u32 s74, s64, 0x0
	s_addc_u32 s75, s65, 0
	global_load_dwordx4 v[128:131], v202, s[74:75]
	s_add_u32 s74, s64, 0x4000
	s_addc_u32 s75, s65, 0
	global_load_dwordx4 v[132:135], v202, s[74:75]
	s_add_u32 s74, s64, 0x8000
	s_addc_u32 s75, s65, 0
	global_load_dwordx4 v[136:139], v202, s[74:75]
	s_add_u32 s74, s64, 0xc000
	s_addc_u32 s75, s65, 0
	global_load_dwordx4 v[140:143], v202, s[74:75]
	s_add_u32 s74, s64, 0x10000
	s_addc_u32 s75, s65, 0
	global_load_dwordx4 v[144:147], v202, s[74:75]
	s_add_u32 s74, s64, 0x14000
	s_addc_u32 s75, s65, 0
	global_load_dwordx4 v[148:151], v202, s[74:75]
	s_add_u32 s74, s64, 0x18000
	s_addc_u32 s75, s65, 0
	global_load_dwordx4 v[152:155], v202, s[74:75]
	s_add_u32 s74, s64, 0x1c000
	s_addc_u32 s75, s65, 0
	global_load_dwordx4 v[156:159], v202, s[74:75]
	s_mov_b32 s74, s79
	s_mov_b32 s75, s72
	v_bfe_u32 v210, v196, 3, 3
	v_and_b32_e32 v211, 7, v196
	v_mul_u32_u24_e32 v216, 272, v210
	v_lshl_add_u32 v216, v211, 4, v216
	v_add_u32_e32 v201, s76, v216
	v_add_u32_e32 v216, s74, v210
	v_lshlrev_b32_e32 v216, 10, v216
	v_lshl_add_u32 v216, v211, 3, v216
	v_add_lshl_u32 v203, v216, s75, 1
	v_mov_b32_e32 v205, 0
	v_mov_b32_e32 v206, 0
	s_waitcnt lgkmcnt(0)
	s_barrier
; DI bfr f2bf(float a) { return (bfr)(pack2(a, 0.f) & 0xffffu); }
; DI int crow(int reg, int h) { return (reg & 3) + 8 * (reg >> 2) + 4 * h; }
; template <bool FIRST, bool HAS_H>
; DI void phase_gemm_resid(const Params& p, const bfr* A, const bfr* Wt, const float* gnext, float* ss, char* smem) {
;     ...
; #pragma unroll
;     for (int i = 0; i < 2; ++i) {
; #pragma unroll
;       for (int qh = 0; qh < 2; ++qh) {
;         float rs[8];
; #pragma unroll
;         for (int q = 0; q < 8; ++q) rs[q] = 0.f;
; #pragma unroll
;         for (int jh = 0; jh < 2; ++jh) {
;           float xo[2][8];
; #pragma unroll
;           for (int jj = 0; jj < 2; ++jj)
; #pragma unroll
;             for (int q = 0; q < 8; ++q)
;               xo[jj][q] = xsrc[(rbase + i * 32 + crow(qh * 8 + q, 0)) * 1024 + cbase + (jh * 2 + jj) * 32];
; #pragma unroll
;           for (int q = 0; q < 8; ++q) {
;             const int o = (rbase + i * 32 + crow(qh * 8 + q, 0)) * 1024 + cbase;
; #pragma unroll
;             for (int jj = 0; jj < 2; ++jj) {
;               const int j = jh * 2 + jj;
;               const float xn = xo[jj][q] + acc[i][j][qh * 8 + q];
;               X[o + j * 32] = xn;
;               if (HAS_H) Hn[o + j * 32] = f2bf(xn * gnext[cbase + j * 32]);
;               rs[q] += xn * xn;
;             }
;           }
;         }
	s_add_u32 s70, s70, 0x1000
	s_addc_u32 s71, s71, 0
	s_waitcnt vmcnt(7)
	ds_write_b128 v200, v[128:131]
	s_waitcnt vmcnt(6)
	ds_write_b128 v200, v[132:135] offset:1088
	s_waitcnt vmcnt(5)
	ds_write_b128 v200, v[136:139] offset:2176
	s_waitcnt vmcnt(4)
	ds_write_b128 v200, v[140:143] offset:3264
	s_waitcnt vmcnt(3)
	ds_write_b128 v200, v[144:147] offset:4352
	s_waitcnt vmcnt(2)
	ds_write_b128 v200, v[148:151] offset:5440
	s_waitcnt vmcnt(1)
	ds_write_b128 v200, v[152:155] offset:6528
	s_waitcnt vmcnt(0)
	ds_write_b128 v200, v[156:159] offset:7616
	s_add_u32 s74, s64, 0x100
	s_addc_u32 s75, s65, 0
	global_load_dwordx4 v[128:131], v202, s[74:75]
	s_add_u32 s74, s64, 0x4100
	s_addc_u32 s75, s65, 0
	global_load_dwordx4 v[132:135], v202, s[74:75]
	s_add_u32 s74, s64, 0x8100
	s_addc_u32 s75, s65, 0
	global_load_dwordx4 v[136:139], v202, s[74:75]
	s_add_u32 s74, s64, 0xc100
	s_addc_u32 s75, s65, 0
	global_load_dwordx4 v[140:143], v202, s[74:75]
	s_add_u32 s74, s64, 0x10100
	s_addc_u32 s75, s65, 0
	global_load_dwordx4 v[144:147], v202, s[74:75]
	s_add_u32 s74, s64, 0x14100
	s_addc_u32 s75, s65, 0
	global_load_dwordx4 v[148:151], v202, s[74:75]
	s_add_u32 s74, s64, 0x18100
	s_addc_u32 s75, s65, 0
	global_load_dwordx4 v[152:155], v202, s[74:75]
	s_add_u32 s74, s64, 0x1c100
	s_addc_u32 s75, s65, 0
	global_load_dwordx4 v[156:159], v202, s[74:75]
	ds_read_b128 v[160:163], v192
	ds_read_b128 v[164:167], v192 offset:32
	ds_read_b128 v[168:171], v192 offset:64
	ds_read_b128 v[172:175], v192 offset:96
	ds_read_b128 v[176:179], v192 offset:128
	ds_read_b128 v[180:183], v192 offset:160
	ds_read_b128 v[184:187], v192 offset:192
	ds_read_b128 v[188:191], v192 offset:224
	s_waitcnt lgkmcnt(7)
	v_add_f32_e32 v112, v160, v112
	v_add_f32_e32 v113, v161, v113
	v_add_f32_e32 v114, v162, v114
	v_add_f32_e32 v115, v163, v115
	v_fmac_f32_e32 v205, v112, v112
	v_fmac_f32_e32 v205, v113, v113
	v_fmac_f32_e32 v205, v114, v114
	v_fmac_f32_e32 v205, v115, v115
	ds_write_b128 v192, v[112:115]
	s_waitcnt lgkmcnt(7)
	v_add_f32_e32 v116, v164, v116
	v_add_f32_e32 v117, v165, v117
	v_add_f32_e32 v118, v166, v118
	v_add_f32_e32 v119, v167, v119
	v_fmac_f32_e32 v205, v116, v116
	v_fmac_f32_e32 v205, v117, v117
	v_fmac_f32_e32 v205, v118, v118
	v_fmac_f32_e32 v205, v119, v119
	ds_write_b128 v192, v[116:119] offset:32
	s_waitcnt lgkmcnt(7)
	v_add_f32_e32 v120, v168, v120
	v_add_f32_e32 v121, v169, v121
	v_add_f32_e32 v122, v170, v122
	v_add_f32_e32 v123, v171, v123
	v_fmac_f32_e32 v205, v120, v120
	v_fmac_f32_e32 v205, v121, v121
	v_fmac_f32_e32 v205, v122, v122
	v_fmac_f32_e32 v205, v123, v123
	ds_write_b128 v192, v[120:123] offset:64
	s_waitcnt lgkmcnt(7)
	v_add_f32_e32 v124, v172, v124
	v_add_f32_e32 v125, v173, v125
	v_add_f32_e32 v126, v174, v126
	v_add_f32_e32 v127, v175, v127
	v_fmac_f32_e32 v205, v124, v124
	v_fmac_f32_e32 v205, v125, v125
	v_fmac_f32_e32 v205, v126, v126
	v_fmac_f32_e32 v205, v127, v127
	ds_write_b128 v192, v[124:127] offset:96
	s_waitcnt lgkmcnt(7)
	v_add_f32_e32 v96, v176, v96
	v_add_f32_e32 v97, v177, v97
	v_add_f32_e32 v98, v178, v98
	v_add_f32_e32 v99, v179, v99
	v_fmac_f32_e32 v205, v96, v96
	v_fmac_f32_e32 v205, v97, v97
	v_fmac_f32_e32 v205, v98, v98
	v_fmac_f32_e32 v205, v99, v99
	ds_write_b128 v192, v[96:99] offset:128
	s_waitcnt lgkmcnt(7)
	v_add_f32_e32 v100, v180, v100
	v_add_f32_e32 v101, v181, v101
	v_add_f32_e32 v102, v182, v102
	v_add_f32_e32 v103, v183, v103
	v_fmac_f32_e32 v205, v100, v100
	v_fmac_f32_e32 v205, v101, v101
	v_fmac_f32_e32 v205, v102, v102
	v_fmac_f32_e32 v205, v103, v103
	ds_write_b128 v192, v[100:103] offset:160
	s_waitcnt lgkmcnt(7)
	v_add_f32_e32 v104, v184, v104
	v_add_f32_e32 v105, v185, v105
	v_add_f32_e32 v106, v186, v106
	v_add_f32_e32 v107, v187, v107
	v_fmac_f32_e32 v205, v104, v104
	v_fmac_f32_e32 v205, v105, v105
	v_fmac_f32_e32 v205, v106, v106
	v_fmac_f32_e32 v205, v107, v107
	ds_write_b128 v192, v[104:107] offset:192
	s_waitcnt lgkmcnt(7)
	v_add_f32_e32 v108, v188, v108
	v_add_f32_e32 v109, v189, v109
	v_add_f32_e32 v110, v190, v110
	v_add_f32_e32 v111, v191, v111
	v_fmac_f32_e32 v205, v108, v108
	v_fmac_f32_e32 v205, v109, v109
	v_fmac_f32_e32 v205, v110, v110
	v_fmac_f32_e32 v205, v111, v111
	ds_write_b128 v192, v[108:111] offset:224
	ds_read_b128 v[160:163], v200
	ds_read_b128 v[164:167], v200 offset:1088
	ds_read_b128 v[168:171], v200 offset:2176
	ds_read_b128 v[172:175], v200 offset:3264
	ds_read_b128 v[176:179], v200 offset:4352
	ds_read_b128 v[180:183], v200 offset:5440
	ds_read_b128 v[184:187], v200 offset:6528
	ds_read_b128 v[188:191], v200 offset:7616
	s_add_u32 s74, s66, 0x0
	s_addc_u32 s75, s67, 0
	s_waitcnt lgkmcnt(7)
	global_store_dwordx4 v202, v[160:163], s[74:75]
	s_add_u32 s74, s66, 0x4000
	s_addc_u32 s75, s67, 0
	s_waitcnt lgkmcnt(6)
	global_store_dwordx4 v202, v[164:167], s[74:75]
	s_add_u32 s74, s66, 0x8000
	s_addc_u32 s75, s67, 0
	s_waitcnt lgkmcnt(5)
	global_store_dwordx4 v202, v[168:171], s[74:75]
	s_add_u32 s74, s66, 0xc000
	s_addc_u32 s75, s67, 0
	s_waitcnt lgkmcnt(4)
	global_store_dwordx4 v202, v[172:175], s[74:75]
	s_add_u32 s74, s66, 0x10000
	s_addc_u32 s75, s67, 0
	s_waitcnt lgkmcnt(3)
	global_store_dwordx4 v202, v[176:179], s[74:75]
	s_add_u32 s74, s66, 0x14000
	s_addc_u32 s75, s67, 0
	s_waitcnt lgkmcnt(2)
	global_store_dwordx4 v202, v[180:183], s[74:75]
	s_add_u32 s74, s66, 0x18000
	s_addc_u32 s75, s67, 0
	s_waitcnt lgkmcnt(1)
	global_store_dwordx4 v202, v[184:187], s[74:75]
	s_add_u32 s74, s66, 0x1c000
	s_addc_u32 s75, s67, 0
	s_waitcnt lgkmcnt(0)
; DI bfr f2bf(float a) { return (bfr)(pack2(a, 0.f) & 0xffffu); }
; DI int crow(int reg, int h) { return (reg & 3) + 8 * (reg >> 2) + 4 * h; }
; template <bool FIRST, bool HAS_H>
; DI void phase_gemm_resid(const Params& p, const bfr* A, const bfr* Wt, const float* gnext, float* ss, char* smem) {
;     ...
; #pragma unroll
;     for (int i = 0; i < 2; ++i) {
; #pragma unroll
;       for (int qh = 0; qh < 2; ++qh) {
;         float rs[8];
; #pragma unroll
;         for (int q = 0; q < 8; ++q) rs[q] = 0.f;
; #pragma unroll
;         for (int jh = 0; jh < 2; ++jh) {
;           float xo[2][8];
; #pragma unroll
;           for (int jj = 0; jj < 2; ++jj)
; #pragma unroll
;             for (int q = 0; q < 8; ++q)
;               xo[jj][q] = xsrc[(rbase + i * 32 + crow(qh * 8 + q, 0)) * 1024 + cbase + (jh * 2 + jj) * 32];
; #pragma unroll
;           for (int q = 0; q < 8; ++q) {
;             const int o = (rbase + i * 32 + crow(qh * 8 + q, 0)) * 1024 + cbase;
; #pragma unroll
;             for (int jj = 0; jj < 2; ++jj) {
;               const int j = jh * 2 + jj;
;               const float xn = xo[jj][q] + acc[i][j][qh * 8 + q];
;               X[o + j * 32] = xn;
;               if (HAS_H) Hn[o + j * 32] = f2bf(xn * gnext[cbase + j * 32]);
;               rs[q] += xn * xn;
;             }
;           }
;         }
	global_store_dwordx4 v202, v[188:191], s[74:75]
	global_load_dwordx4 v[160:163], v204, s[70:71]
	global_load_dwordx4 v[164:167], v204, s[70:71] offset:32
	global_load_dwordx4 v[168:171], v204, s[70:71] offset:64
	global_load_dwordx4 v[172:175], v204, s[70:71] offset:96
	global_load_dwordx4 v[176:179], v204, s[70:71] offset:128
	global_load_dwordx4 v[180:183], v204, s[70:71] offset:160
	global_load_dwordx4 v[184:187], v204, s[70:71] offset:192
	global_load_dwordx4 v[188:191], v204, s[70:71] offset:224
	s_waitcnt vmcnt(7)
	v_mul_f32_e32 v112, v160, v112
	v_mul_f32_e32 v113, v161, v113
	v_mul_f32_e32 v114, v162, v114
	v_mul_f32_e32 v115, v163, v115
	v_cvt_pk_bf16_f32 v112, v112, v113
	v_cvt_pk_bf16_f32 v113, v114, v115
	ds_write_b64 v194, v[112:113]
	s_waitcnt vmcnt(6)
	v_mul_f32_e32 v116, v164, v116
	v_mul_f32_e32 v117, v165, v117
	v_mul_f32_e32 v118, v166, v118
	v_mul_f32_e32 v119, v167, v119
	v_cvt_pk_bf16_f32 v116, v116, v117
	v_cvt_pk_bf16_f32 v117, v118, v119
	ds_write_b64 v194, v[116:117] offset:16
	s_waitcnt vmcnt(5)
	v_mul_f32_e32 v120, v168, v120
	v_mul_f32_e32 v121, v169, v121
	v_mul_f32_e32 v122, v170, v122
	v_mul_f32_e32 v123, v171, v123
	v_cvt_pk_bf16_f32 v120, v120, v121
	v_cvt_pk_bf16_f32 v121, v122, v123
	ds_write_b64 v194, v[120:121] offset:32
	s_waitcnt vmcnt(4)
	v_mul_f32_e32 v124, v172, v124
	v_mul_f32_e32 v125, v173, v125
	v_mul_f32_e32 v126, v174, v126
	v_mul_f32_e32 v127, v175, v127
	v_cvt_pk_bf16_f32 v124, v124, v125
	v_cvt_pk_bf16_f32 v125, v126, v127
	ds_write_b64 v194, v[124:125] offset:48
	s_waitcnt vmcnt(3)
	v_mul_f32_e32 v96, v176, v96
	v_mul_f32_e32 v97, v177, v97
	v_mul_f32_e32 v98, v178, v98
	v_mul_f32_e32 v99, v179, v99
	v_cvt_pk_bf16_f32 v96, v96, v97
	v_cvt_pk_bf16_f32 v97, v98, v99
	ds_write_b64 v194, v[96:97] offset:64
	s_waitcnt vmcnt(2)
	v_mul_f32_e32 v100, v180, v100
	v_mul_f32_e32 v101, v181, v101
	v_mul_f32_e32 v102, v182, v102
	v_mul_f32_e32 v103, v183, v103
	v_cvt_pk_bf16_f32 v100, v100, v101
	v_cvt_pk_bf16_f32 v101, v102, v103
	ds_write_b64 v194, v[100:101] offset:80
	s_waitcnt vmcnt(1)
	v_mul_f32_e32 v104, v184, v104
	v_mul_f32_e32 v105, v185, v105
	v_mul_f32_e32 v106, v186, v106
	v_mul_f32_e32 v107, v187, v107
	v_cvt_pk_bf16_f32 v104, v104, v105
	v_cvt_pk_bf16_f32 v105, v106, v107
	ds_write_b64 v194, v[104:105] offset:96
	s_waitcnt vmcnt(0)
	v_mul_f32_e32 v108, v188, v108
	v_mul_f32_e32 v109, v189, v109
	v_mul_f32_e32 v110, v190, v110
	v_mul_f32_e32 v111, v191, v111
	v_cvt_pk_bf16_f32 v108, v108, v109
	v_cvt_pk_bf16_f32 v109, v110, v111
	ds_write_b64 v194, v[108:109] offset:112
	ds_read_b128 v[160:163], v201
	ds_read_b128 v[164:167], v201 offset:2176
	ds_read_b128 v[168:171], v201 offset:4352
	ds_read_b128 v[172:175], v201 offset:6528
	s_add_u32 s74, s68, 0x0
	s_addc_u32 s75, s69, 0
	s_waitcnt lgkmcnt(3)
	global_store_dwordx4 v203, v[160:163], s[74:75]
	s_add_u32 s74, s68, 0x4000
	s_addc_u32 s75, s69, 0
	s_waitcnt lgkmcnt(2)
	global_store_dwordx4 v203, v[164:167], s[74:75]
	s_add_u32 s74, s68, 0x8000
	s_addc_u32 s75, s69, 0
	s_waitcnt lgkmcnt(1)
	global_store_dwordx4 v203, v[168:171], s[74:75]
	s_add_u32 s74, s68, 0xc000
	s_addc_u32 s75, s69, 0
	s_waitcnt lgkmcnt(0)
	global_store_dwordx4 v203, v[172:175], s[74:75]
	s_waitcnt vmcnt(4)
	ds_write_b128 v200, v[128:131]
	s_waitcnt vmcnt(4)
	ds_write_b128 v200, v[132:135] offset:1088
	s_waitcnt vmcnt(4)
	ds_write_b128 v200, v[136:139] offset:2176
	s_waitcnt vmcnt(4)
	ds_write_b128 v200, v[140:143] offset:3264
	s_waitcnt vmcnt(4)
	ds_write_b128 v200, v[144:147] offset:4352
	s_waitcnt vmcnt(4)
	ds_write_b128 v200, v[148:151] offset:5440
	s_waitcnt vmcnt(4)
	ds_write_b128 v200, v[152:155] offset:6528
	s_waitcnt vmcnt(4)
	ds_write_b128 v200, v[156:159] offset:7616
	s_add_u32 s74, s64, 0x20000
	s_addc_u32 s75, s65, 0
	global_load_dwordx4 v[128:131], v202, s[74:75]
	s_add_u32 s74, s64, 0x24000
	s_addc_u32 s75, s65, 0
	global_load_dwordx4 v[132:135], v202, s[74:75]
	s_add_u32 s74, s64, 0x28000
	s_addc_u32 s75, s65, 0
	global_load_dwordx4 v[136:139], v202, s[74:75]
	s_add_u32 s74, s64, 0x2c000
	s_addc_u32 s75, s65, 0
	global_load_dwordx4 v[140:143], v202, s[74:75]
	s_add_u32 s74, s64, 0x30000
	s_addc_u32 s75, s65, 0
	global_load_dwordx4 v[144:147], v202, s[74:75]
	s_add_u32 s74, s64, 0x34000
	s_addc_u32 s75, s65, 0
	global_load_dwordx4 v[148:151], v202, s[74:75]
	s_add_u32 s74, s64, 0x38000
	s_addc_u32 s75, s65, 0
	global_load_dwordx4 v[152:155], v202, s[74:75]
	s_add_u32 s74, s64, 0x3c000
	s_addc_u32 s75, s65, 0
	global_load_dwordx4 v[156:159], v202, s[74:75]
	ds_read_b128 v[160:163], v192
	ds_read_b128 v[164:167], v192 offset:32
	ds_read_b128 v[168:171], v192 offset:64
	ds_read_b128 v[172:175], v192 offset:96
	ds_read_b128 v[176:179], v192 offset:128
	ds_read_b128 v[180:183], v192 offset:160
	ds_read_b128 v[184:187], v192 offset:192
	ds_read_b128 v[188:191], v192 offset:224
	s_waitcnt lgkmcnt(7)
	v_add_f32_e32 v80, v160, v80
	v_add_f32_e32 v81, v161, v81
	v_add_f32_e32 v82, v162, v82
	v_add_f32_e32 v83, v163, v83
	v_fmac_f32_e32 v205, v80, v80
	v_fmac_f32_e32 v205, v81, v81
	v_fmac_f32_e32 v205, v82, v82
	v_fmac_f32_e32 v205, v83, v83
	ds_write_b128 v192, v[80:83]
	s_waitcnt lgkmcnt(7)
	v_add_f32_e32 v84, v164, v84
	v_add_f32_e32 v85, v165, v85
	v_add_f32_e32 v86, v166, v86
	v_add_f32_e32 v87, v167, v87
	v_fmac_f32_e32 v205, v84, v84
	v_fmac_f32_e32 v205, v85, v85
	v_fmac_f32_e32 v205, v86, v86
	v_fmac_f32_e32 v205, v87, v87
	ds_write_b128 v192, v[84:87] offset:32
	s_waitcnt lgkmcnt(7)
	v_add_f32_e32 v88, v168, v88
	v_add_f32_e32 v89, v169, v89
	v_add_f32_e32 v90, v170, v90
	v_add_f32_e32 v91, v171, v91
	v_fmac_f32_e32 v205, v88, v88
	v_fmac_f32_e32 v205, v89, v89
	v_fmac_f32_e32 v205, v90, v90
	v_fmac_f32_e32 v205, v91, v91
	ds_write_b128 v192, v[88:91] offset:64
	s_waitcnt lgkmcnt(7)
; DI bfr f2bf(float a) { return (bfr)(pack2(a, 0.f) & 0xffffu); }
; DI int crow(int reg, int h) { return (reg & 3) + 8 * (reg >> 2) + 4 * h; }
; template <bool FIRST, bool HAS_H>
; DI void phase_gemm_resid(const Params& p, const bfr* A, const bfr* Wt, const float* gnext, float* ss, char* smem) {
;     ...
; #pragma unroll
;     for (int i = 0; i < 2; ++i) {
; #pragma unroll
;       for (int qh = 0; qh < 2; ++qh) {
;         float rs[8];
; #pragma unroll
;         for (int q = 0; q < 8; ++q) rs[q] = 0.f;
; #pragma unroll
;         for (int jh = 0; jh < 2; ++jh) {
;           float xo[2][8];
; #pragma unroll
;           for (int jj = 0; jj < 2; ++jj)
; #pragma unroll
;             for (int q = 0; q < 8; ++q)
;               xo[jj][q] = xsrc[(rbase + i * 32 + crow(qh * 8 + q, 0)) * 1024 + cbase + (jh * 2 + jj) * 32];
; #pragma unroll
;           for (int q = 0; q < 8; ++q) {
;             const int o = (rbase + i * 32 + crow(qh * 8 + q, 0)) * 1024 + cbase;
; #pragma unroll
;             for (int jj = 0; jj < 2; ++jj) {
;               const int j = jh * 2 + jj;
;               const float xn = xo[jj][q] + acc[i][j][qh * 8 + q];
;               X[o + j * 32] = xn;
;               if (HAS_H) Hn[o + j * 32] = f2bf(xn * gnext[cbase + j * 32]);
;               rs[q] += xn * xn;
;             }
;           }
;         }
	v_add_f32_e32 v92, v172, v92
	v_add_f32_e32 v93, v173, v93
	v_add_f32_e32 v94, v174, v94
	v_add_f32_e32 v95, v175, v95
	v_fmac_f32_e32 v205, v92, v92
	v_fmac_f32_e32 v205, v93, v93
	v_fmac_f32_e32 v205, v94, v94
	v_fmac_f32_e32 v205, v95, v95
	ds_write_b128 v192, v[92:95] offset:96
	s_waitcnt lgkmcnt(7)
	v_add_f32_e32 v64, v176, v64
	v_add_f32_e32 v65, v177, v65
	v_add_f32_e32 v66, v178, v66
	v_add_f32_e32 v67, v179, v67
	v_fmac_f32_e32 v205, v64, v64
	v_fmac_f32_e32 v205, v65, v65
	v_fmac_f32_e32 v205, v66, v66
	v_fmac_f32_e32 v205, v67, v67
	ds_write_b128 v192, v[64:67] offset:128
	s_waitcnt lgkmcnt(7)
	v_add_f32_e32 v68, v180, v68
	v_add_f32_e32 v69, v181, v69
	v_add_f32_e32 v70, v182, v70
	v_add_f32_e32 v71, v183, v71
	v_fmac_f32_e32 v205, v68, v68
	v_fmac_f32_e32 v205, v69, v69
	v_fmac_f32_e32 v205, v70, v70
	v_fmac_f32_e32 v205, v71, v71
	ds_write_b128 v192, v[68:71] offset:160
	s_waitcnt lgkmcnt(7)
	v_add_f32_e32 v72, v184, v72
	v_add_f32_e32 v73, v185, v73
	v_add_f32_e32 v74, v186, v74
	v_add_f32_e32 v75, v187, v75
	v_fmac_f32_e32 v205, v72, v72
	v_fmac_f32_e32 v205, v73, v73
	v_fmac_f32_e32 v205, v74, v74
	v_fmac_f32_e32 v205, v75, v75
	ds_write_b128 v192, v[72:75] offset:192
	s_waitcnt lgkmcnt(7)
	v_add_f32_e32 v76, v188, v76
	v_add_f32_e32 v77, v189, v77
	v_add_f32_e32 v78, v190, v78
	v_add_f32_e32 v79, v191, v79
	v_fmac_f32_e32 v205, v76, v76
	v_fmac_f32_e32 v205, v77, v77
	v_fmac_f32_e32 v205, v78, v78
	v_fmac_f32_e32 v205, v79, v79
	ds_write_b128 v192, v[76:79] offset:224
	ds_read_b128 v[160:163], v200
	ds_read_b128 v[164:167], v200 offset:1088
	ds_read_b128 v[168:171], v200 offset:2176
	ds_read_b128 v[172:175], v200 offset:3264
	ds_read_b128 v[176:179], v200 offset:4352
	ds_read_b128 v[180:183], v200 offset:5440
	ds_read_b128 v[184:187], v200 offset:6528
	ds_read_b128 v[188:191], v200 offset:7616
	s_add_u32 s74, s66, 0x100
	s_addc_u32 s75, s67, 0
	s_waitcnt lgkmcnt(7)
	global_store_dwordx4 v202, v[160:163], s[74:75]
	s_add_u32 s74, s66, 0x4100
	s_addc_u32 s75, s67, 0
	s_waitcnt lgkmcnt(6)
	global_store_dwordx4 v202, v[164:167], s[74:75]
	s_add_u32 s74, s66, 0x8100
	s_addc_u32 s75, s67, 0
	s_waitcnt lgkmcnt(5)
	global_store_dwordx4 v202, v[168:171], s[74:75]
	s_add_u32 s74, s66, 0xc100
	s_addc_u32 s75, s67, 0
	s_waitcnt lgkmcnt(4)
	global_store_dwordx4 v202, v[172:175], s[74:75]
	s_add_u32 s74, s66, 0x10100
	s_addc_u32 s75, s67, 0
	s_waitcnt lgkmcnt(3)
	global_store_dwordx4 v202, v[176:179], s[74:75]
	s_add_u32 s74, s66, 0x14100
	s_addc_u32 s75, s67, 0
	s_waitcnt lgkmcnt(2)
	global_store_dwordx4 v202, v[180:183], s[74:75]
	s_add_u32 s74, s66, 0x18100
	s_addc_u32 s75, s67, 0
	s_waitcnt lgkmcnt(1)
	global_store_dwordx4 v202, v[184:187], s[74:75]
	s_add_u32 s74, s66, 0x1c100
	s_addc_u32 s75, s67, 0
	s_waitcnt lgkmcnt(0)
	global_store_dwordx4 v202, v[188:191], s[74:75]
	global_load_dwordx4 v[160:163], v204, s[70:71] offset:256
	global_load_dwordx4 v[164:167], v204, s[70:71] offset:288
	global_load_dwordx4 v[168:171], v204, s[70:71] offset:320
	global_load_dwordx4 v[172:175], v204, s[70:71] offset:352
	global_load_dwordx4 v[176:179], v204, s[70:71] offset:384
	global_load_dwordx4 v[180:183], v204, s[70:71] offset:416
	global_load_dwordx4 v[184:187], v204, s[70:71] offset:448
	global_load_dwordx4 v[188:191], v204, s[70:71] offset:480
	s_waitcnt vmcnt(7)
	v_mul_f32_e32 v80, v160, v80
	v_mul_f32_e32 v81, v161, v81
	v_mul_f32_e32 v82, v162, v82
	v_mul_f32_e32 v83, v163, v83
	v_cvt_pk_bf16_f32 v80, v80, v81
	v_cvt_pk_bf16_f32 v81, v82, v83
	ds_write_b64 v194, v[80:81]
	s_waitcnt vmcnt(6)
	v_mul_f32_e32 v84, v164, v84
	v_mul_f32_e32 v85, v165, v85
	v_mul_f32_e32 v86, v166, v86
	v_mul_f32_e32 v87, v167, v87
	v_cvt_pk_bf16_f32 v84, v84, v85
	v_cvt_pk_bf16_f32 v85, v86, v87
	ds_write_b64 v194, v[84:85] offset:16
	s_waitcnt vmcnt(5)
	v_mul_f32_e32 v88, v168, v88
	v_mul_f32_e32 v89, v169, v89
	v_mul_f32_e32 v90, v170, v90
	v_mul_f32_e32 v91, v171, v91
	v_cvt_pk_bf16_f32 v88, v88, v89
	v_cvt_pk_bf16_f32 v89, v90, v91
	ds_write_b64 v194, v[88:89] offset:32
	s_waitcnt vmcnt(4)
	v_mul_f32_e32 v92, v172, v92
	v_mul_f32_e32 v93, v173, v93
	v_mul_f32_e32 v94, v174, v94
	v_mul_f32_e32 v95, v175, v95
	v_cvt_pk_bf16_f32 v92, v92, v93
	v_cvt_pk_bf16_f32 v93, v94, v95
	ds_write_b64 v194, v[92:93] offset:48
	s_waitcnt vmcnt(3)
	v_mul_f32_e32 v64, v176, v64
	v_mul_f32_e32 v65, v177, v65
	v_mul_f32_e32 v66, v178, v66
	v_mul_f32_e32 v67, v179, v67
	v_cvt_pk_bf16_f32 v64, v64, v65
	v_cvt_pk_bf16_f32 v65, v66, v67
	ds_write_b64 v194, v[64:65] offset:64
	s_waitcnt vmcnt(2)
	v_mul_f32_e32 v68, v180, v68
	v_mul_f32_e32 v69, v181, v69
	v_mul_f32_e32 v70, v182, v70
	v_mul_f32_e32 v71, v183, v71
	v_cvt_pk_bf16_f32 v68, v68, v69
	v_cvt_pk_bf16_f32 v69, v70, v71
	ds_write_b64 v194, v[68:69] offset:80
	s_waitcnt vmcnt(1)
	v_mul_f32_e32 v72, v184, v72
	v_mul_f32_e32 v73, v185, v73
	v_mul_f32_e32 v74, v186, v74
	v_mul_f32_e32 v75, v187, v75
	v_cvt_pk_bf16_f32 v72, v72, v73
	v_cvt_pk_bf16_f32 v73, v74, v75
	ds_write_b64 v194, v[72:73] offset:96
	s_waitcnt vmcnt(0)
	v_mul_f32_e32 v76, v188, v76
	v_mul_f32_e32 v77, v189, v77
	v_mul_f32_e32 v78, v190, v78
	v_mul_f32_e32 v79, v191, v79
	v_cvt_pk_bf16_f32 v76, v76, v77
	v_cvt_pk_bf16_f32 v77, v78, v79
	ds_write_b64 v194, v[76:77] offset:112
	ds_read_b128 v[160:163], v201
	ds_read_b128 v[164:167], v201 offset:2176
	ds_read_b128 v[168:171], v201 offset:4352
	ds_read_b128 v[172:175], v201 offset:6528
	s_add_u32 s74, s68, 0x80
	s_addc_u32 s75, s69, 0
	s_waitcnt lgkmcnt(3)
	global_store_dwordx4 v203, v[160:163], s[74:75]
	s_add_u32 s74, s68, 0x4080
	s_addc_u32 s75, s69, 0
	s_waitcnt lgkmcnt(2)
; DI bfr f2bf(float a) { return (bfr)(pack2(a, 0.f) & 0xffffu); }
; DI int crow(int reg, int h) { return (reg & 3) + 8 * (reg >> 2) + 4 * h; }
; template <bool FIRST, bool HAS_H>
; DI void phase_gemm_resid(const Params& p, const bfr* A, const bfr* Wt, const float* gnext, float* ss, char* smem) {
;     ...
; #pragma unroll
;     for (int i = 0; i < 2; ++i) {
; #pragma unroll
;       for (int qh = 0; qh < 2; ++qh) {
;         float rs[8];
; #pragma unroll
;         for (int q = 0; q < 8; ++q) rs[q] = 0.f;
; #pragma unroll
;         for (int jh = 0; jh < 2; ++jh) {
;           float xo[2][8];
; #pragma unroll
;           for (int jj = 0; jj < 2; ++jj)
; #pragma unroll
;             for (int q = 0; q < 8; ++q)
;               xo[jj][q] = xsrc[(rbase + i * 32 + crow(qh * 8 + q, 0)) * 1024 + cbase + (jh * 2 + jj) * 32];
; #pragma unroll
;           for (int q = 0; q < 8; ++q) {
;             const int o = (rbase + i * 32 + crow(qh * 8 + q, 0)) * 1024 + cbase;
; #pragma unroll
;             for (int jj = 0; jj < 2; ++jj) {
;               const int j = jh * 2 + jj;
;               const float xn = xo[jj][q] + acc[i][j][qh * 8 + q];
;               X[o + j * 32] = xn;
;               if (HAS_H) Hn[o + j * 32] = f2bf(xn * gnext[cbase + j * 32]);
;               rs[q] += xn * xn;
;             }
;           }
;         }
	global_store_dwordx4 v203, v[164:167], s[74:75]
	s_add_u32 s74, s68, 0x8080
	s_addc_u32 s75, s69, 0
	s_waitcnt lgkmcnt(1)
	global_store_dwordx4 v203, v[168:171], s[74:75]
	s_add_u32 s74, s68, 0xc080
	s_addc_u32 s75, s69, 0
	s_waitcnt lgkmcnt(0)
	global_store_dwordx4 v203, v[172:175], s[74:75]
	s_waitcnt vmcnt(4)
	ds_write_b128 v200, v[128:131]
	s_waitcnt vmcnt(4)
	ds_write_b128 v200, v[132:135] offset:1088
	s_waitcnt vmcnt(4)
	ds_write_b128 v200, v[136:139] offset:2176
	s_waitcnt vmcnt(4)
	ds_write_b128 v200, v[140:143] offset:3264
	s_waitcnt vmcnt(4)
	ds_write_b128 v200, v[144:147] offset:4352
	s_waitcnt vmcnt(4)
	ds_write_b128 v200, v[148:151] offset:5440
	s_waitcnt vmcnt(4)
	ds_write_b128 v200, v[152:155] offset:6528
	s_waitcnt vmcnt(4)
	ds_write_b128 v200, v[156:159] offset:7616
	s_add_u32 s74, s64, 0x20100
	s_addc_u32 s75, s65, 0
	global_load_dwordx4 v[128:131], v202, s[74:75]
	s_add_u32 s74, s64, 0x24100
	s_addc_u32 s75, s65, 0
	global_load_dwordx4 v[132:135], v202, s[74:75]
	s_add_u32 s74, s64, 0x28100
	s_addc_u32 s75, s65, 0
	global_load_dwordx4 v[136:139], v202, s[74:75]
	s_add_u32 s74, s64, 0x2c100
	s_addc_u32 s75, s65, 0
	global_load_dwordx4 v[140:143], v202, s[74:75]
	s_add_u32 s74, s64, 0x30100
	s_addc_u32 s75, s65, 0
	global_load_dwordx4 v[144:147], v202, s[74:75]
	s_add_u32 s74, s64, 0x34100
	s_addc_u32 s75, s65, 0
	global_load_dwordx4 v[148:151], v202, s[74:75]
	s_add_u32 s74, s64, 0x38100
	s_addc_u32 s75, s65, 0
	global_load_dwordx4 v[152:155], v202, s[74:75]
	s_add_u32 s74, s64, 0x3c100
	s_addc_u32 s75, s65, 0
	global_load_dwordx4 v[156:159], v202, s[74:75]
	ds_read_b128 v[160:163], v192
	ds_read_b128 v[164:167], v192 offset:32
	ds_read_b128 v[168:171], v192 offset:64
	ds_read_b128 v[172:175], v192 offset:96
	ds_read_b128 v[176:179], v192 offset:128
	ds_read_b128 v[180:183], v192 offset:160
	ds_read_b128 v[184:187], v192 offset:192
	ds_read_b128 v[188:191], v192 offset:224
	s_waitcnt lgkmcnt(7)
	v_add_f32_e32 v48, v160, v48
	v_add_f32_e32 v49, v161, v49
	v_add_f32_e32 v50, v162, v50
	v_add_f32_e32 v51, v163, v51
	v_fmac_f32_e32 v206, v48, v48
	v_fmac_f32_e32 v206, v49, v49
	v_fmac_f32_e32 v206, v50, v50
	v_fmac_f32_e32 v206, v51, v51
	ds_write_b128 v192, v[48:51]
	s_waitcnt lgkmcnt(7)
	v_add_f32_e32 v52, v164, v52
	v_add_f32_e32 v53, v165, v53
	v_add_f32_e32 v54, v166, v54
	v_add_f32_e32 v55, v167, v55
	v_fmac_f32_e32 v206, v52, v52
	v_fmac_f32_e32 v206, v53, v53
	v_fmac_f32_e32 v206, v54, v54
	v_fmac_f32_e32 v206, v55, v55
	ds_write_b128 v192, v[52:55] offset:32
	s_waitcnt lgkmcnt(7)
	v_add_f32_e32 v56, v168, v56
	v_add_f32_e32 v57, v169, v57
	v_add_f32_e32 v58, v170, v58
	v_add_f32_e32 v59, v171, v59
	v_fmac_f32_e32 v206, v56, v56
	v_fmac_f32_e32 v206, v57, v57
	v_fmac_f32_e32 v206, v58, v58
	v_fmac_f32_e32 v206, v59, v59
	ds_write_b128 v192, v[56:59] offset:64
	s_waitcnt lgkmcnt(7)
	v_add_f32_e32 v60, v172, v60
	v_add_f32_e32 v61, v173, v61
	v_add_f32_e32 v62, v174, v62
	v_add_f32_e32 v63, v175, v63
	v_fmac_f32_e32 v206, v60, v60
	v_fmac_f32_e32 v206, v61, v61
	v_fmac_f32_e32 v206, v62, v62
	v_fmac_f32_e32 v206, v63, v63
	ds_write_b128 v192, v[60:63] offset:96
	s_waitcnt lgkmcnt(7)
	v_add_f32_e32 v32, v176, v32
	v_add_f32_e32 v33, v177, v33
	v_add_f32_e32 v34, v178, v34
	v_add_f32_e32 v35, v179, v35
	v_fmac_f32_e32 v206, v32, v32
	v_fmac_f32_e32 v206, v33, v33
	v_fmac_f32_e32 v206, v34, v34
	v_fmac_f32_e32 v206, v35, v35
	ds_write_b128 v192, v[32:35] offset:128
	s_waitcnt lgkmcnt(7)
	v_add_f32_e32 v36, v180, v36
	v_add_f32_e32 v37, v181, v37
	v_add_f32_e32 v38, v182, v38
	v_add_f32_e32 v39, v183, v39
	v_fmac_f32_e32 v206, v36, v36
	v_fmac_f32_e32 v206, v37, v37
	v_fmac_f32_e32 v206, v38, v38
	v_fmac_f32_e32 v206, v39, v39
	ds_write_b128 v192, v[36:39] offset:160
	s_waitcnt lgkmcnt(7)
	v_add_f32_e32 v40, v184, v40
	v_add_f32_e32 v41, v185, v41
	v_add_f32_e32 v42, v186, v42
	v_add_f32_e32 v43, v187, v43
	v_fmac_f32_e32 v206, v40, v40
	v_fmac_f32_e32 v206, v41, v41
	v_fmac_f32_e32 v206, v42, v42
	v_fmac_f32_e32 v206, v43, v43
	ds_write_b128 v192, v[40:43] offset:192
	s_waitcnt lgkmcnt(7)
	v_add_f32_e32 v44, v188, v44
	v_add_f32_e32 v45, v189, v45
	v_add_f32_e32 v46, v190, v46
	v_add_f32_e32 v47, v191, v47
	v_fmac_f32_e32 v206, v44, v44
	v_fmac_f32_e32 v206, v45, v45
	v_fmac_f32_e32 v206, v46, v46
	v_fmac_f32_e32 v206, v47, v47
	ds_write_b128 v192, v[44:47] offset:224
	ds_read_b128 v[160:163], v200
	ds_read_b128 v[164:167], v200 offset:1088
	ds_read_b128 v[168:171], v200 offset:2176
	ds_read_b128 v[172:175], v200 offset:3264
	ds_read_b128 v[176:179], v200 offset:4352
	ds_read_b128 v[180:183], v200 offset:5440
	ds_read_b128 v[184:187], v200 offset:6528
	ds_read_b128 v[188:191], v200 offset:7616
	s_add_u32 s74, s66, 0x20000
	s_addc_u32 s75, s67, 0
	s_waitcnt lgkmcnt(7)
	global_store_dwordx4 v202, v[160:163], s[74:75]
	s_add_u32 s74, s66, 0x24000
	s_addc_u32 s75, s67, 0
	s_waitcnt lgkmcnt(6)
	global_store_dwordx4 v202, v[164:167], s[74:75]
	s_add_u32 s74, s66, 0x28000
	s_addc_u32 s75, s67, 0
	s_waitcnt lgkmcnt(5)
	global_store_dwordx4 v202, v[168:171], s[74:75]
	s_add_u32 s74, s66, 0x2c000
	s_addc_u32 s75, s67, 0
	s_waitcnt lgkmcnt(4)
	global_store_dwordx4 v202, v[172:175], s[74:75]
	s_add_u32 s74, s66, 0x30000
	s_addc_u32 s75, s67, 0
	s_waitcnt lgkmcnt(3)
	global_store_dwordx4 v202, v[176:179], s[74:75]
	s_add_u32 s74, s66, 0x34000
	s_addc_u32 s75, s67, 0
	s_waitcnt lgkmcnt(2)
	global_store_dwordx4 v202, v[180:183], s[74:75]
	s_add_u32 s74, s66, 0x38000
	s_addc_u32 s75, s67, 0
	s_waitcnt lgkmcnt(1)
	global_store_dwordx4 v202, v[184:187], s[74:75]
	s_add_u32 s74, s66, 0x3c000
	s_addc_u32 s75, s67, 0
	s_waitcnt lgkmcnt(0)
; DI bfr f2bf(float a) { return (bfr)(pack2(a, 0.f) & 0xffffu); }
; DI int crow(int reg, int h) { return (reg & 3) + 8 * (reg >> 2) + 4 * h; }
; template <bool FIRST, bool HAS_H>
; DI void phase_gemm_resid(const Params& p, const bfr* A, const bfr* Wt, const float* gnext, float* ss, char* smem) {
;     ...
; #pragma unroll
;     for (int i = 0; i < 2; ++i) {
; #pragma unroll
;       for (int qh = 0; qh < 2; ++qh) {
;         float rs[8];
; #pragma unroll
;         for (int q = 0; q < 8; ++q) rs[q] = 0.f;
; #pragma unroll
;         for (int jh = 0; jh < 2; ++jh) {
;           float xo[2][8];
; #pragma unroll
;           for (int jj = 0; jj < 2; ++jj)
; #pragma unroll
;             for (int q = 0; q < 8; ++q)
;               xo[jj][q] = xsrc[(rbase + i * 32 + crow(qh * 8 + q, 0)) * 1024 + cbase + (jh * 2 + jj) * 32];
; #pragma unroll
;           for (int q = 0; q < 8; ++q) {
;             const int o = (rbase + i * 32 + crow(qh * 8 + q, 0)) * 1024 + cbase;
; #pragma unroll
;             for (int jj = 0; jj < 2; ++jj) {
;               const int j = jh * 2 + jj;
;               const float xn = xo[jj][q] + acc[i][j][qh * 8 + q];
;               X[o + j * 32] = xn;
;               if (HAS_H) Hn[o + j * 32] = f2bf(xn * gnext[cbase + j * 32]);
;               rs[q] += xn * xn;
;             }
;           }
;         }
	global_store_dwordx4 v202, v[188:191], s[74:75]
	global_load_dwordx4 v[160:163], v204, s[70:71]
	global_load_dwordx4 v[164:167], v204, s[70:71] offset:32
	global_load_dwordx4 v[168:171], v204, s[70:71] offset:64
	global_load_dwordx4 v[172:175], v204, s[70:71] offset:96
	global_load_dwordx4 v[176:179], v204, s[70:71] offset:128
	global_load_dwordx4 v[180:183], v204, s[70:71] offset:160
	global_load_dwordx4 v[184:187], v204, s[70:71] offset:192
	global_load_dwordx4 v[188:191], v204, s[70:71] offset:224
	s_waitcnt vmcnt(7)
	v_mul_f32_e32 v48, v160, v48
	v_mul_f32_e32 v49, v161, v49
	v_mul_f32_e32 v50, v162, v50
	v_mul_f32_e32 v51, v163, v51
	v_cvt_pk_bf16_f32 v48, v48, v49
	v_cvt_pk_bf16_f32 v49, v50, v51
	ds_write_b64 v194, v[48:49]
	s_waitcnt vmcnt(6)
	v_mul_f32_e32 v52, v164, v52
	v_mul_f32_e32 v53, v165, v53
	v_mul_f32_e32 v54, v166, v54
	v_mul_f32_e32 v55, v167, v55
	v_cvt_pk_bf16_f32 v52, v52, v53
	v_cvt_pk_bf16_f32 v53, v54, v55
	ds_write_b64 v194, v[52:53] offset:16
	s_waitcnt vmcnt(5)
	v_mul_f32_e32 v56, v168, v56
	v_mul_f32_e32 v57, v169, v57
	v_mul_f32_e32 v58, v170, v58
	v_mul_f32_e32 v59, v171, v59
	v_cvt_pk_bf16_f32 v56, v56, v57
	v_cvt_pk_bf16_f32 v57, v58, v59
	ds_write_b64 v194, v[56:57] offset:32
	s_waitcnt vmcnt(4)
	v_mul_f32_e32 v60, v172, v60
	v_mul_f32_e32 v61, v173, v61
	v_mul_f32_e32 v62, v174, v62
	v_mul_f32_e32 v63, v175, v63
	v_cvt_pk_bf16_f32 v60, v60, v61
	v_cvt_pk_bf16_f32 v61, v62, v63
	ds_write_b64 v194, v[60:61] offset:48
	s_waitcnt vmcnt(3)
	v_mul_f32_e32 v32, v176, v32
	v_mul_f32_e32 v33, v177, v33
	v_mul_f32_e32 v34, v178, v34
	v_mul_f32_e32 v35, v179, v35
	v_cvt_pk_bf16_f32 v32, v32, v33
	v_cvt_pk_bf16_f32 v33, v34, v35
	ds_write_b64 v194, v[32:33] offset:64
	s_waitcnt vmcnt(2)
	v_mul_f32_e32 v36, v180, v36
	v_mul_f32_e32 v37, v181, v37
	v_mul_f32_e32 v38, v182, v38
	v_mul_f32_e32 v39, v183, v39
	v_cvt_pk_bf16_f32 v36, v36, v37
	v_cvt_pk_bf16_f32 v37, v38, v39
	ds_write_b64 v194, v[36:37] offset:80
	s_waitcnt vmcnt(1)
	v_mul_f32_e32 v40, v184, v40
	v_mul_f32_e32 v41, v185, v41
	v_mul_f32_e32 v42, v186, v42
	v_mul_f32_e32 v43, v187, v43
	v_cvt_pk_bf16_f32 v40, v40, v41
	v_cvt_pk_bf16_f32 v41, v42, v43
	ds_write_b64 v194, v[40:41] offset:96
	s_waitcnt vmcnt(0)
	v_mul_f32_e32 v44, v188, v44
	v_mul_f32_e32 v45, v189, v45
	v_mul_f32_e32 v46, v190, v46
	v_mul_f32_e32 v47, v191, v47
	v_cvt_pk_bf16_f32 v44, v44, v45
	v_cvt_pk_bf16_f32 v45, v46, v47
	ds_write_b64 v194, v[44:45] offset:112
	ds_read_b128 v[160:163], v201
	ds_read_b128 v[164:167], v201 offset:2176
	ds_read_b128 v[168:171], v201 offset:4352
	ds_read_b128 v[172:175], v201 offset:6528
	s_add_u32 s74, s68, 0x10000
	s_addc_u32 s75, s69, 0
	s_waitcnt lgkmcnt(3)
	global_store_dwordx4 v203, v[160:163], s[74:75]
	s_add_u32 s74, s68, 0x14000
	s_addc_u32 s75, s69, 0
	s_waitcnt lgkmcnt(2)
	global_store_dwordx4 v203, v[164:167], s[74:75]
	s_add_u32 s74, s68, 0x18000
	s_addc_u32 s75, s69, 0
	s_waitcnt lgkmcnt(1)
	global_store_dwordx4 v203, v[168:171], s[74:75]
	s_add_u32 s74, s68, 0x1c000
	s_addc_u32 s75, s69, 0
	s_waitcnt lgkmcnt(0)
	global_store_dwordx4 v203, v[172:175], s[74:75]
	s_waitcnt vmcnt(4)
	ds_write_b128 v200, v[128:131]
	s_waitcnt vmcnt(4)
	ds_write_b128 v200, v[132:135] offset:1088
	s_waitcnt vmcnt(4)
	ds_write_b128 v200, v[136:139] offset:2176
	s_waitcnt vmcnt(4)
	ds_write_b128 v200, v[140:143] offset:3264
	s_waitcnt vmcnt(4)
	ds_write_b128 v200, v[144:147] offset:4352
	s_waitcnt vmcnt(4)
	ds_write_b128 v200, v[148:151] offset:5440
	s_waitcnt vmcnt(4)
	ds_write_b128 v200, v[152:155] offset:6528
	s_waitcnt vmcnt(4)
	ds_write_b128 v200, v[156:159] offset:7616
	ds_read_b128 v[160:163], v192
	ds_read_b128 v[164:167], v192 offset:32
	ds_read_b128 v[168:171], v192 offset:64
	ds_read_b128 v[172:175], v192 offset:96
	ds_read_b128 v[176:179], v192 offset:128
	ds_read_b128 v[180:183], v192 offset:160
	ds_read_b128 v[184:187], v192 offset:192
	ds_read_b128 v[188:191], v192 offset:224
	s_waitcnt lgkmcnt(7)
	v_add_f32_e32 v16, v160, v16
	v_add_f32_e32 v17, v161, v17
	v_add_f32_e32 v18, v162, v18
	v_add_f32_e32 v19, v163, v19
	v_fmac_f32_e32 v206, v16, v16
	v_fmac_f32_e32 v206, v17, v17
	v_fmac_f32_e32 v206, v18, v18
	v_fmac_f32_e32 v206, v19, v19
	ds_write_b128 v192, v[16:19]
	s_waitcnt lgkmcnt(7)
	v_add_f32_e32 v20, v164, v20
	v_add_f32_e32 v21, v165, v21
	v_add_f32_e32 v22, v166, v22
	v_add_f32_e32 v23, v167, v23
	v_fmac_f32_e32 v206, v20, v20
	v_fmac_f32_e32 v206, v21, v21
	v_fmac_f32_e32 v206, v22, v22
	v_fmac_f32_e32 v206, v23, v23
	ds_write_b128 v192, v[20:23] offset:32
	s_waitcnt lgkmcnt(7)
	v_add_f32_e32 v24, v168, v24
	v_add_f32_e32 v25, v169, v25
	v_add_f32_e32 v26, v170, v26
	v_add_f32_e32 v27, v171, v27
	v_fmac_f32_e32 v206, v24, v24
	v_fmac_f32_e32 v206, v25, v25
	v_fmac_f32_e32 v206, v26, v26
	v_fmac_f32_e32 v206, v27, v27
	ds_write_b128 v192, v[24:27] offset:64
	s_waitcnt lgkmcnt(7)
	v_add_f32_e32 v28, v172, v28
	v_add_f32_e32 v29, v173, v29
	v_add_f32_e32 v30, v174, v30
	v_add_f32_e32 v31, v175, v31
	v_fmac_f32_e32 v206, v28, v28
	v_fmac_f32_e32 v206, v29, v29
	v_fmac_f32_e32 v206, v30, v30
	v_fmac_f32_e32 v206, v31, v31
	ds_write_b128 v192, v[28:31] offset:96
	s_waitcnt lgkmcnt(7)
	v_add_f32_e32 v0, v176, v0
	v_add_f32_e32 v1, v177, v1
	v_add_f32_e32 v2, v178, v2
	v_add_f32_e32 v3, v179, v3
	v_fmac_f32_e32 v206, v0, v0
	v_fmac_f32_e32 v206, v1, v1
	v_fmac_f32_e32 v206, v2, v2
	v_fmac_f32_e32 v206, v3, v3
	ds_write_b128 v192, v[0:3] offset:128
	s_waitcnt lgkmcnt(7)
	v_add_f32_e32 v4, v180, v4
	v_add_f32_e32 v5, v181, v5
	v_add_f32_e32 v6, v182, v6
	v_add_f32_e32 v7, v183, v7
	v_fmac_f32_e32 v206, v4, v4
	v_fmac_f32_e32 v206, v5, v5
	v_fmac_f32_e32 v206, v6, v6
	v_fmac_f32_e32 v206, v7, v7
	ds_write_b128 v192, v[4:7] offset:160
	s_waitcnt lgkmcnt(7)
; DI bfr f2bf(float a) { return (bfr)(pack2(a, 0.f) & 0xffffu); }
; DI int crow(int reg, int h) { return (reg & 3) + 8 * (reg >> 2) + 4 * h; }
; template <bool FIRST, bool HAS_H>
; DI void phase_gemm_resid(const Params& p, const bfr* A, const bfr* Wt, const float* gnext, float* ss, char* smem) {
;     ...
; #pragma unroll
;     for (int i = 0; i < 2; ++i) {
; #pragma unroll
;       for (int qh = 0; qh < 2; ++qh) {
;         float rs[8];
; #pragma unroll
;         for (int q = 0; q < 8; ++q) rs[q] = 0.f;
; #pragma unroll
;         for (int jh = 0; jh < 2; ++jh) {
;           float xo[2][8];
; #pragma unroll
;           for (int jj = 0; jj < 2; ++jj)
; #pragma unroll
;             for (int q = 0; q < 8; ++q)
;               xo[jj][q] = xsrc[(rbase + i * 32 + crow(qh * 8 + q, 0)) * 1024 + cbase + (jh * 2 + jj) * 32];
; #pragma unroll
;           for (int q = 0; q < 8; ++q) {
;             const int o = (rbase + i * 32 + crow(qh * 8 + q, 0)) * 1024 + cbase;
; #pragma unroll
;             for (int jj = 0; jj < 2; ++jj) {
;               const int j = jh * 2 + jj;
;               const float xn = xo[jj][q] + acc[i][j][qh * 8 + q];
;               X[o + j * 32] = xn;
;               if (HAS_H) Hn[o + j * 32] = f2bf(xn * gnext[cbase + j * 32]);
;               rs[q] += xn * xn;
;             }
;           }
;         }
; #pragma unroll
;         for (int q = 0; q < 8; ++q) rs[q] = half32_sum_hi(rs[q]);
;         if (r == 31) {
; #pragma unroll
;           for (int q = 0; q < 8; ++q) unsafeAtomicAdd(ss + rbase + i * 32 + crow(qh * 8 + q, 0), rs[q]);
;         }
	v_add_f32_e32 v8, v184, v8
	v_add_f32_e32 v9, v185, v9
	v_add_f32_e32 v10, v186, v10
	v_add_f32_e32 v11, v187, v11
	v_fmac_f32_e32 v206, v8, v8
	v_fmac_f32_e32 v206, v9, v9
	v_fmac_f32_e32 v206, v10, v10
	v_fmac_f32_e32 v206, v11, v11
	ds_write_b128 v192, v[8:11] offset:192
	s_waitcnt lgkmcnt(7)
	v_add_f32_e32 v12, v188, v12
	v_add_f32_e32 v13, v189, v13
	v_add_f32_e32 v14, v190, v14
	v_add_f32_e32 v15, v191, v15
	v_fmac_f32_e32 v206, v12, v12
	v_fmac_f32_e32 v206, v13, v13
	v_fmac_f32_e32 v206, v14, v14
	v_fmac_f32_e32 v206, v15, v15
	ds_write_b128 v192, v[12:15] offset:224
	ds_read_b128 v[160:163], v200
	ds_read_b128 v[164:167], v200 offset:1088
	ds_read_b128 v[168:171], v200 offset:2176
	ds_read_b128 v[172:175], v200 offset:3264
	ds_read_b128 v[176:179], v200 offset:4352
	ds_read_b128 v[180:183], v200 offset:5440
	ds_read_b128 v[184:187], v200 offset:6528
	ds_read_b128 v[188:191], v200 offset:7616
	s_add_u32 s74, s66, 0x20100
	s_addc_u32 s75, s67, 0
	s_waitcnt lgkmcnt(7)
	global_store_dwordx4 v202, v[160:163], s[74:75]
	s_add_u32 s74, s66, 0x24100
	s_addc_u32 s75, s67, 0
	s_waitcnt lgkmcnt(6)
	global_store_dwordx4 v202, v[164:167], s[74:75]
	s_add_u32 s74, s66, 0x28100
	s_addc_u32 s75, s67, 0
	s_waitcnt lgkmcnt(5)
	global_store_dwordx4 v202, v[168:171], s[74:75]
	s_add_u32 s74, s66, 0x2c100
	s_addc_u32 s75, s67, 0
	s_waitcnt lgkmcnt(4)
	global_store_dwordx4 v202, v[172:175], s[74:75]
	s_add_u32 s74, s66, 0x30100
	s_addc_u32 s75, s67, 0
	s_waitcnt lgkmcnt(3)
	global_store_dwordx4 v202, v[176:179], s[74:75]
	s_add_u32 s74, s66, 0x34100
	s_addc_u32 s75, s67, 0
	s_waitcnt lgkmcnt(2)
	global_store_dwordx4 v202, v[180:183], s[74:75]
	s_add_u32 s74, s66, 0x38100
	s_addc_u32 s75, s67, 0
	s_waitcnt lgkmcnt(1)
	global_store_dwordx4 v202, v[184:187], s[74:75]
	s_add_u32 s74, s66, 0x3c100
	s_addc_u32 s75, s67, 0
	s_waitcnt lgkmcnt(0)
	global_store_dwordx4 v202, v[188:191], s[74:75]
	global_load_dwordx4 v[160:163], v204, s[70:71] offset:256
	global_load_dwordx4 v[164:167], v204, s[70:71] offset:288
	global_load_dwordx4 v[168:171], v204, s[70:71] offset:320
	global_load_dwordx4 v[172:175], v204, s[70:71] offset:352
	global_load_dwordx4 v[176:179], v204, s[70:71] offset:384
	global_load_dwordx4 v[180:183], v204, s[70:71] offset:416
	global_load_dwordx4 v[184:187], v204, s[70:71] offset:448
	global_load_dwordx4 v[188:191], v204, s[70:71] offset:480
	s_waitcnt vmcnt(7)
	v_mul_f32_e32 v16, v160, v16
	v_mul_f32_e32 v17, v161, v17
	v_mul_f32_e32 v18, v162, v18
	v_mul_f32_e32 v19, v163, v19
	v_cvt_pk_bf16_f32 v16, v16, v17
	v_cvt_pk_bf16_f32 v17, v18, v19
	ds_write_b64 v194, v[16:17]
	s_waitcnt vmcnt(6)
	v_mul_f32_e32 v20, v164, v20
	v_mul_f32_e32 v21, v165, v21
	v_mul_f32_e32 v22, v166, v22
	v_mul_f32_e32 v23, v167, v23
	v_cvt_pk_bf16_f32 v20, v20, v21
	v_cvt_pk_bf16_f32 v21, v22, v23
	ds_write_b64 v194, v[20:21] offset:16
	s_waitcnt vmcnt(5)
	v_mul_f32_e32 v24, v168, v24
	v_mul_f32_e32 v25, v169, v25
	v_mul_f32_e32 v26, v170, v26
	v_mul_f32_e32 v27, v171, v27
	v_cvt_pk_bf16_f32 v24, v24, v25
	v_cvt_pk_bf16_f32 v25, v26, v27
	ds_write_b64 v194, v[24:25] offset:32
	s_waitcnt vmcnt(4)
	v_mul_f32_e32 v28, v172, v28
	v_mul_f32_e32 v29, v173, v29
	v_mul_f32_e32 v30, v174, v30
	v_mul_f32_e32 v31, v175, v31
	v_cvt_pk_bf16_f32 v28, v28, v29
	v_cvt_pk_bf16_f32 v29, v30, v31
	ds_write_b64 v194, v[28:29] offset:48
	s_waitcnt vmcnt(3)
	v_mul_f32_e32 v0, v176, v0
	v_mul_f32_e32 v1, v177, v1
	v_mul_f32_e32 v2, v178, v2
	v_mul_f32_e32 v3, v179, v3
	v_cvt_pk_bf16_f32 v0, v0, v1
	v_cvt_pk_bf16_f32 v1, v2, v3
	ds_write_b64 v194, v[0:1] offset:64
	s_waitcnt vmcnt(2)
	v_mul_f32_e32 v4, v180, v4
	v_mul_f32_e32 v5, v181, v5
	v_mul_f32_e32 v6, v182, v6
	v_mul_f32_e32 v7, v183, v7
	v_cvt_pk_bf16_f32 v4, v4, v5
	v_cvt_pk_bf16_f32 v5, v6, v7
	ds_write_b64 v194, v[4:5] offset:80
	s_waitcnt vmcnt(1)
	v_mul_f32_e32 v8, v184, v8
	v_mul_f32_e32 v9, v185, v9
	v_mul_f32_e32 v10, v186, v10
	v_mul_f32_e32 v11, v187, v11
	v_cvt_pk_bf16_f32 v8, v8, v9
	v_cvt_pk_bf16_f32 v9, v10, v11
	ds_write_b64 v194, v[8:9] offset:96
	s_waitcnt vmcnt(0)
	v_mul_f32_e32 v12, v188, v12
	v_mul_f32_e32 v13, v189, v13
	v_mul_f32_e32 v14, v190, v14
	v_mul_f32_e32 v15, v191, v15
	v_cvt_pk_bf16_f32 v12, v12, v13
	v_cvt_pk_bf16_f32 v13, v14, v15
	ds_write_b64 v194, v[12:13] offset:112
	ds_read_b128 v[160:163], v201
	ds_read_b128 v[164:167], v201 offset:2176
	ds_read_b128 v[168:171], v201 offset:4352
	ds_read_b128 v[172:175], v201 offset:6528
	s_add_u32 s74, s68, 0x10080
	s_addc_u32 s75, s69, 0
	s_waitcnt lgkmcnt(3)
	global_store_dwordx4 v203, v[160:163], s[74:75]
	s_add_u32 s74, s68, 0x14080
	s_addc_u32 s75, s69, 0
	s_waitcnt lgkmcnt(2)
	global_store_dwordx4 v203, v[164:167], s[74:75]
	s_add_u32 s74, s68, 0x18080
	s_addc_u32 s75, s69, 0
	s_waitcnt lgkmcnt(1)
	global_store_dwordx4 v203, v[168:171], s[74:75]
	s_add_u32 s74, s68, 0x1c080
	s_addc_u32 s75, s69, 0
	s_waitcnt lgkmcnt(0)
	global_store_dwordx4 v203, v[172:175], s[74:75]
	s_load_dwordx2 s[64:65], s[92:93], 0x140
	ds_bpermute_b32 v210, v208, v205
	ds_bpermute_b32 v211, v208, v206
	s_waitcnt lgkmcnt(0)
	s_add_u32 s64, s64, 0x20400
	s_addc_u32 s65, s65, 0
	v_add_f32_e32 v210, v210, v205
	v_add_f32_e32 v211, v211, v206
	s_mov_b32 exec_hi, 0
	s_nop 1
	global_atomic_add_f32 v207, v210, s[64:65]
	global_atomic_add_f32 v207, v211, s[64:65] offset:128
	s_mov_b64 exec, -1
	v_readlane_b32 s64, v209, 0
	v_readlane_b32 s65, v209, 1
	v_readlane_b32 s66, v209, 2
	v_readlane_b32 s67, v209, 3
	v_readlane_b32 s68, v209, 4
	v_readlane_b32 s69, v209, 5
	v_readlane_b32 s70, v209, 6
	v_readlane_b32 s71, v209, 7
	v_readlane_b32 s72, v209, 8
	v_readlane_b32 s73, v209, 9
	v_readlane_b32 s74, v209, 10
	v_readlane_b32 s75, v209, 11
	v_readlane_b32 s76, v209, 12
	v_readlane_b32 s77, v209, 13
	v_readlane_b32 s78, v209, 14
	v_readlane_b32 s79, v209, 15
	s_nop 7
	s_branch .LBB0_1463

; #define MFMA32(a, b, c) __builtin_amdgcn_mfma_f32_32x32x16_bf16((a), (b), (c), 0, 0, 0)
; #define GA_LOAD(pr_) do { _Pragma("unroll") for (int i = 0; i < 4; ++i) ra[i] = *(const u32x4*)(Ab + (i * 32) * lda + (pr_) * 64); } while (0)
; #define GB_LOAD(kt_) do { const bfr* bk_ = Bb + (kt_) * NB * 32; \
;     _Pragma("unroll") for (int i = 0; i < 4; ++i) rb[i] = *(const u32x4*)(bk_ + (i * 64) * 32); } while (0)
; #define G_STORE(kt_) do { bfr* as_ = S0 + ((kt_) & 1) * GSTAGE; bfr* bs_ = as_ + 128 * 40; \
;     if (apar == ((kt_) & 1)) { _Pragma("unroll") for (int i = 0; i < 4; ++i) *(u32x4*)(as_ + asoff + i * 32 * 40) = ra[i]; } \
;     _Pragma("unroll") for (int i = 0; i < 4; ++i) *(u32x4*)(bs_ + bsoff + i * 64 * 40) = rb[i]; } while (0)
; template <int lda>
; DI void gemm_mainloop(const bfr* __restrict__ A, const bfr* __restrict__ Bt, int NB, int K, int m0, int n0, char* smem, f32x16 (&acc)[2][4]) {
;     ...
;   for (int kt = 0; kt < nk; ++kt) {
;     if (kt + 1 < nk) G_STORE(kt + 1);
;     if (kt + 2 < nk) {
;       GB_LOAD(kt + 2);
;       if ((kt & 1) == 0) GA_LOAD((kt >> 1) + 1);
;     }
;     const bfr* As = S0 + (kt & 1) * GSTAGE;
;     const bfr* Bs = As + 128 * 40;
; #pragma unroll
;     for (int ks = 0; ks < 2; ++ks) {
;       bf16x8 af[2], bfg[4];
; #pragma unroll
;       for (int i = 0; i < 2; ++i) af[i] = *(const bf16x8*)(As + (wr * 64 + i * 32 + r) * 40 + ks * 16 + hl * 8);
; #pragma unroll
;       for (int j = 0; j < 4; ++j) bfg[j] = *(const bf16x8*)(Bs + (wc * 128 + j * 32 + r) * 40 + ks * 16 + hl * 8);
; #pragma unroll
;       for (int i = 0; i < 2; ++i)
; #pragma unroll
;         for (int j = 0; j < 4; ++j) acc[i][j] = MFMA32(af[i], bfg[j], acc[i][j]);
;     }
;     __syncthreads();
.Lp17_loop:
	s_waitcnt vmcnt(6) lgkmcnt(0)
	s_barrier
	s_mul_i32 s74, s71, 0x6000
	s_add_u32 s75, s74, 0x2000
	s_cmp_eq_u32 s71, 2
	s_cselect_b32 s75, 0x10000, s75
	v_add_u32_e32 v183, s74, v179
	v_add_u32_e32 v185, s75, v181
	v_add_u32_e32 v184, s74, v180
	v_add_u32_e32 v186, s75, v182
	s_add_u32 s71, s71, 1
	s_cmp_eq_u32 s71, 3
	s_cselect_b32 s71, 0, s71
	ds_read_b128 v[128:131], v183
	ds_read_b128 v[144:147], v185
	ds_read_b128 v[148:151], v185 offset:2048
	ds_read_b128 v[152:155], v185 offset:4096
	ds_read_b128 v[156:159], v185 offset:6144
	ds_read_b128 v[132:135], v183 offset:2048
	v_mfma_f32_32x32x16_bf16 v[112:127], v[160:163], v[136:139], v[112:127]
	s_mul_i32 s74, s70, 0x6000
	s_add_u32 s75, s74, s68
	s_mov_b32 m0, s75
	s_add_u32 s76, s74, 0x2000
	s_cmp_eq_u32 s70, 2
	s_cselect_b32 s76, 0x10000, s76
	global_load_lds_dwordx4 v176, s[64:65]
	v_mfma_f32_32x32x16_bf16 v[96:111], v[164:167], v[136:139], v[96:111]
	s_add_u32 m0, s75, 0x400
	s_add_u32 s76, s76, s69
	global_load_lds_dwordx4 v177, s[64:65]
	v_mfma_f32_32x32x16_bf16 v[80:95], v[168:171], v[136:139], v[80:95]
	s_mov_b32 m0, s76
	s_add_u32 s64, s64, 64
	s_addc_u32 s65, s65, 0
	global_load_lds_dwordx4 v178, s[66:67]
	v_mfma_f32_32x32x16_bf16 v[64:79], v[172:175], v[136:139], v[64:79]
	global_load_lds_dwordx4 v178, s[66:67] offset:1024
	v_mfma_f32_32x32x16_bf16 v[48:63], v[160:163], v[140:143], v[48:63]
	global_load_lds_dwordx4 v178, s[66:67] offset:2048
	v_mfma_f32_32x32x16_bf16 v[32:47], v[164:167], v[140:143], v[32:47]
	global_load_lds_dwordx4 v178, s[66:67] offset:3072
	s_add_u32 s66, s66, 0x10000
	s_addc_u32 s67, s67, 0
	v_mfma_f32_32x32x16_bf16 v[16:31], v[168:171], v[140:143], v[16:31]
	s_add_u32 s70, s70, 1
	s_cmp_eq_u32 s70, 3
	s_cselect_b32 s70, 0, s70
	v_mfma_f32_32x32x16_bf16 v[0:15], v[172:175], v[140:143], v[0:15]
	ds_read_b128 v[136:139], v184
	ds_read_b128 v[160:163], v186
	ds_read_b128 v[164:167], v186 offset:2048
	ds_read_b128 v[168:171], v186 offset:4096
	ds_read_b128 v[172:175], v186 offset:6144
	ds_read_b128 v[140:143], v184 offset:2048
	s_waitcnt lgkmcnt(10)
	v_mfma_f32_32x32x16_bf16 v[112:127], v[144:147], v[128:131], v[112:127]
	s_waitcnt lgkmcnt(9)
	v_mfma_f32_32x32x16_bf16 v[96:111], v[148:151], v[128:131], v[96:111]
	s_waitcnt lgkmcnt(8)
	v_mfma_f32_32x32x16_bf16 v[80:95], v[152:155], v[128:131], v[80:95]
	s_waitcnt lgkmcnt(7)
	v_mfma_f32_32x32x16_bf16 v[64:79], v[156:159], v[128:131], v[64:79]
	s_waitcnt lgkmcnt(6)
	v_mfma_f32_32x32x16_bf16 v[48:63], v[144:147], v[132:135], v[48:63]
	v_mfma_f32_32x32x16_bf16 v[32:47], v[148:151], v[132:135], v[32:47]
	v_mfma_f32_32x32x16_bf16 v[16:31], v[152:155], v[132:135], v[16:31]
	v_mfma_f32_32x32x16_bf16 v[0:15], v[156:159], v[132:135], v[0:15]
	s_add_u32 s72, s72, 1
	s_cmp_lt_u32 s72, 29
	s_cbranch_scc1 .Lp17_loop
	s_waitcnt vmcnt(6) lgkmcnt(0)
	s_barrier
	s_mul_i32 s74, s71, 0x6000
	s_add_u32 s75, s74, 0x2000
	s_cmp_eq_u32 s71, 2
	s_cselect_b32 s75, 0x10000, s75
	v_add_u32_e32 v183, s74, v179
	v_add_u32_e32 v185, s75, v181
	v_add_u32_e32 v184, s74, v180
	v_add_u32_e32 v186, s75, v182
	s_add_u32 s71, s71, 1
	s_cmp_eq_u32 s71, 3
	s_cselect_b32 s71, 0, s71
	ds_read_b128 v[128:131], v183
	ds_read_b128 v[144:147], v185
	ds_read_b128 v[148:151], v185 offset:2048
	ds_read_b128 v[152:155], v185 offset:4096
	ds_read_b128 v[156:159], v185 offset:6144
	ds_read_b128 v[132:135], v183 offset:2048
	v_mfma_f32_32x32x16_bf16 v[112:127], v[160:163], v[136:139], v[112:127]
	v_mfma_f32_32x32x16_bf16 v[96:111], v[164:167], v[136:139], v[96:111]
	v_mfma_f32_32x32x16_bf16 v[80:95], v[168:171], v[136:139], v[80:95]
	v_mfma_f32_32x32x16_bf16 v[64:79], v[172:175], v[136:139], v[64:79]
	v_mfma_f32_32x32x16_bf16 v[48:63], v[160:163], v[140:143], v[48:63]
	v_mfma_f32_32x32x16_bf16 v[32:47], v[164:167], v[140:143], v[32:47]
	v_mfma_f32_32x32x16_bf16 v[16:31], v[168:171], v[140:143], v[16:31]
	v_mfma_f32_32x32x16_bf16 v[0:15], v[172:175], v[140:143], v[0:15]
	ds_read_b128 v[136:139], v184
	ds_read_b128 v[160:163], v186
	ds_read_b128 v[164:167], v186 offset:2048
	ds_read_b128 v[168:171], v186 offset:4096
	ds_read_b128 v[172:175], v186 offset:6144
	ds_read_b128 v[140:143], v184 offset:2048
	s_waitcnt lgkmcnt(10)
	v_mfma_f32_32x32x16_bf16 v[112:127], v[144:147], v[128:131], v[112:127]
	s_waitcnt lgkmcnt(9)
	v_mfma_f32_32x32x16_bf16 v[96:111], v[148:151], v[128:131], v[96:111]
	s_waitcnt lgkmcnt(8)
	v_mfma_f32_32x32x16_bf16 v[80:95], v[152:155], v[128:131], v[80:95]
	s_waitcnt lgkmcnt(7)
	v_mfma_f32_32x32x16_bf16 v[64:79], v[156:159], v[128:131], v[64:79]
	s_waitcnt lgkmcnt(6)
	v_mfma_f32_32x32x16_bf16 v[48:63], v[144:147], v[132:135], v[48:63]
	v_mfma_f32_32x32x16_bf16 v[32:47], v[148:151], v[132:135], v[32:47]
	v_mfma_f32_32x32x16_bf16 v[16:31], v[152:155], v[132:135], v[16:31]
	v_mfma_f32_32x32x16_bf16 v[0:15], v[156:159], v[132:135], v[0:15]
	s_waitcnt vmcnt(0) lgkmcnt(0)
	s_barrier
; #define MFMA32(a, b, c) __builtin_amdgcn_mfma_f32_32x32x16_bf16((a), (b), (c), 0, 0, 0)
; DI bfr f2bf(float a) { return (bfr)(pack2(a, 0.f) & 0xffffu); }
; #define GA_LOAD(pr_) do { _Pragma("unroll") for (int i = 0; i < 4; ++i) ra[i] = *(const u32x4*)(Ab + (i * 32) * lda + (pr_) * 64); } while (0)
; #define GB_LOAD(kt_) do { const bfr* bk_ = Bb + (kt_) * NB * 32; \
;     _Pragma("unroll") for (int i = 0; i < 4; ++i) rb[i] = *(const u32x4*)(bk_ + (i * 64) * 32); } while (0)
; #define G_STORE(kt_) do { bfr* as_ = S0 + ((kt_) & 1) * GSTAGE; bfr* bs_ = as_ + 128 * 40; \
;     if (apar == ((kt_) & 1)) { _Pragma("unroll") for (int i = 0; i < 4; ++i) *(u32x4*)(as_ + asoff + i * 32 * 40) = ra[i]; } \
;     _Pragma("unroll") for (int i = 0; i < 4; ++i) *(u32x4*)(bs_ + bsoff + i * 64 * 40) = rb[i]; } while (0)
; template <int lda>
; DI void gemm_mainloop(const bfr* __restrict__ A, const bfr* __restrict__ Bt, int NB, int K, int m0, int n0, char* smem, f32x16 (&acc)[2][4]) {
;     ...
;   for (int kt = 0; kt < nk; ++kt) {
;     if (kt + 1 < nk) G_STORE(kt + 1);
;     if (kt + 2 < nk) {
;       GB_LOAD(kt + 2);
;       if ((kt & 1) == 0) GA_LOAD((kt >> 1) + 1);
;     }
;     const bfr* As = S0 + (kt & 1) * GSTAGE;
;     const bfr* Bs = As + 128 * 40;
; #pragma unroll
;     for (int ks = 0; ks < 2; ++ks) {
;       bf16x8 af[2], bfg[4];
; #pragma unroll
;       for (int i = 0; i < 2; ++i) af[i] = *(const bf16x8*)(As + (wr * 64 + i * 32 + r) * 40 + ks * 16 + hl * 8);
; #pragma unroll
;       for (int j = 0; j < 4; ++j) bfg[j] = *(const bf16x8*)(Bs + (wc * 128 + j * 32 + r) * 40 + ks * 16 + hl * 8);
; #pragma unroll
;       for (int i = 0; i < 2; ++i)
; #pragma unroll
;         for (int j = 0; j < 4; ++j) acc[i][j] = MFMA32(af[i], bfg[j], acc[i][j]);
;     }
; DI void phase_gemm_bf16out(const Params& p, const bfr* A, const bfr* Wt, bfr* C, int N, const float* ss, char* smem) {
;     ...
;     gemm_tile<1024>(A, Wt, N, 1024, mt * 128, nt * 256, smem,
;               [=](int row, int col, float v) {
;                 float inv = rsqrtf(ss[row] * (1.0f / 1024.0f) + EPSF);
;                 C[(size_t)row * N + col] = f2bf(v * inv);
;               });
	s_mul_i32 s74, s71, 0x6000
	s_add_u32 s75, s74, 0x2000
	s_cmp_eq_u32 s71, 2
	s_cselect_b32 s75, 0x10000, s75
	v_add_u32_e32 v183, s74, v179
	v_add_u32_e32 v185, s75, v181
	v_add_u32_e32 v184, s74, v180
	v_add_u32_e32 v186, s75, v182
	s_add_u32 s71, s71, 1
	s_cmp_eq_u32 s71, 3
	s_cselect_b32 s71, 0, s71
	ds_read_b128 v[128:131], v183
	ds_read_b128 v[144:147], v185
	ds_read_b128 v[148:151], v185 offset:2048
	ds_read_b128 v[152:155], v185 offset:4096
	ds_read_b128 v[156:159], v185 offset:6144
	ds_read_b128 v[132:135], v183 offset:2048
	v_mfma_f32_32x32x16_bf16 v[112:127], v[160:163], v[136:139], v[112:127]
	v_mfma_f32_32x32x16_bf16 v[96:111], v[164:167], v[136:139], v[96:111]
	v_mfma_f32_32x32x16_bf16 v[80:95], v[168:171], v[136:139], v[80:95]
	v_mfma_f32_32x32x16_bf16 v[64:79], v[172:175], v[136:139], v[64:79]
	v_mfma_f32_32x32x16_bf16 v[48:63], v[160:163], v[140:143], v[48:63]
	v_mfma_f32_32x32x16_bf16 v[32:47], v[164:167], v[140:143], v[32:47]
	v_mfma_f32_32x32x16_bf16 v[16:31], v[168:171], v[140:143], v[16:31]
	v_mfma_f32_32x32x16_bf16 v[0:15], v[172:175], v[140:143], v[0:15]
	ds_read_b128 v[136:139], v184
	ds_read_b128 v[160:163], v186
	ds_read_b128 v[164:167], v186 offset:2048
	ds_read_b128 v[168:171], v186 offset:4096
	ds_read_b128 v[172:175], v186 offset:6144
	ds_read_b128 v[140:143], v184 offset:2048
	s_waitcnt lgkmcnt(10)
	v_mfma_f32_32x32x16_bf16 v[112:127], v[144:147], v[128:131], v[112:127]
	s_waitcnt lgkmcnt(9)
	v_mfma_f32_32x32x16_bf16 v[96:111], v[148:151], v[128:131], v[96:111]
	s_waitcnt lgkmcnt(8)
	v_mfma_f32_32x32x16_bf16 v[80:95], v[152:155], v[128:131], v[80:95]
	s_waitcnt lgkmcnt(7)
	v_mfma_f32_32x32x16_bf16 v[64:79], v[156:159], v[128:131], v[64:79]
	s_waitcnt lgkmcnt(6)
	v_mfma_f32_32x32x16_bf16 v[48:63], v[144:147], v[132:135], v[48:63]
	v_mfma_f32_32x32x16_bf16 v[32:47], v[148:151], v[132:135], v[32:47]
	v_mfma_f32_32x32x16_bf16 v[16:31], v[152:155], v[132:135], v[16:31]
	v_mfma_f32_32x32x16_bf16 v[0:15], v[156:159], v[132:135], v[0:15]
	s_waitcnt lgkmcnt(0)
	v_mfma_f32_32x32x16_bf16 v[112:127], v[160:163], v[136:139], v[112:127]
	v_mfma_f32_32x32x16_bf16 v[96:111], v[164:167], v[136:139], v[96:111]
	v_mfma_f32_32x32x16_bf16 v[80:95], v[168:171], v[136:139], v[80:95]
	v_mfma_f32_32x32x16_bf16 v[64:79], v[172:175], v[136:139], v[64:79]
	v_mfma_f32_32x32x16_bf16 v[48:63], v[160:163], v[140:143], v[48:63]
	v_mfma_f32_32x32x16_bf16 v[32:47], v[164:167], v[140:143], v[32:47]
	v_mfma_f32_32x32x16_bf16 v[16:31], v[168:171], v[140:143], v[16:31]
	v_mfma_f32_32x32x16_bf16 v[0:15], v[172:175], v[140:143], v[0:15]
	s_nop 7
	s_nop 3
	s_barrier
	s_load_dwordx2 s[64:65], s[92:93], 0x160
	s_load_dwordx2 s[66:67], s[92:93], 0x140
	v_and_b32_e32 v176, 31, v196
	v_bfe_u32 v177, v196, 5, 1
	s_lshr_b32 s74, s73, 1
	s_lshl_b32 s74, s74, 6
	s_add_u32 s74, s74, s77
	v_add_u32_e32 v178, s74, v176
	s_mul_i32 s76, s73, 8704
	v_mul_u32_u24_e32 v180, 272, v176
	v_lshl_add_u32 v180, v177, 3, v180
	v_add_u32_e32 v180, s76, v180
	v_bfe_u32 v185, v196, 4, 2
	v_and_b32_e32 v186, 15, v196
	v_mul_u32_u24_e32 v181, 272, v185
	v_lshl_add_u32 v181, v186, 4, v181
	v_add_u32_e32 v181, s76, v181
	s_and_b32 s75, s73, 1
	s_lshl_b32 s75, s75, 7
	s_add_u32 s75, s75, s78
	v_add_u32_e32 v179, s74, v185
	v_mul_u32_u24_e32 v179, 0x400, v179
	v_lshl_add_u32 v179, v186, 3, v179
	v_add_lshl_u32 v182, v179, s75, 1
	s_waitcnt lgkmcnt(0)
	s_add_u32 s66, s66, 0x20400
	s_addc_u32 s67, s67, 0
	v_lshlrev_b32_e32 v179, 2, v178
	global_load_dword v183, v179, s[66:67]
	global_load_dword v184, v179, s[66:67] offset:128
	s_waitcnt vmcnt(0)
	v_mul_f32_e32 v183, 0x3a800000, v183
	v_mul_f32_e32 v184, 0x3a800000, v184
	v_add_f32_e32 v183, 0x358637bd, v183
	v_add_f32_e32 v184, 0x358637bd, v184
	v_rsq_f32_e32 v183, v183
	v_rsq_f32_e32 v184, v184
	s_nop 1
	v_mul_f32_e32 v112, v183, v112
	v_mul_f32_e32 v113, v183, v113
	v_mul_f32_e32 v114, v183, v114
	v_mul_f32_e32 v115, v183, v115
	v_cvt_pk_bf16_f32 v112, v112, v113
	v_cvt_pk_bf16_f32 v113, v114, v115
	ds_write_b64 v180, v[112:113]
	v_mul_f32_e32 v116, v183, v116
	v_mul_f32_e32 v117, v183, v117
	v_mul_f32_e32 v118, v183, v118
	v_mul_f32_e32 v119, v183, v119
	v_cvt_pk_bf16_f32 v116, v116, v117
	v_cvt_pk_bf16_f32 v117, v118, v119
	ds_write_b64 v180, v[116:117] offset:16
	v_mul_f32_e32 v120, v183, v120
	v_mul_f32_e32 v121, v183, v121
	v_mul_f32_e32 v122, v183, v122
	v_mul_f32_e32 v123, v183, v123
	v_cvt_pk_bf16_f32 v120, v120, v121
	v_cvt_pk_bf16_f32 v121, v122, v123
	ds_write_b64 v180, v[120:121] offset:32
	v_mul_f32_e32 v124, v183, v124
	v_mul_f32_e32 v125, v183, v125
	v_mul_f32_e32 v126, v183, v126
	v_mul_f32_e32 v127, v183, v127
	v_cvt_pk_bf16_f32 v124, v124, v125
	v_cvt_pk_bf16_f32 v125, v126, v127
	ds_write_b64 v180, v[124:125] offset:48
	v_mul_f32_e32 v96, v183, v96
	v_mul_f32_e32 v97, v183, v97
	v_mul_f32_e32 v98, v183, v98
	v_mul_f32_e32 v99, v183, v99
	v_cvt_pk_bf16_f32 v96, v96, v97
	v_cvt_pk_bf16_f32 v97, v98, v99
	ds_write_b64 v180, v[96:97] offset:64
	v_mul_f32_e32 v100, v183, v100
	v_mul_f32_e32 v101, v183, v101
	v_mul_f32_e32 v102, v183, v102
	v_mul_f32_e32 v103, v183, v103
	v_cvt_pk_bf16_f32 v100, v100, v101
	v_cvt_pk_bf16_f32 v101, v102, v103
	ds_write_b64 v180, v[100:101] offset:80
	v_mul_f32_e32 v104, v183, v104
	v_mul_f32_e32 v105, v183, v105
	v_mul_f32_e32 v106, v183, v106
	v_mul_f32_e32 v107, v183, v107
	v_cvt_pk_bf16_f32 v104, v104, v105
	v_cvt_pk_bf16_f32 v105, v106, v107
	ds_write_b64 v180, v[104:105] offset:96
	v_mul_f32_e32 v108, v183, v108
	v_mul_f32_e32 v109, v183, v109
	v_mul_f32_e32 v110, v183, v110
	v_mul_f32_e32 v111, v183, v111
	v_cvt_pk_bf16_f32 v108, v108, v109
	v_cvt_pk_bf16_f32 v109, v110, v111
; DI bfr f2bf(float a) { return (bfr)(pack2(a, 0.f) & 0xffffu); }
; DI void phase_gemm_bf16out(const Params& p, const bfr* A, const bfr* Wt, bfr* C, int N, const float* ss, char* smem) {
;     ...
;     gemm_tile<1024>(A, Wt, N, 1024, mt * 128, nt * 256, smem,
;               [=](int row, int col, float v) {
;                 float inv = rsqrtf(ss[row] * (1.0f / 1024.0f) + EPSF);
;                 C[(size_t)row * N + col] = f2bf(v * inv);
;               });
	ds_write_b64 v180, v[108:109] offset:112
	v_mul_f32_e32 v80, v183, v80
	v_mul_f32_e32 v81, v183, v81
	v_mul_f32_e32 v82, v183, v82
	v_mul_f32_e32 v83, v183, v83
	v_cvt_pk_bf16_f32 v80, v80, v81
	v_cvt_pk_bf16_f32 v81, v82, v83
	ds_write_b64 v180, v[80:81] offset:128
	v_mul_f32_e32 v84, v183, v84
	v_mul_f32_e32 v85, v183, v85
	v_mul_f32_e32 v86, v183, v86
	v_mul_f32_e32 v87, v183, v87
	v_cvt_pk_bf16_f32 v84, v84, v85
	v_cvt_pk_bf16_f32 v85, v86, v87
	ds_write_b64 v180, v[84:85] offset:144
	v_mul_f32_e32 v88, v183, v88
	v_mul_f32_e32 v89, v183, v89
	v_mul_f32_e32 v90, v183, v90
	v_mul_f32_e32 v91, v183, v91
	v_cvt_pk_bf16_f32 v88, v88, v89
	v_cvt_pk_bf16_f32 v89, v90, v91
	ds_write_b64 v180, v[88:89] offset:160
	v_mul_f32_e32 v92, v183, v92
	v_mul_f32_e32 v93, v183, v93
	v_mul_f32_e32 v94, v183, v94
	v_mul_f32_e32 v95, v183, v95
	v_cvt_pk_bf16_f32 v92, v92, v93
	v_cvt_pk_bf16_f32 v93, v94, v95
	ds_write_b64 v180, v[92:93] offset:176
	v_mul_f32_e32 v64, v183, v64
	v_mul_f32_e32 v65, v183, v65
	v_mul_f32_e32 v66, v183, v66
	v_mul_f32_e32 v67, v183, v67
	v_cvt_pk_bf16_f32 v64, v64, v65
	v_cvt_pk_bf16_f32 v65, v66, v67
	ds_write_b64 v180, v[64:65] offset:192
	v_mul_f32_e32 v68, v183, v68
	v_mul_f32_e32 v69, v183, v69
	v_mul_f32_e32 v70, v183, v70
	v_mul_f32_e32 v71, v183, v71
	v_cvt_pk_bf16_f32 v68, v68, v69
	v_cvt_pk_bf16_f32 v69, v70, v71
	ds_write_b64 v180, v[68:69] offset:208
	v_mul_f32_e32 v72, v183, v72
	v_mul_f32_e32 v73, v183, v73
	v_mul_f32_e32 v74, v183, v74
	v_mul_f32_e32 v75, v183, v75
	v_cvt_pk_bf16_f32 v72, v72, v73
	v_cvt_pk_bf16_f32 v73, v74, v75
	ds_write_b64 v180, v[72:73] offset:224
	v_mul_f32_e32 v76, v183, v76
	v_mul_f32_e32 v77, v183, v77
	v_mul_f32_e32 v78, v183, v78
	v_mul_f32_e32 v79, v183, v79
	v_cvt_pk_bf16_f32 v76, v76, v77
	v_cvt_pk_bf16_f32 v77, v78, v79
	ds_write_b64 v180, v[76:77] offset:240
	s_waitcnt lgkmcnt(0)
	ds_read_b128 v[112:115], v181
	ds_read_b128 v[116:119], v181 offset:1088
	ds_read_b128 v[120:123], v181 offset:2176
	ds_read_b128 v[124:127], v181 offset:3264
	ds_read_b128 v[96:99], v181 offset:4352
	ds_read_b128 v[100:103], v181 offset:5440
	ds_read_b128 v[104:107], v181 offset:6528
	ds_read_b128 v[108:111], v181 offset:7616
	s_add_u32 s66, s64, 0x0
	s_addc_u32 s67, s65, 0
	s_waitcnt lgkmcnt(7)
	global_store_dwordx4 v182, v[112:115], s[66:67]
	s_add_u32 s66, s64, 0x2000
	s_addc_u32 s67, s65, 0
	s_waitcnt lgkmcnt(6)
	global_store_dwordx4 v182, v[116:119], s[66:67]
	s_add_u32 s66, s64, 0x4000
	s_addc_u32 s67, s65, 0
	s_waitcnt lgkmcnt(5)
	global_store_dwordx4 v182, v[120:123], s[66:67]
	s_add_u32 s66, s64, 0x6000
	s_addc_u32 s67, s65, 0
	s_waitcnt lgkmcnt(4)
	global_store_dwordx4 v182, v[124:127], s[66:67]
	s_add_u32 s66, s64, 0x8000
	s_addc_u32 s67, s65, 0
	s_waitcnt lgkmcnt(3)
	global_store_dwordx4 v182, v[96:99], s[66:67]
	s_add_u32 s66, s64, 0xa000
	s_addc_u32 s67, s65, 0
	s_waitcnt lgkmcnt(2)
	global_store_dwordx4 v182, v[100:103], s[66:67]
	s_add_u32 s66, s64, 0xc000
	s_addc_u32 s67, s65, 0
	s_waitcnt lgkmcnt(1)
	global_store_dwordx4 v182, v[104:107], s[66:67]
	s_add_u32 s66, s64, 0xe000
	s_addc_u32 s67, s65, 0
	s_waitcnt lgkmcnt(0)
; DI bfr f2bf(float a) { return (bfr)(pack2(a, 0.f) & 0xffffu); }
; DI void phase_gemm_bf16out(const Params& p, const bfr* A, const bfr* Wt, bfr* C, int N, const float* ss, char* smem) {
;     ...
;   for (int t0 = blockIdx.x; t0 < 128 * ntn; t0 += gridDim.x) {
;     const int t = ((gridDim.x & 7) == 0) ? xcd_tile(t0, ntn) : t0;
;     int mt = t / ntn, nt = t % ntn;
;     gemm_tile<1024>(A, Wt, N, 1024, mt * 128, nt * 256, smem,
;               [=](int row, int col, float v) {
;                 float inv = rsqrtf(ss[row] * (1.0f / 1024.0f) + EPSF);
;                 C[(size_t)row * N + col] = f2bf(v * inv);
;               });
	global_store_dwordx4 v182, v[108:111], s[66:67]
	v_mul_f32_e32 v48, v184, v48
	v_mul_f32_e32 v49, v184, v49
	v_mul_f32_e32 v50, v184, v50
	v_mul_f32_e32 v51, v184, v51
	v_cvt_pk_bf16_f32 v48, v48, v49
	v_cvt_pk_bf16_f32 v49, v50, v51
	ds_write_b64 v180, v[48:49]
	v_mul_f32_e32 v52, v184, v52
	v_mul_f32_e32 v53, v184, v53
	v_mul_f32_e32 v54, v184, v54
	v_mul_f32_e32 v55, v184, v55
	v_cvt_pk_bf16_f32 v52, v52, v53
	v_cvt_pk_bf16_f32 v53, v54, v55
	ds_write_b64 v180, v[52:53] offset:16
	v_mul_f32_e32 v56, v184, v56
	v_mul_f32_e32 v57, v184, v57
	v_mul_f32_e32 v58, v184, v58
	v_mul_f32_e32 v59, v184, v59
	v_cvt_pk_bf16_f32 v56, v56, v57
	v_cvt_pk_bf16_f32 v57, v58, v59
	ds_write_b64 v180, v[56:57] offset:32
	v_mul_f32_e32 v60, v184, v60
	v_mul_f32_e32 v61, v184, v61
	v_mul_f32_e32 v62, v184, v62
	v_mul_f32_e32 v63, v184, v63
	v_cvt_pk_bf16_f32 v60, v60, v61
	v_cvt_pk_bf16_f32 v61, v62, v63
	ds_write_b64 v180, v[60:61] offset:48
	v_mul_f32_e32 v32, v184, v32
	v_mul_f32_e32 v33, v184, v33
	v_mul_f32_e32 v34, v184, v34
	v_mul_f32_e32 v35, v184, v35
	v_cvt_pk_bf16_f32 v32, v32, v33
	v_cvt_pk_bf16_f32 v33, v34, v35
	ds_write_b64 v180, v[32:33] offset:64
	v_mul_f32_e32 v36, v184, v36
	v_mul_f32_e32 v37, v184, v37
	v_mul_f32_e32 v38, v184, v38
	v_mul_f32_e32 v39, v184, v39
	v_cvt_pk_bf16_f32 v36, v36, v37
	v_cvt_pk_bf16_f32 v37, v38, v39
	ds_write_b64 v180, v[36:37] offset:80
	v_mul_f32_e32 v40, v184, v40
	v_mul_f32_e32 v41, v184, v41
	v_mul_f32_e32 v42, v184, v42
	v_mul_f32_e32 v43, v184, v43
	v_cvt_pk_bf16_f32 v40, v40, v41
	v_cvt_pk_bf16_f32 v41, v42, v43
	ds_write_b64 v180, v[40:41] offset:96
	v_mul_f32_e32 v44, v184, v44
	v_mul_f32_e32 v45, v184, v45
	v_mul_f32_e32 v46, v184, v46
	v_mul_f32_e32 v47, v184, v47
	v_cvt_pk_bf16_f32 v44, v44, v45
	v_cvt_pk_bf16_f32 v45, v46, v47
	ds_write_b64 v180, v[44:45] offset:112
	v_mul_f32_e32 v16, v184, v16
	v_mul_f32_e32 v17, v184, v17
	v_mul_f32_e32 v18, v184, v18
	v_mul_f32_e32 v19, v184, v19
	v_cvt_pk_bf16_f32 v16, v16, v17
	v_cvt_pk_bf16_f32 v17, v18, v19
	ds_write_b64 v180, v[16:17] offset:128
	v_mul_f32_e32 v20, v184, v20
	v_mul_f32_e32 v21, v184, v21
	v_mul_f32_e32 v22, v184, v22
	v_mul_f32_e32 v23, v184, v23
	v_cvt_pk_bf16_f32 v20, v20, v21
	v_cvt_pk_bf16_f32 v21, v22, v23
	ds_write_b64 v180, v[20:21] offset:144
	v_mul_f32_e32 v24, v184, v24
	v_mul_f32_e32 v25, v184, v25
	v_mul_f32_e32 v26, v184, v26
	v_mul_f32_e32 v27, v184, v27
	v_cvt_pk_bf16_f32 v24, v24, v25
	v_cvt_pk_bf16_f32 v25, v26, v27
	ds_write_b64 v180, v[24:25] offset:160
	v_mul_f32_e32 v28, v184, v28
	v_mul_f32_e32 v29, v184, v29
	v_mul_f32_e32 v30, v184, v30
	v_mul_f32_e32 v31, v184, v31
	v_cvt_pk_bf16_f32 v28, v28, v29
	v_cvt_pk_bf16_f32 v29, v30, v31
	ds_write_b64 v180, v[28:29] offset:176
	v_mul_f32_e32 v0, v184, v0
	v_mul_f32_e32 v1, v184, v1
	v_mul_f32_e32 v2, v184, v2
	v_mul_f32_e32 v3, v184, v3
	v_cvt_pk_bf16_f32 v0, v0, v1
	v_cvt_pk_bf16_f32 v1, v2, v3
	ds_write_b64 v180, v[0:1] offset:192
	v_mul_f32_e32 v4, v184, v4
	v_mul_f32_e32 v5, v184, v5
	v_mul_f32_e32 v6, v184, v6
	v_mul_f32_e32 v7, v184, v7
	v_cvt_pk_bf16_f32 v4, v4, v5
	v_cvt_pk_bf16_f32 v5, v6, v7
	ds_write_b64 v180, v[4:5] offset:208
	v_mul_f32_e32 v8, v184, v8
	v_mul_f32_e32 v9, v184, v9
	v_mul_f32_e32 v10, v184, v10
	v_mul_f32_e32 v11, v184, v11
	v_cvt_pk_bf16_f32 v8, v8, v9
	v_cvt_pk_bf16_f32 v9, v10, v11
	ds_write_b64 v180, v[8:9] offset:224
	v_mul_f32_e32 v12, v184, v12
	v_mul_f32_e32 v13, v184, v13
	v_mul_f32_e32 v14, v184, v14
	v_mul_f32_e32 v15, v184, v15
	v_cvt_pk_bf16_f32 v12, v12, v13
	v_cvt_pk_bf16_f32 v13, v14, v15
	ds_write_b64 v180, v[12:13] offset:240
	s_waitcnt lgkmcnt(0)
	ds_read_b128 v[48:51], v181
	ds_read_b128 v[52:55], v181 offset:1088
	ds_read_b128 v[56:59], v181 offset:2176
	ds_read_b128 v[60:63], v181 offset:3264
	ds_read_b128 v[32:35], v181 offset:4352
	ds_read_b128 v[36:39], v181 offset:5440
	ds_read_b128 v[40:43], v181 offset:6528
	ds_read_b128 v[44:47], v181 offset:7616
	s_add_u32 s66, s64, 0x10000
	s_addc_u32 s67, s65, 0
	s_waitcnt lgkmcnt(7)
	global_store_dwordx4 v182, v[48:51], s[66:67]
	s_add_u32 s66, s64, 0x12000
	s_addc_u32 s67, s65, 0
	s_waitcnt lgkmcnt(6)
	global_store_dwordx4 v182, v[52:55], s[66:67]
	s_add_u32 s66, s64, 0x14000
	s_addc_u32 s67, s65, 0
	s_waitcnt lgkmcnt(5)
	global_store_dwordx4 v182, v[56:59], s[66:67]
	s_add_u32 s66, s64, 0x16000
	s_addc_u32 s67, s65, 0
	s_waitcnt lgkmcnt(4)
	global_store_dwordx4 v182, v[60:63], s[66:67]
	s_add_u32 s66, s64, 0x18000
	s_addc_u32 s67, s65, 0
	s_waitcnt lgkmcnt(3)
	global_store_dwordx4 v182, v[32:35], s[66:67]
	s_add_u32 s66, s64, 0x1a000
	s_addc_u32 s67, s65, 0
	s_waitcnt lgkmcnt(2)
	global_store_dwordx4 v182, v[36:39], s[66:67]
	s_add_u32 s66, s64, 0x1c000
	s_addc_u32 s67, s65, 0
	s_waitcnt lgkmcnt(1)
	global_store_dwordx4 v182, v[40:43], s[66:67]
	s_add_u32 s66, s64, 0x1e000
	s_addc_u32 s67, s65, 0
	s_waitcnt lgkmcnt(0)
	global_store_dwordx4 v182, v[44:47], s[66:67]
	v_readlane_b32 s64, v187, 0
	v_readlane_b32 s65, v187, 1
	v_readlane_b32 s66, v187, 2
	v_readlane_b32 s67, v187, 3
	v_readlane_b32 s68, v187, 4
	v_readlane_b32 s69, v187, 5
	v_readlane_b32 s70, v187, 6
	v_readlane_b32 s71, v187, 7
	v_readlane_b32 s72, v187, 8
	v_readlane_b32 s73, v187, 9
	v_readlane_b32 s74, v187, 10
	v_readlane_b32 s75, v187, 11
	v_readlane_b32 s76, v187, 12
	v_readlane_b32 s77, v187, 13
	v_readlane_b32 s78, v187, 14
	v_readlane_b32 s79, v187, 15
	s_nop 7
	s_add_i32 s30, s30, s34
	s_cmpk_lt_i32 s30, 0x200
	s_cbranch_scc0 .LBB0_1559
	s_branch .LBB0_1546

; #define MFMA32(a, b, c) __builtin_amdgcn_mfma_f32_32x32x16_bf16((a), (b), (c), 0, 0, 0)
; #define GA_LOAD(pr_) do { _Pragma("unroll") for (int i = 0; i < 4; ++i) ra[i] = *(const u32x4*)(Ab + (i * 32) * lda + (pr_) * 64); } while (0)
; #define GB_LOAD(kt_) do { const bfr* bk_ = Bb + (kt_) * NB * 32; \
;     _Pragma("unroll") for (int i = 0; i < 4; ++i) rb[i] = *(const u32x4*)(bk_ + (i * 64) * 32); } while (0)
; #define G_STORE(kt_) do { bfr* as_ = S0 + ((kt_) & 1) * GSTAGE; bfr* bs_ = as_ + 128 * 40; \
;     if (apar == ((kt_) & 1)) { _Pragma("unroll") for (int i = 0; i < 4; ++i) *(u32x4*)(as_ + asoff + i * 32 * 40) = ra[i]; } \
;     _Pragma("unroll") for (int i = 0; i < 4; ++i) *(u32x4*)(bs_ + bsoff + i * 64 * 40) = rb[i]; } while (0)
; template <int lda>
; DI void gemm_mainloop(const bfr* __restrict__ A, const bfr* __restrict__ Bt, int NB, int K, int m0, int n0, char* smem, f32x16 (&acc)[2][4]) {
;     ...
; #pragma unroll
;   for (int i = 0; i < 2; ++i)
; #pragma unroll
;     for (int j = 0; j < 4; ++j)
; #pragma unroll
;       for (int q = 0; q < 16; ++q) acc[i][j][q] = 0.f;
;   u32x4 ra[4], rb[4];
;   const int nk = K >> 5;
;   const int arow = tid >> 3, ac8 = tid & 7, apar = ac8 >> 2;
;   const bfr* Ab = A + (m0 + arow) * lda + ac8 * 8;
;   const int asoff = arow * 40 + (ac8 & 3) * 8;
;   const int brow = tid >> 2, bc4 = tid & 3;
;   const bfr* Bb = Bt + (n0 + brow) * 32 + bc4 * 8;
;   const int bsoff = brow * 40 + bc4 * 8;
;     ...
;   GA_LOAD(0);
;   GB_LOAD(0);
;   G_STORE(0);
;   GB_LOAD(1);
;   __syncthreads();
;   for (int kt = 0; kt < nk; ++kt) {
;     if (kt + 1 < nk) G_STORE(kt + 1);
;     if (kt + 2 < nk) {
;       GB_LOAD(kt + 2);
;       if ((kt & 1) == 0) GA_LOAD((kt >> 1) + 1);
;     }
;     const bfr* As = S0 + (kt & 1) * GSTAGE;
;     const bfr* Bs = As + 128 * 40;
; #pragma unroll
;     for (int ks = 0; ks < 2; ++ks) {
;       bf16x8 af[2], bfg[4];
; #pragma unroll
;       for (int i = 0; i < 2; ++i) af[i] = *(const bf16x8*)(As + (wr * 64 + i * 32 + r) * 40 + ks * 16 + hl * 8);
; #pragma unroll
;       for (int j = 0; j < 4; ++j) bfg[j] = *(const bf16x8*)(Bs + (wc * 128 + j * 32 + r) * 40 + ks * 16 + hl * 8);
; #pragma unroll
;       for (int i = 0; i < 2; ++i)
; #pragma unroll
;         for (int j = 0; j < 4; ++j) acc[i][j] = MFMA32(af[i], bfg[j], acc[i][j]);
;     }
.Lp19_nostag:
	v_mov_b32_e32 v112, 0
	v_mov_b32_e32 v113, 0
	v_mov_b32_e32 v114, 0
	v_mov_b32_e32 v115, 0
	v_mov_b32_e32 v116, 0
	v_mov_b32_e32 v117, 0
	v_mov_b32_e32 v118, 0
	v_mov_b32_e32 v119, 0
	v_mov_b32_e32 v120, 0
	v_mov_b32_e32 v121, 0
	v_mov_b32_e32 v122, 0
	v_mov_b32_e32 v123, 0
	v_mov_b32_e32 v124, 0
	v_mov_b32_e32 v125, 0
	v_mov_b32_e32 v126, 0
	v_mov_b32_e32 v127, 0
	v_mov_b32_e32 v96, 0
	v_mov_b32_e32 v97, 0
	v_mov_b32_e32 v98, 0
	v_mov_b32_e32 v99, 0
	v_mov_b32_e32 v100, 0
	v_mov_b32_e32 v101, 0
	v_mov_b32_e32 v102, 0
	v_mov_b32_e32 v103, 0
	v_mov_b32_e32 v104, 0
	v_mov_b32_e32 v105, 0
	v_mov_b32_e32 v106, 0
	v_mov_b32_e32 v107, 0
	v_mov_b32_e32 v108, 0
	v_mov_b32_e32 v109, 0
	v_mov_b32_e32 v110, 0
	v_mov_b32_e32 v111, 0
	v_mov_b32_e32 v80, 0
	v_mov_b32_e32 v81, 0
	v_mov_b32_e32 v82, 0
	v_mov_b32_e32 v83, 0
	v_mov_b32_e32 v84, 0
	v_mov_b32_e32 v85, 0
	v_mov_b32_e32 v86, 0
	v_mov_b32_e32 v87, 0
	v_mov_b32_e32 v88, 0
	v_mov_b32_e32 v89, 0
	v_mov_b32_e32 v90, 0
	v_mov_b32_e32 v91, 0
	v_mov_b32_e32 v92, 0
	v_mov_b32_e32 v93, 0
	v_mov_b32_e32 v94, 0
	v_mov_b32_e32 v95, 0
	v_mov_b32_e32 v64, 0
	v_mov_b32_e32 v65, 0
	v_mov_b32_e32 v66, 0
	v_mov_b32_e32 v67, 0
	v_mov_b32_e32 v68, 0
	v_mov_b32_e32 v69, 0
	v_mov_b32_e32 v70, 0
	v_mov_b32_e32 v71, 0
	v_mov_b32_e32 v72, 0
	v_mov_b32_e32 v73, 0
	v_mov_b32_e32 v74, 0
	v_mov_b32_e32 v75, 0
	v_mov_b32_e32 v76, 0
	v_mov_b32_e32 v77, 0
	v_mov_b32_e32 v78, 0
	v_mov_b32_e32 v79, 0
	v_mov_b32_e32 v48, 0
	v_mov_b32_e32 v49, 0
	v_mov_b32_e32 v50, 0
	v_mov_b32_e32 v51, 0
	v_mov_b32_e32 v52, 0
	v_mov_b32_e32 v53, 0
	v_mov_b32_e32 v54, 0
	v_mov_b32_e32 v55, 0
	v_mov_b32_e32 v56, 0
	v_mov_b32_e32 v57, 0
	v_mov_b32_e32 v58, 0
	v_mov_b32_e32 v59, 0
	v_mov_b32_e32 v60, 0
	v_mov_b32_e32 v61, 0
	v_mov_b32_e32 v62, 0
	v_mov_b32_e32 v63, 0
	v_mov_b32_e32 v32, 0
	v_mov_b32_e32 v33, 0
	v_mov_b32_e32 v34, 0
	v_mov_b32_e32 v35, 0
	v_mov_b32_e32 v36, 0
	v_mov_b32_e32 v37, 0
	v_mov_b32_e32 v38, 0
	v_mov_b32_e32 v39, 0
	v_mov_b32_e32 v40, 0
	v_mov_b32_e32 v41, 0
	v_mov_b32_e32 v42, 0
	v_mov_b32_e32 v43, 0
	v_mov_b32_e32 v44, 0
	v_mov_b32_e32 v45, 0
	v_mov_b32_e32 v46, 0
	v_mov_b32_e32 v47, 0
	v_mov_b32_e32 v16, 0
	v_mov_b32_e32 v17, 0
	v_mov_b32_e32 v18, 0
	v_mov_b32_e32 v19, 0
	v_mov_b32_e32 v20, 0
	v_mov_b32_e32 v21, 0
	v_mov_b32_e32 v22, 0
	v_mov_b32_e32 v23, 0
	v_mov_b32_e32 v24, 0
	v_mov_b32_e32 v25, 0
	v_mov_b32_e32 v26, 0
	v_mov_b32_e32 v27, 0
	v_mov_b32_e32 v28, 0
	v_mov_b32_e32 v29, 0
	v_mov_b32_e32 v30, 0
	v_mov_b32_e32 v31, 0
	v_mov_b32_e32 v0, 0
	v_mov_b32_e32 v1, 0
	v_mov_b32_e32 v2, 0
	v_mov_b32_e32 v3, 0
	v_mov_b32_e32 v4, 0
	v_mov_b32_e32 v5, 0
	v_mov_b32_e32 v6, 0
	v_mov_b32_e32 v7, 0
	v_mov_b32_e32 v8, 0
	v_mov_b32_e32 v9, 0
	v_mov_b32_e32 v10, 0
	v_mov_b32_e32 v11, 0
	v_mov_b32_e32 v12, 0
	v_mov_b32_e32 v13, 0
	v_mov_b32_e32 v14, 0
	v_mov_b32_e32 v15, 0
	s_waitcnt vmcnt(6)
	s_barrier
	s_mul_i32 s74, s71, 0x6000
	s_add_u32 s75, s74, 0x2000
	s_cmp_eq_u32 s71, 2
	s_cselect_b32 s75, 0x10000, s75
	v_add_u32_e32 v205, s74, v192
	v_add_u32_e32 v207, s75, v194
	v_add_u32_e32 v206, s74, v193
	v_add_u32_e32 v208, s75, v204
	s_add_u32 s71, s71, 1
	s_cmp_eq_u32 s71, 3
	s_cselect_b32 s71, 0, s71
	ds_read_b128 v[128:131], v205
	ds_read_b128 v[144:147], v207
	ds_read_b128 v[148:151], v207 offset:2048
	ds_read_b128 v[152:155], v207 offset:4096
	ds_read_b128 v[156:159], v207 offset:6144
	ds_read_b128 v[132:135], v205 offset:2048
	ds_read_b128 v[136:139], v206
	ds_read_b128 v[160:163], v208
	ds_read_b128 v[164:167], v208 offset:2048
	ds_read_b128 v[168:171], v208 offset:4096
	ds_read_b128 v[172:175], v208 offset:6144
	ds_read_b128 v[140:143], v206 offset:2048
	s_waitcnt lgkmcnt(10)
	v_mfma_f32_32x32x16_bf16 v[112:127], v[144:147], v[128:131], v[112:127]
	s_mul_i32 s74, s70, 0x6000
	s_add_u32 s75, s74, s68
	s_mov_b32 m0, s75
	s_add_u32 s76, s74, 0x2000
	s_cmp_eq_u32 s70, 2
	s_cselect_b32 s76, 0x10000, s76
	global_load_lds_dwordx4 v180, s[64:65]
	s_waitcnt lgkmcnt(9)
	v_mfma_f32_32x32x16_bf16 v[96:111], v[148:151], v[128:131], v[96:111]
	s_add_u32 m0, s75, 0x400
	s_add_u32 s76, s76, s69
	global_load_lds_dwordx4 v182, s[64:65]
	s_waitcnt lgkmcnt(8)
	v_mfma_f32_32x32x16_bf16 v[80:95], v[152:155], v[128:131], v[80:95]
	s_mov_b32 m0, s76
	s_add_u32 s64, s64, 64
	s_addc_u32 s65, s65, 0
	global_load_lds_dwordx4 v183, s[66:67]
	s_waitcnt lgkmcnt(7)
	v_mfma_f32_32x32x16_bf16 v[64:79], v[156:159], v[128:131], v[64:79]
	global_load_lds_dwordx4 v183, s[66:67] offset:1024
	s_waitcnt lgkmcnt(6)
	v_mfma_f32_32x32x16_bf16 v[48:63], v[144:147], v[132:135], v[48:63]
	global_load_lds_dwordx4 v183, s[66:67] offset:2048
	v_mfma_f32_32x32x16_bf16 v[32:47], v[148:151], v[132:135], v[32:47]
	global_load_lds_dwordx4 v183, s[66:67] offset:3072
	s_add_u32 s66, s66, 0x10000
	s_addc_u32 s67, s67, 0
	v_mfma_f32_32x32x16_bf16 v[16:31], v[152:155], v[132:135], v[16:31]
	s_add_u32 s70, s70, 1
	s_cmp_eq_u32 s70, 3
	s_cselect_b32 s70, 0, s70
	v_mfma_f32_32x32x16_bf16 v[0:15], v[156:159], v[132:135], v[0:15]
; #define MFMA32(a, b, c) __builtin_amdgcn_mfma_f32_32x32x16_bf16((a), (b), (c), 0, 0, 0)
; #define GA_LOAD(pr_) do { _Pragma("unroll") for (int i = 0; i < 4; ++i) ra[i] = *(const u32x4*)(Ab + (i * 32) * lda + (pr_) * 64); } while (0)
; #define GB_LOAD(kt_) do { const bfr* bk_ = Bb + (kt_) * NB * 32; \
;     _Pragma("unroll") for (int i = 0; i < 4; ++i) rb[i] = *(const u32x4*)(bk_ + (i * 64) * 32); } while (0)
; #define G_STORE(kt_) do { bfr* as_ = S0 + ((kt_) & 1) * GSTAGE; bfr* bs_ = as_ + 128 * 40; \
;     if (apar == ((kt_) & 1)) { _Pragma("unroll") for (int i = 0; i < 4; ++i) *(u32x4*)(as_ + asoff + i * 32 * 40) = ra[i]; } \
;     _Pragma("unroll") for (int i = 0; i < 4; ++i) *(u32x4*)(bs_ + bsoff + i * 64 * 40) = rb[i]; } while (0)
; template <int lda>
; DI void gemm_mainloop(const bfr* __restrict__ A, const bfr* __restrict__ Bt, int NB, int K, int m0, int n0, char* smem, f32x16 (&acc)[2][4]) {
;     ...
;   for (int kt = 0; kt < nk; ++kt) {
;     if (kt + 1 < nk) G_STORE(kt + 1);
;     if (kt + 2 < nk) {
;       GB_LOAD(kt + 2);
;       if ((kt & 1) == 0) GA_LOAD((kt >> 1) + 1);
;     }
;     const bfr* As = S0 + (kt & 1) * GSTAGE;
;     const bfr* Bs = As + 128 * 40;
; #pragma unroll
;     for (int ks = 0; ks < 2; ++ks) {
;       bf16x8 af[2], bfg[4];
; #pragma unroll
;       for (int i = 0; i < 2; ++i) af[i] = *(const bf16x8*)(As + (wr * 64 + i * 32 + r) * 40 + ks * 16 + hl * 8);
; #pragma unroll
;       for (int j = 0; j < 4; ++j) bfg[j] = *(const bf16x8*)(Bs + (wc * 128 + j * 32 + r) * 40 + ks * 16 + hl * 8);
; #pragma unroll
;       for (int i = 0; i < 2; ++i)
; #pragma unroll
;         for (int j = 0; j < 4; ++j) acc[i][j] = MFMA32(af[i], bfg[j], acc[i][j]);
;     }
;     __syncthreads();
.Lp19_loop:
	s_waitcnt vmcnt(6) lgkmcnt(0)
	s_barrier
	s_mul_i32 s74, s71, 0x6000
	s_add_u32 s75, s74, 0x2000
	s_cmp_eq_u32 s71, 2
	s_cselect_b32 s75, 0x10000, s75
	v_add_u32_e32 v205, s74, v192
	v_add_u32_e32 v207, s75, v194
	v_add_u32_e32 v206, s74, v193
	v_add_u32_e32 v208, s75, v204
	s_add_u32 s71, s71, 1
	s_cmp_eq_u32 s71, 3
	s_cselect_b32 s71, 0, s71
	ds_read_b128 v[128:131], v205
	ds_read_b128 v[144:147], v207
	ds_read_b128 v[148:151], v207 offset:2048
	ds_read_b128 v[152:155], v207 offset:4096
	ds_read_b128 v[156:159], v207 offset:6144
	ds_read_b128 v[132:135], v205 offset:2048
	v_mfma_f32_32x32x16_bf16 v[112:127], v[160:163], v[136:139], v[112:127]
	s_mul_i32 s74, s70, 0x6000
	s_add_u32 s75, s74, s68
	s_mov_b32 m0, s75
	s_add_u32 s76, s74, 0x2000
	s_cmp_eq_u32 s70, 2
	s_cselect_b32 s76, 0x10000, s76
	global_load_lds_dwordx4 v180, s[64:65]
	v_mfma_f32_32x32x16_bf16 v[96:111], v[164:167], v[136:139], v[96:111]
	s_add_u32 m0, s75, 0x400
	s_add_u32 s76, s76, s69
	global_load_lds_dwordx4 v182, s[64:65]
	v_mfma_f32_32x32x16_bf16 v[80:95], v[168:171], v[136:139], v[80:95]
	s_mov_b32 m0, s76
	s_add_u32 s64, s64, 64
	s_addc_u32 s65, s65, 0
	global_load_lds_dwordx4 v183, s[66:67]
	v_mfma_f32_32x32x16_bf16 v[64:79], v[172:175], v[136:139], v[64:79]
	global_load_lds_dwordx4 v183, s[66:67] offset:1024
	v_mfma_f32_32x32x16_bf16 v[48:63], v[160:163], v[140:143], v[48:63]
	global_load_lds_dwordx4 v183, s[66:67] offset:2048
	v_mfma_f32_32x32x16_bf16 v[32:47], v[164:167], v[140:143], v[32:47]
	global_load_lds_dwordx4 v183, s[66:67] offset:3072
	s_add_u32 s66, s66, 0x10000
	s_addc_u32 s67, s67, 0
	v_mfma_f32_32x32x16_bf16 v[16:31], v[168:171], v[140:143], v[16:31]
	s_add_u32 s70, s70, 1
	s_cmp_eq_u32 s70, 3
	s_cselect_b32 s70, 0, s70
	v_mfma_f32_32x32x16_bf16 v[0:15], v[172:175], v[140:143], v[0:15]
	ds_read_b128 v[136:139], v206
	ds_read_b128 v[160:163], v208
	ds_read_b128 v[164:167], v208 offset:2048
	ds_read_b128 v[168:171], v208 offset:4096
	ds_read_b128 v[172:175], v208 offset:6144
	ds_read_b128 v[140:143], v206 offset:2048
	s_waitcnt lgkmcnt(10)
	v_mfma_f32_32x32x16_bf16 v[112:127], v[144:147], v[128:131], v[112:127]
	s_waitcnt lgkmcnt(9)
	v_mfma_f32_32x32x16_bf16 v[96:111], v[148:151], v[128:131], v[96:111]
	s_waitcnt lgkmcnt(8)
	v_mfma_f32_32x32x16_bf16 v[80:95], v[152:155], v[128:131], v[80:95]
	s_waitcnt lgkmcnt(7)
	v_mfma_f32_32x32x16_bf16 v[64:79], v[156:159], v[128:131], v[64:79]
	s_waitcnt lgkmcnt(6)
	v_mfma_f32_32x32x16_bf16 v[48:63], v[144:147], v[132:135], v[48:63]
	v_mfma_f32_32x32x16_bf16 v[32:47], v[148:151], v[132:135], v[32:47]
	v_mfma_f32_32x32x16_bf16 v[16:31], v[152:155], v[132:135], v[16:31]
	v_mfma_f32_32x32x16_bf16 v[0:15], v[156:159], v[132:135], v[0:15]
	s_add_u32 s72, s72, 1
	s_cmp_lt_u32 s72, 29
	s_cbranch_scc1 .Lp19_loop
	s_waitcnt vmcnt(6) lgkmcnt(0)
	s_barrier
	s_mul_i32 s74, s71, 0x6000
	s_add_u32 s75, s74, 0x2000
	s_cmp_eq_u32 s71, 2
	s_cselect_b32 s75, 0x10000, s75
	v_add_u32_e32 v205, s74, v192
	v_add_u32_e32 v207, s75, v194
	v_add_u32_e32 v206, s74, v193
	v_add_u32_e32 v208, s75, v204
	s_add_u32 s71, s71, 1
	s_cmp_eq_u32 s71, 3
	s_cselect_b32 s71, 0, s71
	ds_read_b128 v[128:131], v205
	ds_read_b128 v[144:147], v207
	ds_read_b128 v[148:151], v207 offset:2048
	ds_read_b128 v[152:155], v207 offset:4096
	ds_read_b128 v[156:159], v207 offset:6144
	ds_read_b128 v[132:135], v205 offset:2048
	v_mfma_f32_32x32x16_bf16 v[112:127], v[160:163], v[136:139], v[112:127]
	v_mfma_f32_32x32x16_bf16 v[96:111], v[164:167], v[136:139], v[96:111]
	v_mfma_f32_32x32x16_bf16 v[80:95], v[168:171], v[136:139], v[80:95]
	v_mfma_f32_32x32x16_bf16 v[64:79], v[172:175], v[136:139], v[64:79]
	v_mfma_f32_32x32x16_bf16 v[48:63], v[160:163], v[140:143], v[48:63]
	v_mfma_f32_32x32x16_bf16 v[32:47], v[164:167], v[140:143], v[32:47]
	v_mfma_f32_32x32x16_bf16 v[16:31], v[168:171], v[140:143], v[16:31]
	v_mfma_f32_32x32x16_bf16 v[0:15], v[172:175], v[140:143], v[0:15]
	ds_read_b128 v[136:139], v206
	ds_read_b128 v[160:163], v208
	ds_read_b128 v[164:167], v208 offset:2048
	ds_read_b128 v[168:171], v208 offset:4096
	ds_read_b128 v[172:175], v208 offset:6144
	ds_read_b128 v[140:143], v206 offset:2048
	s_waitcnt lgkmcnt(10)
	v_mfma_f32_32x32x16_bf16 v[112:127], v[144:147], v[128:131], v[112:127]
	s_waitcnt lgkmcnt(9)
	v_mfma_f32_32x32x16_bf16 v[96:111], v[148:151], v[128:131], v[96:111]
	s_waitcnt lgkmcnt(8)
	v_mfma_f32_32x32x16_bf16 v[80:95], v[152:155], v[128:131], v[80:95]
	s_waitcnt lgkmcnt(7)
	v_mfma_f32_32x32x16_bf16 v[64:79], v[156:159], v[128:131], v[64:79]
	s_waitcnt lgkmcnt(6)
	v_mfma_f32_32x32x16_bf16 v[48:63], v[144:147], v[132:135], v[48:63]
	v_mfma_f32_32x32x16_bf16 v[32:47], v[148:151], v[132:135], v[32:47]
	v_mfma_f32_32x32x16_bf16 v[16:31], v[152:155], v[132:135], v[16:31]
	v_mfma_f32_32x32x16_bf16 v[0:15], v[156:159], v[132:135], v[0:15]
	s_waitcnt vmcnt(0) lgkmcnt(0)
	s_barrier
; #define MFMA32(a, b, c) __builtin_amdgcn_mfma_f32_32x32x16_bf16((a), (b), (c), 0, 0, 0)
; #define GA_LOAD(pr_) do { _Pragma("unroll") for (int i = 0; i < 4; ++i) ra[i] = *(const u32x4*)(Ab + (i * 32) * lda + (pr_) * 64); } while (0)
; #define GB_LOAD(kt_) do { const bfr* bk_ = Bb + (kt_) * NB * 32; \
;     _Pragma("unroll") for (int i = 0; i < 4; ++i) rb[i] = *(const u32x4*)(bk_ + (i * 64) * 32); } while (0)
; template <int lda>
; DI void gemm_mainloop(const bfr* __restrict__ A, const bfr* __restrict__ Bt, int NB, int K, int m0, int n0, char* smem, f32x16 (&acc)[2][4]) {
;     ...
;   for (int kt = 0; kt < nk; ++kt) {
;     if (kt + 1 < nk) G_STORE(kt + 1);
;     if (kt + 2 < nk) {
;       GB_LOAD(kt + 2);
;       if ((kt & 1) == 0) GA_LOAD((kt >> 1) + 1);
;     }
;     const bfr* As = S0 + (kt & 1) * GSTAGE;
;     const bfr* Bs = As + 128 * 40;
; #pragma unroll
;     for (int ks = 0; ks < 2; ++ks) {
;       bf16x8 af[2], bfg[4];
; #pragma unroll
;       for (int i = 0; i < 2; ++i) af[i] = *(const bf16x8*)(As + (wr * 64 + i * 32 + r) * 40 + ks * 16 + hl * 8);
; #pragma unroll
;       for (int j = 0; j < 4; ++j) bfg[j] = *(const bf16x8*)(Bs + (wc * 128 + j * 32 + r) * 40 + ks * 16 + hl * 8);
; #pragma unroll
;       for (int i = 0; i < 2; ++i)
; #pragma unroll
;         for (int j = 0; j < 4; ++j) acc[i][j] = MFMA32(af[i], bfg[j], acc[i][j]);
;     }
; template <bool FIRST, bool HAS_H>
; DI void phase_gemm_resid(const Params& p, const bfr* A, const bfr* Wt, const float* gnext, float* ss, char* smem) {
;     ...
;   for (int t0 = blockIdx.x; t0 < 128 * 4; t0 += gridDim.x) {
;     const int t = ((gridDim.x & 7) == 0) ? xcd_tile(t0, 4) : t0;
;     const int mt = t >> 2, nt = t & 3, m0 = mt * 128, n0 = nt * 256;
;     f32x16 acc[2][4];
;     gemm_mainloop<1024>(A, Wt, 1024, 1024, m0, n0, smem, acc);
;     int tid2 = threadIdx.x;
;     asm volatile("" : "+v"(tid2));
;     const int lane = tid2 & 63, wid = tid2 >> 6, wr = wid >> 1, wc = wid & 1, r = lane & 31, hl = lane >> 5;
;     const float* xsrc = FIRST ? p.x_prompt : X;
;     const int rbase = m0 + wr * 64 + 4 * hl, cbase = n0 + wc * 128 + r;
	s_mul_i32 s74, s71, 0x6000
	s_add_u32 s75, s74, 0x2000
	s_cmp_eq_u32 s71, 2
	s_cselect_b32 s75, 0x10000, s75
	v_add_u32_e32 v205, s74, v192
	v_add_u32_e32 v207, s75, v194
	v_add_u32_e32 v206, s74, v193
	v_add_u32_e32 v208, s75, v204
	s_add_u32 s71, s71, 1
	s_cmp_eq_u32 s71, 3
	s_cselect_b32 s71, 0, s71
	ds_read_b128 v[128:131], v205
	ds_read_b128 v[144:147], v207
	ds_read_b128 v[148:151], v207 offset:2048
	ds_read_b128 v[152:155], v207 offset:4096
	ds_read_b128 v[156:159], v207 offset:6144
	ds_read_b128 v[132:135], v205 offset:2048
	v_mfma_f32_32x32x16_bf16 v[112:127], v[160:163], v[136:139], v[112:127]
	v_mfma_f32_32x32x16_bf16 v[96:111], v[164:167], v[136:139], v[96:111]
	v_mfma_f32_32x32x16_bf16 v[80:95], v[168:171], v[136:139], v[80:95]
	v_mfma_f32_32x32x16_bf16 v[64:79], v[172:175], v[136:139], v[64:79]
	v_mfma_f32_32x32x16_bf16 v[48:63], v[160:163], v[140:143], v[48:63]
	v_mfma_f32_32x32x16_bf16 v[32:47], v[164:167], v[140:143], v[32:47]
	v_mfma_f32_32x32x16_bf16 v[16:31], v[168:171], v[140:143], v[16:31]
	v_mfma_f32_32x32x16_bf16 v[0:15], v[172:175], v[140:143], v[0:15]
	ds_read_b128 v[136:139], v206
	ds_read_b128 v[160:163], v208
	ds_read_b128 v[164:167], v208 offset:2048
	ds_read_b128 v[168:171], v208 offset:4096
	ds_read_b128 v[172:175], v208 offset:6144
	ds_read_b128 v[140:143], v206 offset:2048
	s_waitcnt lgkmcnt(10)
	v_mfma_f32_32x32x16_bf16 v[112:127], v[144:147], v[128:131], v[112:127]
	s_waitcnt lgkmcnt(9)
	v_mfma_f32_32x32x16_bf16 v[96:111], v[148:151], v[128:131], v[96:111]
	s_waitcnt lgkmcnt(8)
	v_mfma_f32_32x32x16_bf16 v[80:95], v[152:155], v[128:131], v[80:95]
	s_waitcnt lgkmcnt(7)
	v_mfma_f32_32x32x16_bf16 v[64:79], v[156:159], v[128:131], v[64:79]
	s_waitcnt lgkmcnt(6)
	v_mfma_f32_32x32x16_bf16 v[48:63], v[144:147], v[132:135], v[48:63]
	v_mfma_f32_32x32x16_bf16 v[32:47], v[148:151], v[132:135], v[32:47]
	v_mfma_f32_32x32x16_bf16 v[16:31], v[152:155], v[132:135], v[16:31]
	v_mfma_f32_32x32x16_bf16 v[0:15], v[156:159], v[132:135], v[0:15]
	s_waitcnt lgkmcnt(0)
	v_mfma_f32_32x32x16_bf16 v[112:127], v[160:163], v[136:139], v[112:127]
	v_mfma_f32_32x32x16_bf16 v[96:111], v[164:167], v[136:139], v[96:111]
	v_mfma_f32_32x32x16_bf16 v[80:95], v[168:171], v[136:139], v[80:95]
	v_mfma_f32_32x32x16_bf16 v[64:79], v[172:175], v[136:139], v[64:79]
	v_mfma_f32_32x32x16_bf16 v[48:63], v[160:163], v[140:143], v[48:63]
	v_mfma_f32_32x32x16_bf16 v[32:47], v[164:167], v[140:143], v[32:47]
	v_mfma_f32_32x32x16_bf16 v[16:31], v[168:171], v[140:143], v[16:31]
	v_mfma_f32_32x32x16_bf16 v[0:15], v[172:175], v[140:143], v[0:15]
	s_nop 7
	s_nop 3
	s_load_dwordx2 s[64:65], s[92:93], 0x100
	s_load_dwordx2 s[66:67], s[92:93], 0x100
	s_mul_i32 s76, s73, 8704
	s_lshr_b32 s74, s73, 1
	s_lshl_b32 s74, s74, 6
	s_add_u32 s74, s74, s77
	s_and_b32 s75, s73, 1
	s_lshl_b32 s75, s75, 7
	s_add_u32 s75, s75, s78
	v_and_b32_e32 v210, 31, v196
	v_bfe_u32 v211, v196, 5, 1
	v_mul_u32_u24_e32 v212, 272, v210
	v_add_u32_e32 v212, s76, v212
	v_lshl_add_u32 v180, v211, 4, v212
	v_lshl_add_u32 v182, v211, 3, v212
	v_lshlrev_b32_e32 v212, 2, v211
	v_add_lshl_u32 v204, v212, s75, 2
	v_add_lshl_u32 v207, v210, s74, 2
	v_and_b32_e32 v212, 63, v196
	v_xor_b32_e32 v212, 32, v212
	v_lshlrev_b32_e32 v208, 2, v212
	v_bfe_u32 v210, v196, 4, 2
	v_and_b32_e32 v211, 15, v196
	v_mul_u32_u24_e32 v212, 272, v210
	v_lshl_add_u32 v212, v211, 4, v212
	v_add_u32_e32 v183, s76, v212
	v_add_u32_e32 v212, s74, v210
	v_lshlrev_b32_e32 v212, 10, v212
	v_lshl_add_u32 v212, v211, 2, v212
	v_add_lshl_u32 v193, v212, s75, 2
	s_mov_b32 s79, s74
	s_mov_b32 s72, s75
	s_waitcnt lgkmcnt(0)
	s_add_u32 s74, s64, 0x0
	s_addc_u32 s75, s65, 0
	global_load_dwordx4 v[128:131], v193, s[74:75]
	s_add_u32 s74, s64, 0x4000
	s_addc_u32 s75, s65, 0
	global_load_dwordx4 v[132:135], v193, s[74:75]
	s_add_u32 s74, s64, 0x8000
	s_addc_u32 s75, s65, 0
	global_load_dwordx4 v[136:139], v193, s[74:75]
	s_add_u32 s74, s64, 0xc000
	s_addc_u32 s75, s65, 0
	global_load_dwordx4 v[140:143], v193, s[74:75]
	s_add_u32 s74, s64, 0x10000
	s_addc_u32 s75, s65, 0
	global_load_dwordx4 v[144:147], v193, s[74:75]
	s_add_u32 s74, s64, 0x14000
	s_addc_u32 s75, s65, 0
	global_load_dwordx4 v[148:151], v193, s[74:75]
	s_add_u32 s74, s64, 0x18000
	s_addc_u32 s75, s65, 0
	global_load_dwordx4 v[152:155], v193, s[74:75]
	s_add_u32 s74, s64, 0x1c000
	s_addc_u32 s75, s65, 0
	global_load_dwordx4 v[156:159], v193, s[74:75]
	s_mov_b32 s74, s79
	s_mov_b32 s75, s72
	v_bfe_u32 v210, v196, 3, 3
	v_and_b32_e32 v211, 7, v196
	v_mul_u32_u24_e32 v212, 272, v210
	v_lshl_add_u32 v212, v211, 4, v212
	v_add_u32_e32 v192, s76, v212
	v_add_u32_e32 v212, s74, v210
	v_lshlrev_b32_e32 v212, 10, v212
	v_lshl_add_u32 v212, v211, 3, v212
	v_add_lshl_u32 v194, v212, s75, 1
	v_mov_b32_e32 v205, 0
	v_mov_b32_e32 v206, 0
	s_waitcnt lgkmcnt(0)
	s_barrier
; DI bfr f2bf(float a) { return (bfr)(pack2(a, 0.f) & 0xffffu); }
; DI int crow(int reg, int h) { return (reg & 3) + 8 * (reg >> 2) + 4 * h; }
; template <bool FIRST, bool HAS_H>
; DI void phase_gemm_resid(const Params& p, const bfr* A, const bfr* Wt, const float* gnext, float* ss, char* smem) {
;     ...
; #pragma unroll
;     for (int i = 0; i < 2; ++i) {
; #pragma unroll
;       for (int qh = 0; qh < 2; ++qh) {
;         float rs[8];
; #pragma unroll
;         for (int q = 0; q < 8; ++q) rs[q] = 0.f;
; #pragma unroll
;         for (int jh = 0; jh < 2; ++jh) {
;           float xo[2][8];
; #pragma unroll
;           for (int jj = 0; jj < 2; ++jj)
; #pragma unroll
;             for (int q = 0; q < 8; ++q)
;               xo[jj][q] = xsrc[(rbase + i * 32 + crow(qh * 8 + q, 0)) * 1024 + cbase + (jh * 2 + jj) * 32];
; #pragma unroll
;           for (int q = 0; q < 8; ++q) {
;             const int o = (rbase + i * 32 + crow(qh * 8 + q, 0)) * 1024 + cbase;
; #pragma unroll
;             for (int jj = 0; jj < 2; ++jj) {
;               const int j = jh * 2 + jj;
;               const float xn = xo[jj][q] + acc[i][j][qh * 8 + q];
;               X[o + j * 32] = xn;
;               if (HAS_H) Hn[o + j * 32] = f2bf(xn * gnext[cbase + j * 32]);
;               rs[q] += xn * xn;
;             }
;           }
;         }
	s_waitcnt vmcnt(7)
	ds_write_b128 v183, v[128:131]
	s_waitcnt vmcnt(6)
	ds_write_b128 v183, v[132:135] offset:1088
	s_waitcnt vmcnt(5)
	ds_write_b128 v183, v[136:139] offset:2176
	s_waitcnt vmcnt(4)
	ds_write_b128 v183, v[140:143] offset:3264
	s_waitcnt vmcnt(3)
	ds_write_b128 v183, v[144:147] offset:4352
	s_waitcnt vmcnt(2)
	ds_write_b128 v183, v[148:151] offset:5440
	s_waitcnt vmcnt(1)
	ds_write_b128 v183, v[152:155] offset:6528
	s_waitcnt vmcnt(0)
	ds_write_b128 v183, v[156:159] offset:7616
	s_add_u32 s74, s64, 0x100
	s_addc_u32 s75, s65, 0
	global_load_dwordx4 v[128:131], v193, s[74:75]
	s_add_u32 s74, s64, 0x4100
	s_addc_u32 s75, s65, 0
	global_load_dwordx4 v[132:135], v193, s[74:75]
	s_add_u32 s74, s64, 0x8100
	s_addc_u32 s75, s65, 0
	global_load_dwordx4 v[136:139], v193, s[74:75]
	s_add_u32 s74, s64, 0xc100
	s_addc_u32 s75, s65, 0
	global_load_dwordx4 v[140:143], v193, s[74:75]
	s_add_u32 s74, s64, 0x10100
	s_addc_u32 s75, s65, 0
	global_load_dwordx4 v[144:147], v193, s[74:75]
	s_add_u32 s74, s64, 0x14100
	s_addc_u32 s75, s65, 0
	global_load_dwordx4 v[148:151], v193, s[74:75]
	s_add_u32 s74, s64, 0x18100
	s_addc_u32 s75, s65, 0
	global_load_dwordx4 v[152:155], v193, s[74:75]
	s_add_u32 s74, s64, 0x1c100
	s_addc_u32 s75, s65, 0
	global_load_dwordx4 v[156:159], v193, s[74:75]
	ds_read_b128 v[160:163], v180
	ds_read_b128 v[164:167], v180 offset:32
	ds_read_b128 v[168:171], v180 offset:64
	ds_read_b128 v[172:175], v180 offset:96
	ds_read_b128 v[176:179], v180 offset:128
	ds_read_b128 v[184:187], v180 offset:160
	ds_read_b128 v[188:191], v180 offset:192
	ds_read_b128 v[200:203], v180 offset:224
	s_waitcnt lgkmcnt(7)
	v_add_f32_e32 v112, v160, v112
	v_add_f32_e32 v113, v161, v113
	v_add_f32_e32 v114, v162, v114
	v_add_f32_e32 v115, v163, v115
	v_fmac_f32_e32 v205, v112, v112
	v_fmac_f32_e32 v205, v113, v113
	v_fmac_f32_e32 v205, v114, v114
	v_fmac_f32_e32 v205, v115, v115
	ds_write_b128 v180, v[112:115]
	s_waitcnt lgkmcnt(7)
	v_add_f32_e32 v116, v164, v116
	v_add_f32_e32 v117, v165, v117
	v_add_f32_e32 v118, v166, v118
	v_add_f32_e32 v119, v167, v119
	v_fmac_f32_e32 v205, v116, v116
	v_fmac_f32_e32 v205, v117, v117
	v_fmac_f32_e32 v205, v118, v118
	v_fmac_f32_e32 v205, v119, v119
	ds_write_b128 v180, v[116:119] offset:32
	s_waitcnt lgkmcnt(7)
	v_add_f32_e32 v120, v168, v120
	v_add_f32_e32 v121, v169, v121
	v_add_f32_e32 v122, v170, v122
	v_add_f32_e32 v123, v171, v123
	v_fmac_f32_e32 v205, v120, v120
	v_fmac_f32_e32 v205, v121, v121
	v_fmac_f32_e32 v205, v122, v122
	v_fmac_f32_e32 v205, v123, v123
	ds_write_b128 v180, v[120:123] offset:64
	s_waitcnt lgkmcnt(7)
	v_add_f32_e32 v124, v172, v124
	v_add_f32_e32 v125, v173, v125
	v_add_f32_e32 v126, v174, v126
	v_add_f32_e32 v127, v175, v127
	v_fmac_f32_e32 v205, v124, v124
	v_fmac_f32_e32 v205, v125, v125
	v_fmac_f32_e32 v205, v126, v126
	v_fmac_f32_e32 v205, v127, v127
	ds_write_b128 v180, v[124:127] offset:96
	s_waitcnt lgkmcnt(7)
	v_add_f32_e32 v96, v176, v96
	v_add_f32_e32 v97, v177, v97
	v_add_f32_e32 v98, v178, v98
	v_add_f32_e32 v99, v179, v99
	v_fmac_f32_e32 v205, v96, v96
	v_fmac_f32_e32 v205, v97, v97
	v_fmac_f32_e32 v205, v98, v98
	v_fmac_f32_e32 v205, v99, v99
	ds_write_b128 v180, v[96:99] offset:128
	s_waitcnt lgkmcnt(7)
	v_add_f32_e32 v100, v184, v100
	v_add_f32_e32 v101, v185, v101
	v_add_f32_e32 v102, v186, v102
	v_add_f32_e32 v103, v187, v103
	v_fmac_f32_e32 v205, v100, v100
	v_fmac_f32_e32 v205, v101, v101
	v_fmac_f32_e32 v205, v102, v102
	v_fmac_f32_e32 v205, v103, v103
	ds_write_b128 v180, v[100:103] offset:160
	s_waitcnt lgkmcnt(7)
	v_add_f32_e32 v104, v188, v104
	v_add_f32_e32 v105, v189, v105
	v_add_f32_e32 v106, v190, v106
	v_add_f32_e32 v107, v191, v107
	v_fmac_f32_e32 v205, v104, v104
	v_fmac_f32_e32 v205, v105, v105
	v_fmac_f32_e32 v205, v106, v106
	v_fmac_f32_e32 v205, v107, v107
	ds_write_b128 v180, v[104:107] offset:192
	s_waitcnt lgkmcnt(7)
	v_add_f32_e32 v108, v200, v108
	v_add_f32_e32 v109, v201, v109
	v_add_f32_e32 v110, v202, v110
	v_add_f32_e32 v111, v203, v111
	v_fmac_f32_e32 v205, v108, v108
	v_fmac_f32_e32 v205, v109, v109
	v_fmac_f32_e32 v205, v110, v110
	v_fmac_f32_e32 v205, v111, v111
	ds_write_b128 v180, v[108:111] offset:224
	ds_read_b128 v[160:163], v183
	ds_read_b128 v[164:167], v183 offset:1088
	ds_read_b128 v[168:171], v183 offset:2176
	ds_read_b128 v[172:175], v183 offset:3264
	ds_read_b128 v[176:179], v183 offset:4352
	ds_read_b128 v[184:187], v183 offset:5440
	ds_read_b128 v[188:191], v183 offset:6528
	ds_read_b128 v[200:203], v183 offset:7616
	s_add_u32 s74, s66, 0x0
	s_addc_u32 s75, s67, 0
	s_waitcnt lgkmcnt(7)
	global_store_dwordx4 v193, v[160:163], s[74:75]
	s_add_u32 s74, s66, 0x4000
	s_addc_u32 s75, s67, 0
	s_waitcnt lgkmcnt(6)
	global_store_dwordx4 v193, v[164:167], s[74:75]
	s_add_u32 s74, s66, 0x8000
	s_addc_u32 s75, s67, 0
	s_waitcnt lgkmcnt(5)
	global_store_dwordx4 v193, v[168:171], s[74:75]
	s_add_u32 s74, s66, 0xc000
	s_addc_u32 s75, s67, 0
	s_waitcnt lgkmcnt(4)
	global_store_dwordx4 v193, v[172:175], s[74:75]
	s_add_u32 s74, s66, 0x10000
	s_addc_u32 s75, s67, 0
	s_waitcnt lgkmcnt(3)
	global_store_dwordx4 v193, v[176:179], s[74:75]
	s_add_u32 s74, s66, 0x14000
	s_addc_u32 s75, s67, 0
	s_waitcnt lgkmcnt(2)
	global_store_dwordx4 v193, v[184:187], s[74:75]
	s_add_u32 s74, s66, 0x18000
	s_addc_u32 s75, s67, 0
	s_waitcnt lgkmcnt(1)
	global_store_dwordx4 v193, v[188:191], s[74:75]
	s_add_u32 s74, s66, 0x1c000
	s_addc_u32 s75, s67, 0
	s_waitcnt lgkmcnt(0)
	global_store_dwordx4 v193, v[200:203], s[74:75]
	s_waitcnt vmcnt(15)
	ds_write_b128 v183, v[128:131]
	s_waitcnt vmcnt(14)
	ds_write_b128 v183, v[132:135] offset:1088
	s_waitcnt vmcnt(13)
; DI bfr f2bf(float a) { return (bfr)(pack2(a, 0.f) & 0xffffu); }
; DI int crow(int reg, int h) { return (reg & 3) + 8 * (reg >> 2) + 4 * h; }
; template <bool FIRST, bool HAS_H>
; DI void phase_gemm_resid(const Params& p, const bfr* A, const bfr* Wt, const float* gnext, float* ss, char* smem) {
;     ...
;     const float* xsrc = FIRST ? p.x_prompt : X;
;     const int rbase = m0 + wr * 64 + 4 * hl, cbase = n0 + wc * 128 + r;
; #pragma unroll
;     for (int i = 0; i < 2; ++i) {
; #pragma unroll
;       for (int qh = 0; qh < 2; ++qh) {
;         float rs[8];
; #pragma unroll
;         for (int q = 0; q < 8; ++q) rs[q] = 0.f;
; #pragma unroll
;         for (int jh = 0; jh < 2; ++jh) {
;           float xo[2][8];
; #pragma unroll
;           for (int jj = 0; jj < 2; ++jj)
; #pragma unroll
;             for (int q = 0; q < 8; ++q)
;               xo[jj][q] = xsrc[(rbase + i * 32 + crow(qh * 8 + q, 0)) * 1024 + cbase + (jh * 2 + jj) * 32];
; #pragma unroll
;           for (int q = 0; q < 8; ++q) {
;             const int o = (rbase + i * 32 + crow(qh * 8 + q, 0)) * 1024 + cbase;
; #pragma unroll
;             for (int jj = 0; jj < 2; ++jj) {
;               const int j = jh * 2 + jj;
;               const float xn = xo[jj][q] + acc[i][j][qh * 8 + q];
;               X[o + j * 32] = xn;
;               if (HAS_H) Hn[o + j * 32] = f2bf(xn * gnext[cbase + j * 32]);
;               rs[q] += xn * xn;
;             }
;           }
;         }
	ds_write_b128 v183, v[136:139] offset:2176
	s_waitcnt vmcnt(12)
	ds_write_b128 v183, v[140:143] offset:3264
	s_waitcnt vmcnt(11)
	ds_write_b128 v183, v[144:147] offset:4352
	s_waitcnt vmcnt(10)
	ds_write_b128 v183, v[148:151] offset:5440
	s_waitcnt vmcnt(9)
	ds_write_b128 v183, v[152:155] offset:6528
	s_waitcnt vmcnt(8)
	ds_write_b128 v183, v[156:159] offset:7616
	s_add_u32 s74, s64, 0x20000
	s_addc_u32 s75, s65, 0
	global_load_dwordx4 v[128:131], v193, s[74:75]
	s_add_u32 s74, s64, 0x24000
	s_addc_u32 s75, s65, 0
	global_load_dwordx4 v[132:135], v193, s[74:75]
	s_add_u32 s74, s64, 0x28000
	s_addc_u32 s75, s65, 0
	global_load_dwordx4 v[136:139], v193, s[74:75]
	s_add_u32 s74, s64, 0x2c000
	s_addc_u32 s75, s65, 0
	global_load_dwordx4 v[140:143], v193, s[74:75]
	s_add_u32 s74, s64, 0x30000
	s_addc_u32 s75, s65, 0
	global_load_dwordx4 v[144:147], v193, s[74:75]
	s_add_u32 s74, s64, 0x34000
	s_addc_u32 s75, s65, 0
	global_load_dwordx4 v[148:151], v193, s[74:75]
	s_add_u32 s74, s64, 0x38000
	s_addc_u32 s75, s65, 0
	global_load_dwordx4 v[152:155], v193, s[74:75]
	s_add_u32 s74, s64, 0x3c000
	s_addc_u32 s75, s65, 0
	global_load_dwordx4 v[156:159], v193, s[74:75]
	ds_read_b128 v[160:163], v180
	ds_read_b128 v[164:167], v180 offset:32
	ds_read_b128 v[168:171], v180 offset:64
	ds_read_b128 v[172:175], v180 offset:96
	ds_read_b128 v[176:179], v180 offset:128
	ds_read_b128 v[184:187], v180 offset:160
	ds_read_b128 v[188:191], v180 offset:192
	ds_read_b128 v[200:203], v180 offset:224
	s_waitcnt lgkmcnt(7)
	v_add_f32_e32 v80, v160, v80
	v_add_f32_e32 v81, v161, v81
	v_add_f32_e32 v82, v162, v82
	v_add_f32_e32 v83, v163, v83
	v_fmac_f32_e32 v205, v80, v80
	v_fmac_f32_e32 v205, v81, v81
	v_fmac_f32_e32 v205, v82, v82
	v_fmac_f32_e32 v205, v83, v83
	ds_write_b128 v180, v[80:83]
	s_waitcnt lgkmcnt(7)
	v_add_f32_e32 v84, v164, v84
	v_add_f32_e32 v85, v165, v85
	v_add_f32_e32 v86, v166, v86
	v_add_f32_e32 v87, v167, v87
	v_fmac_f32_e32 v205, v84, v84
	v_fmac_f32_e32 v205, v85, v85
	v_fmac_f32_e32 v205, v86, v86
	v_fmac_f32_e32 v205, v87, v87
	ds_write_b128 v180, v[84:87] offset:32
	s_waitcnt lgkmcnt(7)
	v_add_f32_e32 v88, v168, v88
	v_add_f32_e32 v89, v169, v89
	v_add_f32_e32 v90, v170, v90
	v_add_f32_e32 v91, v171, v91
	v_fmac_f32_e32 v205, v88, v88
	v_fmac_f32_e32 v205, v89, v89
	v_fmac_f32_e32 v205, v90, v90
	v_fmac_f32_e32 v205, v91, v91
	ds_write_b128 v180, v[88:91] offset:64
	s_waitcnt lgkmcnt(7)
	v_add_f32_e32 v92, v172, v92
	v_add_f32_e32 v93, v173, v93
	v_add_f32_e32 v94, v174, v94
	v_add_f32_e32 v95, v175, v95
	v_fmac_f32_e32 v205, v92, v92
	v_fmac_f32_e32 v205, v93, v93
	v_fmac_f32_e32 v205, v94, v94
	v_fmac_f32_e32 v205, v95, v95
	ds_write_b128 v180, v[92:95] offset:96
	s_waitcnt lgkmcnt(7)
	v_add_f32_e32 v64, v176, v64
	v_add_f32_e32 v65, v177, v65
	v_add_f32_e32 v66, v178, v66
	v_add_f32_e32 v67, v179, v67
	v_fmac_f32_e32 v205, v64, v64
	v_fmac_f32_e32 v205, v65, v65
	v_fmac_f32_e32 v205, v66, v66
	v_fmac_f32_e32 v205, v67, v67
	ds_write_b128 v180, v[64:67] offset:128
	s_waitcnt lgkmcnt(7)
	v_add_f32_e32 v68, v184, v68
	v_add_f32_e32 v69, v185, v69
	v_add_f32_e32 v70, v186, v70
	v_add_f32_e32 v71, v187, v71
	v_fmac_f32_e32 v205, v68, v68
	v_fmac_f32_e32 v205, v69, v69
	v_fmac_f32_e32 v205, v70, v70
	v_fmac_f32_e32 v205, v71, v71
	ds_write_b128 v180, v[68:71] offset:160
	s_waitcnt lgkmcnt(7)
	v_add_f32_e32 v72, v188, v72
	v_add_f32_e32 v73, v189, v73
	v_add_f32_e32 v74, v190, v74
	v_add_f32_e32 v75, v191, v75
	v_fmac_f32_e32 v205, v72, v72
	v_fmac_f32_e32 v205, v73, v73
	v_fmac_f32_e32 v205, v74, v74
	v_fmac_f32_e32 v205, v75, v75
	ds_write_b128 v180, v[72:75] offset:192
	s_waitcnt lgkmcnt(7)
	v_add_f32_e32 v76, v200, v76
	v_add_f32_e32 v77, v201, v77
	v_add_f32_e32 v78, v202, v78
	v_add_f32_e32 v79, v203, v79
	v_fmac_f32_e32 v205, v76, v76
	v_fmac_f32_e32 v205, v77, v77
	v_fmac_f32_e32 v205, v78, v78
	v_fmac_f32_e32 v205, v79, v79
	ds_write_b128 v180, v[76:79] offset:224
	ds_read_b128 v[160:163], v183
	ds_read_b128 v[164:167], v183 offset:1088
	ds_read_b128 v[168:171], v183 offset:2176
	ds_read_b128 v[172:175], v183 offset:3264
	ds_read_b128 v[176:179], v183 offset:4352
	ds_read_b128 v[184:187], v183 offset:5440
	ds_read_b128 v[188:191], v183 offset:6528
	ds_read_b128 v[200:203], v183 offset:7616
	s_add_u32 s74, s66, 0x100
	s_addc_u32 s75, s67, 0
	s_waitcnt lgkmcnt(7)
	global_store_dwordx4 v193, v[160:163], s[74:75]
	s_add_u32 s74, s66, 0x4100
	s_addc_u32 s75, s67, 0
	s_waitcnt lgkmcnt(6)
	global_store_dwordx4 v193, v[164:167], s[74:75]
	s_add_u32 s74, s66, 0x8100
	s_addc_u32 s75, s67, 0
	s_waitcnt lgkmcnt(5)
	global_store_dwordx4 v193, v[168:171], s[74:75]
	s_add_u32 s74, s66, 0xc100
	s_addc_u32 s75, s67, 0
	s_waitcnt lgkmcnt(4)
	global_store_dwordx4 v193, v[172:175], s[74:75]
	s_add_u32 s74, s66, 0x10100
	s_addc_u32 s75, s67, 0
	s_waitcnt lgkmcnt(3)
	global_store_dwordx4 v193, v[176:179], s[74:75]
	s_add_u32 s74, s66, 0x14100
	s_addc_u32 s75, s67, 0
	s_waitcnt lgkmcnt(2)
	global_store_dwordx4 v193, v[184:187], s[74:75]
	s_add_u32 s74, s66, 0x18100
	s_addc_u32 s75, s67, 0
	s_waitcnt lgkmcnt(1)
	global_store_dwordx4 v193, v[188:191], s[74:75]
	s_add_u32 s74, s66, 0x1c100
	s_addc_u32 s75, s67, 0
	s_waitcnt lgkmcnt(0)
	global_store_dwordx4 v193, v[200:203], s[74:75]
	s_waitcnt vmcnt(15)
	ds_write_b128 v183, v[128:131]
	s_waitcnt vmcnt(14)
	ds_write_b128 v183, v[132:135] offset:1088
	s_waitcnt vmcnt(13)
	ds_write_b128 v183, v[136:139] offset:2176
	s_waitcnt vmcnt(12)
	ds_write_b128 v183, v[140:143] offset:3264
	s_waitcnt vmcnt(11)
	ds_write_b128 v183, v[144:147] offset:4352
	s_waitcnt vmcnt(10)
	ds_write_b128 v183, v[148:151] offset:5440
	s_waitcnt vmcnt(9)
; DI bfr f2bf(float a) { return (bfr)(pack2(a, 0.f) & 0xffffu); }
; DI int crow(int reg, int h) { return (reg & 3) + 8 * (reg >> 2) + 4 * h; }
; template <bool FIRST, bool HAS_H>
; DI void phase_gemm_resid(const Params& p, const bfr* A, const bfr* Wt, const float* gnext, float* ss, char* smem) {
;     ...
;     const float* xsrc = FIRST ? p.x_prompt : X;
;     const int rbase = m0 + wr * 64 + 4 * hl, cbase = n0 + wc * 128 + r;
; #pragma unroll
;     for (int i = 0; i < 2; ++i) {
; #pragma unroll
;       for (int qh = 0; qh < 2; ++qh) {
;         float rs[8];
; #pragma unroll
;         for (int q = 0; q < 8; ++q) rs[q] = 0.f;
; #pragma unroll
;         for (int jh = 0; jh < 2; ++jh) {
;           float xo[2][8];
; #pragma unroll
;           for (int jj = 0; jj < 2; ++jj)
; #pragma unroll
;             for (int q = 0; q < 8; ++q)
;               xo[jj][q] = xsrc[(rbase + i * 32 + crow(qh * 8 + q, 0)) * 1024 + cbase + (jh * 2 + jj) * 32];
; #pragma unroll
;           for (int q = 0; q < 8; ++q) {
;             const int o = (rbase + i * 32 + crow(qh * 8 + q, 0)) * 1024 + cbase;
; #pragma unroll
;             for (int jj = 0; jj < 2; ++jj) {
;               const int j = jh * 2 + jj;
;               const float xn = xo[jj][q] + acc[i][j][qh * 8 + q];
;               X[o + j * 32] = xn;
;               if (HAS_H) Hn[o + j * 32] = f2bf(xn * gnext[cbase + j * 32]);
;               rs[q] += xn * xn;
;             }
;           }
;         }
	ds_write_b128 v183, v[152:155] offset:6528
	s_waitcnt vmcnt(8)
	ds_write_b128 v183, v[156:159] offset:7616
	s_add_u32 s74, s64, 0x20100
	s_addc_u32 s75, s65, 0
	global_load_dwordx4 v[128:131], v193, s[74:75]
	s_add_u32 s74, s64, 0x24100
	s_addc_u32 s75, s65, 0
	global_load_dwordx4 v[132:135], v193, s[74:75]
	s_add_u32 s74, s64, 0x28100
	s_addc_u32 s75, s65, 0
	global_load_dwordx4 v[136:139], v193, s[74:75]
	s_add_u32 s74, s64, 0x2c100
	s_addc_u32 s75, s65, 0
	global_load_dwordx4 v[140:143], v193, s[74:75]
	s_add_u32 s74, s64, 0x30100
	s_addc_u32 s75, s65, 0
	global_load_dwordx4 v[144:147], v193, s[74:75]
	s_add_u32 s74, s64, 0x34100
	s_addc_u32 s75, s65, 0
	global_load_dwordx4 v[148:151], v193, s[74:75]
	s_add_u32 s74, s64, 0x38100
	s_addc_u32 s75, s65, 0
	global_load_dwordx4 v[152:155], v193, s[74:75]
	s_add_u32 s74, s64, 0x3c100
	s_addc_u32 s75, s65, 0
	global_load_dwordx4 v[156:159], v193, s[74:75]
	ds_read_b128 v[160:163], v180
	ds_read_b128 v[164:167], v180 offset:32
	ds_read_b128 v[168:171], v180 offset:64
	ds_read_b128 v[172:175], v180 offset:96
	ds_read_b128 v[176:179], v180 offset:128
	ds_read_b128 v[184:187], v180 offset:160
	ds_read_b128 v[188:191], v180 offset:192
	ds_read_b128 v[200:203], v180 offset:224
	s_waitcnt lgkmcnt(7)
	v_add_f32_e32 v48, v160, v48
	v_add_f32_e32 v49, v161, v49
	v_add_f32_e32 v50, v162, v50
	v_add_f32_e32 v51, v163, v51
	v_fmac_f32_e32 v206, v48, v48
	v_fmac_f32_e32 v206, v49, v49
	v_fmac_f32_e32 v206, v50, v50
	v_fmac_f32_e32 v206, v51, v51
	ds_write_b128 v180, v[48:51]
	s_waitcnt lgkmcnt(7)
	v_add_f32_e32 v52, v164, v52
	v_add_f32_e32 v53, v165, v53
	v_add_f32_e32 v54, v166, v54
	v_add_f32_e32 v55, v167, v55
	v_fmac_f32_e32 v206, v52, v52
	v_fmac_f32_e32 v206, v53, v53
	v_fmac_f32_e32 v206, v54, v54
	v_fmac_f32_e32 v206, v55, v55
	ds_write_b128 v180, v[52:55] offset:32
	s_waitcnt lgkmcnt(7)
	v_add_f32_e32 v56, v168, v56
	v_add_f32_e32 v57, v169, v57
	v_add_f32_e32 v58, v170, v58
	v_add_f32_e32 v59, v171, v59
	v_fmac_f32_e32 v206, v56, v56
	v_fmac_f32_e32 v206, v57, v57
	v_fmac_f32_e32 v206, v58, v58
	v_fmac_f32_e32 v206, v59, v59
	ds_write_b128 v180, v[56:59] offset:64
	s_waitcnt lgkmcnt(7)
	v_add_f32_e32 v60, v172, v60
	v_add_f32_e32 v61, v173, v61
	v_add_f32_e32 v62, v174, v62
	v_add_f32_e32 v63, v175, v63
	v_fmac_f32_e32 v206, v60, v60
	v_fmac_f32_e32 v206, v61, v61
	v_fmac_f32_e32 v206, v62, v62
	v_fmac_f32_e32 v206, v63, v63
	ds_write_b128 v180, v[60:63] offset:96
	s_waitcnt lgkmcnt(7)
	v_add_f32_e32 v32, v176, v32
	v_add_f32_e32 v33, v177, v33
	v_add_f32_e32 v34, v178, v34
	v_add_f32_e32 v35, v179, v35
	v_fmac_f32_e32 v206, v32, v32
	v_fmac_f32_e32 v206, v33, v33
	v_fmac_f32_e32 v206, v34, v34
	v_fmac_f32_e32 v206, v35, v35
	ds_write_b128 v180, v[32:35] offset:128
	s_waitcnt lgkmcnt(7)
	v_add_f32_e32 v36, v184, v36
	v_add_f32_e32 v37, v185, v37
	v_add_f32_e32 v38, v186, v38
	v_add_f32_e32 v39, v187, v39
	v_fmac_f32_e32 v206, v36, v36
	v_fmac_f32_e32 v206, v37, v37
	v_fmac_f32_e32 v206, v38, v38
	v_fmac_f32_e32 v206, v39, v39
	ds_write_b128 v180, v[36:39] offset:160
	s_waitcnt lgkmcnt(7)
	v_add_f32_e32 v40, v188, v40
	v_add_f32_e32 v41, v189, v41
	v_add_f32_e32 v42, v190, v42
	v_add_f32_e32 v43, v191, v43
	v_fmac_f32_e32 v206, v40, v40
	v_fmac_f32_e32 v206, v41, v41
	v_fmac_f32_e32 v206, v42, v42
	v_fmac_f32_e32 v206, v43, v43
	ds_write_b128 v180, v[40:43] offset:192
	s_waitcnt lgkmcnt(7)
	v_add_f32_e32 v44, v200, v44
	v_add_f32_e32 v45, v201, v45
	v_add_f32_e32 v46, v202, v46
	v_add_f32_e32 v47, v203, v47
	v_fmac_f32_e32 v206, v44, v44
	v_fmac_f32_e32 v206, v45, v45
	v_fmac_f32_e32 v206, v46, v46
	v_fmac_f32_e32 v206, v47, v47
	ds_write_b128 v180, v[44:47] offset:224
	ds_read_b128 v[160:163], v183
	ds_read_b128 v[164:167], v183 offset:1088
	ds_read_b128 v[168:171], v183 offset:2176
	ds_read_b128 v[172:175], v183 offset:3264
	ds_read_b128 v[176:179], v183 offset:4352
	ds_read_b128 v[184:187], v183 offset:5440
	ds_read_b128 v[188:191], v183 offset:6528
	ds_read_b128 v[200:203], v183 offset:7616
	s_add_u32 s74, s66, 0x20000
	s_addc_u32 s75, s67, 0
	s_waitcnt lgkmcnt(7)
	global_store_dwordx4 v193, v[160:163], s[74:75]
	s_add_u32 s74, s66, 0x24000
	s_addc_u32 s75, s67, 0
	s_waitcnt lgkmcnt(6)
	global_store_dwordx4 v193, v[164:167], s[74:75]
	s_add_u32 s74, s66, 0x28000
	s_addc_u32 s75, s67, 0
	s_waitcnt lgkmcnt(5)
	global_store_dwordx4 v193, v[168:171], s[74:75]
	s_add_u32 s74, s66, 0x2c000
	s_addc_u32 s75, s67, 0
	s_waitcnt lgkmcnt(4)
	global_store_dwordx4 v193, v[172:175], s[74:75]
	s_add_u32 s74, s66, 0x30000
	s_addc_u32 s75, s67, 0
	s_waitcnt lgkmcnt(3)
	global_store_dwordx4 v193, v[176:179], s[74:75]
	s_add_u32 s74, s66, 0x34000
	s_addc_u32 s75, s67, 0
	s_waitcnt lgkmcnt(2)
	global_store_dwordx4 v193, v[184:187], s[74:75]
	s_add_u32 s74, s66, 0x38000
	s_addc_u32 s75, s67, 0
	s_waitcnt lgkmcnt(1)
	global_store_dwordx4 v193, v[188:191], s[74:75]
	s_add_u32 s74, s66, 0x3c000
	s_addc_u32 s75, s67, 0
	s_waitcnt lgkmcnt(0)
	global_store_dwordx4 v193, v[200:203], s[74:75]
	s_waitcnt vmcnt(15)
	ds_write_b128 v183, v[128:131]
	s_waitcnt vmcnt(14)
	ds_write_b128 v183, v[132:135] offset:1088
	s_waitcnt vmcnt(13)
	ds_write_b128 v183, v[136:139] offset:2176
	s_waitcnt vmcnt(12)
; DI bfr f2bf(float a) { return (bfr)(pack2(a, 0.f) & 0xffffu); }
; DI int crow(int reg, int h) { return (reg & 3) + 8 * (reg >> 2) + 4 * h; }
; template <bool FIRST, bool HAS_H>
; DI void phase_gemm_resid(const Params& p, const bfr* A, const bfr* Wt, const float* gnext, float* ss, char* smem) {
;     ...
;     const float* xsrc = FIRST ? p.x_prompt : X;
;     const int rbase = m0 + wr * 64 + 4 * hl, cbase = n0 + wc * 128 + r;
; #pragma unroll
;     for (int i = 0; i < 2; ++i) {
; #pragma unroll
;       for (int qh = 0; qh < 2; ++qh) {
;         float rs[8];
; #pragma unroll
;         for (int q = 0; q < 8; ++q) rs[q] = 0.f;
; #pragma unroll
;         for (int jh = 0; jh < 2; ++jh) {
;           float xo[2][8];
; #pragma unroll
;           for (int jj = 0; jj < 2; ++jj)
; #pragma unroll
;             for (int q = 0; q < 8; ++q)
;               xo[jj][q] = xsrc[(rbase + i * 32 + crow(qh * 8 + q, 0)) * 1024 + cbase + (jh * 2 + jj) * 32];
; #pragma unroll
;           for (int q = 0; q < 8; ++q) {
;             const int o = (rbase + i * 32 + crow(qh * 8 + q, 0)) * 1024 + cbase;
; #pragma unroll
;             for (int jj = 0; jj < 2; ++jj) {
;               const int j = jh * 2 + jj;
;               const float xn = xo[jj][q] + acc[i][j][qh * 8 + q];
;               X[o + j * 32] = xn;
;               if (HAS_H) Hn[o + j * 32] = f2bf(xn * gnext[cbase + j * 32]);
;               rs[q] += xn * xn;
;             }
;           }
;         }
; #pragma unroll
;         for (int q = 0; q < 8; ++q) rs[q] = half32_sum_hi(rs[q]);
;         if (r == 31) {
; #pragma unroll
;           for (int q = 0; q < 8; ++q) unsafeAtomicAdd(ss + rbase + i * 32 + crow(qh * 8 + q, 0), rs[q]);
;         }
	ds_write_b128 v183, v[140:143] offset:3264
	s_waitcnt vmcnt(11)
	ds_write_b128 v183, v[144:147] offset:4352
	s_waitcnt vmcnt(10)
	ds_write_b128 v183, v[148:151] offset:5440
	s_waitcnt vmcnt(9)
	ds_write_b128 v183, v[152:155] offset:6528
	s_waitcnt vmcnt(8)
	ds_write_b128 v183, v[156:159] offset:7616
	ds_read_b128 v[160:163], v180
	ds_read_b128 v[164:167], v180 offset:32
	ds_read_b128 v[168:171], v180 offset:64
	ds_read_b128 v[172:175], v180 offset:96
	ds_read_b128 v[176:179], v180 offset:128
	ds_read_b128 v[184:187], v180 offset:160
	ds_read_b128 v[188:191], v180 offset:192
	ds_read_b128 v[200:203], v180 offset:224
	s_waitcnt lgkmcnt(7)
	v_add_f32_e32 v16, v160, v16
	v_add_f32_e32 v17, v161, v17
	v_add_f32_e32 v18, v162, v18
	v_add_f32_e32 v19, v163, v19
	v_fmac_f32_e32 v206, v16, v16
	v_fmac_f32_e32 v206, v17, v17
	v_fmac_f32_e32 v206, v18, v18
	v_fmac_f32_e32 v206, v19, v19
	ds_write_b128 v180, v[16:19]
	s_waitcnt lgkmcnt(7)
	v_add_f32_e32 v20, v164, v20
	v_add_f32_e32 v21, v165, v21
	v_add_f32_e32 v22, v166, v22
	v_add_f32_e32 v23, v167, v23
	v_fmac_f32_e32 v206, v20, v20
	v_fmac_f32_e32 v206, v21, v21
	v_fmac_f32_e32 v206, v22, v22
	v_fmac_f32_e32 v206, v23, v23
	ds_write_b128 v180, v[20:23] offset:32
	s_waitcnt lgkmcnt(7)
	v_add_f32_e32 v24, v168, v24
	v_add_f32_e32 v25, v169, v25
	v_add_f32_e32 v26, v170, v26
	v_add_f32_e32 v27, v171, v27
	v_fmac_f32_e32 v206, v24, v24
	v_fmac_f32_e32 v206, v25, v25
	v_fmac_f32_e32 v206, v26, v26
	v_fmac_f32_e32 v206, v27, v27
	ds_write_b128 v180, v[24:27] offset:64
	s_waitcnt lgkmcnt(7)
	v_add_f32_e32 v28, v172, v28
	v_add_f32_e32 v29, v173, v29
	v_add_f32_e32 v30, v174, v30
	v_add_f32_e32 v31, v175, v31
	v_fmac_f32_e32 v206, v28, v28
	v_fmac_f32_e32 v206, v29, v29
	v_fmac_f32_e32 v206, v30, v30
	v_fmac_f32_e32 v206, v31, v31
	ds_write_b128 v180, v[28:31] offset:96
	s_waitcnt lgkmcnt(7)
	v_add_f32_e32 v0, v176, v0
	v_add_f32_e32 v1, v177, v1
	v_add_f32_e32 v2, v178, v2
	v_add_f32_e32 v3, v179, v3
	v_fmac_f32_e32 v206, v0, v0
	v_fmac_f32_e32 v206, v1, v1
	v_fmac_f32_e32 v206, v2, v2
	v_fmac_f32_e32 v206, v3, v3
	ds_write_b128 v180, v[0:3] offset:128
	s_waitcnt lgkmcnt(7)
	v_add_f32_e32 v4, v184, v4
	v_add_f32_e32 v5, v185, v5
	v_add_f32_e32 v6, v186, v6
	v_add_f32_e32 v7, v187, v7
	v_fmac_f32_e32 v206, v4, v4
	v_fmac_f32_e32 v206, v5, v5
	v_fmac_f32_e32 v206, v6, v6
	v_fmac_f32_e32 v206, v7, v7
	ds_write_b128 v180, v[4:7] offset:160
	s_waitcnt lgkmcnt(7)
	v_add_f32_e32 v8, v188, v8
	v_add_f32_e32 v9, v189, v9
	v_add_f32_e32 v10, v190, v10
	v_add_f32_e32 v11, v191, v11
	v_fmac_f32_e32 v206, v8, v8
	v_fmac_f32_e32 v206, v9, v9
	v_fmac_f32_e32 v206, v10, v10
	v_fmac_f32_e32 v206, v11, v11
	ds_write_b128 v180, v[8:11] offset:192
	s_waitcnt lgkmcnt(7)
	v_add_f32_e32 v12, v200, v12
	v_add_f32_e32 v13, v201, v13
	v_add_f32_e32 v14, v202, v14
	v_add_f32_e32 v15, v203, v15
	v_fmac_f32_e32 v206, v12, v12
	v_fmac_f32_e32 v206, v13, v13
	v_fmac_f32_e32 v206, v14, v14
	v_fmac_f32_e32 v206, v15, v15
	ds_write_b128 v180, v[12:15] offset:224
	ds_read_b128 v[160:163], v183
	ds_read_b128 v[164:167], v183 offset:1088
	ds_read_b128 v[168:171], v183 offset:2176
	ds_read_b128 v[172:175], v183 offset:3264
	ds_read_b128 v[176:179], v183 offset:4352
	ds_read_b128 v[184:187], v183 offset:5440
	ds_read_b128 v[188:191], v183 offset:6528
	ds_read_b128 v[200:203], v183 offset:7616
	s_add_u32 s74, s66, 0x20100
	s_addc_u32 s75, s67, 0
	s_waitcnt lgkmcnt(7)
	global_store_dwordx4 v193, v[160:163], s[74:75]
	s_add_u32 s74, s66, 0x24100
	s_addc_u32 s75, s67, 0
	s_waitcnt lgkmcnt(6)
	global_store_dwordx4 v193, v[164:167], s[74:75]
	s_add_u32 s74, s66, 0x28100
	s_addc_u32 s75, s67, 0
	s_waitcnt lgkmcnt(5)
	global_store_dwordx4 v193, v[168:171], s[74:75]
	s_add_u32 s74, s66, 0x2c100
	s_addc_u32 s75, s67, 0
	s_waitcnt lgkmcnt(4)
	global_store_dwordx4 v193, v[172:175], s[74:75]
	s_add_u32 s74, s66, 0x30100
	s_addc_u32 s75, s67, 0
	s_waitcnt lgkmcnt(3)
	global_store_dwordx4 v193, v[176:179], s[74:75]
	s_add_u32 s74, s66, 0x34100
	s_addc_u32 s75, s67, 0
	s_waitcnt lgkmcnt(2)
	global_store_dwordx4 v193, v[184:187], s[74:75]
	s_add_u32 s74, s66, 0x38100
	s_addc_u32 s75, s67, 0
	s_waitcnt lgkmcnt(1)
	global_store_dwordx4 v193, v[188:191], s[74:75]
	s_add_u32 s74, s66, 0x3c100
	s_addc_u32 s75, s67, 0
	s_waitcnt lgkmcnt(0)
	global_store_dwordx4 v193, v[200:203], s[74:75]
	s_load_dwordx2 s[64:65], s[92:93], 0x140
	ds_bpermute_b32 v210, v208, v205
	ds_bpermute_b32 v211, v208, v206
	s_waitcnt lgkmcnt(0)
	s_add_u32 s64, s64, 0x30600
	s_addc_u32 s65, s65, 0
	v_add_f32_e32 v210, v210, v205
	v_add_f32_e32 v211, v211, v206
	s_mov_b32 exec_hi, 0
	s_nop 1
	global_atomic_add_f32 v207, v210, s[64:65]
	global_atomic_add_f32 v207, v211, s[64:65] offset:128
	s_mov_b64 exec, -1
	v_readlane_b32 s64, v209, 0
	v_readlane_b32 s65, v209, 1
	v_readlane_b32 s66, v209, 2
	v_readlane_b32 s67, v209, 3
	v_readlane_b32 s68, v209, 4
	v_readlane_b32 s69, v209, 5
	v_readlane_b32 s70, v209, 6
	v_readlane_b32 s71, v209, 7
	v_readlane_b32 s72, v209, 8
	v_readlane_b32 s73, v209, 9
	v_readlane_b32 s74, v209, 10
	v_readlane_b32 s75, v209, 11
	v_readlane_b32 s76, v209, 12
	v_readlane_b32 s77, v209, 13
	v_readlane_b32 s78, v209, 14
	v_readlane_b32 s79, v209, 15
	s_nop 7
	s_branch .LBB0_1718
